# RWKV scan: state carried as S/W within a chunk (running decay products from P1 via permlane32_swap), 32 packed ops per step instead of 40, no decay reads in the step loop; GEMM loop tail counters used
# speedup vs baseline: 1.0296x; 1.0046x over previous
.LBB0_259:
	s_and_b32 s8, s7, 0x4000
	s_xor_b32 s9, s8, 0x4000
	s_lshl_b32 s9, s9, 1
	s_add_i32 s9, s9, 32
	s_add_u32 s90, s52, s4
	s_addc_u32 s91, s53, s5
	s_add_i32 m0, s9, s82
	s_lshl_b32 s8, s8, 1
	global_load_lds_dwordx4 v184, s[90:91]
	s_add_i32 m0, s9, s83
	s_add_i32 s8, s8, 32
	global_load_lds_dwordx4 v185, s[90:91]
	s_add_i32 m0, s9, s84
	v_lshl_add_u32 v64, v120, 1, s8
	global_load_lds_dwordx4 v186, s[90:91]
	s_add_i32 m0, s9, s85
	v_lshl_add_u32 v95, v121, 1, s8
	global_load_lds_dwordx4 v187, s[90:91]
	s_add_i32 m0, s9, s86
	v_add_u32_e32 v166, v64, v142
	global_load_lds_dwordx4 v188, s[90:91]
	s_add_i32 m0, s9, s87
	v_add_u32_e32 v174, v95, v142
	global_load_lds_dwordx4 v189, s[90:91]
	s_add_i32 m0, s9, s88
	s_addk_i32 s7, 0x4000
	global_load_lds_dwordx4 v190, s[90:91]
	s_add_i32 m0, s9, s89
	s_add_u32 s4, s4, 0x80
	s_addc_u32 s5, s5, 0
	global_load_lds_dwordx4 v191, s[90:91]
	ds_read_b128 v[146:149], v166
	ds_read_b128 v[150:153], v166 offset:2048
	ds_read_b128 v[154:157], v174 offset:16384
	ds_read_b128 v[158:161], v174 offset:18432
	ds_read_b128 v[162:165], v166 offset:4096
	ds_read_b128 v[166:169], v166 offset:6144
	ds_read_b128 v[170:173], v174 offset:20480
	ds_read_b128 v[174:177], v174 offset:22528
	s_setprio 1
	s_waitcnt lgkmcnt(0)
	v_mfma_f32_16x16x32_bf16 v[60:63], v[146:149], v[154:157], v[60:63]
	v_mfma_f32_16x16x32_bf16 v[56:59], v[146:149], v[158:161], v[56:59]
	v_mfma_f32_16x16x32_bf16 v[52:55], v[146:149], v[170:173], v[52:55]
	v_mfma_f32_16x16x32_bf16 v[48:51], v[146:149], v[174:177], v[48:51]
	v_mfma_f32_16x16x32_bf16 v[44:47], v[150:153], v[154:157], v[44:47]
	v_mfma_f32_16x16x32_bf16 v[40:43], v[150:153], v[158:161], v[40:43]
	v_mfma_f32_16x16x32_bf16 v[36:39], v[150:153], v[170:173], v[36:39]
	v_mfma_f32_16x16x32_bf16 v[32:35], v[150:153], v[174:177], v[32:35]
	v_mfma_f32_16x16x32_bf16 v[28:31], v[162:165], v[154:157], v[28:31]
	v_mfma_f32_16x16x32_bf16 v[24:27], v[162:165], v[158:161], v[24:27]
	v_mfma_f32_16x16x32_bf16 v[20:23], v[162:165], v[170:173], v[20:23]
	v_mfma_f32_16x16x32_bf16 v[16:19], v[162:165], v[174:177], v[16:19]
	v_mfma_f32_16x16x32_bf16 v[12:15], v[166:169], v[154:157], v[12:15]
	v_mfma_f32_16x16x32_bf16 v[8:11], v[166:169], v[158:161], v[8:11]
	v_mfma_f32_16x16x32_bf16 v[4:7], v[166:169], v[170:173], v[4:7]
	v_mfma_f32_16x16x32_bf16 v[0:3], v[166:169], v[174:177], v[0:3]
	s_setprio 0
	v_add_u32_e32 v64, v64, v143
	v_add_u32_e32 v95, v95, v143
	ds_read_b128 v[146:149], v64
	ds_read_b128 v[150:153], v64 offset:2048
	ds_read_b128 v[154:157], v95 offset:16384
	ds_read_b128 v[158:161], v95 offset:18432
	ds_read_b128 v[162:165], v64 offset:4096
	ds_read_b128 v[166:169], v64 offset:6144
	ds_read_b128 v[170:173], v95 offset:20480
	ds_read_b128 v[174:177], v95 offset:22528
	s_setprio 1
	s_waitcnt lgkmcnt(0)
	v_mfma_f32_16x16x32_bf16 v[60:63], v[146:149], v[154:157], v[60:63]
	v_mfma_f32_16x16x32_bf16 v[56:59], v[146:149], v[158:161], v[56:59]
	v_mfma_f32_16x16x32_bf16 v[52:55], v[146:149], v[170:173], v[52:55]
	v_mfma_f32_16x16x32_bf16 v[48:51], v[146:149], v[174:177], v[48:51]
	v_mfma_f32_16x16x32_bf16 v[44:47], v[150:153], v[154:157], v[44:47]
	v_mfma_f32_16x16x32_bf16 v[40:43], v[150:153], v[158:161], v[40:43]
	v_mfma_f32_16x16x32_bf16 v[36:39], v[150:153], v[170:173], v[36:39]
	v_mfma_f32_16x16x32_bf16 v[32:35], v[150:153], v[174:177], v[32:35]
	v_mfma_f32_16x16x32_bf16 v[28:31], v[162:165], v[154:157], v[28:31]
	v_mfma_f32_16x16x32_bf16 v[24:27], v[162:165], v[158:161], v[24:27]
	v_mfma_f32_16x16x32_bf16 v[20:23], v[162:165], v[170:173], v[20:23]
	v_mfma_f32_16x16x32_bf16 v[16:19], v[162:165], v[174:177], v[16:19]
	v_mfma_f32_16x16x32_bf16 v[12:15], v[166:169], v[154:157], v[12:15]
	v_mfma_f32_16x16x32_bf16 v[8:11], v[166:169], v[158:161], v[8:11]
	v_mfma_f32_16x16x32_bf16 v[4:7], v[166:169], v[170:173], v[4:7]
	v_mfma_f32_16x16x32_bf16 v[0:3], v[166:169], v[174:177], v[0:3]
	s_setprio 0
	s_cmpk_eq_i32 s4, 0x780
	s_waitcnt vmcnt(0)
	s_barrier
	s_cbranch_scc0 .LBB0_259
	ds_read_b128 v[96:99], v122 offset:55296
	ds_read_b128 v[100:103], v122 offset:53248
	ds_read_b128 v[104:107], v123 offset:38912
	ds_read_b128 v[108:111], v123 offset:36864
	ds_read_b128 v[146:149], v122 offset:51200
	ds_read_b128 v[150:153], v122 offset:49152
	ds_read_b128 v[154:157], v123 offset:34816
	ds_read_b128 v[158:161], v123 offset:32768
	s_setprio 1
	s_waitcnt lgkmcnt(3)
	v_mfma_f32_16x16x32_bf16 v[24:27], v[108:111], v[146:149], v[24:27]
	v_mfma_f32_16x16x32_bf16 v[20:23], v[108:111], v[100:103], v[20:23]
	v_mfma_f32_16x16x32_bf16 v[16:19], v[108:111], v[96:99], v[16:19]
	s_waitcnt lgkmcnt(0)
	v_mfma_f32_16x16x32_bf16 v[60:63], v[158:161], v[150:153], v[60:63]
	v_mfma_f32_16x16x32_bf16 v[56:59], v[158:161], v[146:149], v[56:59]
	v_mfma_f32_16x16x32_bf16 v[52:55], v[158:161], v[100:103], v[52:55]
	v_mfma_f32_16x16x32_bf16 v[48:51], v[158:161], v[96:99], v[48:51]
	v_mfma_f32_16x16x32_bf16 v[44:47], v[154:157], v[150:153], v[44:47]
	v_mfma_f32_16x16x32_bf16 v[40:43], v[154:157], v[146:149], v[40:43]
	v_mfma_f32_16x16x32_bf16 v[36:39], v[154:157], v[100:103], v[36:39]
	v_mfma_f32_16x16x32_bf16 v[32:35], v[154:157], v[96:99], v[32:35]
	v_mfma_f32_16x16x32_bf16 v[28:31], v[108:111], v[150:153], v[28:31]
	v_mfma_f32_16x16x32_bf16 v[12:15], v[104:107], v[150:153], v[12:15]
	v_mfma_f32_16x16x32_bf16 v[8:11], v[104:107], v[146:149], v[8:11]
	v_mfma_f32_16x16x32_bf16 v[4:7], v[104:107], v[100:103], v[4:7]
	v_mfma_f32_16x16x32_bf16 v[0:3], v[104:107], v[96:99], v[0:3]
	s_setprio 0
	ds_read_b128 v[96:99], v124 offset:32768
	ds_read_b128 v[100:103], v124 offset:34816
	ds_read_b128 v[104:107], v125 offset:49152
	ds_read_b128 v[108:111], v125 offset:51200
	ds_read_b128 v[146:149], v124 offset:36864
	ds_read_b128 v[150:153], v124 offset:38912
	ds_read_b128 v[154:157], v125 offset:53248
	ds_read_b128 v[158:161], v125 offset:55296
	s_setprio 1
	s_waitcnt lgkmcnt(3)
	v_mfma_f32_16x16x32_bf16 v[24:27], v[146:149], v[108:111], v[24:27]
	s_waitcnt lgkmcnt(1)
	v_mfma_f32_16x16x32_bf16 v[20:23], v[146:149], v[154:157], v[20:23]
	s_waitcnt lgkmcnt(0)
	v_mfma_f32_16x16x32_bf16 v[16:19], v[146:149], v[158:161], v[16:19]
	v_mfma_f32_16x16x32_bf16 v[60:63], v[96:99], v[104:107], v[60:63]
	v_mfma_f32_16x16x32_bf16 v[56:59], v[96:99], v[108:111], v[56:59]
	v_mfma_f32_16x16x32_bf16 v[52:55], v[96:99], v[154:157], v[52:55]
	v_mfma_f32_16x16x32_bf16 v[48:51], v[96:99], v[158:161], v[48:51]
	v_mfma_f32_16x16x32_bf16 v[44:47], v[100:103], v[104:107], v[44:47]
	v_mfma_f32_16x16x32_bf16 v[40:43], v[100:103], v[108:111], v[40:43]
	v_mfma_f32_16x16x32_bf16 v[36:39], v[100:103], v[154:157], v[36:39]
	v_mfma_f32_16x16x32_bf16 v[32:35], v[100:103], v[158:161], v[32:35]
	v_mfma_f32_16x16x32_bf16 v[28:31], v[146:149], v[104:107], v[28:31]
	v_mfma_f32_16x16x32_bf16 v[12:15], v[150:153], v[104:107], v[12:15]
	v_mfma_f32_16x16x32_bf16 v[8:11], v[150:153], v[108:111], v[8:11]
	v_mfma_f32_16x16x32_bf16 v[4:7], v[150:153], v[154:157], v[4:7]
	v_mfma_f32_16x16x32_bf16 v[0:3], v[150:153], v[158:161], v[0:3]
	s_setprio 0
	s_barrier
	ds_write2_b32 v126, v60, v56 offset1:16
	ds_write2_b32 v126, v61, v57 offset0:132 offset1:148
	v_add_u32_e32 v56, 0x400, v126
	ds_write2_b32 v56, v62, v58 offset0:8 offset1:24
	ds_write2_b32 v56, v63, v59 offset0:140 offset1:156
	ds_write2_b32 v126, v52, v48 offset0:32 offset1:48
	ds_write2_b32 v126, v53, v49 offset0:164 offset1:180
	ds_write2_b32 v56, v54, v50 offset0:40 offset1:56
	ds_write2_b32 v56, v55, v51 offset0:172 offset1:188
	v_add_u32_e32 v48, 0x2000, v126
	ds_write2_b32 v48, v44, v40 offset0:64 offset1:80
	ds_write2_b32 v48, v45, v41 offset0:196 offset1:212
	v_add_u32_e32 v40, 0x2400, v126
	ds_write2_b32 v40, v46, v42 offset0:72 offset1:88
	ds_write2_b32 v40, v47, v43 offset0:204 offset1:220
	ds_write2_b32 v48, v36, v32 offset0:96 offset1:112
	ds_write2_b32 v48, v37, v33 offset0:228 offset1:244
	ds_write2_b32 v40, v38, v34 offset0:104 offset1:120
	ds_write2_b32 v40, v39, v35 offset0:236 offset1:252
	v_add_u32_e32 v32, 0x4000, v126
	ds_write2_b32 v32, v28, v24 offset0:128 offset1:144
	v_add_u32_e32 v24, 0x4400, v126
	ds_write2_b32 v24, v29, v25 offset0:4 offset1:20
	ds_write2_b32 v24, v30, v26 offset0:136 offset1:152
	v_add_u32_e32 v25, 0x4800, v126
	ds_write2_b32 v25, v31, v27 offset0:12 offset1:28
	ds_write2_b32 v32, v20, v16 offset0:160 offset1:176
	ds_write2_b32 v24, v21, v17 offset0:36 offset1:52
	ds_write2_b32 v24, v22, v18 offset0:168 offset1:184
	ds_write2_b32 v25, v23, v19 offset0:44 offset1:60
	v_add_u32_e32 v16, 0x6000, v126
	ds_write2_b32 v16, v12, v8 offset0:192 offset1:208
	v_add_u32_e32 v8, 0x6400, v126
	ds_write2_b32 v8, v13, v9 offset0:68 offset1:84
	ds_write2_b32 v8, v14, v10 offset0:200 offset1:216
	v_add_u32_e32 v9, 0x6800, v126
	v_or_b32_e32 v64, s6, v127
	ds_write2_b32 v9, v15, v11 offset0:76 offset1:92
	ds_write2_b32 v16, v4, v0 offset0:224 offset1:240
	ds_write2_b32 v8, v5, v1 offset0:100 offset1:116
	ds_write2_b32 v8, v6, v2 offset0:232 offset1:248
	ds_write2_b32 v9, v7, v3 offset0:108 offset1:124
	v_ashrrev_i32_e32 v1, 31, v64
	v_mov_b32_e32 v0, v64
	v_lshlrev_b64 v[2:3], 1, v[64:65]
	v_lshl_add_u64 v[20:21], v[0:1], 1, s[10:11]
	v_mov_b32_e32 v0, s15
	v_mov_b32_e32 v1, s13
	v_cmp_gt_i32_e64 s[8:9], s38, v64
	v_lshl_add_u64 v[16:17], s[18:19], 0, v[2:3]
	v_lshl_add_u64 v[18:19], s[16:17], 0, v[2:3]
	v_cndmask_b32_e64 v1, v0, v1, s[8:9]
	v_mov_b32_e32 v0, s14
	v_mov_b32_e32 v2, s12
	v_cndmask_b32_e64 v0, v0, v2, s[8:9]
	v_mov_b32_e32 v95, v65
	v_cmp_lt_i32_e64 s[4:5], s39, v64
	v_cmp_lt_i32_e64 s[6:7], s40, v64
	v_lshl_add_u64 v[22:23], v[0:1], 0, v[94:95]
	v_add_u32_e32 v24, s30, v135
	s_mov_b32 s45, 0
	s_waitcnt lgkmcnt(0)
	s_barrier
	s_branch .LBB0_263

.LBB0_278:
	s_and_b32 s8, s7, 0x4000
	s_xor_b32 s9, s8, 0x4000
	s_lshl_b32 s9, s9, 1
	s_add_i32 s9, s9, 32
	s_add_u32 s90, s52, s4
	s_addc_u32 s91, s53, s5
	s_add_i32 m0, s9, s82
	s_lshl_b32 s8, s8, 1
	global_load_lds_dwordx4 v184, s[90:91]
	s_add_i32 m0, s9, s83
	s_add_i32 s8, s8, 32
	global_load_lds_dwordx4 v185, s[90:91]
	s_add_i32 m0, s9, s84
	v_lshl_add_u32 v64, v121, 1, s8
	global_load_lds_dwordx4 v186, s[90:91]
	s_add_i32 m0, s9, s85
	v_lshl_add_u32 v95, v122, 1, s8
	global_load_lds_dwordx4 v187, s[90:91]
	s_add_i32 m0, s9, s86
	v_add_u32_e32 v164, v64, v139
	global_load_lds_dwordx4 v188, s[90:91]
	s_add_i32 m0, s9, s87
	v_add_u32_e32 v172, v95, v139
	global_load_lds_dwordx4 v189, s[90:91]
	s_add_i32 m0, s9, s88
	s_addk_i32 s7, 0x4000
	global_load_lds_dwordx4 v190, s[90:91]
	s_add_i32 m0, s9, s89
	s_add_u32 s4, s4, 0x80
	s_addc_u32 s5, s5, 0
	global_load_lds_dwordx4 v191, s[90:91]
	ds_read_b128 v[144:147], v164
	ds_read_b128 v[148:151], v164 offset:2048
	ds_read_b128 v[152:155], v172 offset:16384
	ds_read_b128 v[156:159], v172 offset:18432
	ds_read_b128 v[160:163], v164 offset:4096
	ds_read_b128 v[164:167], v164 offset:6144
	ds_read_b128 v[168:171], v172 offset:20480
	ds_read_b128 v[172:175], v172 offset:22528
	s_setprio 1
	s_waitcnt lgkmcnt(0)
	v_mfma_f32_16x16x32_bf16 v[60:63], v[144:147], v[152:155], v[60:63]
	v_mfma_f32_16x16x32_bf16 v[56:59], v[144:147], v[156:159], v[56:59]
	v_mfma_f32_16x16x32_bf16 v[52:55], v[144:147], v[168:171], v[52:55]
	v_mfma_f32_16x16x32_bf16 v[48:51], v[144:147], v[172:175], v[48:51]
	v_mfma_f32_16x16x32_bf16 v[44:47], v[148:151], v[152:155], v[44:47]
	v_mfma_f32_16x16x32_bf16 v[40:43], v[148:151], v[156:159], v[40:43]
	v_mfma_f32_16x16x32_bf16 v[36:39], v[148:151], v[168:171], v[36:39]
	v_mfma_f32_16x16x32_bf16 v[32:35], v[148:151], v[172:175], v[32:35]
	v_mfma_f32_16x16x32_bf16 v[28:31], v[160:163], v[152:155], v[28:31]
	v_mfma_f32_16x16x32_bf16 v[24:27], v[160:163], v[156:159], v[24:27]
	v_mfma_f32_16x16x32_bf16 v[20:23], v[160:163], v[168:171], v[20:23]
	v_mfma_f32_16x16x32_bf16 v[16:19], v[160:163], v[172:175], v[16:19]
	v_mfma_f32_16x16x32_bf16 v[12:15], v[164:167], v[152:155], v[12:15]
	v_mfma_f32_16x16x32_bf16 v[8:11], v[164:167], v[156:159], v[8:11]
	v_mfma_f32_16x16x32_bf16 v[4:7], v[164:167], v[168:171], v[4:7]
	v_mfma_f32_16x16x32_bf16 v[0:3], v[164:167], v[172:175], v[0:3]
	s_setprio 0
	v_add_u32_e32 v64, v64, v140
	v_add_u32_e32 v95, v95, v140
	ds_read_b128 v[144:147], v64
	ds_read_b128 v[148:151], v64 offset:2048
	ds_read_b128 v[152:155], v95 offset:16384
	ds_read_b128 v[156:159], v95 offset:18432
	ds_read_b128 v[160:163], v64 offset:4096
	ds_read_b128 v[164:167], v64 offset:6144
	ds_read_b128 v[168:171], v95 offset:20480
	ds_read_b128 v[172:175], v95 offset:22528
	s_setprio 1
	s_waitcnt lgkmcnt(0)
	v_mfma_f32_16x16x32_bf16 v[60:63], v[144:147], v[152:155], v[60:63]
	v_mfma_f32_16x16x32_bf16 v[56:59], v[144:147], v[156:159], v[56:59]
	v_mfma_f32_16x16x32_bf16 v[52:55], v[144:147], v[168:171], v[52:55]
	v_mfma_f32_16x16x32_bf16 v[48:51], v[144:147], v[172:175], v[48:51]
	v_mfma_f32_16x16x32_bf16 v[44:47], v[148:151], v[152:155], v[44:47]
	v_mfma_f32_16x16x32_bf16 v[40:43], v[148:151], v[156:159], v[40:43]
	v_mfma_f32_16x16x32_bf16 v[36:39], v[148:151], v[168:171], v[36:39]
	v_mfma_f32_16x16x32_bf16 v[32:35], v[148:151], v[172:175], v[32:35]
	v_mfma_f32_16x16x32_bf16 v[28:31], v[160:163], v[152:155], v[28:31]
	v_mfma_f32_16x16x32_bf16 v[24:27], v[160:163], v[156:159], v[24:27]
	v_mfma_f32_16x16x32_bf16 v[20:23], v[160:163], v[168:171], v[20:23]
	v_mfma_f32_16x16x32_bf16 v[16:19], v[160:163], v[172:175], v[16:19]
	v_mfma_f32_16x16x32_bf16 v[12:15], v[164:167], v[152:155], v[12:15]
	v_mfma_f32_16x16x32_bf16 v[8:11], v[164:167], v[156:159], v[8:11]
	v_mfma_f32_16x16x32_bf16 v[4:7], v[164:167], v[168:171], v[4:7]
	v_mfma_f32_16x16x32_bf16 v[0:3], v[164:167], v[172:175], v[0:3]
	s_setprio 0
	s_cmpk_eq_i32 s4, 0x780
	s_waitcnt vmcnt(0)
	s_barrier
	s_cbranch_scc0 .LBB0_278
	ds_read_b128 v[96:99], v123 offset:55296
	ds_read_b128 v[100:103], v123 offset:53248
	ds_read_b128 v[104:107], v124 offset:38912
	ds_read_b128 v[108:111], v124 offset:36864
	ds_read_b128 v[144:147], v123 offset:51200
	ds_read_b128 v[148:151], v123 offset:49152
	ds_read_b128 v[152:155], v124 offset:34816
	ds_read_b128 v[156:159], v124 offset:32768
	s_setprio 1
	s_waitcnt lgkmcnt(3)
	v_mfma_f32_16x16x32_bf16 v[24:27], v[108:111], v[144:147], v[24:27]
	v_mfma_f32_16x16x32_bf16 v[20:23], v[108:111], v[100:103], v[20:23]
	v_mfma_f32_16x16x32_bf16 v[16:19], v[108:111], v[96:99], v[16:19]
	s_waitcnt lgkmcnt(0)
	v_mfma_f32_16x16x32_bf16 v[60:63], v[156:159], v[148:151], v[60:63]
	v_mfma_f32_16x16x32_bf16 v[56:59], v[156:159], v[144:147], v[56:59]
	v_mfma_f32_16x16x32_bf16 v[52:55], v[156:159], v[100:103], v[52:55]
	v_mfma_f32_16x16x32_bf16 v[48:51], v[156:159], v[96:99], v[48:51]
	v_mfma_f32_16x16x32_bf16 v[44:47], v[152:155], v[148:151], v[44:47]
	v_mfma_f32_16x16x32_bf16 v[40:43], v[152:155], v[144:147], v[40:43]
	v_mfma_f32_16x16x32_bf16 v[36:39], v[152:155], v[100:103], v[36:39]
	v_mfma_f32_16x16x32_bf16 v[32:35], v[152:155], v[96:99], v[32:35]
	v_mfma_f32_16x16x32_bf16 v[28:31], v[108:111], v[148:151], v[28:31]
	v_mfma_f32_16x16x32_bf16 v[12:15], v[104:107], v[148:151], v[12:15]
	v_mfma_f32_16x16x32_bf16 v[8:11], v[104:107], v[144:147], v[8:11]
	v_mfma_f32_16x16x32_bf16 v[4:7], v[104:107], v[100:103], v[4:7]
	v_mfma_f32_16x16x32_bf16 v[0:3], v[104:107], v[96:99], v[0:3]
	s_setprio 0
	ds_read_b128 v[96:99], v125 offset:32768
	ds_read_b128 v[100:103], v125 offset:34816
	ds_read_b128 v[104:107], v126 offset:49152
	ds_read_b128 v[108:111], v126 offset:51200
	ds_read_b128 v[144:147], v125 offset:36864
	ds_read_b128 v[148:151], v125 offset:38912
	ds_read_b128 v[152:155], v126 offset:53248
	ds_read_b128 v[156:159], v126 offset:55296
	s_setprio 1
	s_waitcnt lgkmcnt(3)
	v_mfma_f32_16x16x32_bf16 v[24:27], v[144:147], v[108:111], v[24:27]
	s_waitcnt lgkmcnt(1)
	v_mfma_f32_16x16x32_bf16 v[20:23], v[144:147], v[152:155], v[20:23]
	s_waitcnt lgkmcnt(0)
	v_mfma_f32_16x16x32_bf16 v[16:19], v[144:147], v[156:159], v[16:19]
	v_mfma_f32_16x16x32_bf16 v[60:63], v[96:99], v[104:107], v[60:63]
	v_mfma_f32_16x16x32_bf16 v[56:59], v[96:99], v[108:111], v[56:59]
	v_mfma_f32_16x16x32_bf16 v[52:55], v[96:99], v[152:155], v[52:55]
	v_mfma_f32_16x16x32_bf16 v[48:51], v[96:99], v[156:159], v[48:51]
	v_mfma_f32_16x16x32_bf16 v[44:47], v[100:103], v[104:107], v[44:47]
	v_mfma_f32_16x16x32_bf16 v[40:43], v[100:103], v[108:111], v[40:43]
	v_mfma_f32_16x16x32_bf16 v[36:39], v[100:103], v[152:155], v[36:39]
	v_mfma_f32_16x16x32_bf16 v[32:35], v[100:103], v[156:159], v[32:35]
	v_mfma_f32_16x16x32_bf16 v[28:31], v[144:147], v[104:107], v[28:31]
	v_mfma_f32_16x16x32_bf16 v[12:15], v[148:151], v[104:107], v[12:15]
	v_mfma_f32_16x16x32_bf16 v[8:11], v[148:151], v[108:111], v[8:11]
	v_mfma_f32_16x16x32_bf16 v[4:7], v[148:151], v[152:155], v[4:7]
	v_mfma_f32_16x16x32_bf16 v[0:3], v[148:151], v[156:159], v[0:3]
	s_setprio 0
	s_barrier
	ds_write2_b32 v127, v60, v56 offset1:16
	ds_write2_b32 v127, v61, v57 offset0:132 offset1:148
	v_add_u32_e32 v56, 0x400, v127
	ds_write2_b32 v56, v62, v58 offset0:8 offset1:24
	ds_write2_b32 v56, v63, v59 offset0:140 offset1:156
	ds_write2_b32 v127, v52, v48 offset0:32 offset1:48
	ds_write2_b32 v127, v53, v49 offset0:164 offset1:180
	ds_write2_b32 v56, v54, v50 offset0:40 offset1:56
	ds_write2_b32 v56, v55, v51 offset0:172 offset1:188
	v_add_u32_e32 v48, 0x2000, v127
	ds_write2_b32 v48, v44, v40 offset0:64 offset1:80
	ds_write2_b32 v48, v45, v41 offset0:196 offset1:212
	v_add_u32_e32 v40, 0x2400, v127
	ds_write2_b32 v40, v46, v42 offset0:72 offset1:88
	ds_write2_b32 v40, v47, v43 offset0:204 offset1:220
	ds_write2_b32 v48, v36, v32 offset0:96 offset1:112
	ds_write2_b32 v48, v37, v33 offset0:228 offset1:244
	ds_write2_b32 v40, v38, v34 offset0:104 offset1:120
	ds_write2_b32 v40, v39, v35 offset0:236 offset1:252
	v_add_u32_e32 v32, 0x4000, v127
	ds_write2_b32 v32, v28, v24 offset0:128 offset1:144
	v_add_u32_e32 v24, 0x4400, v127
	ds_write2_b32 v24, v29, v25 offset0:4 offset1:20
	ds_write2_b32 v24, v30, v26 offset0:136 offset1:152
	v_add_u32_e32 v25, 0x4800, v127
	ds_write2_b32 v25, v31, v27 offset0:12 offset1:28
	ds_write2_b32 v32, v20, v16 offset0:160 offset1:176
	ds_write2_b32 v24, v21, v17 offset0:36 offset1:52
	ds_write2_b32 v24, v22, v18 offset0:168 offset1:184
	ds_write2_b32 v25, v23, v19 offset0:44 offset1:60
	v_add_u32_e32 v16, 0x6000, v127
	ds_write2_b32 v16, v12, v8 offset0:192 offset1:208
	v_add_u32_e32 v8, 0x6400, v127
	ds_write2_b32 v8, v13, v9 offset0:68 offset1:84
	ds_write2_b32 v8, v14, v10 offset0:200 offset1:216
	v_add_u32_e32 v9, 0x6800, v127
	v_or_b32_e32 v64, s6, v128
	ds_write2_b32 v9, v15, v11 offset0:76 offset1:92
	ds_write2_b32 v16, v4, v0 offset0:224 offset1:240
	ds_write2_b32 v8, v5, v1 offset0:100 offset1:116
	ds_write2_b32 v8, v6, v2 offset0:232 offset1:248
	ds_write2_b32 v9, v7, v3 offset0:108 offset1:124
	v_ashrrev_i32_e32 v1, 31, v64
	v_mov_b32_e32 v0, v64
	v_lshlrev_b64 v[2:3], 1, v[64:65]
	v_lshl_add_u64 v[20:21], v[0:1], 1, s[10:11]
	v_mov_b32_e32 v0, s15
	v_mov_b32_e32 v1, s13
	v_cmp_gt_i32_e64 s[8:9], s24, v64
	v_lshl_add_u64 v[16:17], s[18:19], 0, v[2:3]
	v_lshl_add_u64 v[18:19], s[16:17], 0, v[2:3]
	v_cndmask_b32_e64 v1, v0, v1, s[8:9]
	v_mov_b32_e32 v0, s14
	v_mov_b32_e32 v2, s12
	v_cndmask_b32_e64 v0, v0, v2, s[8:9]
	v_mov_b32_e32 v95, v65
	v_cmp_lt_i32_e64 s[4:5], s26, v64
	v_cmp_lt_i32_e64 s[6:7], s27, v64
	v_lshl_add_u64 v[22:23], v[0:1], 0, v[94:95]
	v_add_u32_e32 v24, v132, v143
	s_mov_b32 s35, 0
	s_waitcnt lgkmcnt(0)
	s_barrier
	s_branch .LBB0_282

.LBB0_423:
	s_and_b32 s25, s24, 0x4000
	s_xor_b32 s26, s25, 0x4000
	s_lshl_b32 s26, s26, 1
	s_add_i32 s26, s26, 32
	s_add_u32 s90, s52, s14
	s_addc_u32 s91, s53, s15
	s_add_i32 m0, s26, s82
	s_lshl_b32 s25, s25, 1
	global_load_lds_dwordx4 v188, s[90:91]
	s_add_i32 m0, s26, s83
	s_add_i32 s25, s25, 32
	global_load_lds_dwordx4 v189, s[90:91]
	s_add_i32 m0, s26, s84
	v_add3_u32 v170, s25, v114, v135
	global_load_lds_dwordx4 v190, s[90:91]
	s_add_i32 m0, s26, s85
	v_add3_u32 v171, s25, v115, v135
	global_load_lds_dwordx4 v191, s[90:91]
	s_add_i32 m0, s26, s86
	v_add_u32_e32 v158, v170, v136
	global_load_lds_dwordx4 v192, s[90:91]
	s_add_i32 m0, s26, s87
	v_add_u32_e32 v166, v171, v136
	global_load_lds_dwordx4 v193, s[90:91]
	s_add_i32 m0, s26, s88
	s_addk_i32 s24, 0x4000
	global_load_lds_dwordx4 v194, s[90:91]
	s_add_i32 m0, s26, s89
	s_add_u32 s14, s14, 0x80
	s_addc_u32 s15, s15, 0
	global_load_lds_dwordx4 v195, s[90:91]
	ds_read_b128 v[138:141], v158
	ds_read_b128 v[142:145], v158 offset:2048
	ds_read_b128 v[146:149], v166 offset:16384
	ds_read_b128 v[150:153], v166 offset:18432
	ds_read_b128 v[154:157], v158 offset:4096
	ds_read_b128 v[158:161], v158 offset:6144
	ds_read_b128 v[162:165], v166 offset:20480
	ds_read_b128 v[166:169], v166 offset:22528
	s_setprio 1
	s_waitcnt lgkmcnt(0)
	v_mfma_f32_16x16x32_bf16 v[60:63], v[138:141], v[146:149], v[60:63]
	v_mfma_f32_16x16x32_bf16 v[56:59], v[138:141], v[150:153], v[56:59]
	v_mfma_f32_16x16x32_bf16 v[52:55], v[138:141], v[162:165], v[52:55]
	v_mfma_f32_16x16x32_bf16 v[48:51], v[138:141], v[166:169], v[48:51]
	v_mfma_f32_16x16x32_bf16 v[44:47], v[142:145], v[146:149], v[44:47]
	v_mfma_f32_16x16x32_bf16 v[40:43], v[142:145], v[150:153], v[40:43]
	v_mfma_f32_16x16x32_bf16 v[36:39], v[142:145], v[162:165], v[36:39]
	v_mfma_f32_16x16x32_bf16 v[32:35], v[142:145], v[166:169], v[32:35]
	v_mfma_f32_16x16x32_bf16 v[28:31], v[154:157], v[146:149], v[28:31]
	v_mfma_f32_16x16x32_bf16 v[24:27], v[154:157], v[150:153], v[24:27]
	v_mfma_f32_16x16x32_bf16 v[20:23], v[154:157], v[162:165], v[20:23]
	v_mfma_f32_16x16x32_bf16 v[16:19], v[154:157], v[166:169], v[16:19]
	v_mfma_f32_16x16x32_bf16 v[12:15], v[158:161], v[146:149], v[12:15]
	v_mfma_f32_16x16x32_bf16 v[8:11], v[158:161], v[150:153], v[8:11]
	v_mfma_f32_16x16x32_bf16 v[4:7], v[158:161], v[162:165], v[4:7]
	v_mfma_f32_16x16x32_bf16 v[0:3], v[158:161], v[166:169], v[0:3]
	s_setprio 0
	v_add_u32_e32 v158, v170, v137
	v_add_u32_e32 v166, v171, v137
	ds_read_b128 v[138:141], v158
	ds_read_b128 v[142:145], v158 offset:2048
	ds_read_b128 v[146:149], v166 offset:16384
	ds_read_b128 v[150:153], v166 offset:18432
	ds_read_b128 v[154:157], v158 offset:4096
	ds_read_b128 v[158:161], v158 offset:6144
	ds_read_b128 v[162:165], v166 offset:20480
	ds_read_b128 v[166:169], v166 offset:22528
	s_setprio 1
	s_waitcnt lgkmcnt(0)
	v_mfma_f32_16x16x32_bf16 v[60:63], v[138:141], v[146:149], v[60:63]
	v_mfma_f32_16x16x32_bf16 v[56:59], v[138:141], v[150:153], v[56:59]
	v_mfma_f32_16x16x32_bf16 v[52:55], v[138:141], v[162:165], v[52:55]
	v_mfma_f32_16x16x32_bf16 v[48:51], v[138:141], v[166:169], v[48:51]
	v_mfma_f32_16x16x32_bf16 v[44:47], v[142:145], v[146:149], v[44:47]
	v_mfma_f32_16x16x32_bf16 v[40:43], v[142:145], v[150:153], v[40:43]
	v_mfma_f32_16x16x32_bf16 v[36:39], v[142:145], v[162:165], v[36:39]
	v_mfma_f32_16x16x32_bf16 v[32:35], v[142:145], v[166:169], v[32:35]
	v_mfma_f32_16x16x32_bf16 v[28:31], v[154:157], v[146:149], v[28:31]
	v_mfma_f32_16x16x32_bf16 v[24:27], v[154:157], v[150:153], v[24:27]
	v_mfma_f32_16x16x32_bf16 v[20:23], v[154:157], v[162:165], v[20:23]
	v_mfma_f32_16x16x32_bf16 v[16:19], v[154:157], v[166:169], v[16:19]
	v_mfma_f32_16x16x32_bf16 v[12:15], v[158:161], v[146:149], v[12:15]
	v_mfma_f32_16x16x32_bf16 v[8:11], v[158:161], v[150:153], v[8:11]
	v_mfma_f32_16x16x32_bf16 v[4:7], v[158:161], v[162:165], v[4:7]
	v_mfma_f32_16x16x32_bf16 v[0:3], v[158:161], v[166:169], v[0:3]
	s_setprio 0
	s_cmpk_eq_i32 s14, 0x780
	s_waitcnt vmcnt(0)
	s_barrier
	s_cbranch_scc0 .LBB0_423
	ds_read_b128 v[90:93], v118 offset:55296
	ds_read_b128 v[94:97], v118 offset:53248
	ds_read_b128 v[98:101], v119 offset:38912
	ds_read_b128 v[102:105], v119 offset:36864
	ds_read_b128 v[138:141], v118 offset:51200
	ds_read_b128 v[142:145], v118 offset:49152
	ds_read_b128 v[146:149], v119 offset:34816
	ds_read_b128 v[150:153], v119 offset:32768
	s_setprio 1
	s_waitcnt lgkmcnt(5)
	v_mfma_f32_16x16x32_bf16 v[4:7], v[98:101], v[94:97], v[4:7]
	v_mfma_f32_16x16x32_bf16 v[0:3], v[98:101], v[90:93], v[0:3]
	s_waitcnt lgkmcnt(0)
	v_mfma_f32_16x16x32_bf16 v[60:63], v[150:153], v[142:145], v[60:63]
	v_mfma_f32_16x16x32_bf16 v[56:59], v[150:153], v[138:141], v[56:59]
	v_mfma_f32_16x16x32_bf16 v[52:55], v[150:153], v[94:97], v[52:55]
	v_mfma_f32_16x16x32_bf16 v[48:51], v[150:153], v[90:93], v[48:51]
	v_mfma_f32_16x16x32_bf16 v[44:47], v[146:149], v[142:145], v[44:47]
	v_mfma_f32_16x16x32_bf16 v[40:43], v[146:149], v[138:141], v[40:43]
	v_mfma_f32_16x16x32_bf16 v[36:39], v[146:149], v[94:97], v[36:39]
	v_mfma_f32_16x16x32_bf16 v[32:35], v[146:149], v[90:93], v[32:35]
	v_mfma_f32_16x16x32_bf16 v[28:31], v[102:105], v[142:145], v[28:31]
	v_mfma_f32_16x16x32_bf16 v[24:27], v[102:105], v[138:141], v[24:27]
	v_mfma_f32_16x16x32_bf16 v[20:23], v[102:105], v[94:97], v[20:23]
	v_mfma_f32_16x16x32_bf16 v[16:19], v[102:105], v[90:93], v[16:19]
	v_mfma_f32_16x16x32_bf16 v[12:15], v[98:101], v[142:145], v[12:15]
	v_mfma_f32_16x16x32_bf16 v[8:11], v[98:101], v[138:141], v[8:11]
	s_setprio 0
	ds_read_b128 v[90:93], v120 offset:32768
	ds_read_b128 v[94:97], v120 offset:34816
	ds_read_b128 v[98:101], v121 offset:49152
	ds_read_b128 v[102:105], v121 offset:51200
	ds_read_b128 v[138:141], v120 offset:36864
	ds_read_b128 v[142:145], v120 offset:38912
	ds_read_b128 v[146:149], v121 offset:53248
	ds_read_b128 v[150:153], v121 offset:55296
	s_setprio 1
	s_waitcnt lgkmcnt(1)
	v_mfma_f32_16x16x32_bf16 v[4:7], v[142:145], v[146:149], v[4:7]
	s_waitcnt lgkmcnt(0)
	v_mfma_f32_16x16x32_bf16 v[0:3], v[142:145], v[150:153], v[0:3]
	v_mfma_f32_16x16x32_bf16 v[60:63], v[90:93], v[98:101], v[60:63]
	v_mfma_f32_16x16x32_bf16 v[56:59], v[90:93], v[102:105], v[56:59]
	v_mfma_f32_16x16x32_bf16 v[52:55], v[90:93], v[146:149], v[52:55]
	v_mfma_f32_16x16x32_bf16 v[48:51], v[90:93], v[150:153], v[48:51]
	v_mfma_f32_16x16x32_bf16 v[44:47], v[94:97], v[98:101], v[44:47]
	v_mfma_f32_16x16x32_bf16 v[40:43], v[94:97], v[102:105], v[40:43]
	v_mfma_f32_16x16x32_bf16 v[36:39], v[94:97], v[146:149], v[36:39]
	v_mfma_f32_16x16x32_bf16 v[32:35], v[94:97], v[150:153], v[32:35]
	v_mfma_f32_16x16x32_bf16 v[28:31], v[138:141], v[98:101], v[28:31]
	v_mfma_f32_16x16x32_bf16 v[24:27], v[138:141], v[102:105], v[24:27]
	v_mfma_f32_16x16x32_bf16 v[20:23], v[138:141], v[146:149], v[20:23]
	v_mfma_f32_16x16x32_bf16 v[16:19], v[138:141], v[150:153], v[16:19]
	v_mfma_f32_16x16x32_bf16 v[12:15], v[142:145], v[98:101], v[12:15]
	v_mfma_f32_16x16x32_bf16 v[8:11], v[142:145], v[102:105], v[8:11]
	s_setprio 0
	s_barrier
	ds_write2_b32 v116, v60, v56 offset1:16
	ds_write2_b32 v116, v61, v57 offset0:132 offset1:148
	v_add_u32_e32 v56, 0x400, v116
	ds_write2_b32 v56, v62, v58 offset0:8 offset1:24
	ds_write2_b32 v56, v63, v59 offset0:140 offset1:156
	ds_write2_b32 v116, v52, v48 offset0:32 offset1:48
	ds_write2_b32 v116, v53, v49 offset0:164 offset1:180
	ds_write2_b32 v56, v54, v50 offset0:40 offset1:56
	ds_write2_b32 v56, v55, v51 offset0:172 offset1:188
	v_add_u32_e32 v48, 0x2000, v116
	ds_write2_b32 v48, v44, v40 offset0:64 offset1:80
	ds_write2_b32 v48, v45, v41 offset0:196 offset1:212
	v_add_u32_e32 v40, 0x2400, v116
	ds_write2_b32 v40, v46, v42 offset0:72 offset1:88
	ds_write2_b32 v40, v47, v43 offset0:204 offset1:220
	ds_write2_b32 v48, v36, v32 offset0:96 offset1:112
	ds_write2_b32 v48, v37, v33 offset0:228 offset1:244
	ds_write2_b32 v40, v38, v34 offset0:104 offset1:120
	ds_write2_b32 v40, v39, v35 offset0:236 offset1:252
	v_add_u32_e32 v32, 0x4000, v116
	ds_write2_b32 v32, v28, v24 offset0:128 offset1:144
	v_add_u32_e32 v24, 0x4400, v116
	ds_write2_b32 v24, v29, v25 offset0:4 offset1:20
	ds_write2_b32 v24, v30, v26 offset0:136 offset1:152
	v_add_u32_e32 v25, 0x4800, v116
	ds_write2_b32 v25, v31, v27 offset0:12 offset1:28
	ds_write2_b32 v32, v20, v16 offset0:160 offset1:176
	ds_write2_b32 v24, v21, v17 offset0:36 offset1:52
	ds_write2_b32 v24, v22, v18 offset0:168 offset1:184
	ds_write2_b32 v25, v23, v19 offset0:44 offset1:60
	v_add_u32_e32 v16, 0x6000, v116
	ds_write2_b32 v16, v12, v8 offset0:192 offset1:208
	v_add_u32_e32 v8, 0x6400, v116
	ds_write2_b32 v8, v13, v9 offset0:68 offset1:84
	ds_write2_b32 v8, v14, v10 offset0:200 offset1:216
	v_add_u32_e32 v9, 0x6800, v116
	ds_write2_b32 v9, v15, v11 offset0:76 offset1:92
	ds_write2_b32 v16, v4, v0 offset0:224 offset1:240
	ds_write2_b32 v8, v5, v1 offset0:100 offset1:116
	ds_write2_b32 v8, v6, v2 offset0:232 offset1:248
	ds_write2_b32 v9, v7, v3 offset0:108 offset1:124
	v_or_b32_e32 v0, s23, v117
	v_ashrrev_i32_e32 v1, 31, v0
	v_lshlrev_b64 v[2:3], 2, v[0:1]
	v_lshl_add_u64 v[0:1], s[12:13], 0, v[2:3]
	v_lshl_add_u64 v[2:3], s[8:9], 0, v[2:3]
	v_add_u32_e32 v4, s22, v128
	s_mov_b32 s14, 0
	s_waitcnt lgkmcnt(0)
	s_barrier

.LBB0_432:
	s_and_b32 s26, s25, 0x4000
	s_xor_b32 s27, s26, 0x4000
	s_lshl_b32 s27, s27, 1
	s_add_i32 s27, s27, 32
	s_add_u32 s90, s52, s14
	s_addc_u32 s91, s53, s15
	s_add_i32 m0, s27, s82
	s_lshl_b32 s26, s26, 1
	global_load_lds_dwordx4 v188, s[90:91]
	s_add_i32 m0, s27, s83
	s_add_i32 s26, s26, 32
	global_load_lds_dwordx4 v189, s[90:91]
	s_add_i32 m0, s27, s84
	v_add3_u32 v139, s26, v113, v136
	global_load_lds_dwordx4 v190, s[90:91]
	s_add_i32 m0, s27, s85
	v_add3_u32 v172, s26, v114, v136
	global_load_lds_dwordx4 v191, s[90:91]
	s_add_i32 m0, s27, s86
	v_add_u32_e32 v160, v139, v137
	global_load_lds_dwordx4 v192, s[90:91]
	s_add_i32 m0, s27, s87
	v_add_u32_e32 v168, v172, v137
	global_load_lds_dwordx4 v193, s[90:91]
	s_add_i32 m0, s27, s88
	s_addk_i32 s25, 0x4000
	global_load_lds_dwordx4 v194, s[90:91]
	s_add_i32 m0, s27, s89
	s_add_u32 s14, s14, 0x80
	s_addc_u32 s15, s15, 0
	global_load_lds_dwordx4 v195, s[90:91]
	ds_read_b128 v[140:143], v160
	ds_read_b128 v[144:147], v160 offset:2048
	ds_read_b128 v[148:151], v168 offset:16384
	ds_read_b128 v[152:155], v168 offset:18432
	ds_read_b128 v[156:159], v160 offset:4096
	ds_read_b128 v[160:163], v160 offset:6144
	ds_read_b128 v[164:167], v168 offset:20480
	ds_read_b128 v[168:171], v168 offset:22528
	s_setprio 1
	s_waitcnt lgkmcnt(0)
	v_mfma_f32_16x16x32_bf16 v[60:63], v[140:143], v[148:151], v[60:63]
	v_mfma_f32_16x16x32_bf16 v[56:59], v[140:143], v[152:155], v[56:59]
	v_mfma_f32_16x16x32_bf16 v[52:55], v[140:143], v[164:167], v[52:55]
	v_mfma_f32_16x16x32_bf16 v[48:51], v[140:143], v[168:171], v[48:51]
	v_mfma_f32_16x16x32_bf16 v[44:47], v[144:147], v[148:151], v[44:47]
	v_mfma_f32_16x16x32_bf16 v[40:43], v[144:147], v[152:155], v[40:43]
	v_mfma_f32_16x16x32_bf16 v[36:39], v[144:147], v[164:167], v[36:39]
	v_mfma_f32_16x16x32_bf16 v[32:35], v[144:147], v[168:171], v[32:35]
	v_mfma_f32_16x16x32_bf16 v[28:31], v[156:159], v[148:151], v[28:31]
	v_mfma_f32_16x16x32_bf16 v[24:27], v[156:159], v[152:155], v[24:27]
	v_mfma_f32_16x16x32_bf16 v[20:23], v[156:159], v[164:167], v[20:23]
	v_mfma_f32_16x16x32_bf16 v[16:19], v[156:159], v[168:171], v[16:19]
	v_mfma_f32_16x16x32_bf16 v[12:15], v[160:163], v[148:151], v[12:15]
	v_mfma_f32_16x16x32_bf16 v[8:11], v[160:163], v[152:155], v[8:11]
	v_mfma_f32_16x16x32_bf16 v[4:7], v[160:163], v[164:167], v[4:7]
	v_mfma_f32_16x16x32_bf16 v[0:3], v[160:163], v[168:171], v[0:3]
	s_setprio 0
	v_add_u32_e32 v139, v139, v138
	v_add_u32_e32 v168, v172, v138
	ds_read_b128 v[140:143], v139
	ds_read_b128 v[144:147], v139 offset:2048
	ds_read_b128 v[148:151], v168 offset:16384
	ds_read_b128 v[152:155], v168 offset:18432
	ds_read_b128 v[156:159], v139 offset:4096
	ds_read_b128 v[160:163], v139 offset:6144
	ds_read_b128 v[164:167], v168 offset:20480
	ds_read_b128 v[168:171], v168 offset:22528
	s_setprio 1
	s_waitcnt lgkmcnt(0)
	v_mfma_f32_16x16x32_bf16 v[60:63], v[140:143], v[148:151], v[60:63]
	v_mfma_f32_16x16x32_bf16 v[56:59], v[140:143], v[152:155], v[56:59]
	v_mfma_f32_16x16x32_bf16 v[52:55], v[140:143], v[164:167], v[52:55]
	v_mfma_f32_16x16x32_bf16 v[48:51], v[140:143], v[168:171], v[48:51]
	v_mfma_f32_16x16x32_bf16 v[44:47], v[144:147], v[148:151], v[44:47]
	v_mfma_f32_16x16x32_bf16 v[40:43], v[144:147], v[152:155], v[40:43]
	v_mfma_f32_16x16x32_bf16 v[36:39], v[144:147], v[164:167], v[36:39]
	v_mfma_f32_16x16x32_bf16 v[32:35], v[144:147], v[168:171], v[32:35]
	v_mfma_f32_16x16x32_bf16 v[28:31], v[156:159], v[148:151], v[28:31]
	v_mfma_f32_16x16x32_bf16 v[24:27], v[156:159], v[152:155], v[24:27]
	v_mfma_f32_16x16x32_bf16 v[20:23], v[156:159], v[164:167], v[20:23]
	v_mfma_f32_16x16x32_bf16 v[16:19], v[156:159], v[168:171], v[16:19]
	v_mfma_f32_16x16x32_bf16 v[12:15], v[160:163], v[148:151], v[12:15]
	v_mfma_f32_16x16x32_bf16 v[8:11], v[160:163], v[152:155], v[8:11]
	v_mfma_f32_16x16x32_bf16 v[4:7], v[160:163], v[164:167], v[4:7]
	v_mfma_f32_16x16x32_bf16 v[0:3], v[160:163], v[168:171], v[0:3]
	s_setprio 0
	s_cmpk_eq_i32 s14, 0x780
	s_waitcnt vmcnt(0)
	s_barrier
	s_cbranch_scc0 .LBB0_432
	ds_read_b128 v[88:91], v117 offset:55296
	ds_read_b128 v[92:95], v117 offset:53248
	ds_read_b128 v[96:99], v118 offset:38912
	ds_read_b128 v[100:103], v118 offset:36864
	ds_read_b128 v[140:143], v117 offset:51200
	ds_read_b128 v[144:147], v117 offset:49152
	ds_read_b128 v[148:151], v118 offset:34816
	ds_read_b128 v[152:155], v118 offset:32768
	s_setprio 1
	s_waitcnt lgkmcnt(5)
	v_mfma_f32_16x16x32_bf16 v[4:7], v[96:99], v[92:95], v[4:7]
	v_mfma_f32_16x16x32_bf16 v[0:3], v[96:99], v[88:91], v[0:3]
	s_waitcnt lgkmcnt(0)
	v_mfma_f32_16x16x32_bf16 v[60:63], v[152:155], v[144:147], v[60:63]
	v_mfma_f32_16x16x32_bf16 v[56:59], v[152:155], v[140:143], v[56:59]
	v_mfma_f32_16x16x32_bf16 v[52:55], v[152:155], v[92:95], v[52:55]
	v_mfma_f32_16x16x32_bf16 v[48:51], v[152:155], v[88:91], v[48:51]
	v_mfma_f32_16x16x32_bf16 v[44:47], v[148:151], v[144:147], v[44:47]
	v_mfma_f32_16x16x32_bf16 v[40:43], v[148:151], v[140:143], v[40:43]
	v_mfma_f32_16x16x32_bf16 v[36:39], v[148:151], v[92:95], v[36:39]
	v_mfma_f32_16x16x32_bf16 v[32:35], v[148:151], v[88:91], v[32:35]
	v_mfma_f32_16x16x32_bf16 v[28:31], v[100:103], v[144:147], v[28:31]
	v_mfma_f32_16x16x32_bf16 v[24:27], v[100:103], v[140:143], v[24:27]
	v_mfma_f32_16x16x32_bf16 v[20:23], v[100:103], v[92:95], v[20:23]
	v_mfma_f32_16x16x32_bf16 v[16:19], v[100:103], v[88:91], v[16:19]
	v_mfma_f32_16x16x32_bf16 v[12:15], v[96:99], v[144:147], v[12:15]
	v_mfma_f32_16x16x32_bf16 v[8:11], v[96:99], v[140:143], v[8:11]
	s_setprio 0
	ds_read_b128 v[88:91], v119 offset:32768
	ds_read_b128 v[92:95], v119 offset:34816
	ds_read_b128 v[96:99], v120 offset:49152
	ds_read_b128 v[100:103], v120 offset:51200
	ds_read_b128 v[140:143], v119 offset:36864
	ds_read_b128 v[144:147], v119 offset:38912
	ds_read_b128 v[148:151], v120 offset:53248
	ds_read_b128 v[152:155], v120 offset:55296
	s_setprio 1
	s_waitcnt lgkmcnt(1)
	v_mfma_f32_16x16x32_bf16 v[4:7], v[144:147], v[148:151], v[4:7]
	s_waitcnt lgkmcnt(0)
	v_mfma_f32_16x16x32_bf16 v[0:3], v[144:147], v[152:155], v[0:3]
	v_mfma_f32_16x16x32_bf16 v[60:63], v[88:91], v[96:99], v[60:63]
	v_mfma_f32_16x16x32_bf16 v[56:59], v[88:91], v[100:103], v[56:59]
	v_mfma_f32_16x16x32_bf16 v[52:55], v[88:91], v[148:151], v[52:55]
	v_mfma_f32_16x16x32_bf16 v[48:51], v[88:91], v[152:155], v[48:51]
	v_mfma_f32_16x16x32_bf16 v[44:47], v[92:95], v[96:99], v[44:47]
	v_mfma_f32_16x16x32_bf16 v[40:43], v[92:95], v[100:103], v[40:43]
	v_mfma_f32_16x16x32_bf16 v[36:39], v[92:95], v[148:151], v[36:39]
	v_mfma_f32_16x16x32_bf16 v[32:35], v[92:95], v[152:155], v[32:35]
	v_mfma_f32_16x16x32_bf16 v[28:31], v[140:143], v[96:99], v[28:31]
	v_mfma_f32_16x16x32_bf16 v[24:27], v[140:143], v[100:103], v[24:27]
	v_mfma_f32_16x16x32_bf16 v[20:23], v[140:143], v[148:151], v[20:23]
	v_mfma_f32_16x16x32_bf16 v[16:19], v[140:143], v[152:155], v[16:19]
	v_mfma_f32_16x16x32_bf16 v[12:15], v[144:147], v[96:99], v[12:15]
	v_mfma_f32_16x16x32_bf16 v[8:11], v[144:147], v[100:103], v[8:11]
	s_setprio 0
	s_barrier
	ds_write2_b32 v115, v60, v56 offset1:16
	ds_write2_b32 v115, v61, v57 offset0:132 offset1:148
	v_add_u32_e32 v56, 0x400, v115
	ds_write2_b32 v56, v62, v58 offset0:8 offset1:24
	ds_write2_b32 v56, v63, v59 offset0:140 offset1:156
	ds_write2_b32 v115, v52, v48 offset0:32 offset1:48
	ds_write2_b32 v115, v53, v49 offset0:164 offset1:180
	ds_write2_b32 v56, v54, v50 offset0:40 offset1:56
	ds_write2_b32 v56, v55, v51 offset0:172 offset1:188
	v_add_u32_e32 v48, 0x2000, v115
	ds_write2_b32 v48, v44, v40 offset0:64 offset1:80
	ds_write2_b32 v48, v45, v41 offset0:196 offset1:212
	v_add_u32_e32 v40, 0x2400, v115
	ds_write2_b32 v40, v46, v42 offset0:72 offset1:88
	ds_write2_b32 v40, v47, v43 offset0:204 offset1:220
	ds_write2_b32 v48, v36, v32 offset0:96 offset1:112
	ds_write2_b32 v48, v37, v33 offset0:228 offset1:244
	ds_write2_b32 v40, v38, v34 offset0:104 offset1:120
	ds_write2_b32 v40, v39, v35 offset0:236 offset1:252
	v_add_u32_e32 v32, 0x4000, v115
	ds_write2_b32 v32, v28, v24 offset0:128 offset1:144
	v_add_u32_e32 v24, 0x4400, v115
	ds_write2_b32 v24, v29, v25 offset0:4 offset1:20
	ds_write2_b32 v24, v30, v26 offset0:136 offset1:152
	v_add_u32_e32 v25, 0x4800, v115
	ds_write2_b32 v25, v31, v27 offset0:12 offset1:28
	ds_write2_b32 v32, v20, v16 offset0:160 offset1:176
	ds_write2_b32 v24, v21, v17 offset0:36 offset1:52
	ds_write2_b32 v24, v22, v18 offset0:168 offset1:184
	ds_write2_b32 v25, v23, v19 offset0:44 offset1:60
	v_add_u32_e32 v16, 0x6000, v115
	ds_write2_b32 v16, v12, v8 offset0:192 offset1:208
	v_add_u32_e32 v8, 0x6400, v115
	ds_write2_b32 v8, v13, v9 offset0:68 offset1:84
	ds_write2_b32 v8, v14, v10 offset0:200 offset1:216
	v_add_u32_e32 v9, 0x6800, v115
	ds_write2_b32 v9, v15, v11 offset0:76 offset1:92
	ds_write2_b32 v16, v4, v0 offset0:224 offset1:240
	ds_write2_b32 v8, v5, v1 offset0:100 offset1:116
	ds_write2_b32 v8, v6, v2 offset0:232 offset1:248
	ds_write2_b32 v9, v7, v3 offset0:108 offset1:124
	v_or_b32_e32 v0, s23, v116
	v_ashrrev_i32_e32 v1, 31, v0
	v_lshlrev_b64 v[2:3], 2, v[0:1]
	v_lshl_add_u64 v[0:1], s[12:13], 0, v[2:3]
	v_lshl_add_u64 v[2:3], s[8:9], 0, v[2:3]
	v_add_u32_e32 v4, s24, v129
	s_mov_b32 s14, 0
	s_waitcnt lgkmcnt(0)
	s_barrier

.LBB0_605:
	s_and_b32 s18, s17, 0x4000
	s_xor_b32 s19, s18, 0x4000
	s_lshl_b32 s19, s19, 1
	s_add_i32 s19, s19, 32
	s_add_u32 s90, s52, s10
	s_addc_u32 s91, s53, s11
	s_add_i32 m0, s19, s82
	s_lshl_b32 s18, s18, 1
	global_load_lds_dwordx4 v184, s[90:91]
	s_add_i32 m0, s19, s83
	s_add_i32 s18, s18, 32
	global_load_lds_dwordx4 v185, s[90:91]
	s_add_i32 m0, s19, s84
	v_lshl_add_u32 v137, v114, 1, s18
	global_load_lds_dwordx4 v186, s[90:91]
	s_add_i32 m0, s19, s85
	v_lshl_add_u32 v170, v115, 1, s18
	global_load_lds_dwordx4 v187, s[90:91]
	s_add_i32 m0, s19, s86
	v_add_u32_e32 v158, v137, v135
	global_load_lds_dwordx4 v188, s[90:91]
	s_add_i32 m0, s19, s87
	v_add_u32_e32 v166, v170, v135
	global_load_lds_dwordx4 v189, s[90:91]
	s_add_i32 m0, s19, s88
	s_addk_i32 s17, 0x4000
	global_load_lds_dwordx4 v190, s[90:91]
	s_add_i32 m0, s19, s89
	s_add_u32 s10, s10, 0x80
	s_addc_u32 s11, s11, 0
	global_load_lds_dwordx4 v191, s[90:91]
	ds_read_b128 v[138:141], v158
	ds_read_b128 v[142:145], v158 offset:2048
	ds_read_b128 v[146:149], v166 offset:16384
	ds_read_b128 v[150:153], v166 offset:18432
	ds_read_b128 v[154:157], v158 offset:4096
	ds_read_b128 v[158:161], v158 offset:6144
	ds_read_b128 v[162:165], v166 offset:20480
	ds_read_b128 v[166:169], v166 offset:22528
	s_setprio 1
	s_waitcnt lgkmcnt(0)
	v_mfma_f32_16x16x32_bf16 v[60:63], v[138:141], v[146:149], v[60:63]
	v_mfma_f32_16x16x32_bf16 v[56:59], v[138:141], v[150:153], v[56:59]
	v_mfma_f32_16x16x32_bf16 v[52:55], v[138:141], v[162:165], v[52:55]
	v_mfma_f32_16x16x32_bf16 v[48:51], v[138:141], v[166:169], v[48:51]
	v_mfma_f32_16x16x32_bf16 v[44:47], v[142:145], v[146:149], v[44:47]
	v_mfma_f32_16x16x32_bf16 v[40:43], v[142:145], v[150:153], v[40:43]
	v_mfma_f32_16x16x32_bf16 v[36:39], v[142:145], v[162:165], v[36:39]
	v_mfma_f32_16x16x32_bf16 v[32:35], v[142:145], v[166:169], v[32:35]
	v_mfma_f32_16x16x32_bf16 v[28:31], v[154:157], v[146:149], v[28:31]
	v_mfma_f32_16x16x32_bf16 v[24:27], v[154:157], v[150:153], v[24:27]
	v_mfma_f32_16x16x32_bf16 v[20:23], v[154:157], v[162:165], v[20:23]
	v_mfma_f32_16x16x32_bf16 v[16:19], v[154:157], v[166:169], v[16:19]
	v_mfma_f32_16x16x32_bf16 v[12:15], v[158:161], v[146:149], v[12:15]
	v_mfma_f32_16x16x32_bf16 v[8:11], v[158:161], v[150:153], v[8:11]
	v_mfma_f32_16x16x32_bf16 v[4:7], v[158:161], v[162:165], v[4:7]
	v_mfma_f32_16x16x32_bf16 v[0:3], v[158:161], v[166:169], v[0:3]
	s_setprio 0
	v_add_u32_e32 v137, v137, v136
	v_add_u32_e32 v166, v170, v136
	ds_read_b128 v[138:141], v137
	ds_read_b128 v[142:145], v137 offset:2048
	ds_read_b128 v[146:149], v166 offset:16384
	ds_read_b128 v[150:153], v166 offset:18432
	ds_read_b128 v[154:157], v137 offset:4096
	ds_read_b128 v[158:161], v137 offset:6144
	ds_read_b128 v[162:165], v166 offset:20480
	ds_read_b128 v[166:169], v166 offset:22528
	s_setprio 1
	s_waitcnt lgkmcnt(0)
	v_mfma_f32_16x16x32_bf16 v[60:63], v[138:141], v[146:149], v[60:63]
	v_mfma_f32_16x16x32_bf16 v[56:59], v[138:141], v[150:153], v[56:59]
	v_mfma_f32_16x16x32_bf16 v[52:55], v[138:141], v[162:165], v[52:55]
	v_mfma_f32_16x16x32_bf16 v[48:51], v[138:141], v[166:169], v[48:51]
	v_mfma_f32_16x16x32_bf16 v[44:47], v[142:145], v[146:149], v[44:47]
	v_mfma_f32_16x16x32_bf16 v[40:43], v[142:145], v[150:153], v[40:43]
	v_mfma_f32_16x16x32_bf16 v[36:39], v[142:145], v[162:165], v[36:39]
	v_mfma_f32_16x16x32_bf16 v[32:35], v[142:145], v[166:169], v[32:35]
	v_mfma_f32_16x16x32_bf16 v[28:31], v[154:157], v[146:149], v[28:31]
	v_mfma_f32_16x16x32_bf16 v[24:27], v[154:157], v[150:153], v[24:27]
	v_mfma_f32_16x16x32_bf16 v[20:23], v[154:157], v[162:165], v[20:23]
	v_mfma_f32_16x16x32_bf16 v[16:19], v[154:157], v[166:169], v[16:19]
	v_mfma_f32_16x16x32_bf16 v[12:15], v[158:161], v[146:149], v[12:15]
	v_mfma_f32_16x16x32_bf16 v[8:11], v[158:161], v[150:153], v[8:11]
	v_mfma_f32_16x16x32_bf16 v[4:7], v[158:161], v[162:165], v[4:7]
	v_mfma_f32_16x16x32_bf16 v[0:3], v[158:161], v[166:169], v[0:3]
	s_setprio 0
	s_cmpk_eq_i32 s10, 0x780
	s_waitcnt vmcnt(0)
	s_barrier
	s_cbranch_scc0 .LBB0_605
	ds_read_b128 v[90:93], v116 offset:55296
	ds_read_b128 v[94:97], v116 offset:53248
	ds_read_b128 v[98:101], v117 offset:38912
	ds_read_b128 v[102:105], v117 offset:36864
	ds_read_b128 v[138:141], v116 offset:51200
	ds_read_b128 v[142:145], v116 offset:49152
	ds_read_b128 v[146:149], v117 offset:34816
	ds_read_b128 v[150:153], v117 offset:32768
	s_setprio 1
	s_waitcnt lgkmcnt(5)
	v_mfma_f32_16x16x32_bf16 v[0:3], v[98:101], v[90:93], v[0:3]
	s_waitcnt lgkmcnt(0)
	v_mfma_f32_16x16x32_bf16 v[60:63], v[150:153], v[142:145], v[60:63]
	v_mfma_f32_16x16x32_bf16 v[56:59], v[150:153], v[138:141], v[56:59]
	v_mfma_f32_16x16x32_bf16 v[52:55], v[150:153], v[94:97], v[52:55]
	v_mfma_f32_16x16x32_bf16 v[48:51], v[150:153], v[90:93], v[48:51]
	v_mfma_f32_16x16x32_bf16 v[44:47], v[146:149], v[142:145], v[44:47]
	v_mfma_f32_16x16x32_bf16 v[40:43], v[146:149], v[138:141], v[40:43]
	v_mfma_f32_16x16x32_bf16 v[36:39], v[146:149], v[94:97], v[36:39]
	v_mfma_f32_16x16x32_bf16 v[32:35], v[146:149], v[90:93], v[32:35]
	v_mfma_f32_16x16x32_bf16 v[28:31], v[102:105], v[142:145], v[28:31]
	v_mfma_f32_16x16x32_bf16 v[24:27], v[102:105], v[138:141], v[24:27]
	v_mfma_f32_16x16x32_bf16 v[20:23], v[102:105], v[94:97], v[20:23]
	v_mfma_f32_16x16x32_bf16 v[16:19], v[102:105], v[90:93], v[16:19]
	v_mfma_f32_16x16x32_bf16 v[12:15], v[98:101], v[142:145], v[12:15]
	v_mfma_f32_16x16x32_bf16 v[8:11], v[98:101], v[138:141], v[8:11]
	v_mfma_f32_16x16x32_bf16 v[4:7], v[98:101], v[94:97], v[4:7]
	s_setprio 0
	ds_read_b128 v[90:93], v118 offset:32768
	ds_read_b128 v[94:97], v118 offset:34816
	ds_read_b128 v[98:101], v119 offset:49152
	ds_read_b128 v[102:105], v119 offset:51200
	ds_read_b128 v[138:141], v118 offset:36864
	ds_read_b128 v[142:145], v118 offset:38912
	ds_read_b128 v[146:149], v119 offset:53248
	ds_read_b128 v[150:153], v119 offset:55296
	s_setprio 1
	s_waitcnt lgkmcnt(0)
	v_mfma_f32_16x16x32_bf16 v[0:3], v[142:145], v[150:153], v[0:3]
	v_mfma_f32_16x16x32_bf16 v[60:63], v[90:93], v[98:101], v[60:63]
	v_mfma_f32_16x16x32_bf16 v[56:59], v[90:93], v[102:105], v[56:59]
	v_mfma_f32_16x16x32_bf16 v[52:55], v[90:93], v[146:149], v[52:55]
	v_mfma_f32_16x16x32_bf16 v[48:51], v[90:93], v[150:153], v[48:51]
	v_mfma_f32_16x16x32_bf16 v[44:47], v[94:97], v[98:101], v[44:47]
	v_mfma_f32_16x16x32_bf16 v[40:43], v[94:97], v[102:105], v[40:43]
	v_mfma_f32_16x16x32_bf16 v[36:39], v[94:97], v[146:149], v[36:39]
	v_mfma_f32_16x16x32_bf16 v[32:35], v[94:97], v[150:153], v[32:35]
	v_mfma_f32_16x16x32_bf16 v[28:31], v[138:141], v[98:101], v[28:31]
	v_mfma_f32_16x16x32_bf16 v[24:27], v[138:141], v[102:105], v[24:27]
	v_mfma_f32_16x16x32_bf16 v[20:23], v[138:141], v[146:149], v[20:23]
	v_mfma_f32_16x16x32_bf16 v[16:19], v[138:141], v[150:153], v[16:19]
	v_mfma_f32_16x16x32_bf16 v[12:15], v[142:145], v[98:101], v[12:15]
	v_mfma_f32_16x16x32_bf16 v[8:11], v[142:145], v[102:105], v[8:11]
	v_mfma_f32_16x16x32_bf16 v[4:7], v[142:145], v[146:149], v[4:7]
	s_setprio 0
	s_barrier
	ds_write2_b32 v120, v60, v56 offset1:16
	ds_write2_b32 v120, v61, v57 offset0:132 offset1:148
	v_add_u32_e32 v56, 0x400, v120
	ds_write2_b32 v56, v62, v58 offset0:8 offset1:24
	ds_write2_b32 v56, v63, v59 offset0:140 offset1:156
	ds_write2_b32 v120, v52, v48 offset0:32 offset1:48
	ds_write2_b32 v120, v53, v49 offset0:164 offset1:180
	ds_write2_b32 v56, v54, v50 offset0:40 offset1:56
	ds_write2_b32 v56, v55, v51 offset0:172 offset1:188
	v_add_u32_e32 v48, 0x2000, v120
	ds_write2_b32 v48, v44, v40 offset0:64 offset1:80
	ds_write2_b32 v48, v45, v41 offset0:196 offset1:212
	v_add_u32_e32 v40, 0x2400, v120
	ds_write2_b32 v40, v46, v42 offset0:72 offset1:88
	ds_write2_b32 v40, v47, v43 offset0:204 offset1:220
	ds_write2_b32 v48, v36, v32 offset0:96 offset1:112
	ds_write2_b32 v48, v37, v33 offset0:228 offset1:244
	ds_write2_b32 v40, v38, v34 offset0:104 offset1:120
	ds_write2_b32 v40, v39, v35 offset0:236 offset1:252
	v_add_u32_e32 v32, 0x4000, v120
	ds_write2_b32 v32, v28, v24 offset0:128 offset1:144
	v_add_u32_e32 v24, 0x4400, v120
	ds_write2_b32 v24, v29, v25 offset0:4 offset1:20
	ds_write2_b32 v24, v30, v26 offset0:136 offset1:152
	v_add_u32_e32 v25, 0x4800, v120
	ds_write2_b32 v25, v31, v27 offset0:12 offset1:28
	ds_write2_b32 v32, v20, v16 offset0:160 offset1:176
	ds_write2_b32 v24, v21, v17 offset0:36 offset1:52
	ds_write2_b32 v24, v22, v18 offset0:168 offset1:184
	ds_write2_b32 v25, v23, v19 offset0:44 offset1:60
	v_add_u32_e32 v16, 0x6000, v120
	ds_write2_b32 v16, v12, v8 offset0:192 offset1:208
	v_add_u32_e32 v8, 0x6400, v120
	ds_write2_b32 v8, v13, v9 offset0:68 offset1:84
	ds_write2_b32 v8, v14, v10 offset0:200 offset1:216
	v_add_u32_e32 v9, 0x6800, v120
	ds_write2_b32 v9, v15, v11 offset0:76 offset1:92
	ds_write2_b32 v16, v4, v0 offset0:224 offset1:240
	ds_write2_b32 v8, v5, v1 offset0:100 offset1:116
	ds_write2_b32 v8, v6, v2 offset0:232 offset1:248
	ds_write2_b32 v9, v7, v3 offset0:108 offset1:124
	v_or_b32_e32 v0, s16, v121
	v_ashrrev_i32_e32 v1, 31, v0
	v_lshl_add_u64 v[0:1], v[0:1], 1, s[4:5]
	v_add_u32_e32 v2, s15, v128
	s_mov_b32 s10, 0
	s_waitcnt lgkmcnt(0)
	s_barrier

.LBB0_616:
	s_and_b32 s15, s14, 0x4000
	s_xor_b32 s16, s15, 0x4000
	s_lshl_b32 s16, s16, 1
	s_add_i32 s16, s16, 32
	s_add_u32 s90, s52, s6
	s_addc_u32 s91, s53, s7
	s_add_i32 m0, s16, s82
	s_lshl_b32 s15, s15, 1
	global_load_lds_dwordx4 v184, s[90:91]
	s_add_i32 m0, s16, s83
	s_add_i32 s15, s15, 32
	global_load_lds_dwordx4 v185, s[90:91]
	s_add_i32 m0, s16, s84
	v_lshl_add_u32 v137, v113, 1, s15
	global_load_lds_dwordx4 v186, s[90:91]
	s_add_i32 m0, s16, s85
	v_lshl_add_u32 v170, v114, 1, s15
	global_load_lds_dwordx4 v187, s[90:91]
	s_add_i32 m0, s16, s86
	v_add_u32_e32 v158, v137, v135
	global_load_lds_dwordx4 v188, s[90:91]
	s_add_i32 m0, s16, s87
	v_add_u32_e32 v166, v170, v135
	global_load_lds_dwordx4 v189, s[90:91]
	s_add_i32 m0, s16, s88
	s_addk_i32 s14, 0x4000
	global_load_lds_dwordx4 v190, s[90:91]
	s_add_i32 m0, s16, s89
	s_add_u32 s6, s6, 0x80
	s_addc_u32 s7, s7, 0
	global_load_lds_dwordx4 v191, s[90:91]
	ds_read_b128 v[138:141], v158
	ds_read_b128 v[142:145], v158 offset:2048
	ds_read_b128 v[146:149], v166 offset:16384
	ds_read_b128 v[150:153], v166 offset:18432
	ds_read_b128 v[154:157], v158 offset:4096
	ds_read_b128 v[158:161], v158 offset:6144
	ds_read_b128 v[162:165], v166 offset:20480
	ds_read_b128 v[166:169], v166 offset:22528
	s_setprio 1
	s_waitcnt lgkmcnt(0)
	v_mfma_f32_16x16x32_bf16 v[60:63], v[138:141], v[146:149], v[60:63]
	v_mfma_f32_16x16x32_bf16 v[56:59], v[138:141], v[150:153], v[56:59]
	v_mfma_f32_16x16x32_bf16 v[52:55], v[138:141], v[162:165], v[52:55]
	v_mfma_f32_16x16x32_bf16 v[48:51], v[138:141], v[166:169], v[48:51]
	v_mfma_f32_16x16x32_bf16 v[44:47], v[142:145], v[146:149], v[44:47]
	v_mfma_f32_16x16x32_bf16 v[40:43], v[142:145], v[150:153], v[40:43]
	v_mfma_f32_16x16x32_bf16 v[36:39], v[142:145], v[162:165], v[36:39]
	v_mfma_f32_16x16x32_bf16 v[32:35], v[142:145], v[166:169], v[32:35]
	v_mfma_f32_16x16x32_bf16 v[28:31], v[154:157], v[146:149], v[28:31]
	v_mfma_f32_16x16x32_bf16 v[24:27], v[154:157], v[150:153], v[24:27]
	v_mfma_f32_16x16x32_bf16 v[20:23], v[154:157], v[162:165], v[20:23]
	v_mfma_f32_16x16x32_bf16 v[16:19], v[154:157], v[166:169], v[16:19]
	v_mfma_f32_16x16x32_bf16 v[12:15], v[158:161], v[146:149], v[12:15]
	v_mfma_f32_16x16x32_bf16 v[8:11], v[158:161], v[150:153], v[8:11]
	v_mfma_f32_16x16x32_bf16 v[4:7], v[158:161], v[162:165], v[4:7]
	v_mfma_f32_16x16x32_bf16 v[0:3], v[158:161], v[166:169], v[0:3]
	s_setprio 0
	v_add_u32_e32 v137, v137, v136
	v_add_u32_e32 v166, v170, v136
	ds_read_b128 v[138:141], v137
	ds_read_b128 v[142:145], v137 offset:2048
	ds_read_b128 v[146:149], v166 offset:16384
	ds_read_b128 v[150:153], v166 offset:18432
	ds_read_b128 v[154:157], v137 offset:4096
	ds_read_b128 v[158:161], v137 offset:6144
	ds_read_b128 v[162:165], v166 offset:20480
	ds_read_b128 v[166:169], v166 offset:22528
	s_setprio 1
	s_waitcnt lgkmcnt(0)
	v_mfma_f32_16x16x32_bf16 v[60:63], v[138:141], v[146:149], v[60:63]
	v_mfma_f32_16x16x32_bf16 v[56:59], v[138:141], v[150:153], v[56:59]
	v_mfma_f32_16x16x32_bf16 v[52:55], v[138:141], v[162:165], v[52:55]
	v_mfma_f32_16x16x32_bf16 v[48:51], v[138:141], v[166:169], v[48:51]
	v_mfma_f32_16x16x32_bf16 v[44:47], v[142:145], v[146:149], v[44:47]
	v_mfma_f32_16x16x32_bf16 v[40:43], v[142:145], v[150:153], v[40:43]
	v_mfma_f32_16x16x32_bf16 v[36:39], v[142:145], v[162:165], v[36:39]
	v_mfma_f32_16x16x32_bf16 v[32:35], v[142:145], v[166:169], v[32:35]
	v_mfma_f32_16x16x32_bf16 v[28:31], v[154:157], v[146:149], v[28:31]
	v_mfma_f32_16x16x32_bf16 v[24:27], v[154:157], v[150:153], v[24:27]
	v_mfma_f32_16x16x32_bf16 v[20:23], v[154:157], v[162:165], v[20:23]
	v_mfma_f32_16x16x32_bf16 v[16:19], v[154:157], v[166:169], v[16:19]
	v_mfma_f32_16x16x32_bf16 v[12:15], v[158:161], v[146:149], v[12:15]
	v_mfma_f32_16x16x32_bf16 v[8:11], v[158:161], v[150:153], v[8:11]
	v_mfma_f32_16x16x32_bf16 v[4:7], v[158:161], v[162:165], v[4:7]
	v_mfma_f32_16x16x32_bf16 v[0:3], v[158:161], v[166:169], v[0:3]
	s_setprio 0
	s_cmpk_eq_i32 s6, 0x780
	s_waitcnt vmcnt(0)
	s_barrier
	s_cbranch_scc0 .LBB0_616
	ds_read_b128 v[88:91], v115 offset:55296
	ds_read_b128 v[92:95], v115 offset:53248
	ds_read_b128 v[96:99], v116 offset:38912
	ds_read_b128 v[100:103], v116 offset:36864
	ds_read_b128 v[138:141], v115 offset:51200
	ds_read_b128 v[142:145], v115 offset:49152
	ds_read_b128 v[146:149], v116 offset:34816
	ds_read_b128 v[150:153], v116 offset:32768
	s_setprio 1
	s_waitcnt lgkmcnt(5)
	v_mfma_f32_16x16x32_bf16 v[0:3], v[96:99], v[88:91], v[0:3]
	s_waitcnt lgkmcnt(0)
	v_mfma_f32_16x16x32_bf16 v[60:63], v[150:153], v[142:145], v[60:63]
	v_mfma_f32_16x16x32_bf16 v[56:59], v[150:153], v[138:141], v[56:59]
	v_mfma_f32_16x16x32_bf16 v[52:55], v[150:153], v[92:95], v[52:55]
	v_mfma_f32_16x16x32_bf16 v[48:51], v[150:153], v[88:91], v[48:51]
	v_mfma_f32_16x16x32_bf16 v[44:47], v[146:149], v[142:145], v[44:47]
	v_mfma_f32_16x16x32_bf16 v[40:43], v[146:149], v[138:141], v[40:43]
	v_mfma_f32_16x16x32_bf16 v[36:39], v[146:149], v[92:95], v[36:39]
	v_mfma_f32_16x16x32_bf16 v[32:35], v[146:149], v[88:91], v[32:35]
	v_mfma_f32_16x16x32_bf16 v[28:31], v[100:103], v[142:145], v[28:31]
	v_mfma_f32_16x16x32_bf16 v[24:27], v[100:103], v[138:141], v[24:27]
	v_mfma_f32_16x16x32_bf16 v[20:23], v[100:103], v[92:95], v[20:23]
	v_mfma_f32_16x16x32_bf16 v[16:19], v[100:103], v[88:91], v[16:19]
	v_mfma_f32_16x16x32_bf16 v[12:15], v[96:99], v[142:145], v[12:15]
	v_mfma_f32_16x16x32_bf16 v[8:11], v[96:99], v[138:141], v[8:11]
	v_mfma_f32_16x16x32_bf16 v[4:7], v[96:99], v[92:95], v[4:7]
	s_setprio 0
	ds_read_b128 v[88:91], v117 offset:32768
	ds_read_b128 v[92:95], v117 offset:34816
	ds_read_b128 v[96:99], v118 offset:49152
	ds_read_b128 v[100:103], v118 offset:51200
	ds_read_b128 v[138:141], v117 offset:36864
	ds_read_b128 v[142:145], v117 offset:38912
	ds_read_b128 v[146:149], v118 offset:53248
	ds_read_b128 v[150:153], v118 offset:55296
	s_setprio 1
	s_waitcnt lgkmcnt(0)
	v_mfma_f32_16x16x32_bf16 v[0:3], v[142:145], v[150:153], v[0:3]
	v_mfma_f32_16x16x32_bf16 v[60:63], v[88:91], v[96:99], v[60:63]
	v_mfma_f32_16x16x32_bf16 v[56:59], v[88:91], v[100:103], v[56:59]
	v_mfma_f32_16x16x32_bf16 v[52:55], v[88:91], v[146:149], v[52:55]
	v_mfma_f32_16x16x32_bf16 v[48:51], v[88:91], v[150:153], v[48:51]
	v_mfma_f32_16x16x32_bf16 v[44:47], v[92:95], v[96:99], v[44:47]
	v_mfma_f32_16x16x32_bf16 v[40:43], v[92:95], v[100:103], v[40:43]
	v_mfma_f32_16x16x32_bf16 v[36:39], v[92:95], v[146:149], v[36:39]
	v_mfma_f32_16x16x32_bf16 v[32:35], v[92:95], v[150:153], v[32:35]
	v_mfma_f32_16x16x32_bf16 v[28:31], v[138:141], v[96:99], v[28:31]
	v_mfma_f32_16x16x32_bf16 v[24:27], v[138:141], v[100:103], v[24:27]
	v_mfma_f32_16x16x32_bf16 v[20:23], v[138:141], v[146:149], v[20:23]
	v_mfma_f32_16x16x32_bf16 v[16:19], v[138:141], v[150:153], v[16:19]
	v_mfma_f32_16x16x32_bf16 v[12:15], v[142:145], v[96:99], v[12:15]
	v_mfma_f32_16x16x32_bf16 v[8:11], v[142:145], v[100:103], v[8:11]
	v_mfma_f32_16x16x32_bf16 v[4:7], v[142:145], v[146:149], v[4:7]
	s_setprio 0
	s_barrier
	ds_write2_b32 v119, v60, v56 offset1:16
	ds_write2_b32 v119, v61, v57 offset0:132 offset1:148
	v_add_u32_e32 v56, 0x400, v119
	ds_write2_b32 v56, v62, v58 offset0:8 offset1:24
	ds_write2_b32 v56, v63, v59 offset0:140 offset1:156
	ds_write2_b32 v119, v52, v48 offset0:32 offset1:48
	ds_write2_b32 v119, v53, v49 offset0:164 offset1:180
	ds_write2_b32 v56, v54, v50 offset0:40 offset1:56
	ds_write2_b32 v56, v55, v51 offset0:172 offset1:188
	v_add_u32_e32 v48, 0x2000, v119
	ds_write2_b32 v48, v44, v40 offset0:64 offset1:80
	ds_write2_b32 v48, v45, v41 offset0:196 offset1:212
	v_add_u32_e32 v40, 0x2400, v119
	ds_write2_b32 v40, v46, v42 offset0:72 offset1:88
	ds_write2_b32 v40, v47, v43 offset0:204 offset1:220
	ds_write2_b32 v48, v36, v32 offset0:96 offset1:112
	ds_write2_b32 v48, v37, v33 offset0:228 offset1:244
	ds_write2_b32 v40, v38, v34 offset0:104 offset1:120
	ds_write2_b32 v40, v39, v35 offset0:236 offset1:252
	v_add_u32_e32 v32, 0x4000, v119
	ds_write2_b32 v32, v28, v24 offset0:128 offset1:144
	v_add_u32_e32 v24, 0x4400, v119
	ds_write2_b32 v24, v29, v25 offset0:4 offset1:20
	ds_write2_b32 v24, v30, v26 offset0:136 offset1:152
	v_add_u32_e32 v25, 0x4800, v119
	ds_write2_b32 v25, v31, v27 offset0:12 offset1:28
	ds_write2_b32 v32, v20, v16 offset0:160 offset1:176
	ds_write2_b32 v24, v21, v17 offset0:36 offset1:52
	ds_write2_b32 v24, v22, v18 offset0:168 offset1:184
	ds_write2_b32 v25, v23, v19 offset0:44 offset1:60
	v_add_u32_e32 v16, 0x6000, v119
	ds_write2_b32 v16, v12, v8 offset0:192 offset1:208
	v_add_u32_e32 v8, 0x6400, v119
	ds_write2_b32 v8, v13, v9 offset0:68 offset1:84
	ds_write2_b32 v8, v14, v10 offset0:200 offset1:216
	v_add_u32_e32 v9, 0x6800, v119
	ds_write2_b32 v9, v15, v11 offset0:76 offset1:92
	ds_write2_b32 v16, v4, v0 offset0:224 offset1:240
	ds_write2_b32 v8, v5, v1 offset0:100 offset1:116
	ds_write2_b32 v8, v6, v2 offset0:232 offset1:248
	ds_write2_b32 v9, v7, v3 offset0:108 offset1:124
	v_or_b32_e32 v0, s12, v120
	v_ashrrev_i32_e32 v1, 31, v0
	v_lshl_add_u64 v[0:1], v[0:1], 1, s[4:5]
	v_add_u32_e32 v2, s13, v128
	s_mov_b32 s6, 0
	s_waitcnt lgkmcnt(0)
	s_barrier

.LBB0_682:
	s_and_b32 s25, s24, 0x4000
	s_xor_b32 s26, s25, 0x4000
	s_lshl_b32 s26, s26, 1
	s_add_i32 s26, s26, 32
	s_add_u32 s90, s52, s14
	s_addc_u32 s91, s53, s15
	s_add_i32 m0, s26, s82
	s_lshl_b32 s25, s25, 1
	global_load_lds_dwordx4 v192, s[90:91]
	s_add_i32 m0, s26, s83
	s_add_i32 s25, s25, 32
	global_load_lds_dwordx4 v193, s[90:91]
	s_add_i32 m0, s26, s84
	v_add3_u32 v170, s25, v114, v135
	global_load_lds_dwordx4 v194, s[90:91]
	s_add_i32 m0, s26, s85
	v_add3_u32 v171, s25, v115, v135
	global_load_lds_dwordx4 v195, s[90:91]
	s_add_i32 m0, s26, s86
	v_add_u32_e32 v158, v170, v136
	global_load_lds_dwordx4 v196, s[90:91]
	s_add_i32 m0, s26, s87
	v_add_u32_e32 v166, v171, v136
	global_load_lds_dwordx4 v197, s[90:91]
	s_add_i32 m0, s26, s88
	s_addk_i32 s24, 0x4000
	global_load_lds_dwordx4 v198, s[90:91]
	s_add_i32 m0, s26, s89
	s_add_u32 s14, s14, 0x80
	s_addc_u32 s15, s15, 0
	global_load_lds_dwordx4 v199, s[90:91]
	ds_read_b128 v[138:141], v158
	ds_read_b128 v[142:145], v158 offset:2048
	ds_read_b128 v[146:149], v166 offset:16384
	ds_read_b128 v[150:153], v166 offset:18432
	ds_read_b128 v[154:157], v158 offset:4096
	ds_read_b128 v[158:161], v158 offset:6144
	ds_read_b128 v[162:165], v166 offset:20480
	ds_read_b128 v[166:169], v166 offset:22528
	s_setprio 1
	s_waitcnt lgkmcnt(0)
	v_mfma_f32_16x16x32_bf16 v[60:63], v[138:141], v[146:149], v[60:63]
	v_mfma_f32_16x16x32_bf16 v[56:59], v[138:141], v[150:153], v[56:59]
	v_mfma_f32_16x16x32_bf16 v[52:55], v[138:141], v[162:165], v[52:55]
	v_mfma_f32_16x16x32_bf16 v[48:51], v[138:141], v[166:169], v[48:51]
	v_mfma_f32_16x16x32_bf16 v[44:47], v[142:145], v[146:149], v[44:47]
	v_mfma_f32_16x16x32_bf16 v[40:43], v[142:145], v[150:153], v[40:43]
	v_mfma_f32_16x16x32_bf16 v[36:39], v[142:145], v[162:165], v[36:39]
	v_mfma_f32_16x16x32_bf16 v[32:35], v[142:145], v[166:169], v[32:35]
	v_mfma_f32_16x16x32_bf16 v[28:31], v[154:157], v[146:149], v[28:31]
	v_mfma_f32_16x16x32_bf16 v[24:27], v[154:157], v[150:153], v[24:27]
	v_mfma_f32_16x16x32_bf16 v[20:23], v[154:157], v[162:165], v[20:23]
	v_mfma_f32_16x16x32_bf16 v[16:19], v[154:157], v[166:169], v[16:19]
	v_mfma_f32_16x16x32_bf16 v[12:15], v[158:161], v[146:149], v[12:15]
	v_mfma_f32_16x16x32_bf16 v[8:11], v[158:161], v[150:153], v[8:11]
	v_mfma_f32_16x16x32_bf16 v[4:7], v[158:161], v[162:165], v[4:7]
	v_mfma_f32_16x16x32_bf16 v[0:3], v[158:161], v[166:169], v[0:3]
	s_setprio 0
	v_add_u32_e32 v158, v170, v137
	v_add_u32_e32 v166, v171, v137
	ds_read_b128 v[138:141], v158
	ds_read_b128 v[142:145], v158 offset:2048
	ds_read_b128 v[146:149], v166 offset:16384
	ds_read_b128 v[150:153], v166 offset:18432
	ds_read_b128 v[154:157], v158 offset:4096
	ds_read_b128 v[158:161], v158 offset:6144
	ds_read_b128 v[162:165], v166 offset:20480
	ds_read_b128 v[166:169], v166 offset:22528
	s_setprio 1
	s_waitcnt lgkmcnt(0)
	v_mfma_f32_16x16x32_bf16 v[60:63], v[138:141], v[146:149], v[60:63]
	v_mfma_f32_16x16x32_bf16 v[56:59], v[138:141], v[150:153], v[56:59]
	v_mfma_f32_16x16x32_bf16 v[52:55], v[138:141], v[162:165], v[52:55]
	v_mfma_f32_16x16x32_bf16 v[48:51], v[138:141], v[166:169], v[48:51]
	v_mfma_f32_16x16x32_bf16 v[44:47], v[142:145], v[146:149], v[44:47]
	v_mfma_f32_16x16x32_bf16 v[40:43], v[142:145], v[150:153], v[40:43]
	v_mfma_f32_16x16x32_bf16 v[36:39], v[142:145], v[162:165], v[36:39]
	v_mfma_f32_16x16x32_bf16 v[32:35], v[142:145], v[166:169], v[32:35]
	v_mfma_f32_16x16x32_bf16 v[28:31], v[154:157], v[146:149], v[28:31]
	v_mfma_f32_16x16x32_bf16 v[24:27], v[154:157], v[150:153], v[24:27]
	v_mfma_f32_16x16x32_bf16 v[20:23], v[154:157], v[162:165], v[20:23]
	v_mfma_f32_16x16x32_bf16 v[16:19], v[154:157], v[166:169], v[16:19]
	v_mfma_f32_16x16x32_bf16 v[12:15], v[158:161], v[146:149], v[12:15]
	v_mfma_f32_16x16x32_bf16 v[8:11], v[158:161], v[150:153], v[8:11]
	v_mfma_f32_16x16x32_bf16 v[4:7], v[158:161], v[162:165], v[4:7]
	v_mfma_f32_16x16x32_bf16 v[0:3], v[158:161], v[166:169], v[0:3]
	s_setprio 0
	s_cmpk_eq_i32 s14, 0x1f80
	s_waitcnt vmcnt(0)
	s_barrier
	s_cbranch_scc0 .LBB0_682
	ds_read_b128 v[90:93], v118 offset:55296
	ds_read_b128 v[94:97], v118 offset:53248
	ds_read_b128 v[98:101], v119 offset:38912
	ds_read_b128 v[102:105], v119 offset:36864
	ds_read_b128 v[138:141], v118 offset:51200
	ds_read_b128 v[142:145], v118 offset:49152
	ds_read_b128 v[146:149], v119 offset:34816
	ds_read_b128 v[150:153], v119 offset:32768
	s_setprio 1
	s_waitcnt lgkmcnt(5)
	v_mfma_f32_16x16x32_bf16 v[4:7], v[98:101], v[94:97], v[4:7]
	v_mfma_f32_16x16x32_bf16 v[0:3], v[98:101], v[90:93], v[0:3]
	s_waitcnt lgkmcnt(0)
	v_mfma_f32_16x16x32_bf16 v[60:63], v[150:153], v[142:145], v[60:63]
	v_mfma_f32_16x16x32_bf16 v[56:59], v[150:153], v[138:141], v[56:59]
	v_mfma_f32_16x16x32_bf16 v[52:55], v[150:153], v[94:97], v[52:55]
	v_mfma_f32_16x16x32_bf16 v[48:51], v[150:153], v[90:93], v[48:51]
	v_mfma_f32_16x16x32_bf16 v[44:47], v[146:149], v[142:145], v[44:47]
	v_mfma_f32_16x16x32_bf16 v[40:43], v[146:149], v[138:141], v[40:43]
	v_mfma_f32_16x16x32_bf16 v[36:39], v[146:149], v[94:97], v[36:39]
	v_mfma_f32_16x16x32_bf16 v[32:35], v[146:149], v[90:93], v[32:35]
	v_mfma_f32_16x16x32_bf16 v[28:31], v[102:105], v[142:145], v[28:31]
	v_mfma_f32_16x16x32_bf16 v[24:27], v[102:105], v[138:141], v[24:27]
	v_mfma_f32_16x16x32_bf16 v[20:23], v[102:105], v[94:97], v[20:23]
	v_mfma_f32_16x16x32_bf16 v[16:19], v[102:105], v[90:93], v[16:19]
	v_mfma_f32_16x16x32_bf16 v[12:15], v[98:101], v[142:145], v[12:15]
	v_mfma_f32_16x16x32_bf16 v[8:11], v[98:101], v[138:141], v[8:11]
	s_setprio 0
	ds_read_b128 v[90:93], v120 offset:32768
	ds_read_b128 v[94:97], v120 offset:34816
	ds_read_b128 v[98:101], v121 offset:49152
	ds_read_b128 v[102:105], v121 offset:51200
	ds_read_b128 v[138:141], v120 offset:36864
	ds_read_b128 v[142:145], v120 offset:38912
	ds_read_b128 v[146:149], v121 offset:53248
	ds_read_b128 v[150:153], v121 offset:55296
	s_setprio 1
	s_waitcnt lgkmcnt(1)
	v_mfma_f32_16x16x32_bf16 v[4:7], v[142:145], v[146:149], v[4:7]
	s_waitcnt lgkmcnt(0)
	v_mfma_f32_16x16x32_bf16 v[0:3], v[142:145], v[150:153], v[0:3]
	v_mfma_f32_16x16x32_bf16 v[60:63], v[90:93], v[98:101], v[60:63]
	v_mfma_f32_16x16x32_bf16 v[56:59], v[90:93], v[102:105], v[56:59]
	v_mfma_f32_16x16x32_bf16 v[52:55], v[90:93], v[146:149], v[52:55]
	v_mfma_f32_16x16x32_bf16 v[48:51], v[90:93], v[150:153], v[48:51]
	v_mfma_f32_16x16x32_bf16 v[44:47], v[94:97], v[98:101], v[44:47]
	v_mfma_f32_16x16x32_bf16 v[40:43], v[94:97], v[102:105], v[40:43]
	v_mfma_f32_16x16x32_bf16 v[36:39], v[94:97], v[146:149], v[36:39]
	v_mfma_f32_16x16x32_bf16 v[32:35], v[94:97], v[150:153], v[32:35]
	v_mfma_f32_16x16x32_bf16 v[28:31], v[138:141], v[98:101], v[28:31]
	v_mfma_f32_16x16x32_bf16 v[24:27], v[138:141], v[102:105], v[24:27]
	v_mfma_f32_16x16x32_bf16 v[20:23], v[138:141], v[146:149], v[20:23]
	v_mfma_f32_16x16x32_bf16 v[16:19], v[138:141], v[150:153], v[16:19]
	v_mfma_f32_16x16x32_bf16 v[12:15], v[142:145], v[98:101], v[12:15]
	v_mfma_f32_16x16x32_bf16 v[8:11], v[142:145], v[102:105], v[8:11]
	s_setprio 0
	s_barrier
	ds_write2_b32 v116, v60, v56 offset1:16
	ds_write2_b32 v116, v61, v57 offset0:132 offset1:148
	v_add_u32_e32 v56, 0x400, v116
	ds_write2_b32 v56, v62, v58 offset0:8 offset1:24
	ds_write2_b32 v56, v63, v59 offset0:140 offset1:156
	ds_write2_b32 v116, v52, v48 offset0:32 offset1:48
	ds_write2_b32 v116, v53, v49 offset0:164 offset1:180
	ds_write2_b32 v56, v54, v50 offset0:40 offset1:56
	ds_write2_b32 v56, v55, v51 offset0:172 offset1:188
	v_add_u32_e32 v48, 0x2000, v116
	ds_write2_b32 v48, v44, v40 offset0:64 offset1:80
	ds_write2_b32 v48, v45, v41 offset0:196 offset1:212
	v_add_u32_e32 v40, 0x2400, v116
	ds_write2_b32 v40, v46, v42 offset0:72 offset1:88
	ds_write2_b32 v40, v47, v43 offset0:204 offset1:220
	ds_write2_b32 v48, v36, v32 offset0:96 offset1:112
	ds_write2_b32 v48, v37, v33 offset0:228 offset1:244
	ds_write2_b32 v40, v38, v34 offset0:104 offset1:120
	ds_write2_b32 v40, v39, v35 offset0:236 offset1:252
	v_add_u32_e32 v32, 0x4000, v116
	ds_write2_b32 v32, v28, v24 offset0:128 offset1:144
	v_add_u32_e32 v24, 0x4400, v116
	ds_write2_b32 v24, v29, v25 offset0:4 offset1:20
	ds_write2_b32 v24, v30, v26 offset0:136 offset1:152
	v_add_u32_e32 v25, 0x4800, v116
	ds_write2_b32 v25, v31, v27 offset0:12 offset1:28
	ds_write2_b32 v32, v20, v16 offset0:160 offset1:176
	ds_write2_b32 v24, v21, v17 offset0:36 offset1:52
	ds_write2_b32 v24, v22, v18 offset0:168 offset1:184
	ds_write2_b32 v25, v23, v19 offset0:44 offset1:60
	v_add_u32_e32 v16, 0x6000, v116
	ds_write2_b32 v16, v12, v8 offset0:192 offset1:208
	v_add_u32_e32 v8, 0x6400, v116
	ds_write2_b32 v8, v13, v9 offset0:68 offset1:84
	ds_write2_b32 v8, v14, v10 offset0:200 offset1:216
	v_add_u32_e32 v9, 0x6800, v116
	ds_write2_b32 v9, v15, v11 offset0:76 offset1:92
	ds_write2_b32 v16, v4, v0 offset0:224 offset1:240
	ds_write2_b32 v8, v5, v1 offset0:100 offset1:116
	ds_write2_b32 v8, v6, v2 offset0:232 offset1:248
	ds_write2_b32 v9, v7, v3 offset0:108 offset1:124
	v_or_b32_e32 v0, s23, v117
	v_ashrrev_i32_e32 v1, 31, v0
	v_lshlrev_b64 v[2:3], 2, v[0:1]
	v_lshl_add_u64 v[0:1], s[12:13], 0, v[2:3]
	v_lshl_add_u64 v[2:3], s[10:11], 0, v[2:3]
	v_add_u32_e32 v4, s22, v128
	s_mov_b32 s14, 0
	s_waitcnt lgkmcnt(0)
	s_barrier

.LBB0_691:
	s_and_b32 s26, s25, 0x4000
	s_xor_b32 s27, s26, 0x4000
	s_lshl_b32 s27, s27, 1
	s_add_i32 s27, s27, 32
	s_add_u32 s90, s52, s14
	s_addc_u32 s91, s53, s15
	s_add_i32 m0, s27, s82
	s_lshl_b32 s26, s26, 1
	global_load_lds_dwordx4 v192, s[90:91]
	s_add_i32 m0, s27, s83
	s_add_i32 s26, s26, 32
	global_load_lds_dwordx4 v193, s[90:91]
	s_add_i32 m0, s27, s84
	v_add3_u32 v139, s26, v113, v136
	global_load_lds_dwordx4 v194, s[90:91]
	s_add_i32 m0, s27, s85
	v_add3_u32 v172, s26, v114, v136
	global_load_lds_dwordx4 v195, s[90:91]
	s_add_i32 m0, s27, s86
	v_add_u32_e32 v160, v139, v137
	global_load_lds_dwordx4 v196, s[90:91]
	s_add_i32 m0, s27, s87
	v_add_u32_e32 v168, v172, v137
	global_load_lds_dwordx4 v197, s[90:91]
	s_add_i32 m0, s27, s88
	s_addk_i32 s25, 0x4000
	global_load_lds_dwordx4 v198, s[90:91]
	s_add_i32 m0, s27, s89
	s_add_u32 s14, s14, 0x80
	s_addc_u32 s15, s15, 0
	global_load_lds_dwordx4 v199, s[90:91]
	ds_read_b128 v[140:143], v160
	ds_read_b128 v[144:147], v160 offset:2048
	ds_read_b128 v[148:151], v168 offset:16384
	ds_read_b128 v[152:155], v168 offset:18432
	ds_read_b128 v[156:159], v160 offset:4096
	ds_read_b128 v[160:163], v160 offset:6144
	ds_read_b128 v[164:167], v168 offset:20480
	ds_read_b128 v[168:171], v168 offset:22528
	s_setprio 1
	s_waitcnt lgkmcnt(0)
	v_mfma_f32_16x16x32_bf16 v[60:63], v[140:143], v[148:151], v[60:63]
	v_mfma_f32_16x16x32_bf16 v[56:59], v[140:143], v[152:155], v[56:59]
	v_mfma_f32_16x16x32_bf16 v[52:55], v[140:143], v[164:167], v[52:55]
	v_mfma_f32_16x16x32_bf16 v[48:51], v[140:143], v[168:171], v[48:51]
	v_mfma_f32_16x16x32_bf16 v[44:47], v[144:147], v[148:151], v[44:47]
	v_mfma_f32_16x16x32_bf16 v[40:43], v[144:147], v[152:155], v[40:43]
	v_mfma_f32_16x16x32_bf16 v[36:39], v[144:147], v[164:167], v[36:39]
	v_mfma_f32_16x16x32_bf16 v[32:35], v[144:147], v[168:171], v[32:35]
	v_mfma_f32_16x16x32_bf16 v[28:31], v[156:159], v[148:151], v[28:31]
	v_mfma_f32_16x16x32_bf16 v[24:27], v[156:159], v[152:155], v[24:27]
	v_mfma_f32_16x16x32_bf16 v[20:23], v[156:159], v[164:167], v[20:23]
	v_mfma_f32_16x16x32_bf16 v[16:19], v[156:159], v[168:171], v[16:19]
	v_mfma_f32_16x16x32_bf16 v[12:15], v[160:163], v[148:151], v[12:15]
	v_mfma_f32_16x16x32_bf16 v[8:11], v[160:163], v[152:155], v[8:11]
	v_mfma_f32_16x16x32_bf16 v[4:7], v[160:163], v[164:167], v[4:7]
	v_mfma_f32_16x16x32_bf16 v[0:3], v[160:163], v[168:171], v[0:3]
	s_setprio 0
	v_add_u32_e32 v139, v139, v138
	v_add_u32_e32 v168, v172, v138
	ds_read_b128 v[140:143], v139
	ds_read_b128 v[144:147], v139 offset:2048
	ds_read_b128 v[148:151], v168 offset:16384
	ds_read_b128 v[152:155], v168 offset:18432
	ds_read_b128 v[156:159], v139 offset:4096
	ds_read_b128 v[160:163], v139 offset:6144
	ds_read_b128 v[164:167], v168 offset:20480
	ds_read_b128 v[168:171], v168 offset:22528
	s_setprio 1
	s_waitcnt lgkmcnt(0)
	v_mfma_f32_16x16x32_bf16 v[60:63], v[140:143], v[148:151], v[60:63]
	v_mfma_f32_16x16x32_bf16 v[56:59], v[140:143], v[152:155], v[56:59]
	v_mfma_f32_16x16x32_bf16 v[52:55], v[140:143], v[164:167], v[52:55]
	v_mfma_f32_16x16x32_bf16 v[48:51], v[140:143], v[168:171], v[48:51]
	v_mfma_f32_16x16x32_bf16 v[44:47], v[144:147], v[148:151], v[44:47]
	v_mfma_f32_16x16x32_bf16 v[40:43], v[144:147], v[152:155], v[40:43]
	v_mfma_f32_16x16x32_bf16 v[36:39], v[144:147], v[164:167], v[36:39]
	v_mfma_f32_16x16x32_bf16 v[32:35], v[144:147], v[168:171], v[32:35]
	v_mfma_f32_16x16x32_bf16 v[28:31], v[156:159], v[148:151], v[28:31]
	v_mfma_f32_16x16x32_bf16 v[24:27], v[156:159], v[152:155], v[24:27]
	v_mfma_f32_16x16x32_bf16 v[20:23], v[156:159], v[164:167], v[20:23]
	v_mfma_f32_16x16x32_bf16 v[16:19], v[156:159], v[168:171], v[16:19]
	v_mfma_f32_16x16x32_bf16 v[12:15], v[160:163], v[148:151], v[12:15]
	v_mfma_f32_16x16x32_bf16 v[8:11], v[160:163], v[152:155], v[8:11]
	v_mfma_f32_16x16x32_bf16 v[4:7], v[160:163], v[164:167], v[4:7]
	v_mfma_f32_16x16x32_bf16 v[0:3], v[160:163], v[168:171], v[0:3]
	s_setprio 0
	s_cmpk_eq_i32 s14, 0x1f80
	s_waitcnt vmcnt(0)
	s_barrier
	s_cbranch_scc0 .LBB0_691
	ds_read_b128 v[88:91], v117 offset:55296
	ds_read_b128 v[92:95], v117 offset:53248
	ds_read_b128 v[96:99], v118 offset:38912
	ds_read_b128 v[100:103], v118 offset:36864
	ds_read_b128 v[140:143], v117 offset:51200
	ds_read_b128 v[144:147], v117 offset:49152
	ds_read_b128 v[148:151], v118 offset:34816
	ds_read_b128 v[152:155], v118 offset:32768
	s_setprio 1
	s_waitcnt lgkmcnt(5)
	v_mfma_f32_16x16x32_bf16 v[4:7], v[96:99], v[92:95], v[4:7]
	v_mfma_f32_16x16x32_bf16 v[0:3], v[96:99], v[88:91], v[0:3]
	s_waitcnt lgkmcnt(0)
	v_mfma_f32_16x16x32_bf16 v[60:63], v[152:155], v[144:147], v[60:63]
	v_mfma_f32_16x16x32_bf16 v[56:59], v[152:155], v[140:143], v[56:59]
	v_mfma_f32_16x16x32_bf16 v[52:55], v[152:155], v[92:95], v[52:55]
	v_mfma_f32_16x16x32_bf16 v[48:51], v[152:155], v[88:91], v[48:51]
	v_mfma_f32_16x16x32_bf16 v[44:47], v[148:151], v[144:147], v[44:47]
	v_mfma_f32_16x16x32_bf16 v[40:43], v[148:151], v[140:143], v[40:43]
	v_mfma_f32_16x16x32_bf16 v[36:39], v[148:151], v[92:95], v[36:39]
	v_mfma_f32_16x16x32_bf16 v[32:35], v[148:151], v[88:91], v[32:35]
	v_mfma_f32_16x16x32_bf16 v[28:31], v[100:103], v[144:147], v[28:31]
	v_mfma_f32_16x16x32_bf16 v[24:27], v[100:103], v[140:143], v[24:27]
	v_mfma_f32_16x16x32_bf16 v[20:23], v[100:103], v[92:95], v[20:23]
	v_mfma_f32_16x16x32_bf16 v[16:19], v[100:103], v[88:91], v[16:19]
	v_mfma_f32_16x16x32_bf16 v[12:15], v[96:99], v[144:147], v[12:15]
	v_mfma_f32_16x16x32_bf16 v[8:11], v[96:99], v[140:143], v[8:11]
	s_setprio 0
	ds_read_b128 v[88:91], v119 offset:32768
	ds_read_b128 v[92:95], v119 offset:34816
	ds_read_b128 v[96:99], v120 offset:49152
	ds_read_b128 v[100:103], v120 offset:51200
	ds_read_b128 v[140:143], v119 offset:36864
	ds_read_b128 v[144:147], v119 offset:38912
	ds_read_b128 v[148:151], v120 offset:53248
	ds_read_b128 v[152:155], v120 offset:55296
	s_setprio 1
	s_waitcnt lgkmcnt(1)
	v_mfma_f32_16x16x32_bf16 v[4:7], v[144:147], v[148:151], v[4:7]
	s_waitcnt lgkmcnt(0)
	v_mfma_f32_16x16x32_bf16 v[0:3], v[144:147], v[152:155], v[0:3]
	v_mfma_f32_16x16x32_bf16 v[60:63], v[88:91], v[96:99], v[60:63]
	v_mfma_f32_16x16x32_bf16 v[56:59], v[88:91], v[100:103], v[56:59]
	v_mfma_f32_16x16x32_bf16 v[52:55], v[88:91], v[148:151], v[52:55]
	v_mfma_f32_16x16x32_bf16 v[48:51], v[88:91], v[152:155], v[48:51]
	v_mfma_f32_16x16x32_bf16 v[44:47], v[92:95], v[96:99], v[44:47]
	v_mfma_f32_16x16x32_bf16 v[40:43], v[92:95], v[100:103], v[40:43]
	v_mfma_f32_16x16x32_bf16 v[36:39], v[92:95], v[148:151], v[36:39]
	v_mfma_f32_16x16x32_bf16 v[32:35], v[92:95], v[152:155], v[32:35]
	v_mfma_f32_16x16x32_bf16 v[28:31], v[140:143], v[96:99], v[28:31]
	v_mfma_f32_16x16x32_bf16 v[24:27], v[140:143], v[100:103], v[24:27]
	v_mfma_f32_16x16x32_bf16 v[20:23], v[140:143], v[148:151], v[20:23]
	v_mfma_f32_16x16x32_bf16 v[16:19], v[140:143], v[152:155], v[16:19]
	v_mfma_f32_16x16x32_bf16 v[12:15], v[144:147], v[96:99], v[12:15]
	v_mfma_f32_16x16x32_bf16 v[8:11], v[144:147], v[100:103], v[8:11]
	s_setprio 0
	s_barrier
	ds_write2_b32 v115, v60, v56 offset1:16
	ds_write2_b32 v115, v61, v57 offset0:132 offset1:148
	v_add_u32_e32 v56, 0x400, v115
	ds_write2_b32 v56, v62, v58 offset0:8 offset1:24
	ds_write2_b32 v56, v63, v59 offset0:140 offset1:156
	ds_write2_b32 v115, v52, v48 offset0:32 offset1:48
	ds_write2_b32 v115, v53, v49 offset0:164 offset1:180
	ds_write2_b32 v56, v54, v50 offset0:40 offset1:56
	ds_write2_b32 v56, v55, v51 offset0:172 offset1:188
	v_add_u32_e32 v48, 0x2000, v115
	ds_write2_b32 v48, v44, v40 offset0:64 offset1:80
	ds_write2_b32 v48, v45, v41 offset0:196 offset1:212
	v_add_u32_e32 v40, 0x2400, v115
	ds_write2_b32 v40, v46, v42 offset0:72 offset1:88
	ds_write2_b32 v40, v47, v43 offset0:204 offset1:220
	ds_write2_b32 v48, v36, v32 offset0:96 offset1:112
	ds_write2_b32 v48, v37, v33 offset0:228 offset1:244
	ds_write2_b32 v40, v38, v34 offset0:104 offset1:120
	ds_write2_b32 v40, v39, v35 offset0:236 offset1:252
	v_add_u32_e32 v32, 0x4000, v115
	ds_write2_b32 v32, v28, v24 offset0:128 offset1:144
	v_add_u32_e32 v24, 0x4400, v115
	ds_write2_b32 v24, v29, v25 offset0:4 offset1:20
	ds_write2_b32 v24, v30, v26 offset0:136 offset1:152
	v_add_u32_e32 v25, 0x4800, v115
	ds_write2_b32 v25, v31, v27 offset0:12 offset1:28
	ds_write2_b32 v32, v20, v16 offset0:160 offset1:176
	ds_write2_b32 v24, v21, v17 offset0:36 offset1:52
	ds_write2_b32 v24, v22, v18 offset0:168 offset1:184
	ds_write2_b32 v25, v23, v19 offset0:44 offset1:60
	v_add_u32_e32 v16, 0x6000, v115
	ds_write2_b32 v16, v12, v8 offset0:192 offset1:208
	v_add_u32_e32 v8, 0x6400, v115
	ds_write2_b32 v8, v13, v9 offset0:68 offset1:84
	ds_write2_b32 v8, v14, v10 offset0:200 offset1:216
	v_add_u32_e32 v9, 0x6800, v115
	ds_write2_b32 v9, v15, v11 offset0:76 offset1:92
	ds_write2_b32 v16, v4, v0 offset0:224 offset1:240
	ds_write2_b32 v8, v5, v1 offset0:100 offset1:116
	ds_write2_b32 v8, v6, v2 offset0:232 offset1:248
	ds_write2_b32 v9, v7, v3 offset0:108 offset1:124
	v_or_b32_e32 v0, s23, v116
	v_ashrrev_i32_e32 v1, 31, v0
	v_lshlrev_b64 v[2:3], 2, v[0:1]
	v_lshl_add_u64 v[0:1], s[12:13], 0, v[2:3]
	v_lshl_add_u64 v[2:3], s[10:11], 0, v[2:3]
	v_add_u32_e32 v4, s24, v129
	s_mov_b32 s14, 0
	s_waitcnt lgkmcnt(0)
	s_barrier

.LBB0_1594:
	s_or_b64 exec, exec, s[4:5]
	s_load_dword s4, s[0:1], 0x1f8
	v_cmp_lt_i32_e32 vcc, 12, v0
	s_waitcnt lgkmcnt(0)
	s_cmp_lt_i32 s4, 13
	s_cselect_b64 s[4:5], -1, 0
	s_and_b64 s[4:5], s[4:5], vcc
	s_and_saveexec_b64 s[10:11], s[4:5]
	s_cbranch_execz .LBB0_1746
	s_cmpk_gt_i32 s2, 0xff
	s_cbranch_scc1 .LBB0_1691
	s_load_dwordx2 s[16:17], s[0:1], 0x1f0
	s_movk_i32 s6, 0x80
	v_mov_b32_e32 v3, 0x13e80000
	v_mov_b32_e32 v4, 0x13a00000
	v_cmp_gt_u32_e32 vcc, s6, v180
	s_waitcnt lgkmcnt(0)
	s_add_u32 s18, s16, 0x8600000
	s_addc_u32 s19, s17, 0
	s_add_u32 s20, s16, 0xaa00000
	s_addc_u32 s21, s17, 0
	s_add_u32 s22, s16, 0xce00000
	s_addc_u32 s23, s17, 0
	v_and_b32_e32 v154, 63, v180
	s_add_u32 s40, s16, 0x14780000
	v_cndmask_b32_e32 v112, v3, v4, vcc
	v_and_b32_e32 v3, 7, v180
	s_load_dwordx2 s[28:29], s[0:1], 0x98
	s_load_dwordx2 s[30:31], s[0:1], 0xb0
	v_lshrrev_b32_e32 v155, 6, v180
	s_addc_u32 s41, s17, 0
	v_lshrrev_b32_e32 v0, 1, v180
	s_add_i32 s6, 32, 0x6000
	v_lshl_add_u32 v158, v3, 5, 32
	v_cmp_eq_u32_e64 s[8:9], 0, v3
	v_lshlrev_b32_e32 v3, 2, v154
	v_and_b32_e32 v156, 31, v180
	v_and_b32_e32 v2, 32, v0
	v_mov_b32_e32 v4, s6
	v_lshl_or_b32 v3, v155, 8, v3
	v_bfe_u32 v1, v180, 5, 1
	v_or_b32_e32 v157, v2, v156
	v_mov_b32_e32 v113, 0
	v_cndmask_b32_e64 v4, v4, 32, vcc
	v_lshlrev_b32_e32 v2, 2, v2
	v_lshlrev_b32_e32 v5, 2, v156
	v_add_u32_e32 v3, 32, v3
	s_load_dwordx2 s[26:27], s[0:1], 0xe8
	s_load_dwordx4 s[12:15], s[0:1], 0xd8
	v_lshlrev_b32_e32 v0, 3, v1
	v_lshl_add_u64 v[114:115], s[16:17], 0, v[112:113]
	v_add3_u32 v4, v4, v2, v5
	v_lshlrev_b32_e32 v5, 10, v1
	v_lshlrev_b32_e32 v112, 4, v1
	v_and_b32_e32 v1, 0x3f8, v180
	v_add_u32_e32 v162, 0x400, v3
	v_add_u32_e32 v163, 0x800, v3
	v_add_u32_e32 v164, 0xc00, v3
	v_add_u32_e32 v165, 0x1000, v3
	v_add_u32_e32 v166, 0x1400, v3
	v_add_u32_e32 v167, 0x1800, v3
	v_add_u32_e32 v168, 0x1c00, v3
	v_mov_b32_e32 v3, 0x1740000
	v_mov_b32_e32 v6, 0x1700000
	v_lshl_add_u64 v[116:117], v[114:115], 0, v[112:113]
	v_add_u32_e32 v159, 32, v1
	v_lshlrev_b32_e32 v1, 3, v180
	v_cndmask_b32_e32 v112, v3, v6, vcc
	s_waitcnt lgkmcnt(0)
	v_mov_b32_e32 v3, s31
	v_mov_b32_e32 v6, s29
	s_movk_i32 s4, 0x7f
	v_lshl_add_u32 v161, v180, 5, 32
	v_lshl_add_u32 v208, v180, 4, 32
	v_add_u32_e32 v208, 0xe000, v208
	v_lshlrev_b32_e32 v209, 1, v154
	v_lshl_add_u32 v209, v155, 7, v209
	v_add_u32_e32 v209, 0xe020, v209
	v_and_b32_e32 v2, 56, v1
	v_mul_i32_i24_e32 v1, 0xffffffe4, v180
	v_cndmask_b32_e32 v121, v3, v6, vcc
	v_mov_b32_e32 v3, s30
	v_mov_b32_e32 v6, s28
	v_cmp_lt_u32_e64 s[4:5], s4, v180
	s_mov_b32 s25, 0
	v_cmp_eq_u32_e64 s[6:7], 0, v154
	v_lshrrev_b32_e32 v160, 3, v180
	v_lshl_add_u64 v[118:119], s[16:17], 0, v[112:113]
	v_cndmask_b32_e32 v120, v3, v6, vcc
	v_add_u32_e32 v169, 0xa100, v159
	v_add_u32_e32 v170, 0x100, v158
	s_mov_b32 s42, 0x6200000
	v_lshlrev_b32_e32 v122, 1, v0
	v_mov_b32_e32 v123, v113
	v_lshlrev_b32_e32 v124, 1, v2
	v_mov_b32_e32 v125, v113
	s_mov_b32 s43, 0xbf1b4598
	s_movk_i32 s44, 0x9ff
	v_add_u32_e32 v171, v4, v5
	v_add_u32_e32 v172, v161, v1
	v_cmp_gt_u32_e64 s[76:77], 64, v180
	v_add_u32_e32 v210, 0xffffff00, v172
	v_cndmask_b32_e64 v210, v210, v172, s[76:77]
	s_mov_b32 s45, s2
	s_branch .LBB0_1598

.Lrw_p1_decay:
	v_add_f32_e32 v48, v176, v0
	v_add_f32_e32 v49, v176, v1
	v_max_f32_e32 v48, 0xc2a00000, v48
	v_max_f32_e32 v49, 0xc2a00000, v49
	v_mul_f32_e32 v48, 0xbfb8aa3b, v48
	v_mul_f32_e32 v49, 0xbfb8aa3b, v49
	v_exp_f32_e32 v48, v48
	v_exp_f32_e32 v49, v49
	v_add_f32_e32 v50, 1.0, v48
	v_add_f32_e32 v51, 1.0, v49
	v_rcp_f32_e32 v56, v50
	v_rcp_f32_e32 v57, v51
	v_fma_f32 v54, -v50, v56, 1.0
	v_fma_f32 v55, -v51, v57, 1.0
	v_fma_f32 v56, v56, v54, v56
	v_fma_f32 v57, v57, v55, v57
	v_mul_f32_e32 v56, s43, v56
	v_mul_f32_e32 v57, s43, v57
	v_mul_f32_e32 v56, 0x3fb8aa3b, v56
	v_mul_f32_e32 v57, 0x3fb8aa3b, v57
	v_exp_f32_e32 v56, v56
	v_exp_f32_e32 v57, v57
	v_add_f32_e32 v48, v176, v2
	v_add_f32_e32 v49, v176, v3
	v_max_f32_e32 v48, 0xc2a00000, v48
	v_max_f32_e32 v49, 0xc2a00000, v49
	v_mul_f32_e32 v48, 0xbfb8aa3b, v48
	v_mul_f32_e32 v49, 0xbfb8aa3b, v49
	v_exp_f32_e32 v48, v48
	v_exp_f32_e32 v49, v49
	v_add_f32_e32 v50, 1.0, v48
	v_add_f32_e32 v51, 1.0, v49
	v_rcp_f32_e32 v58, v50
	v_rcp_f32_e32 v59, v51
	v_fma_f32 v54, -v50, v58, 1.0
	v_fma_f32 v55, -v51, v59, 1.0
	v_fma_f32 v58, v58, v54, v58
	v_fma_f32 v59, v59, v55, v59
	v_mul_f32_e32 v58, s43, v58
	v_mul_f32_e32 v59, s43, v59
	v_mul_f32_e32 v58, 0x3fb8aa3b, v58
	v_mul_f32_e32 v59, 0x3fb8aa3b, v59
	v_exp_f32_e32 v58, v58
	v_exp_f32_e32 v59, v59
	v_add_f32_e32 v48, v176, v4
	v_add_f32_e32 v49, v176, v5
	v_max_f32_e32 v48, 0xc2a00000, v48
	v_max_f32_e32 v49, 0xc2a00000, v49
	v_mul_f32_e32 v48, 0xbfb8aa3b, v48
	v_mul_f32_e32 v49, 0xbfb8aa3b, v49
	v_exp_f32_e32 v48, v48
	v_exp_f32_e32 v49, v49
	v_add_f32_e32 v50, 1.0, v48
	v_add_f32_e32 v51, 1.0, v49
	v_rcp_f32_e32 v60, v50
	v_rcp_f32_e32 v61, v51
	v_fma_f32 v54, -v50, v60, 1.0
	v_fma_f32 v55, -v51, v61, 1.0
	v_fma_f32 v60, v60, v54, v60
	v_fma_f32 v61, v61, v55, v61
	v_mul_f32_e32 v60, s43, v60
	v_mul_f32_e32 v61, s43, v61
	v_mul_f32_e32 v60, 0x3fb8aa3b, v60
	v_mul_f32_e32 v61, 0x3fb8aa3b, v61
	v_exp_f32_e32 v60, v60
	v_exp_f32_e32 v61, v61
	v_add_f32_e32 v48, v176, v6
	v_add_f32_e32 v49, v176, v7
	v_max_f32_e32 v48, 0xc2a00000, v48
	v_max_f32_e32 v49, 0xc2a00000, v49
	v_mul_f32_e32 v48, 0xbfb8aa3b, v48
	v_mul_f32_e32 v49, 0xbfb8aa3b, v49
	v_exp_f32_e32 v48, v48
	v_exp_f32_e32 v49, v49
	v_add_f32_e32 v50, 1.0, v48
	v_add_f32_e32 v51, 1.0, v49
	v_rcp_f32_e32 v62, v50
	v_rcp_f32_e32 v63, v51
	v_fma_f32 v54, -v50, v62, 1.0
	v_fma_f32 v55, -v51, v63, 1.0
	v_fma_f32 v62, v62, v54, v62
	v_fma_f32 v63, v63, v55, v63
	v_mul_f32_e32 v62, s43, v62
	v_mul_f32_e32 v63, s43, v63
	v_mul_f32_e32 v62, 0x3fb8aa3b, v62
	v_mul_f32_e32 v63, 0x3fb8aa3b, v63
	v_exp_f32_e32 v62, v62
	v_exp_f32_e32 v63, v63
	v_add_f32_e32 v48, v176, v8
	v_add_f32_e32 v49, v176, v9
	v_max_f32_e32 v48, 0xc2a00000, v48
	v_max_f32_e32 v49, 0xc2a00000, v49
	v_mul_f32_e32 v48, 0xbfb8aa3b, v48
	v_mul_f32_e32 v49, 0xbfb8aa3b, v49
	v_exp_f32_e32 v48, v48
	v_exp_f32_e32 v49, v49
	v_add_f32_e32 v50, 1.0, v48
	v_add_f32_e32 v51, 1.0, v49
	v_rcp_f32_e32 v64, v50
	v_rcp_f32_e32 v65, v51
	v_fma_f32 v54, -v50, v64, 1.0
	v_fma_f32 v55, -v51, v65, 1.0
	v_fma_f32 v64, v64, v54, v64
	v_fma_f32 v65, v65, v55, v65
	v_mul_f32_e32 v64, s43, v64
	v_mul_f32_e32 v65, s43, v65
	v_mul_f32_e32 v64, 0x3fb8aa3b, v64
	v_mul_f32_e32 v65, 0x3fb8aa3b, v65
	v_exp_f32_e32 v64, v64
	v_exp_f32_e32 v65, v65
	v_add_f32_e32 v48, v176, v10
	v_add_f32_e32 v49, v176, v11
	v_max_f32_e32 v48, 0xc2a00000, v48
	v_max_f32_e32 v49, 0xc2a00000, v49
	v_mul_f32_e32 v48, 0xbfb8aa3b, v48
	v_mul_f32_e32 v49, 0xbfb8aa3b, v49
	v_exp_f32_e32 v48, v48
	v_exp_f32_e32 v49, v49
	v_add_f32_e32 v50, 1.0, v48
	v_add_f32_e32 v51, 1.0, v49
	v_rcp_f32_e32 v66, v50
	v_rcp_f32_e32 v67, v51
	v_fma_f32 v54, -v50, v66, 1.0
	v_fma_f32 v55, -v51, v67, 1.0
	v_fma_f32 v66, v66, v54, v66
	v_fma_f32 v67, v67, v55, v67
	v_mul_f32_e32 v66, s43, v66
	v_mul_f32_e32 v67, s43, v67
	v_mul_f32_e32 v66, 0x3fb8aa3b, v66
	v_mul_f32_e32 v67, 0x3fb8aa3b, v67
	v_exp_f32_e32 v66, v66
	v_exp_f32_e32 v67, v67
	v_add_f32_e32 v48, v176, v12
	v_add_f32_e32 v49, v176, v13
	v_max_f32_e32 v48, 0xc2a00000, v48
	v_max_f32_e32 v49, 0xc2a00000, v49
	v_mul_f32_e32 v48, 0xbfb8aa3b, v48
	v_mul_f32_e32 v49, 0xbfb8aa3b, v49
	v_exp_f32_e32 v48, v48
	v_exp_f32_e32 v49, v49
	v_add_f32_e32 v50, 1.0, v48
	v_add_f32_e32 v51, 1.0, v49
	v_rcp_f32_e32 v68, v50
	v_rcp_f32_e32 v69, v51
	v_fma_f32 v54, -v50, v68, 1.0
	v_fma_f32 v55, -v51, v69, 1.0
	v_fma_f32 v68, v68, v54, v68
	v_fma_f32 v69, v69, v55, v69
	v_mul_f32_e32 v68, s43, v68
	v_mul_f32_e32 v69, s43, v69
	v_mul_f32_e32 v68, 0x3fb8aa3b, v68
	v_mul_f32_e32 v69, 0x3fb8aa3b, v69
	v_exp_f32_e32 v68, v68
	v_exp_f32_e32 v69, v69
	v_add_f32_e32 v48, v176, v14
	v_add_f32_e32 v49, v176, v15
	v_max_f32_e32 v48, 0xc2a00000, v48
	v_max_f32_e32 v49, 0xc2a00000, v49
	v_mul_f32_e32 v48, 0xbfb8aa3b, v48
	v_mul_f32_e32 v49, 0xbfb8aa3b, v49
	v_exp_f32_e32 v48, v48
	v_exp_f32_e32 v49, v49
	v_add_f32_e32 v50, 1.0, v48
	v_add_f32_e32 v51, 1.0, v49
	v_rcp_f32_e32 v70, v50
	v_rcp_f32_e32 v71, v51
	v_fma_f32 v54, -v50, v70, 1.0
	v_fma_f32 v55, -v51, v71, 1.0
	v_fma_f32 v70, v70, v54, v70
	v_fma_f32 v71, v71, v55, v71
	v_mul_f32_e32 v70, s43, v70
	v_mul_f32_e32 v71, s43, v71
	v_mul_f32_e32 v70, 0x3fb8aa3b, v70
	v_mul_f32_e32 v71, 0x3fb8aa3b, v71
	v_exp_f32_e32 v70, v70
	v_exp_f32_e32 v71, v71
	s_nop 0
	v_mul_f32_e32 v57, v56, v57
	v_mul_f32_e32 v61, v60, v61
	v_mul_f32_e32 v65, v64, v65
	v_mul_f32_e32 v69, v68, v69
	v_mul_f32_e32 v58, v57, v58
	v_mul_f32_e32 v62, v61, v62
	v_mul_f32_e32 v66, v65, v66
	v_mul_f32_e32 v70, v69, v70
	v_mul_f32_e32 v59, v58, v59
	v_mul_f32_e32 v63, v62, v63
	v_mul_f32_e32 v67, v66, v67
	v_mul_f32_e32 v71, v70, v71
	v_mov_b32_e32 v72, v59
	v_mov_b32_e32 v73, v63
	v_mov_b32_e32 v74, v67
	v_mov_b32_e32 v75, v71
	v_mov_b32_e32 v76, v59
	v_mov_b32_e32 v77, v63
	v_mov_b32_e32 v78, v67
	v_mov_b32_e32 v79, v71
	v_permlane32_swap_b32_e32 v72, v76
	v_permlane32_swap_b32_e32 v73, v77
	v_permlane32_swap_b32_e32 v74, v78
	v_permlane32_swap_b32_e32 v75, v79
	v_mul_f32_e32 v82, v72, v76
	s_mov_b32 s36, 0
	s_mov_b32 s37, -1
	v_mul_f32_e32 v83, v82, v73
	s_nop 0
	v_mul_f32_e32 v84, v83, v77
	s_nop 0
	v_mul_f32_e32 v85, v84, v74
	s_nop 0
	v_mul_f32_e32 v86, v85, v78
	s_nop 0
	v_mul_f32_e32 v87, v86, v75
	v_cndmask_b32_e64 v88, 1.0, v72, s[36:37]
	v_cndmask_b32_e64 v89, v82, v83, s[36:37]
	v_cndmask_b32_e64 v90, v84, v85, s[36:37]
	v_cndmask_b32_e64 v91, v86, v87, s[36:37]
	v_mul_f32_e32 v56, v88, v56
	v_mul_f32_e32 v57, v88, v57
	v_mul_f32_e32 v58, v88, v58
	v_mul_f32_e32 v59, v88, v59
	v_mul_f32_e32 v60, v89, v60
	v_mul_f32_e32 v61, v89, v61
	v_mul_f32_e32 v62, v89, v62
	v_mul_f32_e32 v63, v89, v63
	v_mul_f32_e32 v64, v90, v64
	v_mul_f32_e32 v65, v90, v65
	v_mul_f32_e32 v66, v90, v66
	v_mul_f32_e32 v67, v90, v67
	v_mul_f32_e32 v68, v91, v68
	v_mul_f32_e32 v69, v91, v69
	v_mul_f32_e32 v70, v91, v70
	v_mul_f32_e32 v71, v91, v71
	ds_write_b32 v171, v56
	ds_write_b32 v171, v57 offset:256
	ds_write_b32 v171, v58 offset:512
	ds_write_b32 v171, v59 offset:768
	ds_write_b32 v171, v60 offset:2048
	ds_write_b32 v171, v61 offset:2304
	ds_write_b32 v171, v62 offset:2560
	ds_write_b32 v171, v63 offset:2816
	ds_write_b32 v171, v64 offset:4096
	ds_write_b32 v171, v65 offset:4352
	ds_write_b32 v171, v66 offset:4608
	ds_write_b32 v171, v67 offset:4864
	ds_write_b32 v171, v68 offset:6144
	ds_write_b32 v171, v69 offset:6400
	ds_write_b32 v171, v70 offset:6656
	ds_write_b32 v171, v71 offset:6912
.Lrw_p1_done:
	s_waitcnt lgkmcnt(0)
	s_barrier
	s_lshl_b32 s38, s48, 5
	s_cmp_lt_u32 s48, 8
	s_cselect_b32 s36, 0xff, s44
	s_sub_i32 s39, s36, s38
	s_and_b64 s[36:37], s[28:29], exec
	s_cselect_b32 s49, s38, s39
	ds_read_b32 v48, v172 offset:24576
	ds_read_b32 v49, v162 offset:24576
	ds_read_b32 v50, v163 offset:24576
	ds_read_b32 v51, v164 offset:24576
	ds_read_b32 v52, v165 offset:24576
	ds_read_b32 v53, v166 offset:24576
	ds_read_b32 v54, v167 offset:24576
	ds_read_b32 v55, v168 offset:24576
	ds_read_b32 v0, v172
	ds_read_b32 v1, v162
	ds_read_b32 v2, v163
	ds_read_b32 v3, v164
	ds_read_b32 v4, v165
	ds_read_b32 v5, v166
	ds_read_b32 v6, v167
	ds_read_b32 v7, v168
	ds_read_b32 v8, v210
	ds_read_b32 v9, v172 offset:768
	ds_read_b32 v10, v162 offset:768
	ds_read_b32 v11, v163 offset:768
	ds_read_b32 v12, v164 offset:768
	ds_read_b32 v13, v165 offset:768
	ds_read_b32 v14, v166 offset:768
	ds_read_b32 v15, v167 offset:768
	ds_read_u16 v56, v209 offset:0
	ds_read_u16 v32, v209 offset:4096
	ds_read_u16 v64, v209 offset:8192
	ds_read_u16 v57, v209 offset:512
	ds_read_u16 v33, v209 offset:4608
	ds_read_u16 v65, v209 offset:8704
	ds_read_u16 v58, v209 offset:1024
	ds_read_u16 v34, v209 offset:5120
	ds_read_u16 v66, v209 offset:9216
	ds_read_u16 v59, v209 offset:1536
	ds_read_u16 v35, v209 offset:5632
	ds_read_u16 v67, v209 offset:9728
	ds_read_u16 v60, v209 offset:2048
	ds_read_u16 v36, v209 offset:6144
	ds_read_u16 v68, v209 offset:10240
	ds_read_u16 v61, v209 offset:2560
	ds_read_u16 v37, v209 offset:6656
	ds_read_u16 v69, v209 offset:10752
	ds_read_u16 v62, v209 offset:3072
	ds_read_u16 v38, v209 offset:7168
	ds_read_u16 v70, v209 offset:11264
	ds_read_u16 v63, v209 offset:3584
	ds_read_u16 v39, v209 offset:7680
	ds_read_u16 v71, v209 offset:11776
	s_waitcnt vmcnt(0) lgkmcnt(0)
	v_cndmask_b32_e64 v8, v8, 1.0, s[76:77]
	v_lshlrev_b32_e32 v56, 16, v56
	v_lshlrev_b32_e32 v57, 16, v57
	v_lshlrev_b32_e32 v64, 16, v64
	v_lshlrev_b32_e32 v65, 16, v65
	v_add_f32_e32 v104, -1.0, v48
	v_add_f32_e32 v105, -1.0, v49
	v_fma_f32 v72, v174, v104, 1.0
	v_fma_f32 v73, v174, v105, 1.0
	v_mul_f32_e32 v80, v173, v56
	v_mul_f32_e32 v81, v173, v57
	v_mul_f32_e32 v72, v72, v56
	v_mul_f32_e32 v73, v73, v57
	v_mul_f32_e32 v88, v80, v80
	v_mul_f32_e32 v89, v81, v81
	v_mul_f32_e32 v96, v72, v64
	v_mul_f32_e32 v97, v73, v65
	v_mul_f32_e32 v96, v175, v96
	v_mul_f32_e32 v97, v175, v97
	v_add_f32_dpp v88, v88, v88 quad_perm:[1,0,3,2] row_mask:0xf bank_mask:0xf bound_ctrl:1
	v_add_f32_dpp v96, v96, v96 quad_perm:[1,0,3,2] row_mask:0xf bank_mask:0xf bound_ctrl:1
	v_add_f32_dpp v89, v89, v89 quad_perm:[1,0,3,2] row_mask:0xf bank_mask:0xf bound_ctrl:1
	v_add_f32_dpp v97, v97, v97 quad_perm:[1,0,3,2] row_mask:0xf bank_mask:0xf bound_ctrl:1
	v_add_f32_dpp v88, v88, v88 quad_perm:[2,3,0,1] row_mask:0xf bank_mask:0xf bound_ctrl:1
	v_add_f32_dpp v96, v96, v96 quad_perm:[2,3,0,1] row_mask:0xf bank_mask:0xf bound_ctrl:1
	v_add_f32_dpp v89, v89, v89 quad_perm:[2,3,0,1] row_mask:0xf bank_mask:0xf bound_ctrl:1
	v_add_f32_dpp v97, v97, v97 quad_perm:[2,3,0,1] row_mask:0xf bank_mask:0xf bound_ctrl:1
	v_add_f32_dpp v88, v88, v88 row_half_mirror row_mask:0xf bank_mask:0xf bound_ctrl:1
	v_add_f32_dpp v96, v96, v96 row_half_mirror row_mask:0xf bank_mask:0xf bound_ctrl:1
	v_add_f32_dpp v89, v89, v89 row_half_mirror row_mask:0xf bank_mask:0xf bound_ctrl:1
	v_add_f32_dpp v97, v97, v97 row_half_mirror row_mask:0xf bank_mask:0xf bound_ctrl:1
	v_add_f32_dpp v88, v88, v88 row_mirror row_mask:0xf bank_mask:0xf bound_ctrl:1
	v_add_f32_dpp v96, v96, v96 row_mirror row_mask:0xf bank_mask:0xf bound_ctrl:1
	v_add_f32_dpp v89, v89, v89 row_mirror row_mask:0xf bank_mask:0xf bound_ctrl:1
	v_add_f32_dpp v97, v97, v97 row_mirror row_mask:0xf bank_mask:0xf bound_ctrl:1
	v_add_f32_dpp v88, v88, v88 row_bcast:15 row_mask:0xa bank_mask:0xf
	v_add_f32_dpp v96, v96, v96 row_bcast:15 row_mask:0xa bank_mask:0xf
	v_add_f32_dpp v89, v89, v89 row_bcast:15 row_mask:0xa bank_mask:0xf
	v_add_f32_dpp v97, v97, v97 row_bcast:15 row_mask:0xa bank_mask:0xf
	v_add_f32_dpp v88, v88, v88 row_bcast:31 row_mask:0xc bank_mask:0xf
	v_add_f32_dpp v96, v96, v96 row_bcast:31 row_mask:0xc bank_mask:0xf
	v_add_f32_dpp v89, v89, v89 row_bcast:31 row_mask:0xc bank_mask:0xf
	v_add_f32_dpp v97, v97, v97 row_bcast:31 row_mask:0xc bank_mask:0xf
	v_readlane_b32 s50, v88, 63
	v_readlane_b32 s51, v89, 63
	v_readlane_b32 s64, v96, 63
	v_readlane_b32 s65, v97, 63
	s_max_u32 s50, s50, 0x179abe15
	s_max_u32 s51, s51, 0x179abe15
	v_rsq_f32_e32 v104, s50
	v_rsq_f32_e32 v105, s51
	v_lshlrev_b32_e32 v88, 16, v32
	v_lshlrev_b32_e32 v89, 16, v33
	v_mul_f32_e64 v80, v80, -v104
	v_mul_f32_e64 v81, v81, -v105
	v_mul_f32_e64 v96, v48, -v80
	v_mul_f32_e64 v97, v49, -v81
	v_rcp_f32_e32 v104, v0
	v_rcp_f32_e32 v105, v1
	v_mul_f32_e32 v80, v80, v8
	v_mul_f32_e32 v81, v81, v9
	v_fma_f32 v8, -v0, v104, 1.0
	v_fma_f32 v9, -v1, v105, 1.0
	v_mul_f32_e32 v64, v64, v0
	v_mul_f32_e32 v65, v65, v1
	v_fma_f32 v104, v104, v8, v104
	v_fma_f32 v105, v105, v9, v105
	v_mul_f32_e32 v96, v96, v104
	v_mul_f32_e32 v97, v97, v105
	v_mul_f32_e32 v72, v72, v104
	v_mul_f32_e32 v73, v73, v105
	ds_write2st64_b32 v172, v72, v80 offset0:32 offset1:64
	ds_write2st64_b32 v172, v96, v64 offset0:96 offset1:128
	ds_write_b32 v172, v88 offset:40960
	ds_write2st64_b32 v162, v73, v81 offset0:32 offset1:64
	ds_write2st64_b32 v162, v97, v65 offset0:96 offset1:128
	ds_write_b32 v162, v89 offset:40960
	v_lshlrev_b32_e32 v58, 16, v58
	v_lshlrev_b32_e32 v59, 16, v59
	v_lshlrev_b32_e32 v66, 16, v66
	v_lshlrev_b32_e32 v67, 16, v67
	v_add_f32_e32 v106, -1.0, v50
	v_add_f32_e32 v107, -1.0, v51
	v_fma_f32 v74, v174, v106, 1.0
	v_fma_f32 v75, v174, v107, 1.0
	v_mul_f32_e32 v82, v173, v58
	v_mul_f32_e32 v83, v173, v59
	v_mul_f32_e32 v74, v74, v58
	v_mul_f32_e32 v75, v75, v59
	v_mul_f32_e32 v90, v82, v82
	v_mul_f32_e32 v91, v83, v83
	v_mul_f32_e32 v98, v74, v66
	v_mul_f32_e32 v99, v75, v67
	v_mul_f32_e32 v98, v175, v98
	v_mul_f32_e32 v99, v175, v99
	v_add_f32_dpp v90, v90, v90 quad_perm:[1,0,3,2] row_mask:0xf bank_mask:0xf bound_ctrl:1
	v_add_f32_dpp v98, v98, v98 quad_perm:[1,0,3,2] row_mask:0xf bank_mask:0xf bound_ctrl:1
	v_add_f32_dpp v91, v91, v91 quad_perm:[1,0,3,2] row_mask:0xf bank_mask:0xf bound_ctrl:1
	v_add_f32_dpp v99, v99, v99 quad_perm:[1,0,3,2] row_mask:0xf bank_mask:0xf bound_ctrl:1
	v_add_f32_dpp v90, v90, v90 quad_perm:[2,3,0,1] row_mask:0xf bank_mask:0xf bound_ctrl:1
	v_add_f32_dpp v98, v98, v98 quad_perm:[2,3,0,1] row_mask:0xf bank_mask:0xf bound_ctrl:1
	v_add_f32_dpp v91, v91, v91 quad_perm:[2,3,0,1] row_mask:0xf bank_mask:0xf bound_ctrl:1
	v_add_f32_dpp v99, v99, v99 quad_perm:[2,3,0,1] row_mask:0xf bank_mask:0xf bound_ctrl:1
	v_add_f32_dpp v90, v90, v90 row_half_mirror row_mask:0xf bank_mask:0xf bound_ctrl:1
	v_add_f32_dpp v98, v98, v98 row_half_mirror row_mask:0xf bank_mask:0xf bound_ctrl:1
	v_add_f32_dpp v91, v91, v91 row_half_mirror row_mask:0xf bank_mask:0xf bound_ctrl:1
	v_add_f32_dpp v99, v99, v99 row_half_mirror row_mask:0xf bank_mask:0xf bound_ctrl:1
	v_add_f32_dpp v90, v90, v90 row_mirror row_mask:0xf bank_mask:0xf bound_ctrl:1
	v_add_f32_dpp v98, v98, v98 row_mirror row_mask:0xf bank_mask:0xf bound_ctrl:1
	v_add_f32_dpp v91, v91, v91 row_mirror row_mask:0xf bank_mask:0xf bound_ctrl:1
	v_add_f32_dpp v99, v99, v99 row_mirror row_mask:0xf bank_mask:0xf bound_ctrl:1
	v_add_f32_dpp v90, v90, v90 row_bcast:15 row_mask:0xa bank_mask:0xf
	v_add_f32_dpp v98, v98, v98 row_bcast:15 row_mask:0xa bank_mask:0xf
	v_add_f32_dpp v91, v91, v91 row_bcast:15 row_mask:0xa bank_mask:0xf
	v_add_f32_dpp v99, v99, v99 row_bcast:15 row_mask:0xa bank_mask:0xf
	v_add_f32_dpp v90, v90, v90 row_bcast:31 row_mask:0xc bank_mask:0xf
	v_add_f32_dpp v98, v98, v98 row_bcast:31 row_mask:0xc bank_mask:0xf
	v_add_f32_dpp v91, v91, v91 row_bcast:31 row_mask:0xc bank_mask:0xf
	v_add_f32_dpp v99, v99, v99 row_bcast:31 row_mask:0xc bank_mask:0xf
	v_readlane_b32 s50, v90, 63
	v_readlane_b32 s51, v91, 63
	v_readlane_b32 s66, v98, 63
	v_readlane_b32 s67, v99, 63
	s_max_u32 s50, s50, 0x179abe15
	s_max_u32 s51, s51, 0x179abe15
	v_rsq_f32_e32 v106, s50
	v_rsq_f32_e32 v107, s51
	v_lshlrev_b32_e32 v90, 16, v34
	v_lshlrev_b32_e32 v91, 16, v35
	v_mul_f32_e64 v82, v82, -v106
	v_mul_f32_e64 v83, v83, -v107
	v_mul_f32_e64 v98, v50, -v82
	v_mul_f32_e64 v99, v51, -v83
	v_rcp_f32_e32 v106, v2
	v_rcp_f32_e32 v107, v3
	v_mul_f32_e32 v82, v82, v10
	v_mul_f32_e32 v83, v83, v11
	v_fma_f32 v10, -v2, v106, 1.0
	v_fma_f32 v11, -v3, v107, 1.0
	v_mul_f32_e32 v66, v66, v2
	v_mul_f32_e32 v67, v67, v3
	v_fma_f32 v106, v106, v10, v106
	v_fma_f32 v107, v107, v11, v107
	v_mul_f32_e32 v98, v98, v106
	v_mul_f32_e32 v99, v99, v107
	v_mul_f32_e32 v74, v74, v106
	v_mul_f32_e32 v75, v75, v107
	ds_write2st64_b32 v163, v74, v82 offset0:32 offset1:64
	ds_write2st64_b32 v163, v98, v66 offset0:96 offset1:128
	ds_write_b32 v163, v90 offset:40960
	ds_write2st64_b32 v164, v75, v83 offset0:32 offset1:64
	ds_write2st64_b32 v164, v99, v67 offset0:96 offset1:128
	ds_write_b32 v164, v91 offset:40960
	v_lshlrev_b32_e32 v60, 16, v60
	v_lshlrev_b32_e32 v61, 16, v61
	v_lshlrev_b32_e32 v68, 16, v68
	v_lshlrev_b32_e32 v69, 16, v69
	v_add_f32_e32 v108, -1.0, v52
	v_add_f32_e32 v109, -1.0, v53
	v_fma_f32 v76, v174, v108, 1.0
	v_fma_f32 v77, v174, v109, 1.0
	v_mul_f32_e32 v84, v173, v60
	v_mul_f32_e32 v85, v173, v61
	v_mul_f32_e32 v76, v76, v60
	v_mul_f32_e32 v77, v77, v61
	v_mul_f32_e32 v92, v84, v84
	v_mul_f32_e32 v93, v85, v85
	v_mul_f32_e32 v100, v76, v68
	v_mul_f32_e32 v101, v77, v69
	v_mul_f32_e32 v100, v175, v100
	v_mul_f32_e32 v101, v175, v101
	v_add_f32_dpp v92, v92, v92 quad_perm:[1,0,3,2] row_mask:0xf bank_mask:0xf bound_ctrl:1
	v_add_f32_dpp v100, v100, v100 quad_perm:[1,0,3,2] row_mask:0xf bank_mask:0xf bound_ctrl:1
	v_add_f32_dpp v93, v93, v93 quad_perm:[1,0,3,2] row_mask:0xf bank_mask:0xf bound_ctrl:1
	v_add_f32_dpp v101, v101, v101 quad_perm:[1,0,3,2] row_mask:0xf bank_mask:0xf bound_ctrl:1
	v_add_f32_dpp v92, v92, v92 quad_perm:[2,3,0,1] row_mask:0xf bank_mask:0xf bound_ctrl:1
	v_add_f32_dpp v100, v100, v100 quad_perm:[2,3,0,1] row_mask:0xf bank_mask:0xf bound_ctrl:1
	v_add_f32_dpp v93, v93, v93 quad_perm:[2,3,0,1] row_mask:0xf bank_mask:0xf bound_ctrl:1
	v_add_f32_dpp v101, v101, v101 quad_perm:[2,3,0,1] row_mask:0xf bank_mask:0xf bound_ctrl:1
	v_add_f32_dpp v92, v92, v92 row_half_mirror row_mask:0xf bank_mask:0xf bound_ctrl:1
	v_add_f32_dpp v100, v100, v100 row_half_mirror row_mask:0xf bank_mask:0xf bound_ctrl:1
	v_add_f32_dpp v93, v93, v93 row_half_mirror row_mask:0xf bank_mask:0xf bound_ctrl:1
	v_add_f32_dpp v101, v101, v101 row_half_mirror row_mask:0xf bank_mask:0xf bound_ctrl:1
	v_add_f32_dpp v92, v92, v92 row_mirror row_mask:0xf bank_mask:0xf bound_ctrl:1
	v_add_f32_dpp v100, v100, v100 row_mirror row_mask:0xf bank_mask:0xf bound_ctrl:1
	v_add_f32_dpp v93, v93, v93 row_mirror row_mask:0xf bank_mask:0xf bound_ctrl:1
	v_add_f32_dpp v101, v101, v101 row_mirror row_mask:0xf bank_mask:0xf bound_ctrl:1
	v_add_f32_dpp v92, v92, v92 row_bcast:15 row_mask:0xa bank_mask:0xf
	v_add_f32_dpp v100, v100, v100 row_bcast:15 row_mask:0xa bank_mask:0xf
	v_add_f32_dpp v93, v93, v93 row_bcast:15 row_mask:0xa bank_mask:0xf
	v_add_f32_dpp v101, v101, v101 row_bcast:15 row_mask:0xa bank_mask:0xf
	v_add_f32_dpp v92, v92, v92 row_bcast:31 row_mask:0xc bank_mask:0xf
	v_add_f32_dpp v100, v100, v100 row_bcast:31 row_mask:0xc bank_mask:0xf
	v_add_f32_dpp v93, v93, v93 row_bcast:31 row_mask:0xc bank_mask:0xf
	v_add_f32_dpp v101, v101, v101 row_bcast:31 row_mask:0xc bank_mask:0xf
	v_readlane_b32 s50, v92, 63
	v_readlane_b32 s51, v93, 63
	v_readlane_b32 s68, v100, 63
	v_readlane_b32 s69, v101, 63
	s_max_u32 s50, s50, 0x179abe15
	s_max_u32 s51, s51, 0x179abe15
	v_rsq_f32_e32 v108, s50
	v_rsq_f32_e32 v109, s51
	v_lshlrev_b32_e32 v92, 16, v36
	v_lshlrev_b32_e32 v93, 16, v37
	v_mul_f32_e64 v84, v84, -v108
	v_mul_f32_e64 v85, v85, -v109
	v_mul_f32_e64 v100, v52, -v84
	v_mul_f32_e64 v101, v53, -v85
	v_rcp_f32_e32 v108, v4
	v_rcp_f32_e32 v109, v5
	v_mul_f32_e32 v84, v84, v12
	v_mul_f32_e32 v85, v85, v13
	v_fma_f32 v12, -v4, v108, 1.0
	v_fma_f32 v13, -v5, v109, 1.0
	v_mul_f32_e32 v68, v68, v4
	v_mul_f32_e32 v69, v69, v5
	v_fma_f32 v108, v108, v12, v108
	v_fma_f32 v109, v109, v13, v109
	v_mul_f32_e32 v100, v100, v108
	v_mul_f32_e32 v101, v101, v109
	v_mul_f32_e32 v76, v76, v108
	v_mul_f32_e32 v77, v77, v109
	ds_write2st64_b32 v165, v76, v84 offset0:32 offset1:64
	ds_write2st64_b32 v165, v100, v68 offset0:96 offset1:128
	ds_write_b32 v165, v92 offset:40960
	ds_write2st64_b32 v166, v77, v85 offset0:32 offset1:64
	ds_write2st64_b32 v166, v101, v69 offset0:96 offset1:128
	ds_write_b32 v166, v93 offset:40960
	v_lshlrev_b32_e32 v62, 16, v62
	v_lshlrev_b32_e32 v63, 16, v63
	v_lshlrev_b32_e32 v70, 16, v70
	v_lshlrev_b32_e32 v71, 16, v71
	v_add_f32_e32 v110, -1.0, v54
	v_add_f32_e32 v111, -1.0, v55
	v_fma_f32 v78, v174, v110, 1.0
	v_fma_f32 v79, v174, v111, 1.0
	v_mul_f32_e32 v86, v173, v62
	v_mul_f32_e32 v87, v173, v63
	v_mul_f32_e32 v78, v78, v62
	v_mul_f32_e32 v79, v79, v63
	v_mul_f32_e32 v94, v86, v86
	v_mul_f32_e32 v95, v87, v87
	v_mul_f32_e32 v102, v78, v70
	v_mul_f32_e32 v103, v79, v71
	v_mul_f32_e32 v102, v175, v102
	v_mul_f32_e32 v103, v175, v103
	v_add_f32_dpp v94, v94, v94 quad_perm:[1,0,3,2] row_mask:0xf bank_mask:0xf bound_ctrl:1
	v_add_f32_dpp v102, v102, v102 quad_perm:[1,0,3,2] row_mask:0xf bank_mask:0xf bound_ctrl:1
	v_add_f32_dpp v95, v95, v95 quad_perm:[1,0,3,2] row_mask:0xf bank_mask:0xf bound_ctrl:1
	v_add_f32_dpp v103, v103, v103 quad_perm:[1,0,3,2] row_mask:0xf bank_mask:0xf bound_ctrl:1
	v_add_f32_dpp v94, v94, v94 quad_perm:[2,3,0,1] row_mask:0xf bank_mask:0xf bound_ctrl:1
	v_add_f32_dpp v102, v102, v102 quad_perm:[2,3,0,1] row_mask:0xf bank_mask:0xf bound_ctrl:1
	v_add_f32_dpp v95, v95, v95 quad_perm:[2,3,0,1] row_mask:0xf bank_mask:0xf bound_ctrl:1
	v_add_f32_dpp v103, v103, v103 quad_perm:[2,3,0,1] row_mask:0xf bank_mask:0xf bound_ctrl:1
	v_add_f32_dpp v94, v94, v94 row_half_mirror row_mask:0xf bank_mask:0xf bound_ctrl:1
	v_add_f32_dpp v102, v102, v102 row_half_mirror row_mask:0xf bank_mask:0xf bound_ctrl:1
	v_add_f32_dpp v95, v95, v95 row_half_mirror row_mask:0xf bank_mask:0xf bound_ctrl:1
	v_add_f32_dpp v103, v103, v103 row_half_mirror row_mask:0xf bank_mask:0xf bound_ctrl:1
	v_add_f32_dpp v94, v94, v94 row_mirror row_mask:0xf bank_mask:0xf bound_ctrl:1
	v_add_f32_dpp v102, v102, v102 row_mirror row_mask:0xf bank_mask:0xf bound_ctrl:1
	v_add_f32_dpp v95, v95, v95 row_mirror row_mask:0xf bank_mask:0xf bound_ctrl:1
	v_add_f32_dpp v103, v103, v103 row_mirror row_mask:0xf bank_mask:0xf bound_ctrl:1
	v_add_f32_dpp v94, v94, v94 row_bcast:15 row_mask:0xa bank_mask:0xf
	v_add_f32_dpp v102, v102, v102 row_bcast:15 row_mask:0xa bank_mask:0xf
	v_add_f32_dpp v95, v95, v95 row_bcast:15 row_mask:0xa bank_mask:0xf
	v_add_f32_dpp v103, v103, v103 row_bcast:15 row_mask:0xa bank_mask:0xf
	v_add_f32_dpp v94, v94, v94 row_bcast:31 row_mask:0xc bank_mask:0xf
	v_add_f32_dpp v102, v102, v102 row_bcast:31 row_mask:0xc bank_mask:0xf
	v_add_f32_dpp v95, v95, v95 row_bcast:31 row_mask:0xc bank_mask:0xf
	v_add_f32_dpp v103, v103, v103 row_bcast:31 row_mask:0xc bank_mask:0xf
	v_readlane_b32 s50, v94, 63
	v_readlane_b32 s51, v95, 63
	v_readlane_b32 s70, v102, 63
	v_readlane_b32 s71, v103, 63
	s_max_u32 s50, s50, 0x179abe15
	s_max_u32 s51, s51, 0x179abe15
	v_rsq_f32_e32 v110, s50
	v_rsq_f32_e32 v111, s51
	v_lshlrev_b32_e32 v94, 16, v38
	v_lshlrev_b32_e32 v95, 16, v39
	v_mul_f32_e64 v86, v86, -v110
	v_mul_f32_e64 v87, v87, -v111
	v_mul_f32_e64 v102, v54, -v86
	v_mul_f32_e64 v103, v55, -v87
	v_rcp_f32_e32 v110, v6
	v_rcp_f32_e32 v111, v7
	v_mul_f32_e32 v86, v86, v14
	v_mul_f32_e32 v87, v87, v15
	v_fma_f32 v14, -v6, v110, 1.0
	v_fma_f32 v15, -v7, v111, 1.0
	v_mul_f32_e32 v70, v70, v6
	v_mul_f32_e32 v71, v71, v7
	v_fma_f32 v110, v110, v14, v110
	v_fma_f32 v111, v111, v15, v111
	v_mul_f32_e32 v102, v102, v110
	v_mul_f32_e32 v103, v103, v111
	v_mul_f32_e32 v78, v78, v110
	v_mul_f32_e32 v79, v79, v111
	ds_write2st64_b32 v167, v78, v86 offset0:32 offset1:64
	ds_write2st64_b32 v167, v102, v70 offset0:96 offset1:128
	ds_write_b32 v167, v94 offset:40960
	ds_write2st64_b32 v168, v79, v87 offset0:32 offset1:64
	ds_write2st64_b32 v168, v103, v71 offset0:96 offset1:128
	ds_write_b32 v168, v95 offset:40960
	v_writelane_b32 v1, s64, 0
	v_writelane_b32 v1, s65, 1
	v_writelane_b32 v1, s66, 2
	v_writelane_b32 v1, s67, 3
	v_writelane_b32 v1, s68, 4
	v_writelane_b32 v1, s69, 5
	v_writelane_b32 v1, s70, 6
	v_writelane_b32 v1, s71, 7
	v_lshl_add_u32 v4, v194, 2, v195
	v_add_u32_e32 v4, s49, v4
	v_ashrrev_i32_e32 v5, 31, v4
	v_lshl_add_u64 v[4:5], s[30:31], 0, v[4:5]
	v_lshlrev_b64 v[4:5], 6, v[4:5]
	v_lshl_add_u64 v[4:5], s[34:35], 0, v[4:5]
	s_mov_b64 exec, 0xff
	global_store_dword v[4:5], v1, off
	s_mov_b64 exec, -1
	s_add_i32 s50, s48, 1
	s_cmpk_eq_i32 s48, 0x47
	s_waitcnt lgkmcnt(0)
	s_barrier
	s_cbranch_scc1 .LBB0_1682
	s_lshl_b32 s38, s50, 5
	s_cmp_lt_u32 s48, 7
	s_cselect_b32 s36, 0xff, s44
	s_sub_i32 s39, s36, s38
	s_and_b64 s[36:37], s[28:29], exec
	s_cselect_b32 s36, s38, s39
	v_add_u32_e32 v0, s36, v194
	v_ashrrev_i32_e32 v1, 31, v0
	v_lshl_add_u64 v[0:1], v[0:1], 0, s[24:25]
	v_lshlrev_b64 v[0:1], 8, v[0:1]
	v_lshl_add_u64 v[0:1], v[126:127], 0, v[0:1]
	global_load_dwordx4 v[32:35], v[0:1], off
	global_load_dwordx4 v[36:39], v[0:1], off offset:32
	global_load_dwordx4 v[40:43], v[0:1], off offset:64
	global_load_dwordx4 v[44:47], v[0:1], off offset:96
	v_add_u32_e32 v2, s36, v196
	v_ashrrev_i32_e32 v3, 31, v2
	v_lshl_add_u64 v[2:3], v[2:3], 0, s[24:25]
	v_lshlrev_b64 v[2:3], 11, v[2:3]
	v_lshl_add_u64 v[4:5], v[202:203], 0, v[2:3]
	v_lshl_add_u64 v[6:7], v[204:205], 0, v[2:3]
	v_lshl_add_u64 v[8:9], v[206:207], 0, v[2:3]
	global_load_dwordx4 v[184:187], v[4:5], off
	global_load_dwordx4 v[188:191], v[6:7], off
	global_load_dwordx4 v[198:201], v[8:9], off
.LBB0_1682:
	ds_read_b128 v[0:3], v158 offset:16384
	ds_read_b128 v[4:7], v158 offset:16400
	ds_read_b128 v[48:51], v158 offset:24576
	ds_read_b128 v[52:55], v158 offset:24592
	ds_read_b128 v[56:59], v158 offset:8192
	ds_read_b128 v[60:63], v158 offset:8208
	ds_read_b128 v[64:67], v158 offset:32768
	ds_read_b128 v[68:71], v158 offset:32784
	ds_read_b64 v[146:147], v159 offset:40960
	ds_read_b128 v[72:75], v158 offset:16640
	ds_read_b128 v[76:79], v158 offset:16656
	ds_read_b128 v[88:91], v158 offset:24832
	ds_read_b128 v[92:95], v158 offset:24848
	ds_read_b128 v[96:99], v158 offset:8448
	ds_read_b128 v[100:103], v158 offset:8464
	ds_read_b128 v[104:107], v158 offset:33024
	ds_read_b128 v[108:111], v158 offset:33040
	ds_read_b64 v[148:149], v159 offset:41216
	s_mov_b32 s48, 0
	v_mov_b32_e32 v112, v158
	v_mov_b32_e32 v214, v159
	s_waitcnt lgkmcnt(9)
.Lrwkv_step2:
	s_waitcnt lgkmcnt(10)
	v_pk_mul_f32 v[150:151], v[138:139], v[0:1]
	v_pk_mul_f32 v[152:153], v[130:131], v[0:1]
	v_pk_fma_f32 v[150:151], v[140:141], v[2:3], v[150:151]
	v_pk_fma_f32 v[152:153], v[132:133], v[2:3], v[152:153]
	v_pk_fma_f32 v[150:151], v[142:143], v[4:5], v[150:151]
	v_pk_fma_f32 v[152:153], v[134:135], v[4:5], v[152:153]
	v_pk_fma_f32 v[150:151], v[144:145], v[6:7], v[150:151]
	v_pk_fma_f32 v[152:153], v[136:137], v[6:7], v[152:153]
	v_pk_fma_f32 v[138:139], v[56:57], v[146:147], v[138:139] op_sel_hi:[1,0,1]
	v_add_f32_e32 v216, v150, v151
	v_add_f32_e32 v217, v152, v153
	v_pk_fma_f32 v[130:131], v[56:57], v[146:147], v[130:131] op_sel:[0,1,0]
	v_pk_fma_f32 v[140:141], v[58:59], v[146:147], v[140:141] op_sel_hi:[1,0,1]
	v_add_f32_dpp v216, v216, v216 quad_perm:[1,0,3,2] row_mask:0xf bank_mask:0xf bound_ctrl:1
	v_add_f32_dpp v217, v217, v217 quad_perm:[1,0,3,2] row_mask:0xf bank_mask:0xf bound_ctrl:1
	v_pk_fma_f32 v[132:133], v[58:59], v[146:147], v[132:133] op_sel:[0,1,0]
	v_pk_fma_f32 v[142:143], v[60:61], v[146:147], v[142:143] op_sel_hi:[1,0,1]
	v_add_f32_dpp v216, v216, v216 quad_perm:[2,3,0,1] row_mask:0xf bank_mask:0xf bound_ctrl:1
	v_add_f32_dpp v217, v217, v217 quad_perm:[2,3,0,1] row_mask:0xf bank_mask:0xf bound_ctrl:1
	v_pk_fma_f32 v[134:135], v[60:61], v[146:147], v[134:135] op_sel:[0,1,0]
	v_pk_fma_f32 v[144:145], v[62:63], v[146:147], v[144:145] op_sel_hi:[1,0,1]
	v_add_f32_dpp v216, v216, v216 row_half_mirror row_mask:0xf bank_mask:0xf bound_ctrl:1
	v_add_f32_dpp v217, v217, v217 row_half_mirror row_mask:0xf bank_mask:0xf bound_ctrl:1
	v_pk_fma_f32 v[136:137], v[62:63], v[146:147], v[136:137] op_sel:[0,1,0]
	v_pk_fma_f32 v[138:139], v[48:49], v[216:217], v[138:139] op_sel_hi:[1,0,1]
	v_pk_fma_f32 v[130:131], v[48:49], v[216:217], v[130:131] op_sel:[0,1,0]
	v_pk_fma_f32 v[140:141], v[50:51], v[216:217], v[140:141] op_sel_hi:[1,0,1]
	v_pk_fma_f32 v[132:133], v[50:51], v[216:217], v[132:133] op_sel:[0,1,0]
	v_pk_fma_f32 v[142:143], v[52:53], v[216:217], v[142:143] op_sel_hi:[1,0,1]
	v_pk_fma_f32 v[134:135], v[52:53], v[216:217], v[134:135] op_sel:[0,1,0]
	v_pk_fma_f32 v[144:145], v[54:55], v[216:217], v[144:145] op_sel_hi:[1,0,1]
	v_pk_fma_f32 v[136:137], v[54:55], v[216:217], v[136:137] op_sel:[0,1,0]
	v_pk_mul_f32 v[234:235], v[138:139], v[64:65]
	v_pk_mul_f32 v[236:237], v[130:131], v[64:65]
	v_pk_fma_f32 v[234:235], v[140:141], v[66:67], v[234:235]
	v_pk_fma_f32 v[236:237], v[132:133], v[66:67], v[236:237]
	v_pk_fma_f32 v[234:235], v[142:143], v[68:69], v[234:235]
	v_pk_fma_f32 v[236:237], v[134:135], v[68:69], v[236:237]
	v_pk_fma_f32 v[234:235], v[144:145], v[70:71], v[234:235]
	v_pk_fma_f32 v[236:237], v[136:137], v[70:71], v[236:237]
	ds_read_b128 v[0:3], v112 offset:16896
	v_add_f32_e32 v238, v234, v235
	v_add_f32_e32 v239, v236, v237
	ds_read_b128 v[4:7], v112 offset:16912
	ds_read_b128 v[48:51], v112 offset:25088
	v_add_f32_dpp v238, v238, v238 quad_perm:[1,0,3,2] row_mask:0xf bank_mask:0xf bound_ctrl:1
	v_add_f32_dpp v239, v239, v239 quad_perm:[1,0,3,2] row_mask:0xf bank_mask:0xf bound_ctrl:1
	ds_read_b128 v[52:55], v112 offset:25104
	ds_read_b128 v[56:59], v112 offset:8704
	v_add_f32_dpp v238, v238, v238 quad_perm:[2,3,0,1] row_mask:0xf bank_mask:0xf bound_ctrl:1
	v_add_f32_dpp v239, v239, v239 quad_perm:[2,3,0,1] row_mask:0xf bank_mask:0xf bound_ctrl:1
	ds_read_b128 v[60:63], v112 offset:8720
	ds_read_b128 v[64:67], v112 offset:33280
	v_add_f32_dpp v238, v238, v238 row_half_mirror row_mask:0xf bank_mask:0xf bound_ctrl:1
	v_add_f32_dpp v239, v239, v239 row_half_mirror row_mask:0xf bank_mask:0xf bound_ctrl:1
	ds_read_b128 v[68:71], v112 offset:33296
	ds_read_b64 v[146:147], v214 offset:41472
	s_and_saveexec_b64 s[36:37], s[8:9]
	ds_write_b64 v214, v[238:239] offset:49152
	s_or_b64 exec, exec, s[36:37]
	s_waitcnt lgkmcnt(10)
	v_pk_mul_f32 v[150:151], v[138:139], v[72:73]
	v_pk_mul_f32 v[152:153], v[130:131], v[72:73]
	v_pk_fma_f32 v[150:151], v[140:141], v[74:75], v[150:151]
	v_pk_fma_f32 v[152:153], v[132:133], v[74:75], v[152:153]
	v_pk_fma_f32 v[150:151], v[142:143], v[76:77], v[150:151]
	v_pk_fma_f32 v[152:153], v[134:135], v[76:77], v[152:153]
	v_pk_fma_f32 v[150:151], v[144:145], v[78:79], v[150:151]
	v_pk_fma_f32 v[152:153], v[136:137], v[78:79], v[152:153]
	v_pk_fma_f32 v[138:139], v[96:97], v[148:149], v[138:139] op_sel_hi:[1,0,1]
	v_add_f32_e32 v216, v150, v151
	v_add_f32_e32 v217, v152, v153
	v_pk_fma_f32 v[130:131], v[96:97], v[148:149], v[130:131] op_sel:[0,1,0]
	v_pk_fma_f32 v[140:141], v[98:99], v[148:149], v[140:141] op_sel_hi:[1,0,1]
	v_add_f32_dpp v216, v216, v216 quad_perm:[1,0,3,2] row_mask:0xf bank_mask:0xf bound_ctrl:1
	v_add_f32_dpp v217, v217, v217 quad_perm:[1,0,3,2] row_mask:0xf bank_mask:0xf bound_ctrl:1
	v_pk_fma_f32 v[132:133], v[98:99], v[148:149], v[132:133] op_sel:[0,1,0]
	v_pk_fma_f32 v[142:143], v[100:101], v[148:149], v[142:143] op_sel_hi:[1,0,1]
	v_add_f32_dpp v216, v216, v216 quad_perm:[2,3,0,1] row_mask:0xf bank_mask:0xf bound_ctrl:1
	v_add_f32_dpp v217, v217, v217 quad_perm:[2,3,0,1] row_mask:0xf bank_mask:0xf bound_ctrl:1
	v_pk_fma_f32 v[134:135], v[100:101], v[148:149], v[134:135] op_sel:[0,1,0]
	v_pk_fma_f32 v[144:145], v[102:103], v[148:149], v[144:145] op_sel_hi:[1,0,1]
	v_add_f32_dpp v216, v216, v216 row_half_mirror row_mask:0xf bank_mask:0xf bound_ctrl:1
	v_add_f32_dpp v217, v217, v217 row_half_mirror row_mask:0xf bank_mask:0xf bound_ctrl:1
	v_pk_fma_f32 v[136:137], v[102:103], v[148:149], v[136:137] op_sel:[0,1,0]
	v_pk_fma_f32 v[138:139], v[88:89], v[216:217], v[138:139] op_sel_hi:[1,0,1]
	v_pk_fma_f32 v[130:131], v[88:89], v[216:217], v[130:131] op_sel:[0,1,0]
	v_pk_fma_f32 v[140:141], v[90:91], v[216:217], v[140:141] op_sel_hi:[1,0,1]
	v_pk_fma_f32 v[132:133], v[90:91], v[216:217], v[132:133] op_sel:[0,1,0]
	v_pk_fma_f32 v[142:143], v[92:93], v[216:217], v[142:143] op_sel_hi:[1,0,1]
	v_pk_fma_f32 v[134:135], v[92:93], v[216:217], v[134:135] op_sel:[0,1,0]
	v_pk_fma_f32 v[144:145], v[94:95], v[216:217], v[144:145] op_sel_hi:[1,0,1]
	v_pk_fma_f32 v[136:137], v[94:95], v[216:217], v[136:137] op_sel:[0,1,0]
	v_pk_mul_f32 v[234:235], v[138:139], v[104:105]
	v_pk_mul_f32 v[236:237], v[130:131], v[104:105]
	v_pk_fma_f32 v[234:235], v[140:141], v[106:107], v[234:235]
	v_pk_fma_f32 v[236:237], v[132:133], v[106:107], v[236:237]
	v_pk_fma_f32 v[234:235], v[142:143], v[108:109], v[234:235]
	v_pk_fma_f32 v[236:237], v[134:135], v[108:109], v[236:237]
	v_pk_fma_f32 v[234:235], v[144:145], v[110:111], v[234:235]
	v_pk_fma_f32 v[236:237], v[136:137], v[110:111], v[236:237]
	ds_read_b128 v[72:75], v112 offset:17152
	v_add_f32_e32 v238, v234, v235
	v_add_f32_e32 v239, v236, v237
	ds_read_b128 v[76:79], v112 offset:17168
	ds_read_b128 v[88:91], v112 offset:25344
	v_add_f32_dpp v238, v238, v238 quad_perm:[1,0,3,2] row_mask:0xf bank_mask:0xf bound_ctrl:1
	v_add_f32_dpp v239, v239, v239 quad_perm:[1,0,3,2] row_mask:0xf bank_mask:0xf bound_ctrl:1
	ds_read_b128 v[92:95], v112 offset:25360
	ds_read_b128 v[96:99], v112 offset:8960
	v_add_f32_dpp v238, v238, v238 quad_perm:[2,3,0,1] row_mask:0xf bank_mask:0xf bound_ctrl:1
	v_add_f32_dpp v239, v239, v239 quad_perm:[2,3,0,1] row_mask:0xf bank_mask:0xf bound_ctrl:1
	ds_read_b128 v[100:103], v112 offset:8976
	ds_read_b128 v[104:107], v112 offset:33536
	v_add_f32_dpp v238, v238, v238 row_half_mirror row_mask:0xf bank_mask:0xf bound_ctrl:1
	v_add_f32_dpp v239, v239, v239 row_half_mirror row_mask:0xf bank_mask:0xf bound_ctrl:1
	ds_read_b128 v[108:111], v112 offset:33552
	ds_read_b64 v[148:149], v214 offset:41728
	s_and_saveexec_b64 s[36:37], s[8:9]
	ds_write_b64 v214, v[238:239] offset:49408
	s_or_b64 exec, exec, s[36:37]
	s_add_i32 s48, s48, 2
	v_add_u32_e32 v112, 0x200, v112
	v_add_u32_e32 v214, 0x200, v214
	s_cmp_lt_u32 s48, 32
	s_cbranch_scc1 .Lrwkv_step2
	ds_read_b128 v[8:11], v158 offset:7936
	ds_read_b128 v[12:15], v158 offset:7952
	s_waitcnt lgkmcnt(0)
	v_pk_mul_f32 v[138:139], v[138:139], v[8:9]
	v_pk_mul_f32 v[140:141], v[140:141], v[10:11]
	v_pk_mul_f32 v[142:143], v[142:143], v[12:13]
	v_pk_mul_f32 v[144:145], v[144:145], v[14:15]
	v_pk_mul_f32 v[130:131], v[130:131], v[8:9]
	v_pk_mul_f32 v[132:133], v[132:133], v[10:11]
	v_pk_mul_f32 v[134:135], v[134:135], v[12:13]
	v_pk_mul_f32 v[136:137], v[136:137], v[14:15]
	s_branch .LBB0_1599

.LBB0_1814:
	s_and_b32 s27, s26, 0x4000
	s_xor_b32 s28, s27, 0x4000
	s_lshl_b32 s28, s28, 1
	s_add_i32 s28, s28, 32
	s_add_u32 s90, s52, s16
	s_addc_u32 s91, s53, s17
	s_add_i32 m0, s28, s82
	s_lshl_b32 s27, s27, 1
	global_load_lds_dwordx4 v188, s[90:91]
	s_add_i32 m0, s28, s83
	s_add_i32 s27, s27, 32
	global_load_lds_dwordx4 v189, s[90:91]
	s_add_i32 m0, s28, s84
	v_add3_u32 v170, s27, v114, v135
	global_load_lds_dwordx4 v190, s[90:91]
	s_add_i32 m0, s28, s85
	v_add3_u32 v171, s27, v115, v135
	global_load_lds_dwordx4 v191, s[90:91]
	s_add_i32 m0, s28, s86
	v_add_u32_e32 v158, v170, v136
	global_load_lds_dwordx4 v192, s[90:91]
	s_add_i32 m0, s28, s87
	v_add_u32_e32 v166, v171, v136
	global_load_lds_dwordx4 v193, s[90:91]
	s_add_i32 m0, s28, s88
	s_addk_i32 s26, 0x4000
	global_load_lds_dwordx4 v194, s[90:91]
	s_add_i32 m0, s28, s89
	s_add_u32 s16, s16, 0x80
	s_addc_u32 s17, s17, 0
	global_load_lds_dwordx4 v195, s[90:91]
	ds_read_b128 v[138:141], v158
	ds_read_b128 v[142:145], v158 offset:2048
	ds_read_b128 v[146:149], v166 offset:16384
	ds_read_b128 v[150:153], v166 offset:18432
	ds_read_b128 v[154:157], v158 offset:4096
	ds_read_b128 v[158:161], v158 offset:6144
	ds_read_b128 v[162:165], v166 offset:20480
	ds_read_b128 v[166:169], v166 offset:22528
	s_setprio 1
	s_waitcnt lgkmcnt(0)
	v_mfma_f32_16x16x32_bf16 v[60:63], v[138:141], v[146:149], v[60:63]
	v_mfma_f32_16x16x32_bf16 v[56:59], v[138:141], v[150:153], v[56:59]
	v_mfma_f32_16x16x32_bf16 v[52:55], v[138:141], v[162:165], v[52:55]
	v_mfma_f32_16x16x32_bf16 v[48:51], v[138:141], v[166:169], v[48:51]
	v_mfma_f32_16x16x32_bf16 v[44:47], v[142:145], v[146:149], v[44:47]
	v_mfma_f32_16x16x32_bf16 v[40:43], v[142:145], v[150:153], v[40:43]
	v_mfma_f32_16x16x32_bf16 v[36:39], v[142:145], v[162:165], v[36:39]
	v_mfma_f32_16x16x32_bf16 v[32:35], v[142:145], v[166:169], v[32:35]
	v_mfma_f32_16x16x32_bf16 v[28:31], v[154:157], v[146:149], v[28:31]
	v_mfma_f32_16x16x32_bf16 v[24:27], v[154:157], v[150:153], v[24:27]
	v_mfma_f32_16x16x32_bf16 v[20:23], v[154:157], v[162:165], v[20:23]
	v_mfma_f32_16x16x32_bf16 v[16:19], v[154:157], v[166:169], v[16:19]
	v_mfma_f32_16x16x32_bf16 v[12:15], v[158:161], v[146:149], v[12:15]
	v_mfma_f32_16x16x32_bf16 v[8:11], v[158:161], v[150:153], v[8:11]
	v_mfma_f32_16x16x32_bf16 v[4:7], v[158:161], v[162:165], v[4:7]
	v_mfma_f32_16x16x32_bf16 v[0:3], v[158:161], v[166:169], v[0:3]
	s_setprio 0
	v_add_u32_e32 v158, v170, v137
	v_add_u32_e32 v166, v171, v137
	ds_read_b128 v[138:141], v158
	ds_read_b128 v[142:145], v158 offset:2048
	ds_read_b128 v[146:149], v166 offset:16384
	ds_read_b128 v[150:153], v166 offset:18432
	ds_read_b128 v[154:157], v158 offset:4096
	ds_read_b128 v[158:161], v158 offset:6144
	ds_read_b128 v[162:165], v166 offset:20480
	ds_read_b128 v[166:169], v166 offset:22528
	s_setprio 1
	s_waitcnt lgkmcnt(0)
	v_mfma_f32_16x16x32_bf16 v[60:63], v[138:141], v[146:149], v[60:63]
	v_mfma_f32_16x16x32_bf16 v[56:59], v[138:141], v[150:153], v[56:59]
	v_mfma_f32_16x16x32_bf16 v[52:55], v[138:141], v[162:165], v[52:55]
	v_mfma_f32_16x16x32_bf16 v[48:51], v[138:141], v[166:169], v[48:51]
	v_mfma_f32_16x16x32_bf16 v[44:47], v[142:145], v[146:149], v[44:47]
	v_mfma_f32_16x16x32_bf16 v[40:43], v[142:145], v[150:153], v[40:43]
	v_mfma_f32_16x16x32_bf16 v[36:39], v[142:145], v[162:165], v[36:39]
	v_mfma_f32_16x16x32_bf16 v[32:35], v[142:145], v[166:169], v[32:35]
	v_mfma_f32_16x16x32_bf16 v[28:31], v[154:157], v[146:149], v[28:31]
	v_mfma_f32_16x16x32_bf16 v[24:27], v[154:157], v[150:153], v[24:27]
	v_mfma_f32_16x16x32_bf16 v[20:23], v[154:157], v[162:165], v[20:23]
	v_mfma_f32_16x16x32_bf16 v[16:19], v[154:157], v[166:169], v[16:19]
	v_mfma_f32_16x16x32_bf16 v[12:15], v[158:161], v[146:149], v[12:15]
	v_mfma_f32_16x16x32_bf16 v[8:11], v[158:161], v[150:153], v[8:11]
	v_mfma_f32_16x16x32_bf16 v[4:7], v[158:161], v[162:165], v[4:7]
	v_mfma_f32_16x16x32_bf16 v[0:3], v[158:161], v[166:169], v[0:3]
	s_setprio 0
	s_cmpk_eq_i32 s16, 0x780
	s_waitcnt vmcnt(0)
	s_barrier
	s_cbranch_scc0 .LBB0_1814
	ds_read_b128 v[90:93], v118 offset:55296
	ds_read_b128 v[94:97], v118 offset:53248
	ds_read_b128 v[98:101], v119 offset:38912
	ds_read_b128 v[102:105], v119 offset:36864
	ds_read_b128 v[138:141], v118 offset:51200
	ds_read_b128 v[142:145], v118 offset:49152
	ds_read_b128 v[146:149], v119 offset:34816
	ds_read_b128 v[150:153], v119 offset:32768
	s_setprio 1
	s_waitcnt lgkmcnt(5)
	v_mfma_f32_16x16x32_bf16 v[4:7], v[98:101], v[94:97], v[4:7]
	v_mfma_f32_16x16x32_bf16 v[0:3], v[98:101], v[90:93], v[0:3]
	s_waitcnt lgkmcnt(0)
	v_mfma_f32_16x16x32_bf16 v[60:63], v[150:153], v[142:145], v[60:63]
	v_mfma_f32_16x16x32_bf16 v[56:59], v[150:153], v[138:141], v[56:59]
	v_mfma_f32_16x16x32_bf16 v[52:55], v[150:153], v[94:97], v[52:55]
	v_mfma_f32_16x16x32_bf16 v[48:51], v[150:153], v[90:93], v[48:51]
	v_mfma_f32_16x16x32_bf16 v[44:47], v[146:149], v[142:145], v[44:47]
	v_mfma_f32_16x16x32_bf16 v[40:43], v[146:149], v[138:141], v[40:43]
	v_mfma_f32_16x16x32_bf16 v[36:39], v[146:149], v[94:97], v[36:39]
	v_mfma_f32_16x16x32_bf16 v[32:35], v[146:149], v[90:93], v[32:35]
	v_mfma_f32_16x16x32_bf16 v[28:31], v[102:105], v[142:145], v[28:31]
	v_mfma_f32_16x16x32_bf16 v[24:27], v[102:105], v[138:141], v[24:27]
	v_mfma_f32_16x16x32_bf16 v[20:23], v[102:105], v[94:97], v[20:23]
	v_mfma_f32_16x16x32_bf16 v[16:19], v[102:105], v[90:93], v[16:19]
	v_mfma_f32_16x16x32_bf16 v[12:15], v[98:101], v[142:145], v[12:15]
	v_mfma_f32_16x16x32_bf16 v[8:11], v[98:101], v[138:141], v[8:11]
	s_setprio 0
	ds_read_b128 v[90:93], v120 offset:32768
	ds_read_b128 v[94:97], v120 offset:34816
	ds_read_b128 v[98:101], v121 offset:49152
	ds_read_b128 v[102:105], v121 offset:51200
	ds_read_b128 v[138:141], v120 offset:36864
	ds_read_b128 v[142:145], v120 offset:38912
	ds_read_b128 v[146:149], v121 offset:53248
	ds_read_b128 v[150:153], v121 offset:55296
	s_setprio 1
	s_waitcnt lgkmcnt(1)
	v_mfma_f32_16x16x32_bf16 v[4:7], v[142:145], v[146:149], v[4:7]
	s_waitcnt lgkmcnt(0)
	v_mfma_f32_16x16x32_bf16 v[0:3], v[142:145], v[150:153], v[0:3]
	v_mfma_f32_16x16x32_bf16 v[60:63], v[90:93], v[98:101], v[60:63]
	v_mfma_f32_16x16x32_bf16 v[56:59], v[90:93], v[102:105], v[56:59]
	v_mfma_f32_16x16x32_bf16 v[52:55], v[90:93], v[146:149], v[52:55]
	v_mfma_f32_16x16x32_bf16 v[48:51], v[90:93], v[150:153], v[48:51]
	v_mfma_f32_16x16x32_bf16 v[44:47], v[94:97], v[98:101], v[44:47]
	v_mfma_f32_16x16x32_bf16 v[40:43], v[94:97], v[102:105], v[40:43]
	v_mfma_f32_16x16x32_bf16 v[36:39], v[94:97], v[146:149], v[36:39]
	v_mfma_f32_16x16x32_bf16 v[32:35], v[94:97], v[150:153], v[32:35]
	v_mfma_f32_16x16x32_bf16 v[28:31], v[138:141], v[98:101], v[28:31]
	v_mfma_f32_16x16x32_bf16 v[24:27], v[138:141], v[102:105], v[24:27]
	v_mfma_f32_16x16x32_bf16 v[20:23], v[138:141], v[146:149], v[20:23]
	v_mfma_f32_16x16x32_bf16 v[16:19], v[138:141], v[150:153], v[16:19]
	v_mfma_f32_16x16x32_bf16 v[12:15], v[142:145], v[98:101], v[12:15]
	v_mfma_f32_16x16x32_bf16 v[8:11], v[142:145], v[102:105], v[8:11]
	s_setprio 0
	s_barrier
	ds_write2_b32 v116, v60, v56 offset1:16
	ds_write2_b32 v116, v61, v57 offset0:132 offset1:148
	v_add_u32_e32 v56, 0x400, v116
	ds_write2_b32 v56, v62, v58 offset0:8 offset1:24
	ds_write2_b32 v56, v63, v59 offset0:140 offset1:156
	ds_write2_b32 v116, v52, v48 offset0:32 offset1:48
	ds_write2_b32 v116, v53, v49 offset0:164 offset1:180
	ds_write2_b32 v56, v54, v50 offset0:40 offset1:56
	ds_write2_b32 v56, v55, v51 offset0:172 offset1:188
	v_add_u32_e32 v48, 0x2000, v116
	ds_write2_b32 v48, v44, v40 offset0:64 offset1:80
	ds_write2_b32 v48, v45, v41 offset0:196 offset1:212
	v_add_u32_e32 v40, 0x2400, v116
	ds_write2_b32 v40, v46, v42 offset0:72 offset1:88
	ds_write2_b32 v40, v47, v43 offset0:204 offset1:220
	ds_write2_b32 v48, v36, v32 offset0:96 offset1:112
	ds_write2_b32 v48, v37, v33 offset0:228 offset1:244
	ds_write2_b32 v40, v38, v34 offset0:104 offset1:120
	ds_write2_b32 v40, v39, v35 offset0:236 offset1:252
	v_add_u32_e32 v32, 0x4000, v116
	ds_write2_b32 v32, v28, v24 offset0:128 offset1:144
	v_add_u32_e32 v24, 0x4400, v116
	ds_write2_b32 v24, v29, v25 offset0:4 offset1:20
	ds_write2_b32 v24, v30, v26 offset0:136 offset1:152
	v_add_u32_e32 v25, 0x4800, v116
	ds_write2_b32 v25, v31, v27 offset0:12 offset1:28
	ds_write2_b32 v32, v20, v16 offset0:160 offset1:176
	ds_write2_b32 v24, v21, v17 offset0:36 offset1:52
	ds_write2_b32 v24, v22, v18 offset0:168 offset1:184
	ds_write2_b32 v25, v23, v19 offset0:44 offset1:60
	v_add_u32_e32 v16, 0x6000, v116
	ds_write2_b32 v16, v12, v8 offset0:192 offset1:208
	v_add_u32_e32 v8, 0x6400, v116
	ds_write2_b32 v8, v13, v9 offset0:68 offset1:84
	ds_write2_b32 v8, v14, v10 offset0:200 offset1:216
	v_add_u32_e32 v9, 0x6800, v116
	ds_write2_b32 v9, v15, v11 offset0:76 offset1:92
	ds_write2_b32 v16, v4, v0 offset0:224 offset1:240
	ds_write2_b32 v8, v5, v1 offset0:100 offset1:116
	ds_write2_b32 v8, v6, v2 offset0:232 offset1:248
	ds_write2_b32 v9, v7, v3 offset0:108 offset1:124
	v_or_b32_e32 v0, s25, v117
	v_ashrrev_i32_e32 v1, 31, v0
	v_lshlrev_b64 v[2:3], 2, v[0:1]
	v_lshl_add_u64 v[0:1], s[14:15], 0, v[2:3]
	v_lshl_add_u64 v[2:3], s[10:11], 0, v[2:3]
	v_add_u32_e32 v4, s24, v128
	s_mov_b32 s16, 0
	s_waitcnt lgkmcnt(0)
	s_barrier

.LBB0_1823:
	s_and_b32 s28, s27, 0x4000
	s_xor_b32 s29, s28, 0x4000
	s_lshl_b32 s29, s29, 1
	s_add_i32 s29, s29, 32
	s_add_u32 s90, s52, s16
	s_addc_u32 s91, s53, s17
	s_add_i32 m0, s29, s82
	s_lshl_b32 s28, s28, 1
	global_load_lds_dwordx4 v188, s[90:91]
	s_add_i32 m0, s29, s83
	s_add_i32 s28, s28, 32
	global_load_lds_dwordx4 v189, s[90:91]
	s_add_i32 m0, s29, s84
	v_add3_u32 v139, s28, v113, v136
	global_load_lds_dwordx4 v190, s[90:91]
	s_add_i32 m0, s29, s85
	v_add3_u32 v172, s28, v114, v136
	global_load_lds_dwordx4 v191, s[90:91]
	s_add_i32 m0, s29, s86
	v_add_u32_e32 v160, v139, v137
	global_load_lds_dwordx4 v192, s[90:91]
	s_add_i32 m0, s29, s87
	v_add_u32_e32 v168, v172, v137
	global_load_lds_dwordx4 v193, s[90:91]
	s_add_i32 m0, s29, s88
	s_addk_i32 s27, 0x4000
	global_load_lds_dwordx4 v194, s[90:91]
	s_add_i32 m0, s29, s89
	s_add_u32 s16, s16, 0x80
	s_addc_u32 s17, s17, 0
	global_load_lds_dwordx4 v195, s[90:91]
	ds_read_b128 v[140:143], v160
	ds_read_b128 v[144:147], v160 offset:2048
	ds_read_b128 v[148:151], v168 offset:16384
	ds_read_b128 v[152:155], v168 offset:18432
	ds_read_b128 v[156:159], v160 offset:4096
	ds_read_b128 v[160:163], v160 offset:6144
	ds_read_b128 v[164:167], v168 offset:20480
	ds_read_b128 v[168:171], v168 offset:22528
	s_setprio 1
	s_waitcnt lgkmcnt(0)
	v_mfma_f32_16x16x32_bf16 v[60:63], v[140:143], v[148:151], v[60:63]
	v_mfma_f32_16x16x32_bf16 v[56:59], v[140:143], v[152:155], v[56:59]
	v_mfma_f32_16x16x32_bf16 v[52:55], v[140:143], v[164:167], v[52:55]
	v_mfma_f32_16x16x32_bf16 v[48:51], v[140:143], v[168:171], v[48:51]
	v_mfma_f32_16x16x32_bf16 v[44:47], v[144:147], v[148:151], v[44:47]
	v_mfma_f32_16x16x32_bf16 v[40:43], v[144:147], v[152:155], v[40:43]
	v_mfma_f32_16x16x32_bf16 v[36:39], v[144:147], v[164:167], v[36:39]
	v_mfma_f32_16x16x32_bf16 v[32:35], v[144:147], v[168:171], v[32:35]
	v_mfma_f32_16x16x32_bf16 v[28:31], v[156:159], v[148:151], v[28:31]
	v_mfma_f32_16x16x32_bf16 v[24:27], v[156:159], v[152:155], v[24:27]
	v_mfma_f32_16x16x32_bf16 v[20:23], v[156:159], v[164:167], v[20:23]
	v_mfma_f32_16x16x32_bf16 v[16:19], v[156:159], v[168:171], v[16:19]
	v_mfma_f32_16x16x32_bf16 v[12:15], v[160:163], v[148:151], v[12:15]
	v_mfma_f32_16x16x32_bf16 v[8:11], v[160:163], v[152:155], v[8:11]
	v_mfma_f32_16x16x32_bf16 v[4:7], v[160:163], v[164:167], v[4:7]
	v_mfma_f32_16x16x32_bf16 v[0:3], v[160:163], v[168:171], v[0:3]
	s_setprio 0
	v_add_u32_e32 v139, v139, v138
	v_add_u32_e32 v168, v172, v138
	ds_read_b128 v[140:143], v139
	ds_read_b128 v[144:147], v139 offset:2048
	ds_read_b128 v[148:151], v168 offset:16384
	ds_read_b128 v[152:155], v168 offset:18432
	ds_read_b128 v[156:159], v139 offset:4096
	ds_read_b128 v[160:163], v139 offset:6144
	ds_read_b128 v[164:167], v168 offset:20480
	ds_read_b128 v[168:171], v168 offset:22528
	s_setprio 1
	s_waitcnt lgkmcnt(0)
	v_mfma_f32_16x16x32_bf16 v[60:63], v[140:143], v[148:151], v[60:63]
	v_mfma_f32_16x16x32_bf16 v[56:59], v[140:143], v[152:155], v[56:59]
	v_mfma_f32_16x16x32_bf16 v[52:55], v[140:143], v[164:167], v[52:55]
	v_mfma_f32_16x16x32_bf16 v[48:51], v[140:143], v[168:171], v[48:51]
	v_mfma_f32_16x16x32_bf16 v[44:47], v[144:147], v[148:151], v[44:47]
	v_mfma_f32_16x16x32_bf16 v[40:43], v[144:147], v[152:155], v[40:43]
	v_mfma_f32_16x16x32_bf16 v[36:39], v[144:147], v[164:167], v[36:39]
	v_mfma_f32_16x16x32_bf16 v[32:35], v[144:147], v[168:171], v[32:35]
	v_mfma_f32_16x16x32_bf16 v[28:31], v[156:159], v[148:151], v[28:31]
	v_mfma_f32_16x16x32_bf16 v[24:27], v[156:159], v[152:155], v[24:27]
	v_mfma_f32_16x16x32_bf16 v[20:23], v[156:159], v[164:167], v[20:23]
	v_mfma_f32_16x16x32_bf16 v[16:19], v[156:159], v[168:171], v[16:19]
	v_mfma_f32_16x16x32_bf16 v[12:15], v[160:163], v[148:151], v[12:15]
	v_mfma_f32_16x16x32_bf16 v[8:11], v[160:163], v[152:155], v[8:11]
	v_mfma_f32_16x16x32_bf16 v[4:7], v[160:163], v[164:167], v[4:7]
	v_mfma_f32_16x16x32_bf16 v[0:3], v[160:163], v[168:171], v[0:3]
	s_setprio 0
	s_cmpk_eq_i32 s16, 0x780
	s_waitcnt vmcnt(0)
	s_barrier
	s_cbranch_scc0 .LBB0_1823
	ds_read_b128 v[88:91], v117 offset:55296
	ds_read_b128 v[92:95], v117 offset:53248
	ds_read_b128 v[96:99], v118 offset:38912
	ds_read_b128 v[100:103], v118 offset:36864
	ds_read_b128 v[140:143], v117 offset:51200
	ds_read_b128 v[144:147], v117 offset:49152
	ds_read_b128 v[148:151], v118 offset:34816
	ds_read_b128 v[152:155], v118 offset:32768
	s_setprio 1
	s_waitcnt lgkmcnt(5)
	v_mfma_f32_16x16x32_bf16 v[4:7], v[96:99], v[92:95], v[4:7]
	v_mfma_f32_16x16x32_bf16 v[0:3], v[96:99], v[88:91], v[0:3]
	s_waitcnt lgkmcnt(0)
	v_mfma_f32_16x16x32_bf16 v[60:63], v[152:155], v[144:147], v[60:63]
	v_mfma_f32_16x16x32_bf16 v[56:59], v[152:155], v[140:143], v[56:59]
	v_mfma_f32_16x16x32_bf16 v[52:55], v[152:155], v[92:95], v[52:55]
	v_mfma_f32_16x16x32_bf16 v[48:51], v[152:155], v[88:91], v[48:51]
	v_mfma_f32_16x16x32_bf16 v[44:47], v[148:151], v[144:147], v[44:47]
	v_mfma_f32_16x16x32_bf16 v[40:43], v[148:151], v[140:143], v[40:43]
	v_mfma_f32_16x16x32_bf16 v[36:39], v[148:151], v[92:95], v[36:39]
	v_mfma_f32_16x16x32_bf16 v[32:35], v[148:151], v[88:91], v[32:35]
	v_mfma_f32_16x16x32_bf16 v[28:31], v[100:103], v[144:147], v[28:31]
	v_mfma_f32_16x16x32_bf16 v[24:27], v[100:103], v[140:143], v[24:27]
	v_mfma_f32_16x16x32_bf16 v[20:23], v[100:103], v[92:95], v[20:23]
	v_mfma_f32_16x16x32_bf16 v[16:19], v[100:103], v[88:91], v[16:19]
	v_mfma_f32_16x16x32_bf16 v[12:15], v[96:99], v[144:147], v[12:15]
	v_mfma_f32_16x16x32_bf16 v[8:11], v[96:99], v[140:143], v[8:11]
	s_setprio 0
	ds_read_b128 v[88:91], v119 offset:32768
	ds_read_b128 v[92:95], v119 offset:34816
	ds_read_b128 v[96:99], v120 offset:49152
	ds_read_b128 v[100:103], v120 offset:51200
	ds_read_b128 v[140:143], v119 offset:36864
	ds_read_b128 v[144:147], v119 offset:38912
	ds_read_b128 v[148:151], v120 offset:53248
	ds_read_b128 v[152:155], v120 offset:55296
	s_setprio 1
	s_waitcnt lgkmcnt(1)
	v_mfma_f32_16x16x32_bf16 v[4:7], v[144:147], v[148:151], v[4:7]
	s_waitcnt lgkmcnt(0)
	v_mfma_f32_16x16x32_bf16 v[0:3], v[144:147], v[152:155], v[0:3]
	v_mfma_f32_16x16x32_bf16 v[60:63], v[88:91], v[96:99], v[60:63]
	v_mfma_f32_16x16x32_bf16 v[56:59], v[88:91], v[100:103], v[56:59]
	v_mfma_f32_16x16x32_bf16 v[52:55], v[88:91], v[148:151], v[52:55]
	v_mfma_f32_16x16x32_bf16 v[48:51], v[88:91], v[152:155], v[48:51]
	v_mfma_f32_16x16x32_bf16 v[44:47], v[92:95], v[96:99], v[44:47]
	v_mfma_f32_16x16x32_bf16 v[40:43], v[92:95], v[100:103], v[40:43]
	v_mfma_f32_16x16x32_bf16 v[36:39], v[92:95], v[148:151], v[36:39]
	v_mfma_f32_16x16x32_bf16 v[32:35], v[92:95], v[152:155], v[32:35]
	v_mfma_f32_16x16x32_bf16 v[28:31], v[140:143], v[96:99], v[28:31]
	v_mfma_f32_16x16x32_bf16 v[24:27], v[140:143], v[100:103], v[24:27]
	v_mfma_f32_16x16x32_bf16 v[20:23], v[140:143], v[148:151], v[20:23]
	v_mfma_f32_16x16x32_bf16 v[16:19], v[140:143], v[152:155], v[16:19]
	v_mfma_f32_16x16x32_bf16 v[12:15], v[144:147], v[96:99], v[12:15]
	v_mfma_f32_16x16x32_bf16 v[8:11], v[144:147], v[100:103], v[8:11]
	s_setprio 0
	s_barrier
	ds_write2_b32 v115, v60, v56 offset1:16
	ds_write2_b32 v115, v61, v57 offset0:132 offset1:148
	v_add_u32_e32 v56, 0x400, v115
	ds_write2_b32 v56, v62, v58 offset0:8 offset1:24
	ds_write2_b32 v56, v63, v59 offset0:140 offset1:156
	ds_write2_b32 v115, v52, v48 offset0:32 offset1:48
	ds_write2_b32 v115, v53, v49 offset0:164 offset1:180
	ds_write2_b32 v56, v54, v50 offset0:40 offset1:56
	ds_write2_b32 v56, v55, v51 offset0:172 offset1:188
	v_add_u32_e32 v48, 0x2000, v115
	ds_write2_b32 v48, v44, v40 offset0:64 offset1:80
	ds_write2_b32 v48, v45, v41 offset0:196 offset1:212
	v_add_u32_e32 v40, 0x2400, v115
	ds_write2_b32 v40, v46, v42 offset0:72 offset1:88
	ds_write2_b32 v40, v47, v43 offset0:204 offset1:220
	ds_write2_b32 v48, v36, v32 offset0:96 offset1:112
	ds_write2_b32 v48, v37, v33 offset0:228 offset1:244
	ds_write2_b32 v40, v38, v34 offset0:104 offset1:120
	ds_write2_b32 v40, v39, v35 offset0:236 offset1:252
	v_add_u32_e32 v32, 0x4000, v115
	ds_write2_b32 v32, v28, v24 offset0:128 offset1:144
	v_add_u32_e32 v24, 0x4400, v115
	ds_write2_b32 v24, v29, v25 offset0:4 offset1:20
	ds_write2_b32 v24, v30, v26 offset0:136 offset1:152
	v_add_u32_e32 v25, 0x4800, v115
	ds_write2_b32 v25, v31, v27 offset0:12 offset1:28
	ds_write2_b32 v32, v20, v16 offset0:160 offset1:176
	ds_write2_b32 v24, v21, v17 offset0:36 offset1:52
	ds_write2_b32 v24, v22, v18 offset0:168 offset1:184
	ds_write2_b32 v25, v23, v19 offset0:44 offset1:60
	v_add_u32_e32 v16, 0x6000, v115
	ds_write2_b32 v16, v12, v8 offset0:192 offset1:208
	v_add_u32_e32 v8, 0x6400, v115
	ds_write2_b32 v8, v13, v9 offset0:68 offset1:84
	ds_write2_b32 v8, v14, v10 offset0:200 offset1:216
	v_add_u32_e32 v9, 0x6800, v115
	ds_write2_b32 v9, v15, v11 offset0:76 offset1:92
	ds_write2_b32 v16, v4, v0 offset0:224 offset1:240
	ds_write2_b32 v8, v5, v1 offset0:100 offset1:116
	ds_write2_b32 v8, v6, v2 offset0:232 offset1:248
	ds_write2_b32 v9, v7, v3 offset0:108 offset1:124
	v_or_b32_e32 v0, s25, v116
	v_ashrrev_i32_e32 v1, 31, v0
	v_lshlrev_b64 v[2:3], 2, v[0:1]
	v_lshl_add_u64 v[0:1], s[14:15], 0, v[2:3]
	v_lshl_add_u64 v[2:3], s[10:11], 0, v[2:3]
	v_add_u32_e32 v4, s26, v129
	s_mov_b32 s16, 0
	s_waitcnt lgkmcnt(0)
	s_barrier

.LBB0_1998:
	s_and_b32 s20, s19, 0x4000
	s_xor_b32 s21, s20, 0x4000
	s_lshl_b32 s21, s21, 1
	s_add_i32 s21, s21, 32
	s_add_u32 s90, s52, s12
	s_addc_u32 s91, s53, s13
	s_add_i32 m0, s21, s82
	s_lshl_b32 s20, s20, 1
	global_load_lds_dwordx4 v184, s[90:91]
	s_add_i32 m0, s21, s83
	s_add_i32 s20, s20, 32
	global_load_lds_dwordx4 v185, s[90:91]
	s_add_i32 m0, s21, s84
	v_lshl_add_u32 v137, v114, 1, s20
	global_load_lds_dwordx4 v186, s[90:91]
	s_add_i32 m0, s21, s85
	v_lshl_add_u32 v170, v115, 1, s20
	global_load_lds_dwordx4 v187, s[90:91]
	s_add_i32 m0, s21, s86
	v_add_u32_e32 v158, v137, v135
	global_load_lds_dwordx4 v188, s[90:91]
	s_add_i32 m0, s21, s87
	v_add_u32_e32 v166, v170, v135
	global_load_lds_dwordx4 v189, s[90:91]
	s_add_i32 m0, s21, s88
	s_addk_i32 s19, 0x4000
	global_load_lds_dwordx4 v190, s[90:91]
	s_add_i32 m0, s21, s89
	s_add_u32 s12, s12, 0x80
	s_addc_u32 s13, s13, 0
	global_load_lds_dwordx4 v191, s[90:91]
	ds_read_b128 v[138:141], v158
	ds_read_b128 v[142:145], v158 offset:2048
	ds_read_b128 v[146:149], v166 offset:16384
	ds_read_b128 v[150:153], v166 offset:18432
	ds_read_b128 v[154:157], v158 offset:4096
	ds_read_b128 v[158:161], v158 offset:6144
	ds_read_b128 v[162:165], v166 offset:20480
	ds_read_b128 v[166:169], v166 offset:22528
	s_setprio 1
	s_waitcnt lgkmcnt(0)
	v_mfma_f32_16x16x32_bf16 v[60:63], v[138:141], v[146:149], v[60:63]
	v_mfma_f32_16x16x32_bf16 v[56:59], v[138:141], v[150:153], v[56:59]
	v_mfma_f32_16x16x32_bf16 v[52:55], v[138:141], v[162:165], v[52:55]
	v_mfma_f32_16x16x32_bf16 v[48:51], v[138:141], v[166:169], v[48:51]
	v_mfma_f32_16x16x32_bf16 v[44:47], v[142:145], v[146:149], v[44:47]
	v_mfma_f32_16x16x32_bf16 v[40:43], v[142:145], v[150:153], v[40:43]
	v_mfma_f32_16x16x32_bf16 v[36:39], v[142:145], v[162:165], v[36:39]
	v_mfma_f32_16x16x32_bf16 v[32:35], v[142:145], v[166:169], v[32:35]
	v_mfma_f32_16x16x32_bf16 v[28:31], v[154:157], v[146:149], v[28:31]
	v_mfma_f32_16x16x32_bf16 v[24:27], v[154:157], v[150:153], v[24:27]
	v_mfma_f32_16x16x32_bf16 v[20:23], v[154:157], v[162:165], v[20:23]
	v_mfma_f32_16x16x32_bf16 v[16:19], v[154:157], v[166:169], v[16:19]
	v_mfma_f32_16x16x32_bf16 v[12:15], v[158:161], v[146:149], v[12:15]
	v_mfma_f32_16x16x32_bf16 v[8:11], v[158:161], v[150:153], v[8:11]
	v_mfma_f32_16x16x32_bf16 v[4:7], v[158:161], v[162:165], v[4:7]
	v_mfma_f32_16x16x32_bf16 v[0:3], v[158:161], v[166:169], v[0:3]
	s_setprio 0
	v_add_u32_e32 v137, v137, v136
	v_add_u32_e32 v166, v170, v136
	ds_read_b128 v[138:141], v137
	ds_read_b128 v[142:145], v137 offset:2048
	ds_read_b128 v[146:149], v166 offset:16384
	ds_read_b128 v[150:153], v166 offset:18432
	ds_read_b128 v[154:157], v137 offset:4096
	ds_read_b128 v[158:161], v137 offset:6144
	ds_read_b128 v[162:165], v166 offset:20480
	ds_read_b128 v[166:169], v166 offset:22528
	s_setprio 1
	s_waitcnt lgkmcnt(0)
	v_mfma_f32_16x16x32_bf16 v[60:63], v[138:141], v[146:149], v[60:63]
	v_mfma_f32_16x16x32_bf16 v[56:59], v[138:141], v[150:153], v[56:59]
	v_mfma_f32_16x16x32_bf16 v[52:55], v[138:141], v[162:165], v[52:55]
	v_mfma_f32_16x16x32_bf16 v[48:51], v[138:141], v[166:169], v[48:51]
	v_mfma_f32_16x16x32_bf16 v[44:47], v[142:145], v[146:149], v[44:47]
	v_mfma_f32_16x16x32_bf16 v[40:43], v[142:145], v[150:153], v[40:43]
	v_mfma_f32_16x16x32_bf16 v[36:39], v[142:145], v[162:165], v[36:39]
	v_mfma_f32_16x16x32_bf16 v[32:35], v[142:145], v[166:169], v[32:35]
	v_mfma_f32_16x16x32_bf16 v[28:31], v[154:157], v[146:149], v[28:31]
	v_mfma_f32_16x16x32_bf16 v[24:27], v[154:157], v[150:153], v[24:27]
	v_mfma_f32_16x16x32_bf16 v[20:23], v[154:157], v[162:165], v[20:23]
	v_mfma_f32_16x16x32_bf16 v[16:19], v[154:157], v[166:169], v[16:19]
	v_mfma_f32_16x16x32_bf16 v[12:15], v[158:161], v[146:149], v[12:15]
	v_mfma_f32_16x16x32_bf16 v[8:11], v[158:161], v[150:153], v[8:11]
	v_mfma_f32_16x16x32_bf16 v[4:7], v[158:161], v[162:165], v[4:7]
	v_mfma_f32_16x16x32_bf16 v[0:3], v[158:161], v[166:169], v[0:3]
	s_setprio 0
	s_cmpk_eq_i32 s12, 0x780
	s_waitcnt vmcnt(0)
	s_barrier
	s_cbranch_scc0 .LBB0_1998
	ds_read_b128 v[90:93], v116 offset:55296
	ds_read_b128 v[94:97], v116 offset:53248
	ds_read_b128 v[98:101], v117 offset:38912
	ds_read_b128 v[102:105], v117 offset:36864
	ds_read_b128 v[138:141], v116 offset:51200
	ds_read_b128 v[142:145], v116 offset:49152
	ds_read_b128 v[146:149], v117 offset:34816
	ds_read_b128 v[150:153], v117 offset:32768
	s_setprio 1
	s_waitcnt lgkmcnt(5)
	v_mfma_f32_16x16x32_bf16 v[0:3], v[98:101], v[90:93], v[0:3]
	s_waitcnt lgkmcnt(0)
	v_mfma_f32_16x16x32_bf16 v[60:63], v[150:153], v[142:145], v[60:63]
	v_mfma_f32_16x16x32_bf16 v[56:59], v[150:153], v[138:141], v[56:59]
	v_mfma_f32_16x16x32_bf16 v[52:55], v[150:153], v[94:97], v[52:55]
	v_mfma_f32_16x16x32_bf16 v[48:51], v[150:153], v[90:93], v[48:51]
	v_mfma_f32_16x16x32_bf16 v[44:47], v[146:149], v[142:145], v[44:47]
	v_mfma_f32_16x16x32_bf16 v[40:43], v[146:149], v[138:141], v[40:43]
	v_mfma_f32_16x16x32_bf16 v[36:39], v[146:149], v[94:97], v[36:39]
	v_mfma_f32_16x16x32_bf16 v[32:35], v[146:149], v[90:93], v[32:35]
	v_mfma_f32_16x16x32_bf16 v[28:31], v[102:105], v[142:145], v[28:31]
	v_mfma_f32_16x16x32_bf16 v[24:27], v[102:105], v[138:141], v[24:27]
	v_mfma_f32_16x16x32_bf16 v[20:23], v[102:105], v[94:97], v[20:23]
	v_mfma_f32_16x16x32_bf16 v[16:19], v[102:105], v[90:93], v[16:19]
	v_mfma_f32_16x16x32_bf16 v[12:15], v[98:101], v[142:145], v[12:15]
	v_mfma_f32_16x16x32_bf16 v[8:11], v[98:101], v[138:141], v[8:11]
	v_mfma_f32_16x16x32_bf16 v[4:7], v[98:101], v[94:97], v[4:7]
	s_setprio 0
	ds_read_b128 v[90:93], v118 offset:32768
	ds_read_b128 v[94:97], v118 offset:34816
	ds_read_b128 v[98:101], v119 offset:49152
	ds_read_b128 v[102:105], v119 offset:51200
	ds_read_b128 v[138:141], v118 offset:36864
	ds_read_b128 v[142:145], v118 offset:38912
	ds_read_b128 v[146:149], v119 offset:53248
	ds_read_b128 v[150:153], v119 offset:55296
	s_setprio 1
	s_waitcnt lgkmcnt(0)
	v_mfma_f32_16x16x32_bf16 v[0:3], v[142:145], v[150:153], v[0:3]
	v_mfma_f32_16x16x32_bf16 v[60:63], v[90:93], v[98:101], v[60:63]
	v_mfma_f32_16x16x32_bf16 v[56:59], v[90:93], v[102:105], v[56:59]
	v_mfma_f32_16x16x32_bf16 v[52:55], v[90:93], v[146:149], v[52:55]
	v_mfma_f32_16x16x32_bf16 v[48:51], v[90:93], v[150:153], v[48:51]
	v_mfma_f32_16x16x32_bf16 v[44:47], v[94:97], v[98:101], v[44:47]
	v_mfma_f32_16x16x32_bf16 v[40:43], v[94:97], v[102:105], v[40:43]
	v_mfma_f32_16x16x32_bf16 v[36:39], v[94:97], v[146:149], v[36:39]
	v_mfma_f32_16x16x32_bf16 v[32:35], v[94:97], v[150:153], v[32:35]
	v_mfma_f32_16x16x32_bf16 v[28:31], v[138:141], v[98:101], v[28:31]
	v_mfma_f32_16x16x32_bf16 v[24:27], v[138:141], v[102:105], v[24:27]
	v_mfma_f32_16x16x32_bf16 v[20:23], v[138:141], v[146:149], v[20:23]
	v_mfma_f32_16x16x32_bf16 v[16:19], v[138:141], v[150:153], v[16:19]
	v_mfma_f32_16x16x32_bf16 v[12:15], v[142:145], v[98:101], v[12:15]
	v_mfma_f32_16x16x32_bf16 v[8:11], v[142:145], v[102:105], v[8:11]
	v_mfma_f32_16x16x32_bf16 v[4:7], v[142:145], v[146:149], v[4:7]
	s_setprio 0
	s_barrier
	ds_write2_b32 v120, v60, v56 offset1:16
	ds_write2_b32 v120, v61, v57 offset0:132 offset1:148
	v_add_u32_e32 v56, 0x400, v120
	ds_write2_b32 v56, v62, v58 offset0:8 offset1:24
	ds_write2_b32 v56, v63, v59 offset0:140 offset1:156
	ds_write2_b32 v120, v52, v48 offset0:32 offset1:48
	ds_write2_b32 v120, v53, v49 offset0:164 offset1:180
	ds_write2_b32 v56, v54, v50 offset0:40 offset1:56
	ds_write2_b32 v56, v55, v51 offset0:172 offset1:188
	v_add_u32_e32 v48, 0x2000, v120
	ds_write2_b32 v48, v44, v40 offset0:64 offset1:80
	ds_write2_b32 v48, v45, v41 offset0:196 offset1:212
	v_add_u32_e32 v40, 0x2400, v120
	ds_write2_b32 v40, v46, v42 offset0:72 offset1:88
	ds_write2_b32 v40, v47, v43 offset0:204 offset1:220
	ds_write2_b32 v48, v36, v32 offset0:96 offset1:112
	ds_write2_b32 v48, v37, v33 offset0:228 offset1:244
	ds_write2_b32 v40, v38, v34 offset0:104 offset1:120
	ds_write2_b32 v40, v39, v35 offset0:236 offset1:252
	v_add_u32_e32 v32, 0x4000, v120
	ds_write2_b32 v32, v28, v24 offset0:128 offset1:144
	v_add_u32_e32 v24, 0x4400, v120
	ds_write2_b32 v24, v29, v25 offset0:4 offset1:20
	ds_write2_b32 v24, v30, v26 offset0:136 offset1:152
	v_add_u32_e32 v25, 0x4800, v120
	ds_write2_b32 v25, v31, v27 offset0:12 offset1:28
	ds_write2_b32 v32, v20, v16 offset0:160 offset1:176
	ds_write2_b32 v24, v21, v17 offset0:36 offset1:52
	ds_write2_b32 v24, v22, v18 offset0:168 offset1:184
	ds_write2_b32 v25, v23, v19 offset0:44 offset1:60
	v_add_u32_e32 v16, 0x6000, v120
	ds_write2_b32 v16, v12, v8 offset0:192 offset1:208
	v_add_u32_e32 v8, 0x6400, v120
	ds_write2_b32 v8, v13, v9 offset0:68 offset1:84
	ds_write2_b32 v8, v14, v10 offset0:200 offset1:216
	v_add_u32_e32 v9, 0x6800, v120
	ds_write2_b32 v9, v15, v11 offset0:76 offset1:92
	ds_write2_b32 v16, v4, v0 offset0:224 offset1:240
	ds_write2_b32 v8, v5, v1 offset0:100 offset1:116
	ds_write2_b32 v8, v6, v2 offset0:232 offset1:248
	ds_write2_b32 v9, v7, v3 offset0:108 offset1:124
	v_or_b32_e32 v0, s18, v121
	v_ashrrev_i32_e32 v1, 31, v0
	v_lshl_add_u64 v[0:1], v[0:1], 1, s[6:7]
	v_add_u32_e32 v2, s17, v128
	s_mov_b32 s12, 0
	s_waitcnt lgkmcnt(0)
	s_barrier

.LBB0_2009:
	s_and_b32 s17, s16, 0x4000
	s_xor_b32 s18, s17, 0x4000
	s_lshl_b32 s18, s18, 1
	s_add_i32 s18, s18, 32
	s_add_u32 s90, s52, s8
	s_addc_u32 s91, s53, s9
	s_add_i32 m0, s18, s82
	s_lshl_b32 s17, s17, 1
	global_load_lds_dwordx4 v184, s[90:91]
	s_add_i32 m0, s18, s83
	s_add_i32 s17, s17, 32
	global_load_lds_dwordx4 v185, s[90:91]
	s_add_i32 m0, s18, s84
	v_lshl_add_u32 v137, v113, 1, s17
	global_load_lds_dwordx4 v186, s[90:91]
	s_add_i32 m0, s18, s85
	v_lshl_add_u32 v170, v114, 1, s17
	global_load_lds_dwordx4 v187, s[90:91]
	s_add_i32 m0, s18, s86
	v_add_u32_e32 v158, v137, v135
	global_load_lds_dwordx4 v188, s[90:91]
	s_add_i32 m0, s18, s87
	v_add_u32_e32 v166, v170, v135
	global_load_lds_dwordx4 v189, s[90:91]
	s_add_i32 m0, s18, s88
	s_addk_i32 s16, 0x4000
	global_load_lds_dwordx4 v190, s[90:91]
	s_add_i32 m0, s18, s89
	s_add_u32 s8, s8, 0x80
	s_addc_u32 s9, s9, 0
	global_load_lds_dwordx4 v191, s[90:91]
	ds_read_b128 v[138:141], v158
	ds_read_b128 v[142:145], v158 offset:2048
	ds_read_b128 v[146:149], v166 offset:16384
	ds_read_b128 v[150:153], v166 offset:18432
	ds_read_b128 v[154:157], v158 offset:4096
	ds_read_b128 v[158:161], v158 offset:6144
	ds_read_b128 v[162:165], v166 offset:20480
	ds_read_b128 v[166:169], v166 offset:22528
	s_setprio 1
	s_waitcnt lgkmcnt(0)
	v_mfma_f32_16x16x32_bf16 v[60:63], v[138:141], v[146:149], v[60:63]
	v_mfma_f32_16x16x32_bf16 v[56:59], v[138:141], v[150:153], v[56:59]
	v_mfma_f32_16x16x32_bf16 v[52:55], v[138:141], v[162:165], v[52:55]
	v_mfma_f32_16x16x32_bf16 v[48:51], v[138:141], v[166:169], v[48:51]
	v_mfma_f32_16x16x32_bf16 v[44:47], v[142:145], v[146:149], v[44:47]
	v_mfma_f32_16x16x32_bf16 v[40:43], v[142:145], v[150:153], v[40:43]
	v_mfma_f32_16x16x32_bf16 v[36:39], v[142:145], v[162:165], v[36:39]
	v_mfma_f32_16x16x32_bf16 v[32:35], v[142:145], v[166:169], v[32:35]
	v_mfma_f32_16x16x32_bf16 v[28:31], v[154:157], v[146:149], v[28:31]
	v_mfma_f32_16x16x32_bf16 v[24:27], v[154:157], v[150:153], v[24:27]
	v_mfma_f32_16x16x32_bf16 v[20:23], v[154:157], v[162:165], v[20:23]
	v_mfma_f32_16x16x32_bf16 v[16:19], v[154:157], v[166:169], v[16:19]
	v_mfma_f32_16x16x32_bf16 v[12:15], v[158:161], v[146:149], v[12:15]
	v_mfma_f32_16x16x32_bf16 v[8:11], v[158:161], v[150:153], v[8:11]
	v_mfma_f32_16x16x32_bf16 v[4:7], v[158:161], v[162:165], v[4:7]
	v_mfma_f32_16x16x32_bf16 v[0:3], v[158:161], v[166:169], v[0:3]
	s_setprio 0
	v_add_u32_e32 v137, v137, v136
	v_add_u32_e32 v166, v170, v136
	ds_read_b128 v[138:141], v137
	ds_read_b128 v[142:145], v137 offset:2048
	ds_read_b128 v[146:149], v166 offset:16384
	ds_read_b128 v[150:153], v166 offset:18432
	ds_read_b128 v[154:157], v137 offset:4096
	ds_read_b128 v[158:161], v137 offset:6144
	ds_read_b128 v[162:165], v166 offset:20480
	ds_read_b128 v[166:169], v166 offset:22528
	s_setprio 1
	s_waitcnt lgkmcnt(0)
	v_mfma_f32_16x16x32_bf16 v[60:63], v[138:141], v[146:149], v[60:63]
	v_mfma_f32_16x16x32_bf16 v[56:59], v[138:141], v[150:153], v[56:59]
	v_mfma_f32_16x16x32_bf16 v[52:55], v[138:141], v[162:165], v[52:55]
	v_mfma_f32_16x16x32_bf16 v[48:51], v[138:141], v[166:169], v[48:51]
	v_mfma_f32_16x16x32_bf16 v[44:47], v[142:145], v[146:149], v[44:47]
	v_mfma_f32_16x16x32_bf16 v[40:43], v[142:145], v[150:153], v[40:43]
	v_mfma_f32_16x16x32_bf16 v[36:39], v[142:145], v[162:165], v[36:39]
	v_mfma_f32_16x16x32_bf16 v[32:35], v[142:145], v[166:169], v[32:35]
	v_mfma_f32_16x16x32_bf16 v[28:31], v[154:157], v[146:149], v[28:31]
	v_mfma_f32_16x16x32_bf16 v[24:27], v[154:157], v[150:153], v[24:27]
	v_mfma_f32_16x16x32_bf16 v[20:23], v[154:157], v[162:165], v[20:23]
	v_mfma_f32_16x16x32_bf16 v[16:19], v[154:157], v[166:169], v[16:19]
	v_mfma_f32_16x16x32_bf16 v[12:15], v[158:161], v[146:149], v[12:15]
	v_mfma_f32_16x16x32_bf16 v[8:11], v[158:161], v[150:153], v[8:11]
	v_mfma_f32_16x16x32_bf16 v[4:7], v[158:161], v[162:165], v[4:7]
	v_mfma_f32_16x16x32_bf16 v[0:3], v[158:161], v[166:169], v[0:3]
	s_setprio 0
	s_cmpk_eq_i32 s8, 0x780
	s_waitcnt vmcnt(0)
	s_barrier
	s_cbranch_scc0 .LBB0_2009
	ds_read_b128 v[88:91], v115 offset:55296
	ds_read_b128 v[92:95], v115 offset:53248
	ds_read_b128 v[96:99], v116 offset:38912
	ds_read_b128 v[100:103], v116 offset:36864
	ds_read_b128 v[138:141], v115 offset:51200
	ds_read_b128 v[142:145], v115 offset:49152
	ds_read_b128 v[146:149], v116 offset:34816
	ds_read_b128 v[150:153], v116 offset:32768
	s_setprio 1
	s_waitcnt lgkmcnt(5)
	v_mfma_f32_16x16x32_bf16 v[0:3], v[96:99], v[88:91], v[0:3]
	s_waitcnt lgkmcnt(0)
	v_mfma_f32_16x16x32_bf16 v[60:63], v[150:153], v[142:145], v[60:63]
	v_mfma_f32_16x16x32_bf16 v[56:59], v[150:153], v[138:141], v[56:59]
	v_mfma_f32_16x16x32_bf16 v[52:55], v[150:153], v[92:95], v[52:55]
	v_mfma_f32_16x16x32_bf16 v[48:51], v[150:153], v[88:91], v[48:51]
	v_mfma_f32_16x16x32_bf16 v[44:47], v[146:149], v[142:145], v[44:47]
	v_mfma_f32_16x16x32_bf16 v[40:43], v[146:149], v[138:141], v[40:43]
	v_mfma_f32_16x16x32_bf16 v[36:39], v[146:149], v[92:95], v[36:39]
	v_mfma_f32_16x16x32_bf16 v[32:35], v[146:149], v[88:91], v[32:35]
	v_mfma_f32_16x16x32_bf16 v[28:31], v[100:103], v[142:145], v[28:31]
	v_mfma_f32_16x16x32_bf16 v[24:27], v[100:103], v[138:141], v[24:27]
	v_mfma_f32_16x16x32_bf16 v[20:23], v[100:103], v[92:95], v[20:23]
	v_mfma_f32_16x16x32_bf16 v[16:19], v[100:103], v[88:91], v[16:19]
	v_mfma_f32_16x16x32_bf16 v[12:15], v[96:99], v[142:145], v[12:15]
	v_mfma_f32_16x16x32_bf16 v[8:11], v[96:99], v[138:141], v[8:11]
	v_mfma_f32_16x16x32_bf16 v[4:7], v[96:99], v[92:95], v[4:7]
	s_setprio 0
	ds_read_b128 v[88:91], v117 offset:32768
	ds_read_b128 v[92:95], v117 offset:34816
	ds_read_b128 v[96:99], v118 offset:49152
	ds_read_b128 v[100:103], v118 offset:51200
	ds_read_b128 v[138:141], v117 offset:36864
	ds_read_b128 v[142:145], v117 offset:38912
	ds_read_b128 v[146:149], v118 offset:53248
	ds_read_b128 v[150:153], v118 offset:55296
	s_setprio 1
	s_waitcnt lgkmcnt(0)
	v_mfma_f32_16x16x32_bf16 v[0:3], v[142:145], v[150:153], v[0:3]
	v_mfma_f32_16x16x32_bf16 v[60:63], v[88:91], v[96:99], v[60:63]
	v_mfma_f32_16x16x32_bf16 v[56:59], v[88:91], v[100:103], v[56:59]
	v_mfma_f32_16x16x32_bf16 v[52:55], v[88:91], v[146:149], v[52:55]
	v_mfma_f32_16x16x32_bf16 v[48:51], v[88:91], v[150:153], v[48:51]
	v_mfma_f32_16x16x32_bf16 v[44:47], v[92:95], v[96:99], v[44:47]
	v_mfma_f32_16x16x32_bf16 v[40:43], v[92:95], v[100:103], v[40:43]
	v_mfma_f32_16x16x32_bf16 v[36:39], v[92:95], v[146:149], v[36:39]
	v_mfma_f32_16x16x32_bf16 v[32:35], v[92:95], v[150:153], v[32:35]
	v_mfma_f32_16x16x32_bf16 v[28:31], v[138:141], v[96:99], v[28:31]
	v_mfma_f32_16x16x32_bf16 v[24:27], v[138:141], v[100:103], v[24:27]
	v_mfma_f32_16x16x32_bf16 v[20:23], v[138:141], v[146:149], v[20:23]
	v_mfma_f32_16x16x32_bf16 v[16:19], v[138:141], v[150:153], v[16:19]
	v_mfma_f32_16x16x32_bf16 v[12:15], v[142:145], v[96:99], v[12:15]
	v_mfma_f32_16x16x32_bf16 v[8:11], v[142:145], v[100:103], v[8:11]
	v_mfma_f32_16x16x32_bf16 v[4:7], v[142:145], v[146:149], v[4:7]
	s_setprio 0
	s_barrier
	ds_write2_b32 v119, v60, v56 offset1:16
	ds_write2_b32 v119, v61, v57 offset0:132 offset1:148
	v_add_u32_e32 v56, 0x400, v119
	ds_write2_b32 v56, v62, v58 offset0:8 offset1:24
	ds_write2_b32 v56, v63, v59 offset0:140 offset1:156
	ds_write2_b32 v119, v52, v48 offset0:32 offset1:48
	ds_write2_b32 v119, v53, v49 offset0:164 offset1:180
	ds_write2_b32 v56, v54, v50 offset0:40 offset1:56
	ds_write2_b32 v56, v55, v51 offset0:172 offset1:188
	v_add_u32_e32 v48, 0x2000, v119
	ds_write2_b32 v48, v44, v40 offset0:64 offset1:80
	ds_write2_b32 v48, v45, v41 offset0:196 offset1:212
	v_add_u32_e32 v40, 0x2400, v119
	ds_write2_b32 v40, v46, v42 offset0:72 offset1:88
	ds_write2_b32 v40, v47, v43 offset0:204 offset1:220
	ds_write2_b32 v48, v36, v32 offset0:96 offset1:112
	ds_write2_b32 v48, v37, v33 offset0:228 offset1:244
	ds_write2_b32 v40, v38, v34 offset0:104 offset1:120
	ds_write2_b32 v40, v39, v35 offset0:236 offset1:252
	v_add_u32_e32 v32, 0x4000, v119
	ds_write2_b32 v32, v28, v24 offset0:128 offset1:144
	v_add_u32_e32 v24, 0x4400, v119
	ds_write2_b32 v24, v29, v25 offset0:4 offset1:20
	ds_write2_b32 v24, v30, v26 offset0:136 offset1:152
	v_add_u32_e32 v25, 0x4800, v119
	ds_write2_b32 v25, v31, v27 offset0:12 offset1:28
	ds_write2_b32 v32, v20, v16 offset0:160 offset1:176
	ds_write2_b32 v24, v21, v17 offset0:36 offset1:52
	ds_write2_b32 v24, v22, v18 offset0:168 offset1:184
	ds_write2_b32 v25, v23, v19 offset0:44 offset1:60
	v_add_u32_e32 v16, 0x6000, v119
	ds_write2_b32 v16, v12, v8 offset0:192 offset1:208
	v_add_u32_e32 v8, 0x6400, v119
	ds_write2_b32 v8, v13, v9 offset0:68 offset1:84
	ds_write2_b32 v8, v14, v10 offset0:200 offset1:216
	v_add_u32_e32 v9, 0x6800, v119
	ds_write2_b32 v9, v15, v11 offset0:76 offset1:92
	ds_write2_b32 v16, v4, v0 offset0:224 offset1:240
	ds_write2_b32 v8, v5, v1 offset0:100 offset1:116
	ds_write2_b32 v8, v6, v2 offset0:232 offset1:248
	ds_write2_b32 v9, v7, v3 offset0:108 offset1:124
	v_or_b32_e32 v0, s14, v120
	v_ashrrev_i32_e32 v1, 31, v0
	v_lshl_add_u64 v[0:1], v[0:1], 1, s[6:7]
	v_add_u32_e32 v2, s15, v128
	s_mov_b32 s8, 0
	s_waitcnt lgkmcnt(0)
	s_barrier

.LBB0_2076:
	s_and_b32 s27, s26, 0x4000
	s_xor_b32 s28, s27, 0x4000
	s_lshl_b32 s28, s28, 1
	s_add_i32 s28, s28, 32
	s_add_u32 s90, s52, s16
	s_addc_u32 s91, s53, s17
	s_add_i32 m0, s28, s82
	s_lshl_b32 s27, s27, 1
	global_load_lds_dwordx4 v192, s[90:91]
	s_add_i32 m0, s28, s83
	s_add_i32 s27, s27, 32
	global_load_lds_dwordx4 v193, s[90:91]
	s_add_i32 m0, s28, s84
	v_add3_u32 v170, s27, v114, v135
	global_load_lds_dwordx4 v194, s[90:91]
	s_add_i32 m0, s28, s85
	v_add3_u32 v171, s27, v115, v135
	global_load_lds_dwordx4 v195, s[90:91]
	s_add_i32 m0, s28, s86
	v_add_u32_e32 v158, v170, v136
	global_load_lds_dwordx4 v196, s[90:91]
	s_add_i32 m0, s28, s87
	v_add_u32_e32 v166, v171, v136
	global_load_lds_dwordx4 v197, s[90:91]
	s_add_i32 m0, s28, s88
	s_addk_i32 s26, 0x4000
	global_load_lds_dwordx4 v198, s[90:91]
	s_add_i32 m0, s28, s89
	s_add_u32 s16, s16, 0x80
	s_addc_u32 s17, s17, 0
	global_load_lds_dwordx4 v199, s[90:91]
	ds_read_b128 v[138:141], v158
	ds_read_b128 v[142:145], v158 offset:2048
	ds_read_b128 v[146:149], v166 offset:16384
	ds_read_b128 v[150:153], v166 offset:18432
	ds_read_b128 v[154:157], v158 offset:4096
	ds_read_b128 v[158:161], v158 offset:6144
	ds_read_b128 v[162:165], v166 offset:20480
	ds_read_b128 v[166:169], v166 offset:22528
	s_setprio 1
	s_waitcnt lgkmcnt(0)
	v_mfma_f32_16x16x32_bf16 v[60:63], v[138:141], v[146:149], v[60:63]
	v_mfma_f32_16x16x32_bf16 v[56:59], v[138:141], v[150:153], v[56:59]
	v_mfma_f32_16x16x32_bf16 v[52:55], v[138:141], v[162:165], v[52:55]
	v_mfma_f32_16x16x32_bf16 v[48:51], v[138:141], v[166:169], v[48:51]
	v_mfma_f32_16x16x32_bf16 v[44:47], v[142:145], v[146:149], v[44:47]
	v_mfma_f32_16x16x32_bf16 v[40:43], v[142:145], v[150:153], v[40:43]
	v_mfma_f32_16x16x32_bf16 v[36:39], v[142:145], v[162:165], v[36:39]
	v_mfma_f32_16x16x32_bf16 v[32:35], v[142:145], v[166:169], v[32:35]
	v_mfma_f32_16x16x32_bf16 v[28:31], v[154:157], v[146:149], v[28:31]
	v_mfma_f32_16x16x32_bf16 v[24:27], v[154:157], v[150:153], v[24:27]
	v_mfma_f32_16x16x32_bf16 v[20:23], v[154:157], v[162:165], v[20:23]
	v_mfma_f32_16x16x32_bf16 v[16:19], v[154:157], v[166:169], v[16:19]
	v_mfma_f32_16x16x32_bf16 v[12:15], v[158:161], v[146:149], v[12:15]
	v_mfma_f32_16x16x32_bf16 v[8:11], v[158:161], v[150:153], v[8:11]
	v_mfma_f32_16x16x32_bf16 v[4:7], v[158:161], v[162:165], v[4:7]
	v_mfma_f32_16x16x32_bf16 v[0:3], v[158:161], v[166:169], v[0:3]
	s_setprio 0
	v_add_u32_e32 v158, v170, v137
	v_add_u32_e32 v166, v171, v137
	ds_read_b128 v[138:141], v158
	ds_read_b128 v[142:145], v158 offset:2048
	ds_read_b128 v[146:149], v166 offset:16384
	ds_read_b128 v[150:153], v166 offset:18432
	ds_read_b128 v[154:157], v158 offset:4096
	ds_read_b128 v[158:161], v158 offset:6144
	ds_read_b128 v[162:165], v166 offset:20480
	ds_read_b128 v[166:169], v166 offset:22528
	s_setprio 1
	s_waitcnt lgkmcnt(0)
	v_mfma_f32_16x16x32_bf16 v[60:63], v[138:141], v[146:149], v[60:63]
	v_mfma_f32_16x16x32_bf16 v[56:59], v[138:141], v[150:153], v[56:59]
	v_mfma_f32_16x16x32_bf16 v[52:55], v[138:141], v[162:165], v[52:55]
	v_mfma_f32_16x16x32_bf16 v[48:51], v[138:141], v[166:169], v[48:51]
	v_mfma_f32_16x16x32_bf16 v[44:47], v[142:145], v[146:149], v[44:47]
	v_mfma_f32_16x16x32_bf16 v[40:43], v[142:145], v[150:153], v[40:43]
	v_mfma_f32_16x16x32_bf16 v[36:39], v[142:145], v[162:165], v[36:39]
	v_mfma_f32_16x16x32_bf16 v[32:35], v[142:145], v[166:169], v[32:35]
	v_mfma_f32_16x16x32_bf16 v[28:31], v[154:157], v[146:149], v[28:31]
	v_mfma_f32_16x16x32_bf16 v[24:27], v[154:157], v[150:153], v[24:27]
	v_mfma_f32_16x16x32_bf16 v[20:23], v[154:157], v[162:165], v[20:23]
	v_mfma_f32_16x16x32_bf16 v[16:19], v[154:157], v[166:169], v[16:19]
	v_mfma_f32_16x16x32_bf16 v[12:15], v[158:161], v[146:149], v[12:15]
	v_mfma_f32_16x16x32_bf16 v[8:11], v[158:161], v[150:153], v[8:11]
	v_mfma_f32_16x16x32_bf16 v[4:7], v[158:161], v[162:165], v[4:7]
	v_mfma_f32_16x16x32_bf16 v[0:3], v[158:161], v[166:169], v[0:3]
	s_setprio 0
	s_cmpk_eq_i32 s16, 0x1f80
	s_waitcnt vmcnt(0)
	s_barrier
	s_cbranch_scc0 .LBB0_2076
	ds_read_b128 v[90:93], v118 offset:55296
	ds_read_b128 v[94:97], v118 offset:53248
	ds_read_b128 v[98:101], v119 offset:38912
	ds_read_b128 v[102:105], v119 offset:36864
	ds_read_b128 v[138:141], v118 offset:51200
	ds_read_b128 v[142:145], v118 offset:49152
	ds_read_b128 v[146:149], v119 offset:34816
	ds_read_b128 v[150:153], v119 offset:32768
	s_setprio 1
	s_waitcnt lgkmcnt(5)
	v_mfma_f32_16x16x32_bf16 v[4:7], v[98:101], v[94:97], v[4:7]
	v_mfma_f32_16x16x32_bf16 v[0:3], v[98:101], v[90:93], v[0:3]
	s_waitcnt lgkmcnt(0)
	v_mfma_f32_16x16x32_bf16 v[60:63], v[150:153], v[142:145], v[60:63]
	v_mfma_f32_16x16x32_bf16 v[56:59], v[150:153], v[138:141], v[56:59]
	v_mfma_f32_16x16x32_bf16 v[52:55], v[150:153], v[94:97], v[52:55]
	v_mfma_f32_16x16x32_bf16 v[48:51], v[150:153], v[90:93], v[48:51]
	v_mfma_f32_16x16x32_bf16 v[44:47], v[146:149], v[142:145], v[44:47]
	v_mfma_f32_16x16x32_bf16 v[40:43], v[146:149], v[138:141], v[40:43]
	v_mfma_f32_16x16x32_bf16 v[36:39], v[146:149], v[94:97], v[36:39]
	v_mfma_f32_16x16x32_bf16 v[32:35], v[146:149], v[90:93], v[32:35]
	v_mfma_f32_16x16x32_bf16 v[28:31], v[102:105], v[142:145], v[28:31]
	v_mfma_f32_16x16x32_bf16 v[24:27], v[102:105], v[138:141], v[24:27]
	v_mfma_f32_16x16x32_bf16 v[20:23], v[102:105], v[94:97], v[20:23]
	v_mfma_f32_16x16x32_bf16 v[16:19], v[102:105], v[90:93], v[16:19]
	v_mfma_f32_16x16x32_bf16 v[12:15], v[98:101], v[142:145], v[12:15]
	v_mfma_f32_16x16x32_bf16 v[8:11], v[98:101], v[138:141], v[8:11]
	s_setprio 0
	ds_read_b128 v[90:93], v120 offset:32768
	ds_read_b128 v[94:97], v120 offset:34816
	ds_read_b128 v[98:101], v121 offset:49152
	ds_read_b128 v[102:105], v121 offset:51200
	ds_read_b128 v[138:141], v120 offset:36864
	ds_read_b128 v[142:145], v120 offset:38912
	ds_read_b128 v[146:149], v121 offset:53248
	ds_read_b128 v[150:153], v121 offset:55296
	s_setprio 1
	s_waitcnt lgkmcnt(1)
	v_mfma_f32_16x16x32_bf16 v[4:7], v[142:145], v[146:149], v[4:7]
	s_waitcnt lgkmcnt(0)
	v_mfma_f32_16x16x32_bf16 v[0:3], v[142:145], v[150:153], v[0:3]
	v_mfma_f32_16x16x32_bf16 v[60:63], v[90:93], v[98:101], v[60:63]
	v_mfma_f32_16x16x32_bf16 v[56:59], v[90:93], v[102:105], v[56:59]
	v_mfma_f32_16x16x32_bf16 v[52:55], v[90:93], v[146:149], v[52:55]
	v_mfma_f32_16x16x32_bf16 v[48:51], v[90:93], v[150:153], v[48:51]
	v_mfma_f32_16x16x32_bf16 v[44:47], v[94:97], v[98:101], v[44:47]
	v_mfma_f32_16x16x32_bf16 v[40:43], v[94:97], v[102:105], v[40:43]
	v_mfma_f32_16x16x32_bf16 v[36:39], v[94:97], v[146:149], v[36:39]
	v_mfma_f32_16x16x32_bf16 v[32:35], v[94:97], v[150:153], v[32:35]
	v_mfma_f32_16x16x32_bf16 v[28:31], v[138:141], v[98:101], v[28:31]
	v_mfma_f32_16x16x32_bf16 v[24:27], v[138:141], v[102:105], v[24:27]
	v_mfma_f32_16x16x32_bf16 v[20:23], v[138:141], v[146:149], v[20:23]
	v_mfma_f32_16x16x32_bf16 v[16:19], v[138:141], v[150:153], v[16:19]
	v_mfma_f32_16x16x32_bf16 v[12:15], v[142:145], v[98:101], v[12:15]
	v_mfma_f32_16x16x32_bf16 v[8:11], v[142:145], v[102:105], v[8:11]
	s_setprio 0
	s_barrier
	ds_write2_b32 v116, v60, v56 offset1:16
	ds_write2_b32 v116, v61, v57 offset0:132 offset1:148
	v_add_u32_e32 v56, 0x400, v116
	ds_write2_b32 v56, v62, v58 offset0:8 offset1:24
	ds_write2_b32 v56, v63, v59 offset0:140 offset1:156
	ds_write2_b32 v116, v52, v48 offset0:32 offset1:48
	ds_write2_b32 v116, v53, v49 offset0:164 offset1:180
	ds_write2_b32 v56, v54, v50 offset0:40 offset1:56
	ds_write2_b32 v56, v55, v51 offset0:172 offset1:188
	v_add_u32_e32 v48, 0x2000, v116
	ds_write2_b32 v48, v44, v40 offset0:64 offset1:80
	ds_write2_b32 v48, v45, v41 offset0:196 offset1:212
	v_add_u32_e32 v40, 0x2400, v116
	ds_write2_b32 v40, v46, v42 offset0:72 offset1:88
	ds_write2_b32 v40, v47, v43 offset0:204 offset1:220
	ds_write2_b32 v48, v36, v32 offset0:96 offset1:112
	ds_write2_b32 v48, v37, v33 offset0:228 offset1:244
	ds_write2_b32 v40, v38, v34 offset0:104 offset1:120
	ds_write2_b32 v40, v39, v35 offset0:236 offset1:252
	v_add_u32_e32 v32, 0x4000, v116
	ds_write2_b32 v32, v28, v24 offset0:128 offset1:144
	v_add_u32_e32 v24, 0x4400, v116
	ds_write2_b32 v24, v29, v25 offset0:4 offset1:20
	ds_write2_b32 v24, v30, v26 offset0:136 offset1:152
	v_add_u32_e32 v25, 0x4800, v116
	ds_write2_b32 v25, v31, v27 offset0:12 offset1:28
	ds_write2_b32 v32, v20, v16 offset0:160 offset1:176
	ds_write2_b32 v24, v21, v17 offset0:36 offset1:52
	ds_write2_b32 v24, v22, v18 offset0:168 offset1:184
	ds_write2_b32 v25, v23, v19 offset0:44 offset1:60
	v_add_u32_e32 v16, 0x6000, v116
	ds_write2_b32 v16, v12, v8 offset0:192 offset1:208
	v_add_u32_e32 v8, 0x6400, v116
	ds_write2_b32 v8, v13, v9 offset0:68 offset1:84
	ds_write2_b32 v8, v14, v10 offset0:200 offset1:216
	v_add_u32_e32 v9, 0x6800, v116
	ds_write2_b32 v9, v15, v11 offset0:76 offset1:92
	ds_write2_b32 v16, v4, v0 offset0:224 offset1:240
	ds_write2_b32 v8, v5, v1 offset0:100 offset1:116
	ds_write2_b32 v8, v6, v2 offset0:232 offset1:248
	ds_write2_b32 v9, v7, v3 offset0:108 offset1:124
	v_or_b32_e32 v0, s25, v117
	v_ashrrev_i32_e32 v1, 31, v0
	v_lshlrev_b64 v[2:3], 2, v[0:1]
	v_lshl_add_u64 v[0:1], s[14:15], 0, v[2:3]
	v_lshl_add_u64 v[2:3], s[12:13], 0, v[2:3]
	v_add_u32_e32 v4, s24, v128
	s_mov_b32 s16, 0
	s_waitcnt lgkmcnt(0)
	s_barrier

.LBB0_2085:
	s_and_b32 s28, s27, 0x4000
	s_xor_b32 s29, s28, 0x4000
	s_lshl_b32 s29, s29, 1
	s_add_i32 s29, s29, 32
	s_add_u32 s90, s52, s16
	s_addc_u32 s91, s53, s17
	s_add_i32 m0, s29, s82
	s_lshl_b32 s28, s28, 1
	global_load_lds_dwordx4 v192, s[90:91]
	s_add_i32 m0, s29, s83
	s_add_i32 s28, s28, 32
	global_load_lds_dwordx4 v193, s[90:91]
	s_add_i32 m0, s29, s84
	v_add3_u32 v139, s28, v113, v136
	global_load_lds_dwordx4 v194, s[90:91]
	s_add_i32 m0, s29, s85
	v_add3_u32 v172, s28, v114, v136
	global_load_lds_dwordx4 v195, s[90:91]
	s_add_i32 m0, s29, s86
	v_add_u32_e32 v160, v139, v137
	global_load_lds_dwordx4 v196, s[90:91]
	s_add_i32 m0, s29, s87
	v_add_u32_e32 v168, v172, v137
	global_load_lds_dwordx4 v197, s[90:91]
	s_add_i32 m0, s29, s88
	s_addk_i32 s27, 0x4000
	global_load_lds_dwordx4 v198, s[90:91]
	s_add_i32 m0, s29, s89
	s_add_u32 s16, s16, 0x80
	s_addc_u32 s17, s17, 0
	global_load_lds_dwordx4 v199, s[90:91]
	ds_read_b128 v[140:143], v160
	ds_read_b128 v[144:147], v160 offset:2048
	ds_read_b128 v[148:151], v168 offset:16384
	ds_read_b128 v[152:155], v168 offset:18432
	ds_read_b128 v[156:159], v160 offset:4096
	ds_read_b128 v[160:163], v160 offset:6144
	ds_read_b128 v[164:167], v168 offset:20480
	ds_read_b128 v[168:171], v168 offset:22528
	s_setprio 1
	s_waitcnt lgkmcnt(0)
	v_mfma_f32_16x16x32_bf16 v[60:63], v[140:143], v[148:151], v[60:63]
	v_mfma_f32_16x16x32_bf16 v[56:59], v[140:143], v[152:155], v[56:59]
	v_mfma_f32_16x16x32_bf16 v[52:55], v[140:143], v[164:167], v[52:55]
	v_mfma_f32_16x16x32_bf16 v[48:51], v[140:143], v[168:171], v[48:51]
	v_mfma_f32_16x16x32_bf16 v[44:47], v[144:147], v[148:151], v[44:47]
	v_mfma_f32_16x16x32_bf16 v[40:43], v[144:147], v[152:155], v[40:43]
	v_mfma_f32_16x16x32_bf16 v[36:39], v[144:147], v[164:167], v[36:39]
	v_mfma_f32_16x16x32_bf16 v[32:35], v[144:147], v[168:171], v[32:35]
	v_mfma_f32_16x16x32_bf16 v[28:31], v[156:159], v[148:151], v[28:31]
	v_mfma_f32_16x16x32_bf16 v[24:27], v[156:159], v[152:155], v[24:27]
	v_mfma_f32_16x16x32_bf16 v[20:23], v[156:159], v[164:167], v[20:23]
	v_mfma_f32_16x16x32_bf16 v[16:19], v[156:159], v[168:171], v[16:19]
	v_mfma_f32_16x16x32_bf16 v[12:15], v[160:163], v[148:151], v[12:15]
	v_mfma_f32_16x16x32_bf16 v[8:11], v[160:163], v[152:155], v[8:11]
	v_mfma_f32_16x16x32_bf16 v[4:7], v[160:163], v[164:167], v[4:7]
	v_mfma_f32_16x16x32_bf16 v[0:3], v[160:163], v[168:171], v[0:3]
	s_setprio 0
	v_add_u32_e32 v139, v139, v138
	v_add_u32_e32 v168, v172, v138
	ds_read_b128 v[140:143], v139
	ds_read_b128 v[144:147], v139 offset:2048
	ds_read_b128 v[148:151], v168 offset:16384
	ds_read_b128 v[152:155], v168 offset:18432
	ds_read_b128 v[156:159], v139 offset:4096
	ds_read_b128 v[160:163], v139 offset:6144
	ds_read_b128 v[164:167], v168 offset:20480
	ds_read_b128 v[168:171], v168 offset:22528
	s_setprio 1
	s_waitcnt lgkmcnt(0)
	v_mfma_f32_16x16x32_bf16 v[60:63], v[140:143], v[148:151], v[60:63]
	v_mfma_f32_16x16x32_bf16 v[56:59], v[140:143], v[152:155], v[56:59]
	v_mfma_f32_16x16x32_bf16 v[52:55], v[140:143], v[164:167], v[52:55]
	v_mfma_f32_16x16x32_bf16 v[48:51], v[140:143], v[168:171], v[48:51]
	v_mfma_f32_16x16x32_bf16 v[44:47], v[144:147], v[148:151], v[44:47]
	v_mfma_f32_16x16x32_bf16 v[40:43], v[144:147], v[152:155], v[40:43]
	v_mfma_f32_16x16x32_bf16 v[36:39], v[144:147], v[164:167], v[36:39]
	v_mfma_f32_16x16x32_bf16 v[32:35], v[144:147], v[168:171], v[32:35]
	v_mfma_f32_16x16x32_bf16 v[28:31], v[156:159], v[148:151], v[28:31]
	v_mfma_f32_16x16x32_bf16 v[24:27], v[156:159], v[152:155], v[24:27]
	v_mfma_f32_16x16x32_bf16 v[20:23], v[156:159], v[164:167], v[20:23]
	v_mfma_f32_16x16x32_bf16 v[16:19], v[156:159], v[168:171], v[16:19]
	v_mfma_f32_16x16x32_bf16 v[12:15], v[160:163], v[148:151], v[12:15]
	v_mfma_f32_16x16x32_bf16 v[8:11], v[160:163], v[152:155], v[8:11]
	v_mfma_f32_16x16x32_bf16 v[4:7], v[160:163], v[164:167], v[4:7]
	v_mfma_f32_16x16x32_bf16 v[0:3], v[160:163], v[168:171], v[0:3]
	s_setprio 0
	s_cmpk_eq_i32 s16, 0x1f80
	s_waitcnt vmcnt(0)
	s_barrier
	s_cbranch_scc0 .LBB0_2085
	ds_read_b128 v[88:91], v117 offset:55296
	ds_read_b128 v[92:95], v117 offset:53248
	ds_read_b128 v[96:99], v118 offset:38912
	ds_read_b128 v[100:103], v118 offset:36864
	ds_read_b128 v[140:143], v117 offset:51200
	ds_read_b128 v[144:147], v117 offset:49152
	ds_read_b128 v[148:151], v118 offset:34816
	ds_read_b128 v[152:155], v118 offset:32768
	s_setprio 1
	s_waitcnt lgkmcnt(5)
	v_mfma_f32_16x16x32_bf16 v[4:7], v[96:99], v[92:95], v[4:7]
	v_mfma_f32_16x16x32_bf16 v[0:3], v[96:99], v[88:91], v[0:3]
	s_waitcnt lgkmcnt(0)
	v_mfma_f32_16x16x32_bf16 v[60:63], v[152:155], v[144:147], v[60:63]
	v_mfma_f32_16x16x32_bf16 v[56:59], v[152:155], v[140:143], v[56:59]
	v_mfma_f32_16x16x32_bf16 v[52:55], v[152:155], v[92:95], v[52:55]
	v_mfma_f32_16x16x32_bf16 v[48:51], v[152:155], v[88:91], v[48:51]
	v_mfma_f32_16x16x32_bf16 v[44:47], v[148:151], v[144:147], v[44:47]
	v_mfma_f32_16x16x32_bf16 v[40:43], v[148:151], v[140:143], v[40:43]
	v_mfma_f32_16x16x32_bf16 v[36:39], v[148:151], v[92:95], v[36:39]
	v_mfma_f32_16x16x32_bf16 v[32:35], v[148:151], v[88:91], v[32:35]
	v_mfma_f32_16x16x32_bf16 v[28:31], v[100:103], v[144:147], v[28:31]
	v_mfma_f32_16x16x32_bf16 v[24:27], v[100:103], v[140:143], v[24:27]
	v_mfma_f32_16x16x32_bf16 v[20:23], v[100:103], v[92:95], v[20:23]
	v_mfma_f32_16x16x32_bf16 v[16:19], v[100:103], v[88:91], v[16:19]
	v_mfma_f32_16x16x32_bf16 v[12:15], v[96:99], v[144:147], v[12:15]
	v_mfma_f32_16x16x32_bf16 v[8:11], v[96:99], v[140:143], v[8:11]
	s_setprio 0
	ds_read_b128 v[88:91], v119 offset:32768
	ds_read_b128 v[92:95], v119 offset:34816
	ds_read_b128 v[96:99], v120 offset:49152
	ds_read_b128 v[100:103], v120 offset:51200
	ds_read_b128 v[140:143], v119 offset:36864
	ds_read_b128 v[144:147], v119 offset:38912
	ds_read_b128 v[148:151], v120 offset:53248
	ds_read_b128 v[152:155], v120 offset:55296
	s_setprio 1
	s_waitcnt lgkmcnt(1)
	v_mfma_f32_16x16x32_bf16 v[4:7], v[144:147], v[148:151], v[4:7]
	s_waitcnt lgkmcnt(0)
	v_mfma_f32_16x16x32_bf16 v[0:3], v[144:147], v[152:155], v[0:3]
	v_mfma_f32_16x16x32_bf16 v[60:63], v[88:91], v[96:99], v[60:63]
	v_mfma_f32_16x16x32_bf16 v[56:59], v[88:91], v[100:103], v[56:59]
	v_mfma_f32_16x16x32_bf16 v[52:55], v[88:91], v[148:151], v[52:55]
	v_mfma_f32_16x16x32_bf16 v[48:51], v[88:91], v[152:155], v[48:51]
	v_mfma_f32_16x16x32_bf16 v[44:47], v[92:95], v[96:99], v[44:47]
	v_mfma_f32_16x16x32_bf16 v[40:43], v[92:95], v[100:103], v[40:43]
	v_mfma_f32_16x16x32_bf16 v[36:39], v[92:95], v[148:151], v[36:39]
	v_mfma_f32_16x16x32_bf16 v[32:35], v[92:95], v[152:155], v[32:35]
	v_mfma_f32_16x16x32_bf16 v[28:31], v[140:143], v[96:99], v[28:31]
	v_mfma_f32_16x16x32_bf16 v[24:27], v[140:143], v[100:103], v[24:27]
	v_mfma_f32_16x16x32_bf16 v[20:23], v[140:143], v[148:151], v[20:23]
	v_mfma_f32_16x16x32_bf16 v[16:19], v[140:143], v[152:155], v[16:19]
	v_mfma_f32_16x16x32_bf16 v[12:15], v[144:147], v[96:99], v[12:15]
	v_mfma_f32_16x16x32_bf16 v[8:11], v[144:147], v[100:103], v[8:11]
	s_setprio 0
	s_barrier
	ds_write2_b32 v115, v60, v56 offset1:16
	ds_write2_b32 v115, v61, v57 offset0:132 offset1:148
	v_add_u32_e32 v56, 0x400, v115
	ds_write2_b32 v56, v62, v58 offset0:8 offset1:24
	ds_write2_b32 v56, v63, v59 offset0:140 offset1:156
	ds_write2_b32 v115, v52, v48 offset0:32 offset1:48
	ds_write2_b32 v115, v53, v49 offset0:164 offset1:180
	ds_write2_b32 v56, v54, v50 offset0:40 offset1:56
	ds_write2_b32 v56, v55, v51 offset0:172 offset1:188
	v_add_u32_e32 v48, 0x2000, v115
	ds_write2_b32 v48, v44, v40 offset0:64 offset1:80
	ds_write2_b32 v48, v45, v41 offset0:196 offset1:212
	v_add_u32_e32 v40, 0x2400, v115
	ds_write2_b32 v40, v46, v42 offset0:72 offset1:88
	ds_write2_b32 v40, v47, v43 offset0:204 offset1:220
	ds_write2_b32 v48, v36, v32 offset0:96 offset1:112
	ds_write2_b32 v48, v37, v33 offset0:228 offset1:244
	ds_write2_b32 v40, v38, v34 offset0:104 offset1:120
	ds_write2_b32 v40, v39, v35 offset0:236 offset1:252
	v_add_u32_e32 v32, 0x4000, v115
	ds_write2_b32 v32, v28, v24 offset0:128 offset1:144
	v_add_u32_e32 v24, 0x4400, v115
	ds_write2_b32 v24, v29, v25 offset0:4 offset1:20
	ds_write2_b32 v24, v30, v26 offset0:136 offset1:152
	v_add_u32_e32 v25, 0x4800, v115
	ds_write2_b32 v25, v31, v27 offset0:12 offset1:28
	ds_write2_b32 v32, v20, v16 offset0:160 offset1:176
	ds_write2_b32 v24, v21, v17 offset0:36 offset1:52
	ds_write2_b32 v24, v22, v18 offset0:168 offset1:184
	ds_write2_b32 v25, v23, v19 offset0:44 offset1:60
	v_add_u32_e32 v16, 0x6000, v115
	ds_write2_b32 v16, v12, v8 offset0:192 offset1:208
	v_add_u32_e32 v8, 0x6400, v115
	ds_write2_b32 v8, v13, v9 offset0:68 offset1:84
	ds_write2_b32 v8, v14, v10 offset0:200 offset1:216
	v_add_u32_e32 v9, 0x6800, v115
	ds_write2_b32 v9, v15, v11 offset0:76 offset1:92
	ds_write2_b32 v16, v4, v0 offset0:224 offset1:240
	ds_write2_b32 v8, v5, v1 offset0:100 offset1:116
	ds_write2_b32 v8, v6, v2 offset0:232 offset1:248
	ds_write2_b32 v9, v7, v3 offset0:108 offset1:124
	v_or_b32_e32 v0, s25, v116
	v_ashrrev_i32_e32 v1, 31, v0
	v_lshlrev_b64 v[2:3], 2, v[0:1]
	v_lshl_add_u64 v[0:1], s[14:15], 0, v[2:3]
	v_lshl_add_u64 v[2:3], s[12:13], 0, v[2:3]
	v_add_u32_e32 v4, s26, v129
	s_mov_b32 s16, 0
	s_waitcnt lgkmcnt(0)
	s_barrier

.LBB0_2270:
	s_and_b32 s31, s30, 0x4000
	s_xor_b32 s34, s31, 0x4000
	s_lshl_b32 s34, s34, 1
	s_add_i32 s34, s34, 32
	s_add_u32 s90, s52, s8
	s_addc_u32 s91, s53, s9
	s_add_i32 m0, s34, s82
	s_lshl_b32 s31, s31, 1
	global_load_lds_dwordx4 v184, s[90:91]
	s_add_i32 m0, s34, s83
	s_add_i32 s31, s31, 32
	global_load_lds_dwordx4 v185, s[90:91]
	s_add_i32 m0, s34, s84
	v_lshl_add_u32 v64, v114, 1, s31
	global_load_lds_dwordx4 v186, s[90:91]
	s_add_i32 m0, s34, s85
	v_lshl_add_u32 v139, v115, 1, s31
	global_load_lds_dwordx4 v187, s[90:91]
	s_add_i32 m0, s34, s86
	v_add_u32_e32 v160, v64, v136
	global_load_lds_dwordx4 v188, s[90:91]
	s_add_i32 m0, s34, s87
	v_add_u32_e32 v168, v139, v136
	global_load_lds_dwordx4 v189, s[90:91]
	s_add_i32 m0, s34, s88
	s_addk_i32 s30, 0x4000
	global_load_lds_dwordx4 v190, s[90:91]
	s_add_i32 m0, s34, s89
	s_add_u32 s8, s8, 0x80
	s_addc_u32 s9, s9, 0
	global_load_lds_dwordx4 v191, s[90:91]
	ds_read_b128 v[140:143], v160
	ds_read_b128 v[144:147], v160 offset:2048
	ds_read_b128 v[148:151], v168 offset:16384
	ds_read_b128 v[152:155], v168 offset:18432
	ds_read_b128 v[156:159], v160 offset:4096
	ds_read_b128 v[160:163], v160 offset:6144
	ds_read_b128 v[164:167], v168 offset:20480
	ds_read_b128 v[168:171], v168 offset:22528
	s_setprio 1
	s_waitcnt lgkmcnt(0)
	v_mfma_f32_16x16x32_bf16 v[60:63], v[140:143], v[148:151], v[60:63]
	v_mfma_f32_16x16x32_bf16 v[56:59], v[140:143], v[152:155], v[56:59]
	v_mfma_f32_16x16x32_bf16 v[52:55], v[140:143], v[164:167], v[52:55]
	v_mfma_f32_16x16x32_bf16 v[48:51], v[140:143], v[168:171], v[48:51]
	v_mfma_f32_16x16x32_bf16 v[44:47], v[144:147], v[148:151], v[44:47]
	v_mfma_f32_16x16x32_bf16 v[40:43], v[144:147], v[152:155], v[40:43]
	v_mfma_f32_16x16x32_bf16 v[36:39], v[144:147], v[164:167], v[36:39]
	v_mfma_f32_16x16x32_bf16 v[32:35], v[144:147], v[168:171], v[32:35]
	v_mfma_f32_16x16x32_bf16 v[28:31], v[156:159], v[148:151], v[28:31]
	v_mfma_f32_16x16x32_bf16 v[24:27], v[156:159], v[152:155], v[24:27]
	v_mfma_f32_16x16x32_bf16 v[20:23], v[156:159], v[164:167], v[20:23]
	v_mfma_f32_16x16x32_bf16 v[16:19], v[156:159], v[168:171], v[16:19]
	v_mfma_f32_16x16x32_bf16 v[12:15], v[160:163], v[148:151], v[12:15]
	v_mfma_f32_16x16x32_bf16 v[8:11], v[160:163], v[152:155], v[8:11]
	v_mfma_f32_16x16x32_bf16 v[4:7], v[160:163], v[164:167], v[4:7]
	v_mfma_f32_16x16x32_bf16 v[0:3], v[160:163], v[168:171], v[0:3]
	s_setprio 0
	v_add_u32_e32 v64, v64, v137
	v_add_u32_e32 v139, v139, v137
	ds_read_b128 v[140:143], v64
	ds_read_b128 v[144:147], v64 offset:2048
	ds_read_b128 v[148:151], v139 offset:16384
	ds_read_b128 v[152:155], v139 offset:18432
	ds_read_b128 v[156:159], v64 offset:4096
	ds_read_b128 v[160:163], v64 offset:6144
	ds_read_b128 v[164:167], v139 offset:20480
	ds_read_b128 v[168:171], v139 offset:22528
	s_setprio 1
	s_waitcnt lgkmcnt(0)
	v_mfma_f32_16x16x32_bf16 v[60:63], v[140:143], v[148:151], v[60:63]
	v_mfma_f32_16x16x32_bf16 v[56:59], v[140:143], v[152:155], v[56:59]
	v_mfma_f32_16x16x32_bf16 v[52:55], v[140:143], v[164:167], v[52:55]
	v_mfma_f32_16x16x32_bf16 v[48:51], v[140:143], v[168:171], v[48:51]
	v_mfma_f32_16x16x32_bf16 v[44:47], v[144:147], v[148:151], v[44:47]
	v_mfma_f32_16x16x32_bf16 v[40:43], v[144:147], v[152:155], v[40:43]
	v_mfma_f32_16x16x32_bf16 v[36:39], v[144:147], v[164:167], v[36:39]
	v_mfma_f32_16x16x32_bf16 v[32:35], v[144:147], v[168:171], v[32:35]
	v_mfma_f32_16x16x32_bf16 v[28:31], v[156:159], v[148:151], v[28:31]
	v_mfma_f32_16x16x32_bf16 v[24:27], v[156:159], v[152:155], v[24:27]
	v_mfma_f32_16x16x32_bf16 v[20:23], v[156:159], v[164:167], v[20:23]
	v_mfma_f32_16x16x32_bf16 v[16:19], v[156:159], v[168:171], v[16:19]
	v_mfma_f32_16x16x32_bf16 v[12:15], v[160:163], v[148:151], v[12:15]
	v_mfma_f32_16x16x32_bf16 v[8:11], v[160:163], v[152:155], v[8:11]
	v_mfma_f32_16x16x32_bf16 v[4:7], v[160:163], v[164:167], v[4:7]
	v_mfma_f32_16x16x32_bf16 v[0:3], v[160:163], v[168:171], v[0:3]
	s_setprio 0
	s_cmpk_eq_i32 s8, 0x780
	s_waitcnt vmcnt(0)
	s_barrier
	s_cbranch_scc0 .LBB0_2270
	ds_read_b128 v[90:93], v116 offset:55296
	ds_read_b128 v[94:97], v116 offset:53248
	ds_read_b128 v[98:101], v117 offset:38912
	ds_read_b128 v[102:105], v117 offset:36864
	ds_read_b128 v[140:143], v116 offset:51200
	ds_read_b128 v[144:147], v116 offset:49152
	ds_read_b128 v[148:151], v117 offset:34816
	ds_read_b128 v[152:155], v117 offset:32768
	s_setprio 1
	s_waitcnt lgkmcnt(4)
	v_mfma_f32_16x16x32_bf16 v[20:23], v[102:105], v[94:97], v[20:23]
	v_mfma_f32_16x16x32_bf16 v[16:19], v[102:105], v[90:93], v[16:19]
	s_waitcnt lgkmcnt(0)
	v_mfma_f32_16x16x32_bf16 v[60:63], v[152:155], v[144:147], v[60:63]
	v_mfma_f32_16x16x32_bf16 v[56:59], v[152:155], v[140:143], v[56:59]
	v_mfma_f32_16x16x32_bf16 v[52:55], v[152:155], v[94:97], v[52:55]
	v_mfma_f32_16x16x32_bf16 v[48:51], v[152:155], v[90:93], v[48:51]
	v_mfma_f32_16x16x32_bf16 v[44:47], v[148:151], v[144:147], v[44:47]
	v_mfma_f32_16x16x32_bf16 v[40:43], v[148:151], v[140:143], v[40:43]
	v_mfma_f32_16x16x32_bf16 v[36:39], v[148:151], v[94:97], v[36:39]
	v_mfma_f32_16x16x32_bf16 v[32:35], v[148:151], v[90:93], v[32:35]
	v_mfma_f32_16x16x32_bf16 v[28:31], v[102:105], v[144:147], v[28:31]
	v_mfma_f32_16x16x32_bf16 v[24:27], v[102:105], v[140:143], v[24:27]
	v_mfma_f32_16x16x32_bf16 v[12:15], v[98:101], v[144:147], v[12:15]
	v_mfma_f32_16x16x32_bf16 v[8:11], v[98:101], v[140:143], v[8:11]
	v_mfma_f32_16x16x32_bf16 v[4:7], v[98:101], v[94:97], v[4:7]
	v_mfma_f32_16x16x32_bf16 v[0:3], v[98:101], v[90:93], v[0:3]
	s_setprio 0
	ds_read_b128 v[90:93], v118 offset:32768
	ds_read_b128 v[94:97], v118 offset:34816
	ds_read_b128 v[98:101], v119 offset:49152
	ds_read_b128 v[102:105], v119 offset:51200
	ds_read_b128 v[140:143], v118 offset:36864
	ds_read_b128 v[144:147], v118 offset:38912
	ds_read_b128 v[148:151], v119 offset:53248
	ds_read_b128 v[152:155], v119 offset:55296
	s_setprio 1
	s_waitcnt lgkmcnt(1)
	v_mfma_f32_16x16x32_bf16 v[20:23], v[140:143], v[148:151], v[20:23]
	s_waitcnt lgkmcnt(0)
	v_mfma_f32_16x16x32_bf16 v[16:19], v[140:143], v[152:155], v[16:19]
	v_mfma_f32_16x16x32_bf16 v[60:63], v[90:93], v[98:101], v[60:63]
	v_mfma_f32_16x16x32_bf16 v[56:59], v[90:93], v[102:105], v[56:59]
	v_mfma_f32_16x16x32_bf16 v[52:55], v[90:93], v[148:151], v[52:55]
	v_mfma_f32_16x16x32_bf16 v[48:51], v[90:93], v[152:155], v[48:51]
	v_mfma_f32_16x16x32_bf16 v[44:47], v[94:97], v[98:101], v[44:47]
	v_mfma_f32_16x16x32_bf16 v[40:43], v[94:97], v[102:105], v[40:43]
	v_mfma_f32_16x16x32_bf16 v[36:39], v[94:97], v[148:151], v[36:39]
	v_mfma_f32_16x16x32_bf16 v[32:35], v[94:97], v[152:155], v[32:35]
	v_mfma_f32_16x16x32_bf16 v[28:31], v[140:143], v[98:101], v[28:31]
	v_mfma_f32_16x16x32_bf16 v[24:27], v[140:143], v[102:105], v[24:27]
	v_mfma_f32_16x16x32_bf16 v[12:15], v[144:147], v[98:101], v[12:15]
	v_mfma_f32_16x16x32_bf16 v[8:11], v[144:147], v[102:105], v[8:11]
	v_mfma_f32_16x16x32_bf16 v[4:7], v[144:147], v[148:151], v[4:7]
	v_mfma_f32_16x16x32_bf16 v[0:3], v[144:147], v[152:155], v[0:3]
	s_setprio 0
	s_barrier
	ds_write2_b32 v120, v60, v56 offset1:16
	ds_write2_b32 v120, v61, v57 offset0:132 offset1:148
	v_add_u32_e32 v56, 0x400, v120
	ds_write2_b32 v56, v62, v58 offset0:8 offset1:24
	ds_write2_b32 v56, v63, v59 offset0:140 offset1:156
	ds_write2_b32 v120, v52, v48 offset0:32 offset1:48
	ds_write2_b32 v120, v53, v49 offset0:164 offset1:180
	ds_write2_b32 v56, v54, v50 offset0:40 offset1:56
	ds_write2_b32 v56, v55, v51 offset0:172 offset1:188
	v_add_u32_e32 v48, 0x2000, v120
	ds_write2_b32 v48, v44, v40 offset0:64 offset1:80
	ds_write2_b32 v48, v45, v41 offset0:196 offset1:212
	v_add_u32_e32 v40, 0x2400, v120
	ds_write2_b32 v40, v46, v42 offset0:72 offset1:88
	ds_write2_b32 v40, v47, v43 offset0:204 offset1:220
	ds_write2_b32 v48, v36, v32 offset0:96 offset1:112
	ds_write2_b32 v48, v37, v33 offset0:228 offset1:244
	ds_write2_b32 v40, v38, v34 offset0:104 offset1:120
	ds_write2_b32 v40, v39, v35 offset0:236 offset1:252
	v_add_u32_e32 v32, 0x4000, v120
	ds_write2_b32 v32, v28, v24 offset0:128 offset1:144
	v_add_u32_e32 v24, 0x4400, v120
	ds_write2_b32 v24, v29, v25 offset0:4 offset1:20
	ds_write2_b32 v24, v30, v26 offset0:136 offset1:152
	v_add_u32_e32 v25, 0x4800, v120
	s_cmp_gt_i32 s28, 5
	ds_write2_b32 v25, v31, v27 offset0:12 offset1:28
	ds_write2_b32 v32, v20, v16 offset0:160 offset1:176
	ds_write2_b32 v24, v21, v17 offset0:36 offset1:52
	ds_write2_b32 v24, v22, v18 offset0:168 offset1:184
	ds_write2_b32 v25, v23, v19 offset0:44 offset1:60
	v_add_u32_e32 v16, 0x6000, v120
	v_or_b32_e32 v64, s29, v121
	s_cselect_b64 s[30:31], -1, 0
	s_ashr_i32 s29, s28, 31
	ds_write2_b32 v16, v12, v8 offset0:192 offset1:208
	v_add_u32_e32 v8, 0x6400, v120
	s_cmp_gt_i32 s28, 3
	ds_write2_b32 v8, v13, v9 offset0:68 offset1:84
	ds_write2_b32 v8, v14, v10 offset0:200 offset1:216
	v_add_u32_e32 v9, 0x6800, v120
	s_cselect_b64 s[34:35], -1, 0
	s_lshl_b64 s[28:29], s[28:29], 2
	ds_write2_b32 v9, v15, v11 offset0:76 offset1:92
	ds_write2_b32 v16, v4, v0 offset0:224 offset1:240
	ds_write2_b32 v8, v5, v1 offset0:100 offset1:116
	ds_write2_b32 v8, v6, v2 offset0:232 offset1:248
	ds_write2_b32 v9, v7, v3 offset0:108 offset1:124
	v_ashrrev_i32_e32 v1, 31, v64
	v_mov_b32_e32 v0, v64
	v_lshlrev_b64 v[2:3], 1, v[64:65]
	s_add_u32 s28, s40, s28
	v_cmp_gt_u32_e64 s[8:9], s44, v64
	v_lshl_add_u64 v[16:17], s[16:17], 0, v[2:3]
	s_addc_u32 s29, s41, s29
	v_lshl_add_u64 v[18:19], s[14:15], 0, v[2:3]
	v_lshl_add_u64 v[20:21], v[0:1], 1, s[12:13]
	v_add_u32_e32 v22, s36, v129
	s_mov_b32 s50, 0
	s_waitcnt lgkmcnt(0)
	s_barrier
	s_branch .LBB0_2273

.LBB0_2292:
	s_and_b32 s24, s23, 0x4000
	s_xor_b32 s25, s24, 0x4000
	s_lshl_b32 s25, s25, 1
	s_add_i32 s25, s25, 32
	s_add_u32 s90, s52, s8
	s_addc_u32 s91, s53, s9
	s_add_i32 m0, s25, s82
	s_lshl_b32 s24, s24, 1
	global_load_lds_dwordx4 v184, s[90:91]
	s_add_i32 m0, s25, s83
	s_add_i32 s24, s24, 32
	global_load_lds_dwordx4 v185, s[90:91]
	s_add_i32 m0, s25, s84
	v_lshl_add_u32 v64, v115, 1, s24
	global_load_lds_dwordx4 v186, s[90:91]
	s_add_i32 m0, s25, s85
	v_lshl_add_u32 v141, v116, 1, s24
	global_load_lds_dwordx4 v187, s[90:91]
	s_add_i32 m0, s25, s86
	v_add_u32_e32 v162, v64, v138
	global_load_lds_dwordx4 v188, s[90:91]
	s_add_i32 m0, s25, s87
	v_add_u32_e32 v170, v141, v138
	global_load_lds_dwordx4 v189, s[90:91]
	s_add_i32 m0, s25, s88
	s_addk_i32 s23, 0x4000
	global_load_lds_dwordx4 v190, s[90:91]
	s_add_i32 m0, s25, s89
	s_add_u32 s8, s8, 0x80
	s_addc_u32 s9, s9, 0
	global_load_lds_dwordx4 v191, s[90:91]
	ds_read_b128 v[142:145], v162
	ds_read_b128 v[146:149], v162 offset:2048
	ds_read_b128 v[150:153], v170 offset:16384
	ds_read_b128 v[154:157], v170 offset:18432
	ds_read_b128 v[158:161], v162 offset:4096
	ds_read_b128 v[162:165], v162 offset:6144
	ds_read_b128 v[166:169], v170 offset:20480
	ds_read_b128 v[170:173], v170 offset:22528
	s_setprio 1
	s_waitcnt lgkmcnt(0)
	v_mfma_f32_16x16x32_bf16 v[60:63], v[142:145], v[150:153], v[60:63]
	v_mfma_f32_16x16x32_bf16 v[56:59], v[142:145], v[154:157], v[56:59]
	v_mfma_f32_16x16x32_bf16 v[52:55], v[142:145], v[166:169], v[52:55]
	v_mfma_f32_16x16x32_bf16 v[48:51], v[142:145], v[170:173], v[48:51]
	v_mfma_f32_16x16x32_bf16 v[44:47], v[146:149], v[150:153], v[44:47]
	v_mfma_f32_16x16x32_bf16 v[40:43], v[146:149], v[154:157], v[40:43]
	v_mfma_f32_16x16x32_bf16 v[36:39], v[146:149], v[166:169], v[36:39]
	v_mfma_f32_16x16x32_bf16 v[32:35], v[146:149], v[170:173], v[32:35]
	v_mfma_f32_16x16x32_bf16 v[28:31], v[158:161], v[150:153], v[28:31]
	v_mfma_f32_16x16x32_bf16 v[24:27], v[158:161], v[154:157], v[24:27]
	v_mfma_f32_16x16x32_bf16 v[20:23], v[158:161], v[166:169], v[20:23]
	v_mfma_f32_16x16x32_bf16 v[16:19], v[158:161], v[170:173], v[16:19]
	v_mfma_f32_16x16x32_bf16 v[12:15], v[162:165], v[150:153], v[12:15]
	v_mfma_f32_16x16x32_bf16 v[8:11], v[162:165], v[154:157], v[8:11]
	v_mfma_f32_16x16x32_bf16 v[4:7], v[162:165], v[166:169], v[4:7]
	v_mfma_f32_16x16x32_bf16 v[0:3], v[162:165], v[170:173], v[0:3]
	s_setprio 0
	v_add_u32_e32 v64, v64, v139
	v_add_u32_e32 v141, v141, v139
	ds_read_b128 v[142:145], v64
	ds_read_b128 v[146:149], v64 offset:2048
	ds_read_b128 v[150:153], v141 offset:16384
	ds_read_b128 v[154:157], v141 offset:18432
	ds_read_b128 v[158:161], v64 offset:4096
	ds_read_b128 v[162:165], v64 offset:6144
	ds_read_b128 v[166:169], v141 offset:20480
	ds_read_b128 v[170:173], v141 offset:22528
	s_setprio 1
	s_waitcnt lgkmcnt(0)
	v_mfma_f32_16x16x32_bf16 v[60:63], v[142:145], v[150:153], v[60:63]
	v_mfma_f32_16x16x32_bf16 v[56:59], v[142:145], v[154:157], v[56:59]
	v_mfma_f32_16x16x32_bf16 v[52:55], v[142:145], v[166:169], v[52:55]
	v_mfma_f32_16x16x32_bf16 v[48:51], v[142:145], v[170:173], v[48:51]
	v_mfma_f32_16x16x32_bf16 v[44:47], v[146:149], v[150:153], v[44:47]
	v_mfma_f32_16x16x32_bf16 v[40:43], v[146:149], v[154:157], v[40:43]
	v_mfma_f32_16x16x32_bf16 v[36:39], v[146:149], v[166:169], v[36:39]
	v_mfma_f32_16x16x32_bf16 v[32:35], v[146:149], v[170:173], v[32:35]
	v_mfma_f32_16x16x32_bf16 v[28:31], v[158:161], v[150:153], v[28:31]
	v_mfma_f32_16x16x32_bf16 v[24:27], v[158:161], v[154:157], v[24:27]
	v_mfma_f32_16x16x32_bf16 v[20:23], v[158:161], v[166:169], v[20:23]
	v_mfma_f32_16x16x32_bf16 v[16:19], v[158:161], v[170:173], v[16:19]
	v_mfma_f32_16x16x32_bf16 v[12:15], v[162:165], v[150:153], v[12:15]
	v_mfma_f32_16x16x32_bf16 v[8:11], v[162:165], v[154:157], v[8:11]
	v_mfma_f32_16x16x32_bf16 v[4:7], v[162:165], v[166:169], v[4:7]
	v_mfma_f32_16x16x32_bf16 v[0:3], v[162:165], v[170:173], v[0:3]
	s_setprio 0
	s_cmpk_eq_i32 s8, 0x780
	s_waitcnt vmcnt(0)
	s_barrier
	s_cbranch_scc0 .LBB0_2292
	ds_read_b128 v[90:93], v117 offset:55296
	ds_read_b128 v[94:97], v117 offset:53248
	ds_read_b128 v[98:101], v118 offset:38912
	ds_read_b128 v[102:105], v118 offset:36864
	ds_read_b128 v[142:145], v117 offset:51200
	ds_read_b128 v[146:149], v117 offset:49152
	ds_read_b128 v[150:153], v118 offset:34816
	ds_read_b128 v[154:157], v118 offset:32768
	s_setprio 1
	s_waitcnt lgkmcnt(4)
	v_mfma_f32_16x16x32_bf16 v[20:23], v[102:105], v[94:97], v[20:23]
	v_mfma_f32_16x16x32_bf16 v[16:19], v[102:105], v[90:93], v[16:19]
	s_waitcnt lgkmcnt(0)
	v_mfma_f32_16x16x32_bf16 v[60:63], v[154:157], v[146:149], v[60:63]
	v_mfma_f32_16x16x32_bf16 v[56:59], v[154:157], v[142:145], v[56:59]
	v_mfma_f32_16x16x32_bf16 v[52:55], v[154:157], v[94:97], v[52:55]
	v_mfma_f32_16x16x32_bf16 v[48:51], v[154:157], v[90:93], v[48:51]
	v_mfma_f32_16x16x32_bf16 v[44:47], v[150:153], v[146:149], v[44:47]
	v_mfma_f32_16x16x32_bf16 v[40:43], v[150:153], v[142:145], v[40:43]
	v_mfma_f32_16x16x32_bf16 v[36:39], v[150:153], v[94:97], v[36:39]
	v_mfma_f32_16x16x32_bf16 v[32:35], v[150:153], v[90:93], v[32:35]
	v_mfma_f32_16x16x32_bf16 v[28:31], v[102:105], v[146:149], v[28:31]
	v_mfma_f32_16x16x32_bf16 v[24:27], v[102:105], v[142:145], v[24:27]
	v_mfma_f32_16x16x32_bf16 v[12:15], v[98:101], v[146:149], v[12:15]
	v_mfma_f32_16x16x32_bf16 v[8:11], v[98:101], v[142:145], v[8:11]
	v_mfma_f32_16x16x32_bf16 v[4:7], v[98:101], v[94:97], v[4:7]
	v_mfma_f32_16x16x32_bf16 v[0:3], v[98:101], v[90:93], v[0:3]
	s_setprio 0
	ds_read_b128 v[90:93], v119 offset:32768
	ds_read_b128 v[94:97], v119 offset:34816
	ds_read_b128 v[98:101], v120 offset:49152
	ds_read_b128 v[102:105], v120 offset:51200
	ds_read_b128 v[142:145], v119 offset:36864
	ds_read_b128 v[146:149], v119 offset:38912
	ds_read_b128 v[150:153], v120 offset:53248
	ds_read_b128 v[154:157], v120 offset:55296
	s_setprio 1
	s_waitcnt lgkmcnt(1)
	v_mfma_f32_16x16x32_bf16 v[20:23], v[142:145], v[150:153], v[20:23]
	s_waitcnt lgkmcnt(0)
	v_mfma_f32_16x16x32_bf16 v[16:19], v[142:145], v[154:157], v[16:19]
	v_mfma_f32_16x16x32_bf16 v[60:63], v[90:93], v[98:101], v[60:63]
	v_mfma_f32_16x16x32_bf16 v[56:59], v[90:93], v[102:105], v[56:59]
	v_mfma_f32_16x16x32_bf16 v[52:55], v[90:93], v[150:153], v[52:55]
	v_mfma_f32_16x16x32_bf16 v[48:51], v[90:93], v[154:157], v[48:51]
	v_mfma_f32_16x16x32_bf16 v[44:47], v[94:97], v[98:101], v[44:47]
	v_mfma_f32_16x16x32_bf16 v[40:43], v[94:97], v[102:105], v[40:43]
	v_mfma_f32_16x16x32_bf16 v[36:39], v[94:97], v[150:153], v[36:39]
	v_mfma_f32_16x16x32_bf16 v[32:35], v[94:97], v[154:157], v[32:35]
	v_mfma_f32_16x16x32_bf16 v[28:31], v[142:145], v[98:101], v[28:31]
	v_mfma_f32_16x16x32_bf16 v[24:27], v[142:145], v[102:105], v[24:27]
	v_mfma_f32_16x16x32_bf16 v[12:15], v[146:149], v[98:101], v[12:15]
	v_mfma_f32_16x16x32_bf16 v[8:11], v[146:149], v[102:105], v[8:11]
	v_mfma_f32_16x16x32_bf16 v[4:7], v[146:149], v[150:153], v[4:7]
	v_mfma_f32_16x16x32_bf16 v[0:3], v[146:149], v[154:157], v[0:3]
	s_setprio 0
	s_barrier
	ds_write2_b32 v121, v60, v56 offset1:16
	ds_write2_b32 v121, v61, v57 offset0:132 offset1:148
	v_add_u32_e32 v56, 0x400, v121
	ds_write2_b32 v56, v62, v58 offset0:8 offset1:24
	ds_write2_b32 v56, v63, v59 offset0:140 offset1:156
	ds_write2_b32 v121, v52, v48 offset0:32 offset1:48
	ds_write2_b32 v121, v53, v49 offset0:164 offset1:180
	ds_write2_b32 v56, v54, v50 offset0:40 offset1:56
	ds_write2_b32 v56, v55, v51 offset0:172 offset1:188
	v_add_u32_e32 v48, 0x2000, v121
	ds_write2_b32 v48, v44, v40 offset0:64 offset1:80
	ds_write2_b32 v48, v45, v41 offset0:196 offset1:212
	v_add_u32_e32 v40, 0x2400, v121
	ds_write2_b32 v40, v46, v42 offset0:72 offset1:88
	ds_write2_b32 v40, v47, v43 offset0:204 offset1:220
	ds_write2_b32 v48, v36, v32 offset0:96 offset1:112
	ds_write2_b32 v48, v37, v33 offset0:228 offset1:244
	ds_write2_b32 v40, v38, v34 offset0:104 offset1:120
	ds_write2_b32 v40, v39, v35 offset0:236 offset1:252
	v_add_u32_e32 v32, 0x4000, v121
	ds_write2_b32 v32, v28, v24 offset0:128 offset1:144
	v_add_u32_e32 v24, 0x4400, v121
	s_ashr_i32 s26, s22, 7
	ds_write2_b32 v24, v29, v25 offset0:4 offset1:20
	ds_write2_b32 v24, v30, v26 offset0:136 offset1:152
	v_add_u32_e32 v25, 0x4800, v121
	s_cmp_gt_i32 s26, 5
	ds_write2_b32 v25, v31, v27 offset0:12 offset1:28
	ds_write2_b32 v32, v20, v16 offset0:160 offset1:176
	ds_write2_b32 v24, v21, v17 offset0:36 offset1:52
	ds_write2_b32 v24, v22, v18 offset0:168 offset1:184
	ds_write2_b32 v25, v23, v19 offset0:44 offset1:60
	v_add_u32_e32 v16, 0x6000, v121
	v_or_b32_e32 v64, s22, v122
	s_cselect_b64 s[22:23], -1, 0
	s_ashr_i32 s27, s26, 31
	ds_write2_b32 v16, v12, v8 offset0:192 offset1:208
	v_add_u32_e32 v8, 0x6400, v121
	s_cmp_gt_i32 s26, 3
	ds_write2_b32 v8, v13, v9 offset0:68 offset1:84
	ds_write2_b32 v8, v14, v10 offset0:200 offset1:216
	v_add_u32_e32 v9, 0x6800, v121
	s_cselect_b64 s[24:25], -1, 0
	s_lshl_b64 s[26:27], s[26:27], 2
	ds_write2_b32 v9, v15, v11 offset0:76 offset1:92
	ds_write2_b32 v16, v4, v0 offset0:224 offset1:240
	ds_write2_b32 v8, v5, v1 offset0:100 offset1:116
	ds_write2_b32 v8, v6, v2 offset0:232 offset1:248
	ds_write2_b32 v9, v7, v3 offset0:108 offset1:124
	v_ashrrev_i32_e32 v1, 31, v64
	v_mov_b32_e32 v0, v64
	v_lshlrev_b64 v[2:3], 1, v[64:65]
	s_add_u32 s26, s40, s26
	v_cmp_gt_u32_e64 s[8:9], s38, v64
	v_lshl_add_u64 v[16:17], s[16:17], 0, v[2:3]
	s_addc_u32 s27, s41, s27
	v_lshl_add_u64 v[18:19], s[14:15], 0, v[2:3]
	v_lshl_add_u64 v[20:21], v[0:1], 1, s[12:13]
	v_add_u32_e32 v22, s28, v131
	s_mov_b32 s43, 0
	s_waitcnt lgkmcnt(0)
	s_barrier
	s_branch .LBB0_2295

.LBB0_2976:
	s_and_b32 s28, s7, 0x4000
	s_xor_b32 s29, s28, 0x4000
	s_lshl_b32 s29, s29, 1
	s_add_i32 s29, s29, 32
	s_add_u32 s90, s52, s4
	s_addc_u32 s91, s53, s5
	s_add_i32 m0, s29, s82
	s_lshl_b32 s28, s28, 1
	global_load_lds_dwordx4 v184, s[90:91]
	s_add_i32 m0, s29, s83
	s_add_i32 s28, s28, 32
	global_load_lds_dwordx4 v185, s[90:91]
	s_add_i32 m0, s29, s84
	v_lshl_add_u32 v64, v114, 1, s28
	global_load_lds_dwordx4 v186, s[90:91]
	s_add_i32 m0, s29, s85
	v_lshl_add_u32 v170, v115, 1, s28
	global_load_lds_dwordx4 v187, s[90:91]
	s_add_i32 m0, s29, s86
	v_add_u32_e32 v158, v64, v136
	global_load_lds_dwordx4 v188, s[90:91]
	s_add_i32 m0, s29, s87
	v_add_u32_e32 v166, v170, v136
	global_load_lds_dwordx4 v189, s[90:91]
	s_add_i32 m0, s29, s88
	s_addk_i32 s7, 0x4000
	global_load_lds_dwordx4 v190, s[90:91]
	s_add_i32 m0, s29, s89
	s_add_u32 s4, s4, 0x80
	s_addc_u32 s5, s5, 0
	global_load_lds_dwordx4 v191, s[90:91]
	ds_read_b128 v[138:141], v158
	ds_read_b128 v[142:145], v158 offset:2048
	ds_read_b128 v[146:149], v166 offset:16384
	ds_read_b128 v[150:153], v166 offset:18432
	ds_read_b128 v[154:157], v158 offset:4096
	ds_read_b128 v[158:161], v158 offset:6144
	ds_read_b128 v[162:165], v166 offset:20480
	ds_read_b128 v[166:169], v166 offset:22528
	s_setprio 1
	s_waitcnt lgkmcnt(0)
	v_mfma_f32_16x16x32_bf16 v[60:63], v[138:141], v[146:149], v[60:63]
	v_mfma_f32_16x16x32_bf16 v[56:59], v[138:141], v[150:153], v[56:59]
	v_mfma_f32_16x16x32_bf16 v[52:55], v[138:141], v[162:165], v[52:55]
	v_mfma_f32_16x16x32_bf16 v[48:51], v[138:141], v[166:169], v[48:51]
	v_mfma_f32_16x16x32_bf16 v[44:47], v[142:145], v[146:149], v[44:47]
	v_mfma_f32_16x16x32_bf16 v[40:43], v[142:145], v[150:153], v[40:43]
	v_mfma_f32_16x16x32_bf16 v[36:39], v[142:145], v[162:165], v[36:39]
	v_mfma_f32_16x16x32_bf16 v[32:35], v[142:145], v[166:169], v[32:35]
	v_mfma_f32_16x16x32_bf16 v[28:31], v[154:157], v[146:149], v[28:31]
	v_mfma_f32_16x16x32_bf16 v[24:27], v[154:157], v[150:153], v[24:27]
	v_mfma_f32_16x16x32_bf16 v[20:23], v[154:157], v[162:165], v[20:23]
	v_mfma_f32_16x16x32_bf16 v[16:19], v[154:157], v[166:169], v[16:19]
	v_mfma_f32_16x16x32_bf16 v[12:15], v[158:161], v[146:149], v[12:15]
	v_mfma_f32_16x16x32_bf16 v[8:11], v[158:161], v[150:153], v[8:11]
	v_mfma_f32_16x16x32_bf16 v[4:7], v[158:161], v[162:165], v[4:7]
	v_mfma_f32_16x16x32_bf16 v[0:3], v[158:161], v[166:169], v[0:3]
	s_setprio 0
	v_add_u32_e32 v64, v64, v137
	v_add_u32_e32 v166, v170, v137
	ds_read_b128 v[138:141], v64
	ds_read_b128 v[142:145], v64 offset:2048
	ds_read_b128 v[146:149], v166 offset:16384
	ds_read_b128 v[150:153], v166 offset:18432
	ds_read_b128 v[154:157], v64 offset:4096
	ds_read_b128 v[158:161], v64 offset:6144
	ds_read_b128 v[162:165], v166 offset:20480
	ds_read_b128 v[166:169], v166 offset:22528
	s_setprio 1
	s_waitcnt lgkmcnt(0)
	v_mfma_f32_16x16x32_bf16 v[60:63], v[138:141], v[146:149], v[60:63]
	v_mfma_f32_16x16x32_bf16 v[56:59], v[138:141], v[150:153], v[56:59]
	v_mfma_f32_16x16x32_bf16 v[52:55], v[138:141], v[162:165], v[52:55]
	v_mfma_f32_16x16x32_bf16 v[48:51], v[138:141], v[166:169], v[48:51]
	v_mfma_f32_16x16x32_bf16 v[44:47], v[142:145], v[146:149], v[44:47]
	v_mfma_f32_16x16x32_bf16 v[40:43], v[142:145], v[150:153], v[40:43]
	v_mfma_f32_16x16x32_bf16 v[36:39], v[142:145], v[162:165], v[36:39]
	v_mfma_f32_16x16x32_bf16 v[32:35], v[142:145], v[166:169], v[32:35]
	v_mfma_f32_16x16x32_bf16 v[28:31], v[154:157], v[146:149], v[28:31]
	v_mfma_f32_16x16x32_bf16 v[24:27], v[154:157], v[150:153], v[24:27]
	v_mfma_f32_16x16x32_bf16 v[20:23], v[154:157], v[162:165], v[20:23]
	v_mfma_f32_16x16x32_bf16 v[16:19], v[154:157], v[166:169], v[16:19]
	v_mfma_f32_16x16x32_bf16 v[12:15], v[158:161], v[146:149], v[12:15]
	v_mfma_f32_16x16x32_bf16 v[8:11], v[158:161], v[150:153], v[8:11]
	v_mfma_f32_16x16x32_bf16 v[4:7], v[158:161], v[162:165], v[4:7]
	v_mfma_f32_16x16x32_bf16 v[0:3], v[158:161], v[166:169], v[0:3]
	s_setprio 0
	s_cmpk_eq_i32 s4, 0x780
	s_waitcnt vmcnt(0)
	s_barrier
	s_cbranch_scc0 .LBB0_2976
	ds_read_b128 v[90:93], v116 offset:55296
	ds_read_b128 v[94:97], v116 offset:53248
	ds_read_b128 v[98:101], v117 offset:38912
	ds_read_b128 v[102:105], v117 offset:36864
	ds_read_b128 v[138:141], v116 offset:51200
	ds_read_b128 v[142:145], v116 offset:49152
	ds_read_b128 v[146:149], v117 offset:34816
	ds_read_b128 v[150:153], v117 offset:32768
	s_setprio 1
	s_waitcnt lgkmcnt(3)
	v_mfma_f32_16x16x32_bf16 v[24:27], v[102:105], v[138:141], v[24:27]
	v_mfma_f32_16x16x32_bf16 v[20:23], v[102:105], v[94:97], v[20:23]
	v_mfma_f32_16x16x32_bf16 v[16:19], v[102:105], v[90:93], v[16:19]
	s_waitcnt lgkmcnt(0)
	v_mfma_f32_16x16x32_bf16 v[60:63], v[150:153], v[142:145], v[60:63]
	v_mfma_f32_16x16x32_bf16 v[56:59], v[150:153], v[138:141], v[56:59]
	v_mfma_f32_16x16x32_bf16 v[52:55], v[150:153], v[94:97], v[52:55]
	v_mfma_f32_16x16x32_bf16 v[48:51], v[150:153], v[90:93], v[48:51]
	v_mfma_f32_16x16x32_bf16 v[44:47], v[146:149], v[142:145], v[44:47]
	v_mfma_f32_16x16x32_bf16 v[40:43], v[146:149], v[138:141], v[40:43]
	v_mfma_f32_16x16x32_bf16 v[36:39], v[146:149], v[94:97], v[36:39]
	v_mfma_f32_16x16x32_bf16 v[32:35], v[146:149], v[90:93], v[32:35]
	v_mfma_f32_16x16x32_bf16 v[28:31], v[102:105], v[142:145], v[28:31]
	v_mfma_f32_16x16x32_bf16 v[12:15], v[98:101], v[142:145], v[12:15]
	v_mfma_f32_16x16x32_bf16 v[8:11], v[98:101], v[138:141], v[8:11]
	v_mfma_f32_16x16x32_bf16 v[4:7], v[98:101], v[94:97], v[4:7]
	v_mfma_f32_16x16x32_bf16 v[0:3], v[98:101], v[90:93], v[0:3]
	s_setprio 0
	ds_read_b128 v[90:93], v118 offset:32768
	ds_read_b128 v[94:97], v118 offset:34816
	ds_read_b128 v[98:101], v119 offset:49152
	ds_read_b128 v[102:105], v119 offset:51200
	ds_read_b128 v[138:141], v118 offset:36864
	ds_read_b128 v[142:145], v118 offset:38912
	ds_read_b128 v[146:149], v119 offset:53248
	ds_read_b128 v[150:153], v119 offset:55296
	s_setprio 1
	s_waitcnt lgkmcnt(3)
	v_mfma_f32_16x16x32_bf16 v[24:27], v[138:141], v[102:105], v[24:27]
	s_waitcnt lgkmcnt(1)
	v_mfma_f32_16x16x32_bf16 v[20:23], v[138:141], v[146:149], v[20:23]
	s_waitcnt lgkmcnt(0)
	v_mfma_f32_16x16x32_bf16 v[16:19], v[138:141], v[150:153], v[16:19]
	v_mfma_f32_16x16x32_bf16 v[60:63], v[90:93], v[98:101], v[60:63]
	v_mfma_f32_16x16x32_bf16 v[56:59], v[90:93], v[102:105], v[56:59]
	v_mfma_f32_16x16x32_bf16 v[52:55], v[90:93], v[146:149], v[52:55]
	v_mfma_f32_16x16x32_bf16 v[48:51], v[90:93], v[150:153], v[48:51]
	v_mfma_f32_16x16x32_bf16 v[44:47], v[94:97], v[98:101], v[44:47]
	v_mfma_f32_16x16x32_bf16 v[40:43], v[94:97], v[102:105], v[40:43]
	v_mfma_f32_16x16x32_bf16 v[36:39], v[94:97], v[146:149], v[36:39]
	v_mfma_f32_16x16x32_bf16 v[32:35], v[94:97], v[150:153], v[32:35]
	v_mfma_f32_16x16x32_bf16 v[28:31], v[138:141], v[98:101], v[28:31]
	v_mfma_f32_16x16x32_bf16 v[12:15], v[142:145], v[98:101], v[12:15]
	v_mfma_f32_16x16x32_bf16 v[8:11], v[142:145], v[102:105], v[8:11]
	v_mfma_f32_16x16x32_bf16 v[4:7], v[142:145], v[146:149], v[4:7]
	v_mfma_f32_16x16x32_bf16 v[0:3], v[142:145], v[150:153], v[0:3]
	s_setprio 0
	s_barrier
	ds_write2_b32 v120, v60, v56 offset1:16
	ds_write2_b32 v120, v61, v57 offset0:132 offset1:148
	v_add_u32_e32 v56, 0x400, v120
	ds_write2_b32 v56, v62, v58 offset0:8 offset1:24
	ds_write2_b32 v56, v63, v59 offset0:140 offset1:156
	ds_write2_b32 v120, v52, v48 offset0:32 offset1:48
	ds_write2_b32 v120, v53, v49 offset0:164 offset1:180
	ds_write2_b32 v56, v54, v50 offset0:40 offset1:56
	ds_write2_b32 v56, v55, v51 offset0:172 offset1:188
	v_add_u32_e32 v48, 0x2000, v120
	ds_write2_b32 v48, v44, v40 offset0:64 offset1:80
	ds_write2_b32 v48, v45, v41 offset0:196 offset1:212
	v_add_u32_e32 v40, 0x2400, v120
	ds_write2_b32 v40, v46, v42 offset0:72 offset1:88
	ds_write2_b32 v40, v47, v43 offset0:204 offset1:220
	ds_write2_b32 v48, v36, v32 offset0:96 offset1:112
	ds_write2_b32 v48, v37, v33 offset0:228 offset1:244
	ds_write2_b32 v40, v38, v34 offset0:104 offset1:120
	ds_write2_b32 v40, v39, v35 offset0:236 offset1:252
	v_add_u32_e32 v32, 0x4000, v120
	ds_write2_b32 v32, v28, v24 offset0:128 offset1:144
	v_add_u32_e32 v24, 0x4400, v120
	ds_write2_b32 v24, v29, v25 offset0:4 offset1:20
	ds_write2_b32 v24, v30, v26 offset0:136 offset1:152
	v_add_u32_e32 v25, 0x4800, v120
	ds_write2_b32 v25, v31, v27 offset0:12 offset1:28
	ds_write2_b32 v32, v20, v16 offset0:160 offset1:176
	ds_write2_b32 v24, v21, v17 offset0:36 offset1:52
	ds_write2_b32 v24, v22, v18 offset0:168 offset1:184
	ds_write2_b32 v25, v23, v19 offset0:44 offset1:60
	v_add_u32_e32 v16, 0x6000, v120
	ds_write2_b32 v16, v12, v8 offset0:192 offset1:208
	v_add_u32_e32 v8, 0x6400, v120
	s_cmpk_gt_u32 s6, 0x3ff
	ds_write2_b32 v8, v13, v9 offset0:68 offset1:84
	ds_write2_b32 v8, v14, v10 offset0:200 offset1:216
	v_add_u32_e32 v9, 0x6800, v120
	v_or_b32_e32 v64, s6, v121
	s_cselect_b64 s[28:29], -1, 0
	s_cmpk_gt_u32 s6, 0x7ff
	ds_write2_b32 v9, v15, v11 offset0:76 offset1:92
	ds_write2_b32 v16, v4, v0 offset0:224 offset1:240
	ds_write2_b32 v8, v5, v1 offset0:100 offset1:116
	ds_write2_b32 v8, v6, v2 offset0:232 offset1:248
	ds_write2_b32 v9, v7, v3 offset0:108 offset1:124
	s_cselect_b64 s[30:31], -1, 0
	s_cmpk_gt_u32 s6, 0xbff
	v_ashrrev_i32_e32 v1, 31, v64
	v_mov_b32_e32 v0, v64
	v_lshlrev_b64 v[2:3], 1, v[64:65]
	v_cmp_lt_i32_e64 s[4:5], s41, v64
	s_cselect_b64 s[34:35], -1, 0
	v_cmp_gt_u32_e64 s[6:7], s42, v64
	v_lshl_add_u64 v[16:17], v[64:65], 2, s[18:19]
	v_lshl_add_u64 v[18:19], s[16:17], 0, v[2:3]
	v_lshl_add_u64 v[20:21], s[14:15], 0, v[2:3]
	v_lshl_add_u64 v[22:23], s[12:13], 0, v[2:3]
	v_lshl_add_u64 v[24:25], v[0:1], 1, s[10:11]
	v_add_u32_e32 v26, s36, v129
	s_mov_b32 s44, 0
	s_waitcnt lgkmcnt(0)
	s_barrier
	s_branch .LBB0_2979

.LBB0_3008:
	s_and_b32 s22, s7, 0x4000
	s_xor_b32 s23, s22, 0x4000
	s_lshl_b32 s23, s23, 1
	s_add_i32 s23, s23, 32
	s_add_u32 s90, s52, s4
	s_addc_u32 s91, s53, s5
	s_add_i32 m0, s23, s82
	s_lshl_b32 s22, s22, 1
	global_load_lds_dwordx4 v184, s[90:91]
	s_add_i32 m0, s23, s83
	s_add_i32 s22, s22, 32
	global_load_lds_dwordx4 v185, s[90:91]
	s_add_i32 m0, s23, s84
	v_lshl_add_u32 v64, v115, 1, s22
	global_load_lds_dwordx4 v186, s[90:91]
	s_add_i32 m0, s23, s85
	v_lshl_add_u32 v168, v116, 1, s22
	global_load_lds_dwordx4 v187, s[90:91]
	s_add_i32 m0, s23, s86
	v_add_u32_e32 v156, v64, v133
	global_load_lds_dwordx4 v188, s[90:91]
	s_add_i32 m0, s23, s87
	v_add_u32_e32 v164, v168, v133
	global_load_lds_dwordx4 v189, s[90:91]
	s_add_i32 m0, s23, s88
	s_addk_i32 s7, 0x4000
	global_load_lds_dwordx4 v190, s[90:91]
	s_add_i32 m0, s23, s89
	s_add_u32 s4, s4, 0x80
	s_addc_u32 s5, s5, 0
	global_load_lds_dwordx4 v191, s[90:91]
	ds_read_b128 v[136:139], v156
	ds_read_b128 v[140:143], v156 offset:2048
	ds_read_b128 v[144:147], v164 offset:16384
	ds_read_b128 v[148:151], v164 offset:18432
	ds_read_b128 v[152:155], v156 offset:4096
	ds_read_b128 v[156:159], v156 offset:6144
	ds_read_b128 v[160:163], v164 offset:20480
	ds_read_b128 v[164:167], v164 offset:22528
	s_setprio 1
	s_waitcnt lgkmcnt(0)
	v_mfma_f32_16x16x32_bf16 v[60:63], v[136:139], v[144:147], v[60:63]
	v_mfma_f32_16x16x32_bf16 v[56:59], v[136:139], v[148:151], v[56:59]
	v_mfma_f32_16x16x32_bf16 v[52:55], v[136:139], v[160:163], v[52:55]
	v_mfma_f32_16x16x32_bf16 v[48:51], v[136:139], v[164:167], v[48:51]
	v_mfma_f32_16x16x32_bf16 v[44:47], v[140:143], v[144:147], v[44:47]
	v_mfma_f32_16x16x32_bf16 v[40:43], v[140:143], v[148:151], v[40:43]
	v_mfma_f32_16x16x32_bf16 v[36:39], v[140:143], v[160:163], v[36:39]
	v_mfma_f32_16x16x32_bf16 v[32:35], v[140:143], v[164:167], v[32:35]
	v_mfma_f32_16x16x32_bf16 v[28:31], v[152:155], v[144:147], v[28:31]
	v_mfma_f32_16x16x32_bf16 v[24:27], v[152:155], v[148:151], v[24:27]
	v_mfma_f32_16x16x32_bf16 v[20:23], v[152:155], v[160:163], v[20:23]
	v_mfma_f32_16x16x32_bf16 v[16:19], v[152:155], v[164:167], v[16:19]
	v_mfma_f32_16x16x32_bf16 v[12:15], v[156:159], v[144:147], v[12:15]
	v_mfma_f32_16x16x32_bf16 v[8:11], v[156:159], v[148:151], v[8:11]
	v_mfma_f32_16x16x32_bf16 v[4:7], v[156:159], v[160:163], v[4:7]
	v_mfma_f32_16x16x32_bf16 v[0:3], v[156:159], v[164:167], v[0:3]
	s_setprio 0
	v_add_u32_e32 v64, v64, v134
	v_add_u32_e32 v164, v168, v134
	ds_read_b128 v[136:139], v64
	ds_read_b128 v[140:143], v64 offset:2048
	ds_read_b128 v[144:147], v164 offset:16384
	ds_read_b128 v[148:151], v164 offset:18432
	ds_read_b128 v[152:155], v64 offset:4096
	ds_read_b128 v[156:159], v64 offset:6144
	ds_read_b128 v[160:163], v164 offset:20480
	ds_read_b128 v[164:167], v164 offset:22528
	s_setprio 1
	s_waitcnt lgkmcnt(0)
	v_mfma_f32_16x16x32_bf16 v[60:63], v[136:139], v[144:147], v[60:63]
	v_mfma_f32_16x16x32_bf16 v[56:59], v[136:139], v[148:151], v[56:59]
	v_mfma_f32_16x16x32_bf16 v[52:55], v[136:139], v[160:163], v[52:55]
	v_mfma_f32_16x16x32_bf16 v[48:51], v[136:139], v[164:167], v[48:51]
	v_mfma_f32_16x16x32_bf16 v[44:47], v[140:143], v[144:147], v[44:47]
	v_mfma_f32_16x16x32_bf16 v[40:43], v[140:143], v[148:151], v[40:43]
	v_mfma_f32_16x16x32_bf16 v[36:39], v[140:143], v[160:163], v[36:39]
	v_mfma_f32_16x16x32_bf16 v[32:35], v[140:143], v[164:167], v[32:35]
	v_mfma_f32_16x16x32_bf16 v[28:31], v[152:155], v[144:147], v[28:31]
	v_mfma_f32_16x16x32_bf16 v[24:27], v[152:155], v[148:151], v[24:27]
	v_mfma_f32_16x16x32_bf16 v[20:23], v[152:155], v[160:163], v[20:23]
	v_mfma_f32_16x16x32_bf16 v[16:19], v[152:155], v[164:167], v[16:19]
	v_mfma_f32_16x16x32_bf16 v[12:15], v[156:159], v[144:147], v[12:15]
	v_mfma_f32_16x16x32_bf16 v[8:11], v[156:159], v[148:151], v[8:11]
	v_mfma_f32_16x16x32_bf16 v[4:7], v[156:159], v[160:163], v[4:7]
	v_mfma_f32_16x16x32_bf16 v[0:3], v[156:159], v[164:167], v[0:3]
	s_setprio 0
	s_cmpk_eq_i32 s4, 0x780
	s_waitcnt vmcnt(0)
	s_barrier
	s_cbranch_scc0 .LBB0_3008
	ds_read_b128 v[90:93], v117 offset:55296
	ds_read_b128 v[94:97], v117 offset:53248
	ds_read_b128 v[98:101], v118 offset:38912
	ds_read_b128 v[102:105], v118 offset:36864
	ds_read_b128 v[136:139], v117 offset:51200
	ds_read_b128 v[140:143], v117 offset:49152
	ds_read_b128 v[144:147], v118 offset:34816
	ds_read_b128 v[148:151], v118 offset:32768
	s_setprio 1
	s_waitcnt lgkmcnt(3)
	v_mfma_f32_16x16x32_bf16 v[24:27], v[102:105], v[136:139], v[24:27]
	v_mfma_f32_16x16x32_bf16 v[20:23], v[102:105], v[94:97], v[20:23]
	v_mfma_f32_16x16x32_bf16 v[16:19], v[102:105], v[90:93], v[16:19]
	s_waitcnt lgkmcnt(0)
	v_mfma_f32_16x16x32_bf16 v[60:63], v[148:151], v[140:143], v[60:63]
	v_mfma_f32_16x16x32_bf16 v[56:59], v[148:151], v[136:139], v[56:59]
	v_mfma_f32_16x16x32_bf16 v[52:55], v[148:151], v[94:97], v[52:55]
	v_mfma_f32_16x16x32_bf16 v[48:51], v[148:151], v[90:93], v[48:51]
	v_mfma_f32_16x16x32_bf16 v[44:47], v[144:147], v[140:143], v[44:47]
	v_mfma_f32_16x16x32_bf16 v[40:43], v[144:147], v[136:139], v[40:43]
	v_mfma_f32_16x16x32_bf16 v[36:39], v[144:147], v[94:97], v[36:39]
	v_mfma_f32_16x16x32_bf16 v[32:35], v[144:147], v[90:93], v[32:35]
	v_mfma_f32_16x16x32_bf16 v[28:31], v[102:105], v[140:143], v[28:31]
	v_mfma_f32_16x16x32_bf16 v[12:15], v[98:101], v[140:143], v[12:15]
	v_mfma_f32_16x16x32_bf16 v[8:11], v[98:101], v[136:139], v[8:11]
	v_mfma_f32_16x16x32_bf16 v[4:7], v[98:101], v[94:97], v[4:7]
	v_mfma_f32_16x16x32_bf16 v[0:3], v[98:101], v[90:93], v[0:3]
	s_setprio 0
	ds_read_b128 v[90:93], v119 offset:32768
	ds_read_b128 v[94:97], v119 offset:34816
	ds_read_b128 v[98:101], v120 offset:49152
	ds_read_b128 v[102:105], v120 offset:51200
	ds_read_b128 v[136:139], v119 offset:36864
	ds_read_b128 v[140:143], v119 offset:38912
	ds_read_b128 v[144:147], v120 offset:53248
	ds_read_b128 v[148:151], v120 offset:55296
	s_setprio 1
	s_waitcnt lgkmcnt(3)
	v_mfma_f32_16x16x32_bf16 v[24:27], v[136:139], v[102:105], v[24:27]
	s_waitcnt lgkmcnt(1)
	v_mfma_f32_16x16x32_bf16 v[20:23], v[136:139], v[144:147], v[20:23]
	s_waitcnt lgkmcnt(0)
	v_mfma_f32_16x16x32_bf16 v[16:19], v[136:139], v[148:151], v[16:19]
	v_mfma_f32_16x16x32_bf16 v[60:63], v[90:93], v[98:101], v[60:63]
	v_mfma_f32_16x16x32_bf16 v[56:59], v[90:93], v[102:105], v[56:59]
	v_mfma_f32_16x16x32_bf16 v[52:55], v[90:93], v[144:147], v[52:55]
	v_mfma_f32_16x16x32_bf16 v[48:51], v[90:93], v[148:151], v[48:51]
	v_mfma_f32_16x16x32_bf16 v[44:47], v[94:97], v[98:101], v[44:47]
	v_mfma_f32_16x16x32_bf16 v[40:43], v[94:97], v[102:105], v[40:43]
	v_mfma_f32_16x16x32_bf16 v[36:39], v[94:97], v[144:147], v[36:39]
	v_mfma_f32_16x16x32_bf16 v[32:35], v[94:97], v[148:151], v[32:35]
	v_mfma_f32_16x16x32_bf16 v[28:31], v[136:139], v[98:101], v[28:31]
	v_mfma_f32_16x16x32_bf16 v[12:15], v[140:143], v[98:101], v[12:15]
	v_mfma_f32_16x16x32_bf16 v[8:11], v[140:143], v[102:105], v[8:11]
	v_mfma_f32_16x16x32_bf16 v[4:7], v[140:143], v[144:147], v[4:7]
	v_mfma_f32_16x16x32_bf16 v[0:3], v[140:143], v[148:151], v[0:3]
	s_setprio 0
	s_barrier
	ds_write2_b32 v121, v60, v56 offset1:16
	ds_write2_b32 v121, v61, v57 offset0:132 offset1:148
	v_add_u32_e32 v56, 0x400, v121
	ds_write2_b32 v56, v62, v58 offset0:8 offset1:24
	ds_write2_b32 v56, v63, v59 offset0:140 offset1:156
	ds_write2_b32 v121, v52, v48 offset0:32 offset1:48
	ds_write2_b32 v121, v53, v49 offset0:164 offset1:180
	ds_write2_b32 v56, v54, v50 offset0:40 offset1:56
	ds_write2_b32 v56, v55, v51 offset0:172 offset1:188
	v_add_u32_e32 v48, 0x2000, v121
	ds_write2_b32 v48, v44, v40 offset0:64 offset1:80
	ds_write2_b32 v48, v45, v41 offset0:196 offset1:212
	v_add_u32_e32 v40, 0x2400, v121
	ds_write2_b32 v40, v46, v42 offset0:72 offset1:88
	ds_write2_b32 v40, v47, v43 offset0:204 offset1:220
	ds_write2_b32 v48, v36, v32 offset0:96 offset1:112
	ds_write2_b32 v48, v37, v33 offset0:228 offset1:244
	ds_write2_b32 v40, v38, v34 offset0:104 offset1:120
	ds_write2_b32 v40, v39, v35 offset0:236 offset1:252
	v_add_u32_e32 v32, 0x4000, v121
	ds_write2_b32 v32, v28, v24 offset0:128 offset1:144
	v_add_u32_e32 v24, 0x4400, v121
	ds_write2_b32 v24, v29, v25 offset0:4 offset1:20
	ds_write2_b32 v24, v30, v26 offset0:136 offset1:152
	v_add_u32_e32 v25, 0x4800, v121
	ds_write2_b32 v25, v31, v27 offset0:12 offset1:28
	ds_write2_b32 v32, v20, v16 offset0:160 offset1:176
	ds_write2_b32 v24, v21, v17 offset0:36 offset1:52
	ds_write2_b32 v24, v22, v18 offset0:168 offset1:184
	ds_write2_b32 v25, v23, v19 offset0:44 offset1:60
	v_add_u32_e32 v16, 0x6000, v121
	ds_write2_b32 v16, v12, v8 offset0:192 offset1:208
	v_add_u32_e32 v8, 0x6400, v121
	s_cmpk_gt_u32 s6, 0x3ff
	ds_write2_b32 v8, v13, v9 offset0:68 offset1:84
	ds_write2_b32 v8, v14, v10 offset0:200 offset1:216
	v_add_u32_e32 v9, 0x6800, v121
	v_or_b32_e32 v64, s6, v122
	s_cselect_b64 s[22:23], -1, 0
	s_cmpk_gt_u32 s6, 0x7ff
	ds_write2_b32 v9, v15, v11 offset0:76 offset1:92
	ds_write2_b32 v16, v4, v0 offset0:224 offset1:240
	ds_write2_b32 v8, v5, v1 offset0:100 offset1:116
	ds_write2_b32 v8, v6, v2 offset0:232 offset1:248
	ds_write2_b32 v9, v7, v3 offset0:108 offset1:124
	s_cselect_b64 s[24:25], -1, 0
	s_cmpk_gt_u32 s6, 0xbff
	v_ashrrev_i32_e32 v1, 31, v64
	v_mov_b32_e32 v0, v64
	v_lshlrev_b64 v[2:3], 1, v[64:65]
	v_cmp_lt_i32_e64 s[4:5], s36, v64
	s_cselect_b64 s[26:27], -1, 0
	v_cmp_gt_u32_e64 s[6:7], s37, v64
	v_lshl_add_u64 v[16:17], v[64:65], 2, s[18:19]
	v_lshl_add_u64 v[18:19], s[16:17], 0, v[2:3]
	v_lshl_add_u64 v[20:21], s[14:15], 0, v[2:3]
	v_lshl_add_u64 v[22:23], s[12:13], 0, v[2:3]
	v_lshl_add_u64 v[24:25], v[0:1], 1, s[10:11]
	v_add_u32_e32 v26, v126, v135
	s_mov_b32 s38, 0
	s_waitcnt lgkmcnt(0)
	s_barrier
	s_branch .LBB0_3011

.LBB0_3222:
	s_and_b32 s27, s26, 0x4000
	s_xor_b32 s28, s27, 0x4000
	s_lshl_b32 s28, s28, 1
	s_add_i32 s28, s28, 32
	s_add_u32 s90, s52, s16
	s_addc_u32 s91, s53, s17
	s_add_i32 m0, s28, s82
	s_lshl_b32 s27, s27, 1
	global_load_lds_dwordx4 v184, s[90:91]
	s_add_i32 m0, s28, s83
	s_add_i32 s27, s27, 32
	global_load_lds_dwordx4 v185, s[90:91]
	s_add_i32 m0, s28, s84
	v_add3_u32 v139, s27, v114, v136
	global_load_lds_dwordx4 v186, s[90:91]
	s_add_i32 m0, s28, s85
	v_add3_u32 v172, s27, v115, v136
	global_load_lds_dwordx4 v187, s[90:91]
	s_add_i32 m0, s28, s86
	v_add_u32_e32 v160, v139, v137
	global_load_lds_dwordx4 v188, s[90:91]
	s_add_i32 m0, s28, s87
	v_add_u32_e32 v168, v172, v137
	global_load_lds_dwordx4 v189, s[90:91]
	s_add_i32 m0, s28, s88
	s_addk_i32 s26, 0x4000
	global_load_lds_dwordx4 v190, s[90:91]
	s_add_i32 m0, s28, s89
	s_add_u32 s16, s16, 0x80
	s_addc_u32 s17, s17, 0
	global_load_lds_dwordx4 v191, s[90:91]
	ds_read_b128 v[140:143], v160
	ds_read_b128 v[144:147], v160 offset:2048
	ds_read_b128 v[148:151], v168 offset:16384
	ds_read_b128 v[152:155], v168 offset:18432
	ds_read_b128 v[156:159], v160 offset:4096
	ds_read_b128 v[160:163], v160 offset:6144
	ds_read_b128 v[164:167], v168 offset:20480
	ds_read_b128 v[168:171], v168 offset:22528
	s_setprio 1
	s_waitcnt lgkmcnt(0)
	v_mfma_f32_16x16x32_bf16 v[60:63], v[140:143], v[148:151], v[60:63]
	v_mfma_f32_16x16x32_bf16 v[56:59], v[140:143], v[152:155], v[56:59]
	v_mfma_f32_16x16x32_bf16 v[52:55], v[140:143], v[164:167], v[52:55]
	v_mfma_f32_16x16x32_bf16 v[48:51], v[140:143], v[168:171], v[48:51]
	v_mfma_f32_16x16x32_bf16 v[44:47], v[144:147], v[148:151], v[44:47]
	v_mfma_f32_16x16x32_bf16 v[40:43], v[144:147], v[152:155], v[40:43]
	v_mfma_f32_16x16x32_bf16 v[36:39], v[144:147], v[164:167], v[36:39]
	v_mfma_f32_16x16x32_bf16 v[32:35], v[144:147], v[168:171], v[32:35]
	v_mfma_f32_16x16x32_bf16 v[28:31], v[156:159], v[148:151], v[28:31]
	v_mfma_f32_16x16x32_bf16 v[24:27], v[156:159], v[152:155], v[24:27]
	v_mfma_f32_16x16x32_bf16 v[20:23], v[156:159], v[164:167], v[20:23]
	v_mfma_f32_16x16x32_bf16 v[16:19], v[156:159], v[168:171], v[16:19]
	v_mfma_f32_16x16x32_bf16 v[12:15], v[160:163], v[148:151], v[12:15]
	v_mfma_f32_16x16x32_bf16 v[8:11], v[160:163], v[152:155], v[8:11]
	v_mfma_f32_16x16x32_bf16 v[4:7], v[160:163], v[164:167], v[4:7]
	v_mfma_f32_16x16x32_bf16 v[0:3], v[160:163], v[168:171], v[0:3]
	s_setprio 0
	v_add_u32_e32 v139, v139, v138
	v_add_u32_e32 v168, v172, v138
	ds_read_b128 v[140:143], v139
	ds_read_b128 v[144:147], v139 offset:2048
	ds_read_b128 v[148:151], v168 offset:16384
	ds_read_b128 v[152:155], v168 offset:18432
	ds_read_b128 v[156:159], v139 offset:4096
	ds_read_b128 v[160:163], v139 offset:6144
	ds_read_b128 v[164:167], v168 offset:20480
	ds_read_b128 v[168:171], v168 offset:22528
	s_setprio 1
	s_waitcnt lgkmcnt(0)
	v_mfma_f32_16x16x32_bf16 v[60:63], v[140:143], v[148:151], v[60:63]
	v_mfma_f32_16x16x32_bf16 v[56:59], v[140:143], v[152:155], v[56:59]
	v_mfma_f32_16x16x32_bf16 v[52:55], v[140:143], v[164:167], v[52:55]
	v_mfma_f32_16x16x32_bf16 v[48:51], v[140:143], v[168:171], v[48:51]
	v_mfma_f32_16x16x32_bf16 v[44:47], v[144:147], v[148:151], v[44:47]
	v_mfma_f32_16x16x32_bf16 v[40:43], v[144:147], v[152:155], v[40:43]
	v_mfma_f32_16x16x32_bf16 v[36:39], v[144:147], v[164:167], v[36:39]
	v_mfma_f32_16x16x32_bf16 v[32:35], v[144:147], v[168:171], v[32:35]
	v_mfma_f32_16x16x32_bf16 v[28:31], v[156:159], v[148:151], v[28:31]
	v_mfma_f32_16x16x32_bf16 v[24:27], v[156:159], v[152:155], v[24:27]
	v_mfma_f32_16x16x32_bf16 v[20:23], v[156:159], v[164:167], v[20:23]
	v_mfma_f32_16x16x32_bf16 v[16:19], v[156:159], v[168:171], v[16:19]
	v_mfma_f32_16x16x32_bf16 v[12:15], v[160:163], v[148:151], v[12:15]
	v_mfma_f32_16x16x32_bf16 v[8:11], v[160:163], v[152:155], v[8:11]
	v_mfma_f32_16x16x32_bf16 v[4:7], v[160:163], v[164:167], v[4:7]
	v_mfma_f32_16x16x32_bf16 v[0:3], v[160:163], v[168:171], v[0:3]
	s_setprio 0
	s_cmpk_eq_i32 s16, 0x780
	s_waitcnt vmcnt(0)
	s_barrier
	s_cbranch_scc0 .LBB0_3222
	ds_read_b128 v[90:93], v118 offset:55296
	ds_read_b128 v[94:97], v118 offset:53248
	ds_read_b128 v[98:101], v119 offset:38912
	ds_read_b128 v[102:105], v119 offset:36864
	ds_read_b128 v[140:143], v118 offset:51200
	ds_read_b128 v[144:147], v118 offset:49152
	ds_read_b128 v[148:151], v119 offset:34816
	ds_read_b128 v[152:155], v119 offset:32768
	s_setprio 1
	s_waitcnt lgkmcnt(5)
	v_mfma_f32_16x16x32_bf16 v[4:7], v[98:101], v[94:97], v[4:7]
	v_mfma_f32_16x16x32_bf16 v[0:3], v[98:101], v[90:93], v[0:3]
	s_waitcnt lgkmcnt(0)
	v_mfma_f32_16x16x32_bf16 v[60:63], v[152:155], v[144:147], v[60:63]
	v_mfma_f32_16x16x32_bf16 v[56:59], v[152:155], v[140:143], v[56:59]
	v_mfma_f32_16x16x32_bf16 v[52:55], v[152:155], v[94:97], v[52:55]
	v_mfma_f32_16x16x32_bf16 v[48:51], v[152:155], v[90:93], v[48:51]
	v_mfma_f32_16x16x32_bf16 v[44:47], v[148:151], v[144:147], v[44:47]
	v_mfma_f32_16x16x32_bf16 v[40:43], v[148:151], v[140:143], v[40:43]
	v_mfma_f32_16x16x32_bf16 v[36:39], v[148:151], v[94:97], v[36:39]
	v_mfma_f32_16x16x32_bf16 v[32:35], v[148:151], v[90:93], v[32:35]
	v_mfma_f32_16x16x32_bf16 v[28:31], v[102:105], v[144:147], v[28:31]
	v_mfma_f32_16x16x32_bf16 v[24:27], v[102:105], v[140:143], v[24:27]
	v_mfma_f32_16x16x32_bf16 v[20:23], v[102:105], v[94:97], v[20:23]
	v_mfma_f32_16x16x32_bf16 v[16:19], v[102:105], v[90:93], v[16:19]
	v_mfma_f32_16x16x32_bf16 v[12:15], v[98:101], v[144:147], v[12:15]
	v_mfma_f32_16x16x32_bf16 v[8:11], v[98:101], v[140:143], v[8:11]
	s_setprio 0
	ds_read_b128 v[90:93], v120 offset:32768
	ds_read_b128 v[94:97], v120 offset:34816
	ds_read_b128 v[98:101], v121 offset:49152
	ds_read_b128 v[102:105], v121 offset:51200
	ds_read_b128 v[140:143], v120 offset:36864
	ds_read_b128 v[144:147], v120 offset:38912
	ds_read_b128 v[148:151], v121 offset:53248
	ds_read_b128 v[152:155], v121 offset:55296
	s_setprio 1
	s_waitcnt lgkmcnt(1)
	v_mfma_f32_16x16x32_bf16 v[4:7], v[144:147], v[148:151], v[4:7]
	s_waitcnt lgkmcnt(0)
	v_mfma_f32_16x16x32_bf16 v[0:3], v[144:147], v[152:155], v[0:3]
	v_mfma_f32_16x16x32_bf16 v[60:63], v[90:93], v[98:101], v[60:63]
	v_mfma_f32_16x16x32_bf16 v[56:59], v[90:93], v[102:105], v[56:59]
	v_mfma_f32_16x16x32_bf16 v[52:55], v[90:93], v[148:151], v[52:55]
	v_mfma_f32_16x16x32_bf16 v[48:51], v[90:93], v[152:155], v[48:51]
	v_mfma_f32_16x16x32_bf16 v[44:47], v[94:97], v[98:101], v[44:47]
	v_mfma_f32_16x16x32_bf16 v[40:43], v[94:97], v[102:105], v[40:43]
	v_mfma_f32_16x16x32_bf16 v[36:39], v[94:97], v[148:151], v[36:39]
	v_mfma_f32_16x16x32_bf16 v[32:35], v[94:97], v[152:155], v[32:35]
	v_mfma_f32_16x16x32_bf16 v[28:31], v[140:143], v[98:101], v[28:31]
	v_mfma_f32_16x16x32_bf16 v[24:27], v[140:143], v[102:105], v[24:27]
	v_mfma_f32_16x16x32_bf16 v[20:23], v[140:143], v[148:151], v[20:23]
	v_mfma_f32_16x16x32_bf16 v[16:19], v[140:143], v[152:155], v[16:19]
	v_mfma_f32_16x16x32_bf16 v[12:15], v[144:147], v[98:101], v[12:15]
	v_mfma_f32_16x16x32_bf16 v[8:11], v[144:147], v[102:105], v[8:11]
	s_setprio 0
	s_barrier
	ds_write2_b32 v116, v60, v56 offset1:16
	ds_write2_b32 v116, v61, v57 offset0:132 offset1:148
	v_add_u32_e32 v56, 0x400, v116
	ds_write2_b32 v56, v62, v58 offset0:8 offset1:24
	ds_write2_b32 v56, v63, v59 offset0:140 offset1:156
	ds_write2_b32 v116, v52, v48 offset0:32 offset1:48
	ds_write2_b32 v116, v53, v49 offset0:164 offset1:180
	ds_write2_b32 v56, v54, v50 offset0:40 offset1:56
	ds_write2_b32 v56, v55, v51 offset0:172 offset1:188
	v_add_u32_e32 v48, 0x2000, v116
	ds_write2_b32 v48, v44, v40 offset0:64 offset1:80
	ds_write2_b32 v48, v45, v41 offset0:196 offset1:212
	v_add_u32_e32 v40, 0x2400, v116
	ds_write2_b32 v40, v46, v42 offset0:72 offset1:88
	ds_write2_b32 v40, v47, v43 offset0:204 offset1:220
	ds_write2_b32 v48, v36, v32 offset0:96 offset1:112
	ds_write2_b32 v48, v37, v33 offset0:228 offset1:244
	ds_write2_b32 v40, v38, v34 offset0:104 offset1:120
	ds_write2_b32 v40, v39, v35 offset0:236 offset1:252
	v_add_u32_e32 v32, 0x4000, v116
	ds_write2_b32 v32, v28, v24 offset0:128 offset1:144
	v_add_u32_e32 v24, 0x4400, v116
	ds_write2_b32 v24, v29, v25 offset0:4 offset1:20
	ds_write2_b32 v24, v30, v26 offset0:136 offset1:152
	v_add_u32_e32 v25, 0x4800, v116
	ds_write2_b32 v25, v31, v27 offset0:12 offset1:28
	ds_write2_b32 v32, v20, v16 offset0:160 offset1:176
	ds_write2_b32 v24, v21, v17 offset0:36 offset1:52
	ds_write2_b32 v24, v22, v18 offset0:168 offset1:184
	ds_write2_b32 v25, v23, v19 offset0:44 offset1:60
	v_add_u32_e32 v16, 0x6000, v116
	ds_write2_b32 v16, v12, v8 offset0:192 offset1:208
	v_add_u32_e32 v8, 0x6400, v116
	ds_write2_b32 v8, v13, v9 offset0:68 offset1:84
	ds_write2_b32 v8, v14, v10 offset0:200 offset1:216
	v_add_u32_e32 v9, 0x6800, v116
	ds_write2_b32 v9, v15, v11 offset0:76 offset1:92
	ds_write2_b32 v16, v4, v0 offset0:224 offset1:240
	ds_write2_b32 v8, v5, v1 offset0:100 offset1:116
	ds_write2_b32 v8, v6, v2 offset0:232 offset1:248
	ds_write2_b32 v9, v7, v3 offset0:108 offset1:124
	v_or_b32_e32 v0, s25, v117
	v_ashrrev_i32_e32 v1, 31, v0
	v_lshlrev_b64 v[2:3], 2, v[0:1]
	v_lshl_add_u64 v[0:1], s[14:15], 0, v[2:3]
	v_lshl_add_u64 v[2:3], s[6:7], 0, v[2:3]
	v_add_u32_e32 v4, s24, v129
	s_mov_b32 s16, 0
	s_waitcnt lgkmcnt(0)
	s_barrier

.LBB0_3231:
	s_and_b32 s23, s22, 0x4000
	s_xor_b32 s24, s23, 0x4000
	s_lshl_b32 s24, s24, 1
	s_add_i32 s24, s24, 32
	s_add_u32 s90, s52, s8
	s_addc_u32 s91, s53, s9
	s_add_i32 m0, s24, s82
	s_lshl_b32 s23, s23, 1
	global_load_lds_dwordx4 v184, s[90:91]
	s_add_i32 m0, s24, s83
	s_add_i32 s23, s23, 32
	global_load_lds_dwordx4 v185, s[90:91]
	s_add_i32 m0, s24, s84
	v_add3_u32 v170, s23, v112, v135
	global_load_lds_dwordx4 v186, s[90:91]
	s_add_i32 m0, s24, s85
	v_add3_u32 v171, s23, v113, v135
	global_load_lds_dwordx4 v187, s[90:91]
	s_add_i32 m0, s24, s86
	v_add_u32_e32 v158, v170, v136
	global_load_lds_dwordx4 v188, s[90:91]
	s_add_i32 m0, s24, s87
	v_add_u32_e32 v166, v171, v136
	global_load_lds_dwordx4 v189, s[90:91]
	s_add_i32 m0, s24, s88
	s_addk_i32 s22, 0x4000
	global_load_lds_dwordx4 v190, s[90:91]
	s_add_i32 m0, s24, s89
	s_add_u32 s8, s8, 0x80
	s_addc_u32 s9, s9, 0
	global_load_lds_dwordx4 v191, s[90:91]
	ds_read_b128 v[138:141], v158
	ds_read_b128 v[142:145], v158 offset:2048
	ds_read_b128 v[146:149], v166 offset:16384
	ds_read_b128 v[150:153], v166 offset:18432
	ds_read_b128 v[154:157], v158 offset:4096
	ds_read_b128 v[158:161], v158 offset:6144
	ds_read_b128 v[162:165], v166 offset:20480
	ds_read_b128 v[166:169], v166 offset:22528
	s_setprio 1
	s_waitcnt lgkmcnt(0)
	v_mfma_f32_16x16x32_bf16 v[60:63], v[138:141], v[146:149], v[60:63]
	v_mfma_f32_16x16x32_bf16 v[56:59], v[138:141], v[150:153], v[56:59]
	v_mfma_f32_16x16x32_bf16 v[52:55], v[138:141], v[162:165], v[52:55]
	v_mfma_f32_16x16x32_bf16 v[48:51], v[138:141], v[166:169], v[48:51]
	v_mfma_f32_16x16x32_bf16 v[44:47], v[142:145], v[146:149], v[44:47]
	v_mfma_f32_16x16x32_bf16 v[40:43], v[142:145], v[150:153], v[40:43]
	v_mfma_f32_16x16x32_bf16 v[36:39], v[142:145], v[162:165], v[36:39]
	v_mfma_f32_16x16x32_bf16 v[32:35], v[142:145], v[166:169], v[32:35]
	v_mfma_f32_16x16x32_bf16 v[28:31], v[154:157], v[146:149], v[28:31]
	v_mfma_f32_16x16x32_bf16 v[24:27], v[154:157], v[150:153], v[24:27]
	v_mfma_f32_16x16x32_bf16 v[20:23], v[154:157], v[162:165], v[20:23]
	v_mfma_f32_16x16x32_bf16 v[16:19], v[154:157], v[166:169], v[16:19]
	v_mfma_f32_16x16x32_bf16 v[12:15], v[158:161], v[146:149], v[12:15]
	v_mfma_f32_16x16x32_bf16 v[8:11], v[158:161], v[150:153], v[8:11]
	v_mfma_f32_16x16x32_bf16 v[4:7], v[158:161], v[162:165], v[4:7]
	v_mfma_f32_16x16x32_bf16 v[0:3], v[158:161], v[166:169], v[0:3]
	s_setprio 0
	v_add_u32_e32 v158, v170, v137
	v_add_u32_e32 v166, v171, v137
	ds_read_b128 v[138:141], v158
	ds_read_b128 v[142:145], v158 offset:2048
	ds_read_b128 v[146:149], v166 offset:16384
	ds_read_b128 v[150:153], v166 offset:18432
	ds_read_b128 v[154:157], v158 offset:4096
	ds_read_b128 v[158:161], v158 offset:6144
	ds_read_b128 v[162:165], v166 offset:20480
	ds_read_b128 v[166:169], v166 offset:22528
	s_setprio 1
	s_waitcnt lgkmcnt(0)
	v_mfma_f32_16x16x32_bf16 v[60:63], v[138:141], v[146:149], v[60:63]
	v_mfma_f32_16x16x32_bf16 v[56:59], v[138:141], v[150:153], v[56:59]
	v_mfma_f32_16x16x32_bf16 v[52:55], v[138:141], v[162:165], v[52:55]
	v_mfma_f32_16x16x32_bf16 v[48:51], v[138:141], v[166:169], v[48:51]
	v_mfma_f32_16x16x32_bf16 v[44:47], v[142:145], v[146:149], v[44:47]
	v_mfma_f32_16x16x32_bf16 v[40:43], v[142:145], v[150:153], v[40:43]
	v_mfma_f32_16x16x32_bf16 v[36:39], v[142:145], v[162:165], v[36:39]
	v_mfma_f32_16x16x32_bf16 v[32:35], v[142:145], v[166:169], v[32:35]
	v_mfma_f32_16x16x32_bf16 v[28:31], v[154:157], v[146:149], v[28:31]
	v_mfma_f32_16x16x32_bf16 v[24:27], v[154:157], v[150:153], v[24:27]
	v_mfma_f32_16x16x32_bf16 v[20:23], v[154:157], v[162:165], v[20:23]
	v_mfma_f32_16x16x32_bf16 v[16:19], v[154:157], v[166:169], v[16:19]
	v_mfma_f32_16x16x32_bf16 v[12:15], v[158:161], v[146:149], v[12:15]
	v_mfma_f32_16x16x32_bf16 v[8:11], v[158:161], v[150:153], v[8:11]
	v_mfma_f32_16x16x32_bf16 v[4:7], v[158:161], v[162:165], v[4:7]
	v_mfma_f32_16x16x32_bf16 v[0:3], v[158:161], v[166:169], v[0:3]
	s_setprio 0
	s_cmpk_eq_i32 s8, 0x780
	s_waitcnt vmcnt(0)
	s_barrier
	s_cbranch_scc0 .LBB0_3231
	ds_read_b128 v[88:91], v116 offset:55296
	ds_read_b128 v[92:95], v116 offset:53248
	ds_read_b128 v[96:99], v117 offset:38912
	ds_read_b128 v[100:103], v117 offset:36864
	ds_read_b128 v[138:141], v116 offset:51200
	ds_read_b128 v[142:145], v116 offset:49152
	ds_read_b128 v[146:149], v117 offset:34816
	ds_read_b128 v[150:153], v117 offset:32768
	s_setprio 1
	s_waitcnt lgkmcnt(5)
	v_mfma_f32_16x16x32_bf16 v[4:7], v[96:99], v[92:95], v[4:7]
	v_mfma_f32_16x16x32_bf16 v[0:3], v[96:99], v[88:91], v[0:3]
	s_waitcnt lgkmcnt(0)
	v_mfma_f32_16x16x32_bf16 v[60:63], v[150:153], v[142:145], v[60:63]
	v_mfma_f32_16x16x32_bf16 v[56:59], v[150:153], v[138:141], v[56:59]
	v_mfma_f32_16x16x32_bf16 v[52:55], v[150:153], v[92:95], v[52:55]
	v_mfma_f32_16x16x32_bf16 v[48:51], v[150:153], v[88:91], v[48:51]
	v_mfma_f32_16x16x32_bf16 v[44:47], v[146:149], v[142:145], v[44:47]
	v_mfma_f32_16x16x32_bf16 v[40:43], v[146:149], v[138:141], v[40:43]
	v_mfma_f32_16x16x32_bf16 v[36:39], v[146:149], v[92:95], v[36:39]
	v_mfma_f32_16x16x32_bf16 v[32:35], v[146:149], v[88:91], v[32:35]
	v_mfma_f32_16x16x32_bf16 v[28:31], v[100:103], v[142:145], v[28:31]
	v_mfma_f32_16x16x32_bf16 v[24:27], v[100:103], v[138:141], v[24:27]
	v_mfma_f32_16x16x32_bf16 v[20:23], v[100:103], v[92:95], v[20:23]
	v_mfma_f32_16x16x32_bf16 v[16:19], v[100:103], v[88:91], v[16:19]
	v_mfma_f32_16x16x32_bf16 v[12:15], v[96:99], v[142:145], v[12:15]
	v_mfma_f32_16x16x32_bf16 v[8:11], v[96:99], v[138:141], v[8:11]
	s_setprio 0
	ds_read_b128 v[88:91], v118 offset:32768
	ds_read_b128 v[92:95], v118 offset:34816
	ds_read_b128 v[96:99], v119 offset:49152
	ds_read_b128 v[100:103], v119 offset:51200
	ds_read_b128 v[138:141], v118 offset:36864
	ds_read_b128 v[142:145], v118 offset:38912
	ds_read_b128 v[146:149], v119 offset:53248
	ds_read_b128 v[150:153], v119 offset:55296
	s_setprio 1
	s_waitcnt lgkmcnt(1)
	v_mfma_f32_16x16x32_bf16 v[4:7], v[142:145], v[146:149], v[4:7]
	s_waitcnt lgkmcnt(0)
	v_mfma_f32_16x16x32_bf16 v[0:3], v[142:145], v[150:153], v[0:3]
	v_mfma_f32_16x16x32_bf16 v[60:63], v[88:91], v[96:99], v[60:63]
	v_mfma_f32_16x16x32_bf16 v[56:59], v[88:91], v[100:103], v[56:59]
	v_mfma_f32_16x16x32_bf16 v[52:55], v[88:91], v[146:149], v[52:55]
	v_mfma_f32_16x16x32_bf16 v[48:51], v[88:91], v[150:153], v[48:51]
	v_mfma_f32_16x16x32_bf16 v[44:47], v[92:95], v[96:99], v[44:47]
	v_mfma_f32_16x16x32_bf16 v[40:43], v[92:95], v[100:103], v[40:43]
	v_mfma_f32_16x16x32_bf16 v[36:39], v[92:95], v[146:149], v[36:39]
	v_mfma_f32_16x16x32_bf16 v[32:35], v[92:95], v[150:153], v[32:35]
	v_mfma_f32_16x16x32_bf16 v[28:31], v[138:141], v[96:99], v[28:31]
	v_mfma_f32_16x16x32_bf16 v[24:27], v[138:141], v[100:103], v[24:27]
	v_mfma_f32_16x16x32_bf16 v[20:23], v[138:141], v[146:149], v[20:23]
	v_mfma_f32_16x16x32_bf16 v[16:19], v[138:141], v[150:153], v[16:19]
	v_mfma_f32_16x16x32_bf16 v[12:15], v[142:145], v[96:99], v[12:15]
	v_mfma_f32_16x16x32_bf16 v[8:11], v[142:145], v[100:103], v[8:11]
	s_setprio 0
	s_barrier
	ds_write2_b32 v114, v60, v56 offset1:16
	ds_write2_b32 v114, v61, v57 offset0:132 offset1:148
	v_add_u32_e32 v56, 0x400, v114
	ds_write2_b32 v56, v62, v58 offset0:8 offset1:24
	ds_write2_b32 v56, v63, v59 offset0:140 offset1:156
	ds_write2_b32 v114, v52, v48 offset0:32 offset1:48
	ds_write2_b32 v114, v53, v49 offset0:164 offset1:180
	ds_write2_b32 v56, v54, v50 offset0:40 offset1:56
	ds_write2_b32 v56, v55, v51 offset0:172 offset1:188
	v_add_u32_e32 v48, 0x2000, v114
	ds_write2_b32 v48, v44, v40 offset0:64 offset1:80
	ds_write2_b32 v48, v45, v41 offset0:196 offset1:212
	v_add_u32_e32 v40, 0x2400, v114
	ds_write2_b32 v40, v46, v42 offset0:72 offset1:88
	ds_write2_b32 v40, v47, v43 offset0:204 offset1:220
	ds_write2_b32 v48, v36, v32 offset0:96 offset1:112
	ds_write2_b32 v48, v37, v33 offset0:228 offset1:244
	ds_write2_b32 v40, v38, v34 offset0:104 offset1:120
	ds_write2_b32 v40, v39, v35 offset0:236 offset1:252
	v_add_u32_e32 v32, 0x4000, v114
	ds_write2_b32 v32, v28, v24 offset0:128 offset1:144
	v_add_u32_e32 v24, 0x4400, v114
	ds_write2_b32 v24, v29, v25 offset0:4 offset1:20
	ds_write2_b32 v24, v30, v26 offset0:136 offset1:152
	v_add_u32_e32 v25, 0x4800, v114
	ds_write2_b32 v25, v31, v27 offset0:12 offset1:28
	ds_write2_b32 v32, v20, v16 offset0:160 offset1:176
	ds_write2_b32 v24, v21, v17 offset0:36 offset1:52
	ds_write2_b32 v24, v22, v18 offset0:168 offset1:184
	ds_write2_b32 v25, v23, v19 offset0:44 offset1:60
	v_add_u32_e32 v16, 0x6000, v114
	ds_write2_b32 v16, v12, v8 offset0:192 offset1:208
	v_add_u32_e32 v8, 0x6400, v114
	ds_write2_b32 v8, v13, v9 offset0:68 offset1:84
	ds_write2_b32 v8, v14, v10 offset0:200 offset1:216
	v_add_u32_e32 v9, 0x6800, v114
	ds_write2_b32 v9, v15, v11 offset0:76 offset1:92
	ds_write2_b32 v16, v4, v0 offset0:224 offset1:240
	ds_write2_b32 v8, v5, v1 offset0:100 offset1:116
	ds_write2_b32 v8, v6, v2 offset0:232 offset1:248
	ds_write2_b32 v9, v7, v3 offset0:108 offset1:124
	v_or_b32_e32 v0, s21, v115
	v_ashrrev_i32_e32 v1, 31, v0
	v_lshlrev_b64 v[2:3], 2, v[0:1]
	v_lshl_add_u64 v[0:1], s[10:11], 0, v[2:3]
	v_lshl_add_u64 v[2:3], s[6:7], 0, v[2:3]
	v_add_u32_e32 v4, s20, v128
	s_mov_b32 s8, 0
	s_waitcnt lgkmcnt(0)
	s_barrier

.LBB0_3388:
	s_and_b32 s20, s19, 0x4000
	s_xor_b32 s21, s20, 0x4000
	s_lshl_b32 s21, s21, 1
	s_add_i32 s21, s21, 32
	s_add_u32 s90, s52, s12
	s_addc_u32 s91, s53, s13
	s_add_i32 m0, s21, s82
	s_lshl_b32 s20, s20, 1
	global_load_lds_dwordx4 v184, s[90:91]
	s_add_i32 m0, s21, s83
	s_add_i32 s20, s20, 32
	global_load_lds_dwordx4 v185, s[90:91]
	s_add_i32 m0, s21, s84
	v_lshl_add_u32 v170, v114, 1, s20
	global_load_lds_dwordx4 v186, s[90:91]
	s_add_i32 m0, s21, s85
	v_lshl_add_u32 v171, v115, 1, s20
	global_load_lds_dwordx4 v187, s[90:91]
	s_add_i32 m0, s21, s86
	v_add_u32_e32 v158, v170, v136
	global_load_lds_dwordx4 v188, s[90:91]
	s_add_i32 m0, s21, s87
	v_add_u32_e32 v166, v171, v136
	global_load_lds_dwordx4 v189, s[90:91]
	s_add_i32 m0, s21, s88
	s_addk_i32 s19, 0x4000
	global_load_lds_dwordx4 v190, s[90:91]
	s_add_i32 m0, s21, s89
	s_add_u32 s12, s12, 0x80
	s_addc_u32 s13, s13, 0
	global_load_lds_dwordx4 v191, s[90:91]
	ds_read_b128 v[138:141], v158
	ds_read_b128 v[142:145], v158 offset:2048
	ds_read_b128 v[146:149], v166 offset:16384
	ds_read_b128 v[150:153], v166 offset:18432
	ds_read_b128 v[154:157], v158 offset:4096
	ds_read_b128 v[158:161], v158 offset:6144
	ds_read_b128 v[162:165], v166 offset:20480
	ds_read_b128 v[166:169], v166 offset:22528
	s_setprio 1
	s_waitcnt lgkmcnt(0)
	v_mfma_f32_16x16x32_bf16 v[60:63], v[138:141], v[146:149], v[60:63]
	v_mfma_f32_16x16x32_bf16 v[56:59], v[138:141], v[150:153], v[56:59]
	v_mfma_f32_16x16x32_bf16 v[52:55], v[138:141], v[162:165], v[52:55]
	v_mfma_f32_16x16x32_bf16 v[48:51], v[138:141], v[166:169], v[48:51]
	v_mfma_f32_16x16x32_bf16 v[44:47], v[142:145], v[146:149], v[44:47]
	v_mfma_f32_16x16x32_bf16 v[40:43], v[142:145], v[150:153], v[40:43]
	v_mfma_f32_16x16x32_bf16 v[36:39], v[142:145], v[162:165], v[36:39]
	v_mfma_f32_16x16x32_bf16 v[32:35], v[142:145], v[166:169], v[32:35]
	v_mfma_f32_16x16x32_bf16 v[28:31], v[154:157], v[146:149], v[28:31]
	v_mfma_f32_16x16x32_bf16 v[24:27], v[154:157], v[150:153], v[24:27]
	v_mfma_f32_16x16x32_bf16 v[20:23], v[154:157], v[162:165], v[20:23]
	v_mfma_f32_16x16x32_bf16 v[16:19], v[154:157], v[166:169], v[16:19]
	v_mfma_f32_16x16x32_bf16 v[12:15], v[158:161], v[146:149], v[12:15]
	v_mfma_f32_16x16x32_bf16 v[8:11], v[158:161], v[150:153], v[8:11]
	v_mfma_f32_16x16x32_bf16 v[4:7], v[158:161], v[162:165], v[4:7]
	v_mfma_f32_16x16x32_bf16 v[0:3], v[158:161], v[166:169], v[0:3]
	s_setprio 0
	v_add_u32_e32 v158, v170, v137
	v_add_u32_e32 v166, v171, v137
	ds_read_b128 v[138:141], v158
	ds_read_b128 v[142:145], v158 offset:2048
	ds_read_b128 v[146:149], v166 offset:16384
	ds_read_b128 v[150:153], v166 offset:18432
	ds_read_b128 v[154:157], v158 offset:4096
	ds_read_b128 v[158:161], v158 offset:6144
	ds_read_b128 v[162:165], v166 offset:20480
	ds_read_b128 v[166:169], v166 offset:22528
	s_setprio 1
	s_waitcnt lgkmcnt(0)
	v_mfma_f32_16x16x32_bf16 v[60:63], v[138:141], v[146:149], v[60:63]
	v_mfma_f32_16x16x32_bf16 v[56:59], v[138:141], v[150:153], v[56:59]
	v_mfma_f32_16x16x32_bf16 v[52:55], v[138:141], v[162:165], v[52:55]
	v_mfma_f32_16x16x32_bf16 v[48:51], v[138:141], v[166:169], v[48:51]
	v_mfma_f32_16x16x32_bf16 v[44:47], v[142:145], v[146:149], v[44:47]
	v_mfma_f32_16x16x32_bf16 v[40:43], v[142:145], v[150:153], v[40:43]
	v_mfma_f32_16x16x32_bf16 v[36:39], v[142:145], v[162:165], v[36:39]
	v_mfma_f32_16x16x32_bf16 v[32:35], v[142:145], v[166:169], v[32:35]
	v_mfma_f32_16x16x32_bf16 v[28:31], v[154:157], v[146:149], v[28:31]
	v_mfma_f32_16x16x32_bf16 v[24:27], v[154:157], v[150:153], v[24:27]
	v_mfma_f32_16x16x32_bf16 v[20:23], v[154:157], v[162:165], v[20:23]
	v_mfma_f32_16x16x32_bf16 v[16:19], v[154:157], v[166:169], v[16:19]
	v_mfma_f32_16x16x32_bf16 v[12:15], v[158:161], v[146:149], v[12:15]
	v_mfma_f32_16x16x32_bf16 v[8:11], v[158:161], v[150:153], v[8:11]
	v_mfma_f32_16x16x32_bf16 v[4:7], v[158:161], v[162:165], v[4:7]
	v_mfma_f32_16x16x32_bf16 v[0:3], v[158:161], v[166:169], v[0:3]
	s_setprio 0
	s_cmpk_eq_i32 s12, 0x780
	s_waitcnt vmcnt(0)
	s_barrier
	s_cbranch_scc0 .LBB0_3388
	ds_read_b128 v[90:93], v116 offset:55296
	ds_read_b128 v[94:97], v116 offset:53248
	ds_read_b128 v[98:101], v117 offset:38912
	ds_read_b128 v[102:105], v117 offset:36864
	ds_read_b128 v[138:141], v116 offset:51200
	ds_read_b128 v[142:145], v116 offset:49152
	ds_read_b128 v[146:149], v117 offset:34816
	ds_read_b128 v[150:153], v117 offset:32768
	s_setprio 1
	s_waitcnt lgkmcnt(5)
	v_mfma_f32_16x16x32_bf16 v[0:3], v[98:101], v[90:93], v[0:3]
	s_waitcnt lgkmcnt(0)
	v_mfma_f32_16x16x32_bf16 v[60:63], v[150:153], v[142:145], v[60:63]
	v_mfma_f32_16x16x32_bf16 v[56:59], v[150:153], v[138:141], v[56:59]
	v_mfma_f32_16x16x32_bf16 v[52:55], v[150:153], v[94:97], v[52:55]
	v_mfma_f32_16x16x32_bf16 v[48:51], v[150:153], v[90:93], v[48:51]
	v_mfma_f32_16x16x32_bf16 v[44:47], v[146:149], v[142:145], v[44:47]
	v_mfma_f32_16x16x32_bf16 v[40:43], v[146:149], v[138:141], v[40:43]
	v_mfma_f32_16x16x32_bf16 v[36:39], v[146:149], v[94:97], v[36:39]
	v_mfma_f32_16x16x32_bf16 v[32:35], v[146:149], v[90:93], v[32:35]
	v_mfma_f32_16x16x32_bf16 v[28:31], v[102:105], v[142:145], v[28:31]
	v_mfma_f32_16x16x32_bf16 v[24:27], v[102:105], v[138:141], v[24:27]
	v_mfma_f32_16x16x32_bf16 v[20:23], v[102:105], v[94:97], v[20:23]
	v_mfma_f32_16x16x32_bf16 v[16:19], v[102:105], v[90:93], v[16:19]
	v_mfma_f32_16x16x32_bf16 v[12:15], v[98:101], v[142:145], v[12:15]
	v_mfma_f32_16x16x32_bf16 v[8:11], v[98:101], v[138:141], v[8:11]
	v_mfma_f32_16x16x32_bf16 v[4:7], v[98:101], v[94:97], v[4:7]
	s_setprio 0
	ds_read_b128 v[90:93], v118 offset:32768
	ds_read_b128 v[94:97], v118 offset:34816
	ds_read_b128 v[98:101], v119 offset:49152
	ds_read_b128 v[102:105], v119 offset:51200
	ds_read_b128 v[138:141], v118 offset:36864
	ds_read_b128 v[142:145], v118 offset:38912
	ds_read_b128 v[146:149], v119 offset:53248
	ds_read_b128 v[150:153], v119 offset:55296
	s_setprio 1
	s_waitcnt lgkmcnt(0)
	v_mfma_f32_16x16x32_bf16 v[0:3], v[142:145], v[150:153], v[0:3]
	v_mfma_f32_16x16x32_bf16 v[60:63], v[90:93], v[98:101], v[60:63]
	v_mfma_f32_16x16x32_bf16 v[56:59], v[90:93], v[102:105], v[56:59]
	v_mfma_f32_16x16x32_bf16 v[52:55], v[90:93], v[146:149], v[52:55]
	v_mfma_f32_16x16x32_bf16 v[48:51], v[90:93], v[150:153], v[48:51]
	v_mfma_f32_16x16x32_bf16 v[44:47], v[94:97], v[98:101], v[44:47]
	v_mfma_f32_16x16x32_bf16 v[40:43], v[94:97], v[102:105], v[40:43]
	v_mfma_f32_16x16x32_bf16 v[36:39], v[94:97], v[146:149], v[36:39]
	v_mfma_f32_16x16x32_bf16 v[32:35], v[94:97], v[150:153], v[32:35]
	v_mfma_f32_16x16x32_bf16 v[28:31], v[138:141], v[98:101], v[28:31]
	v_mfma_f32_16x16x32_bf16 v[24:27], v[138:141], v[102:105], v[24:27]
	v_mfma_f32_16x16x32_bf16 v[20:23], v[138:141], v[146:149], v[20:23]
	v_mfma_f32_16x16x32_bf16 v[16:19], v[138:141], v[150:153], v[16:19]
	v_mfma_f32_16x16x32_bf16 v[12:15], v[142:145], v[98:101], v[12:15]
	v_mfma_f32_16x16x32_bf16 v[8:11], v[142:145], v[102:105], v[8:11]
	v_mfma_f32_16x16x32_bf16 v[4:7], v[142:145], v[146:149], v[4:7]
	s_setprio 0
	s_barrier
	ds_write2_b32 v120, v60, v56 offset1:16
	ds_write2_b32 v120, v61, v57 offset0:132 offset1:148
	v_add_u32_e32 v56, 0x400, v120
	ds_write2_b32 v56, v62, v58 offset0:8 offset1:24
	ds_write2_b32 v56, v63, v59 offset0:140 offset1:156
	ds_write2_b32 v120, v52, v48 offset0:32 offset1:48
	ds_write2_b32 v120, v53, v49 offset0:164 offset1:180
	ds_write2_b32 v56, v54, v50 offset0:40 offset1:56
	ds_write2_b32 v56, v55, v51 offset0:172 offset1:188
	v_add_u32_e32 v48, 0x2000, v120
	ds_write2_b32 v48, v44, v40 offset0:64 offset1:80
	ds_write2_b32 v48, v45, v41 offset0:196 offset1:212
	v_add_u32_e32 v40, 0x2400, v120
	ds_write2_b32 v40, v46, v42 offset0:72 offset1:88
	ds_write2_b32 v40, v47, v43 offset0:204 offset1:220
	ds_write2_b32 v48, v36, v32 offset0:96 offset1:112
	ds_write2_b32 v48, v37, v33 offset0:228 offset1:244
	ds_write2_b32 v40, v38, v34 offset0:104 offset1:120
	ds_write2_b32 v40, v39, v35 offset0:236 offset1:252
	v_add_u32_e32 v32, 0x4000, v120
	ds_write2_b32 v32, v28, v24 offset0:128 offset1:144
	v_add_u32_e32 v24, 0x4400, v120
	ds_write2_b32 v24, v29, v25 offset0:4 offset1:20
	ds_write2_b32 v24, v30, v26 offset0:136 offset1:152
	v_add_u32_e32 v25, 0x4800, v120
	ds_write2_b32 v25, v31, v27 offset0:12 offset1:28
	ds_write2_b32 v32, v20, v16 offset0:160 offset1:176
	ds_write2_b32 v24, v21, v17 offset0:36 offset1:52
	ds_write2_b32 v24, v22, v18 offset0:168 offset1:184
	ds_write2_b32 v25, v23, v19 offset0:44 offset1:60
	v_add_u32_e32 v16, 0x6000, v120
	ds_write2_b32 v16, v12, v8 offset0:192 offset1:208
	v_add_u32_e32 v8, 0x6400, v120
	ds_write2_b32 v8, v13, v9 offset0:68 offset1:84
	ds_write2_b32 v8, v14, v10 offset0:200 offset1:216
	v_add_u32_e32 v9, 0x6800, v120
	ds_write2_b32 v9, v15, v11 offset0:76 offset1:92
	ds_write2_b32 v16, v4, v0 offset0:224 offset1:240
	ds_write2_b32 v8, v5, v1 offset0:100 offset1:116
	ds_write2_b32 v8, v6, v2 offset0:232 offset1:248
	ds_write2_b32 v9, v7, v3 offset0:108 offset1:124
	v_or_b32_e32 v0, s18, v121
	v_ashrrev_i32_e32 v1, 31, v0
	v_lshl_add_u64 v[0:1], v[0:1], 1, s[6:7]
	v_add_u32_e32 v2, s17, v129
	s_mov_b32 s12, 0
	s_waitcnt lgkmcnt(0)
	s_barrier

.LBB0_3399:
	s_and_b32 s18, s17, 0x4000
	s_xor_b32 s19, s18, 0x4000
	s_lshl_b32 s19, s19, 1
	s_add_i32 s19, s19, 32
	s_add_u32 s90, s52, s8
	s_addc_u32 s91, s53, s9
	s_add_i32 m0, s19, s82
	s_lshl_b32 s18, s18, 1
	global_load_lds_dwordx4 v184, s[90:91]
	s_add_i32 m0, s19, s83
	s_add_i32 s18, s18, 32
	global_load_lds_dwordx4 v185, s[90:91]
	s_add_i32 m0, s19, s84
	v_lshl_add_u32 v168, v112, 1, s18
	global_load_lds_dwordx4 v186, s[90:91]
	s_add_i32 m0, s19, s85
	v_lshl_add_u32 v169, v113, 1, s18
	global_load_lds_dwordx4 v187, s[90:91]
	s_add_i32 m0, s19, s86
	v_add_u32_e32 v156, v168, v134
	global_load_lds_dwordx4 v188, s[90:91]
	s_add_i32 m0, s19, s87
	v_add_u32_e32 v164, v169, v134
	global_load_lds_dwordx4 v189, s[90:91]
	s_add_i32 m0, s19, s88
	s_addk_i32 s17, 0x4000
	global_load_lds_dwordx4 v190, s[90:91]
	s_add_i32 m0, s19, s89
	s_add_u32 s8, s8, 0x80
	s_addc_u32 s9, s9, 0
	global_load_lds_dwordx4 v191, s[90:91]
	ds_read_b128 v[136:139], v156
	ds_read_b128 v[140:143], v156 offset:2048
	ds_read_b128 v[144:147], v164 offset:16384
	ds_read_b128 v[148:151], v164 offset:18432
	ds_read_b128 v[152:155], v156 offset:4096
	ds_read_b128 v[156:159], v156 offset:6144
	ds_read_b128 v[160:163], v164 offset:20480
	ds_read_b128 v[164:167], v164 offset:22528
	s_setprio 1
	s_waitcnt lgkmcnt(0)
	v_mfma_f32_16x16x32_bf16 v[60:63], v[136:139], v[144:147], v[60:63]
	v_mfma_f32_16x16x32_bf16 v[56:59], v[136:139], v[148:151], v[56:59]
	v_mfma_f32_16x16x32_bf16 v[52:55], v[136:139], v[160:163], v[52:55]
	v_mfma_f32_16x16x32_bf16 v[48:51], v[136:139], v[164:167], v[48:51]
	v_mfma_f32_16x16x32_bf16 v[44:47], v[140:143], v[144:147], v[44:47]
	v_mfma_f32_16x16x32_bf16 v[40:43], v[140:143], v[148:151], v[40:43]
	v_mfma_f32_16x16x32_bf16 v[36:39], v[140:143], v[160:163], v[36:39]
	v_mfma_f32_16x16x32_bf16 v[32:35], v[140:143], v[164:167], v[32:35]
	v_mfma_f32_16x16x32_bf16 v[28:31], v[152:155], v[144:147], v[28:31]
	v_mfma_f32_16x16x32_bf16 v[24:27], v[152:155], v[148:151], v[24:27]
	v_mfma_f32_16x16x32_bf16 v[20:23], v[152:155], v[160:163], v[20:23]
	v_mfma_f32_16x16x32_bf16 v[16:19], v[152:155], v[164:167], v[16:19]
	v_mfma_f32_16x16x32_bf16 v[12:15], v[156:159], v[144:147], v[12:15]
	v_mfma_f32_16x16x32_bf16 v[8:11], v[156:159], v[148:151], v[8:11]
	v_mfma_f32_16x16x32_bf16 v[4:7], v[156:159], v[160:163], v[4:7]
	v_mfma_f32_16x16x32_bf16 v[0:3], v[156:159], v[164:167], v[0:3]
	s_setprio 0
	v_add_u32_e32 v156, v168, v135
	v_add_u32_e32 v164, v169, v135
	ds_read_b128 v[136:139], v156
	ds_read_b128 v[140:143], v156 offset:2048
	ds_read_b128 v[144:147], v164 offset:16384
	ds_read_b128 v[148:151], v164 offset:18432
	ds_read_b128 v[152:155], v156 offset:4096
	ds_read_b128 v[156:159], v156 offset:6144
	ds_read_b128 v[160:163], v164 offset:20480
	ds_read_b128 v[164:167], v164 offset:22528
	s_setprio 1
	s_waitcnt lgkmcnt(0)
	v_mfma_f32_16x16x32_bf16 v[60:63], v[136:139], v[144:147], v[60:63]
	v_mfma_f32_16x16x32_bf16 v[56:59], v[136:139], v[148:151], v[56:59]
	v_mfma_f32_16x16x32_bf16 v[52:55], v[136:139], v[160:163], v[52:55]
	v_mfma_f32_16x16x32_bf16 v[48:51], v[136:139], v[164:167], v[48:51]
	v_mfma_f32_16x16x32_bf16 v[44:47], v[140:143], v[144:147], v[44:47]
	v_mfma_f32_16x16x32_bf16 v[40:43], v[140:143], v[148:151], v[40:43]
	v_mfma_f32_16x16x32_bf16 v[36:39], v[140:143], v[160:163], v[36:39]
	v_mfma_f32_16x16x32_bf16 v[32:35], v[140:143], v[164:167], v[32:35]
	v_mfma_f32_16x16x32_bf16 v[28:31], v[152:155], v[144:147], v[28:31]
	v_mfma_f32_16x16x32_bf16 v[24:27], v[152:155], v[148:151], v[24:27]
	v_mfma_f32_16x16x32_bf16 v[20:23], v[152:155], v[160:163], v[20:23]
	v_mfma_f32_16x16x32_bf16 v[16:19], v[152:155], v[164:167], v[16:19]
	v_mfma_f32_16x16x32_bf16 v[12:15], v[156:159], v[144:147], v[12:15]
	v_mfma_f32_16x16x32_bf16 v[8:11], v[156:159], v[148:151], v[8:11]
	v_mfma_f32_16x16x32_bf16 v[4:7], v[156:159], v[160:163], v[4:7]
	v_mfma_f32_16x16x32_bf16 v[0:3], v[156:159], v[164:167], v[0:3]
	s_setprio 0
	s_cmpk_eq_i32 s8, 0x780
	s_waitcnt vmcnt(0)
	s_barrier
	s_cbranch_scc0 .LBB0_3399
	ds_read_b128 v[88:91], v114 offset:55296
	ds_read_b128 v[92:95], v114 offset:53248
	ds_read_b128 v[96:99], v115 offset:38912
	ds_read_b128 v[100:103], v115 offset:36864
	ds_read_b128 v[136:139], v114 offset:51200
	ds_read_b128 v[140:143], v114 offset:49152
	ds_read_b128 v[144:147], v115 offset:34816
	ds_read_b128 v[148:151], v115 offset:32768
	s_setprio 1
	s_waitcnt lgkmcnt(5)
	v_mfma_f32_16x16x32_bf16 v[0:3], v[96:99], v[88:91], v[0:3]
	s_waitcnt lgkmcnt(0)
	v_mfma_f32_16x16x32_bf16 v[60:63], v[148:151], v[140:143], v[60:63]
	v_mfma_f32_16x16x32_bf16 v[56:59], v[148:151], v[136:139], v[56:59]
	v_mfma_f32_16x16x32_bf16 v[52:55], v[148:151], v[92:95], v[52:55]
	v_mfma_f32_16x16x32_bf16 v[48:51], v[148:151], v[88:91], v[48:51]
	v_mfma_f32_16x16x32_bf16 v[44:47], v[144:147], v[140:143], v[44:47]
	v_mfma_f32_16x16x32_bf16 v[40:43], v[144:147], v[136:139], v[40:43]
	v_mfma_f32_16x16x32_bf16 v[36:39], v[144:147], v[92:95], v[36:39]
	v_mfma_f32_16x16x32_bf16 v[32:35], v[144:147], v[88:91], v[32:35]
	v_mfma_f32_16x16x32_bf16 v[28:31], v[100:103], v[140:143], v[28:31]
	v_mfma_f32_16x16x32_bf16 v[24:27], v[100:103], v[136:139], v[24:27]
	v_mfma_f32_16x16x32_bf16 v[20:23], v[100:103], v[92:95], v[20:23]
	v_mfma_f32_16x16x32_bf16 v[16:19], v[100:103], v[88:91], v[16:19]
	v_mfma_f32_16x16x32_bf16 v[12:15], v[96:99], v[140:143], v[12:15]
	v_mfma_f32_16x16x32_bf16 v[8:11], v[96:99], v[136:139], v[8:11]
	v_mfma_f32_16x16x32_bf16 v[4:7], v[96:99], v[92:95], v[4:7]
	s_setprio 0
	ds_read_b128 v[88:91], v116 offset:32768
	ds_read_b128 v[92:95], v116 offset:34816
	ds_read_b128 v[96:99], v117 offset:49152
	ds_read_b128 v[100:103], v117 offset:51200
	ds_read_b128 v[136:139], v116 offset:36864
	ds_read_b128 v[140:143], v116 offset:38912
	ds_read_b128 v[144:147], v117 offset:53248
	ds_read_b128 v[148:151], v117 offset:55296
	s_setprio 1
	s_waitcnt lgkmcnt(0)
	v_mfma_f32_16x16x32_bf16 v[0:3], v[140:143], v[148:151], v[0:3]
	v_mfma_f32_16x16x32_bf16 v[60:63], v[88:91], v[96:99], v[60:63]
	v_mfma_f32_16x16x32_bf16 v[56:59], v[88:91], v[100:103], v[56:59]
	v_mfma_f32_16x16x32_bf16 v[52:55], v[88:91], v[144:147], v[52:55]
	v_mfma_f32_16x16x32_bf16 v[48:51], v[88:91], v[148:151], v[48:51]
	v_mfma_f32_16x16x32_bf16 v[44:47], v[92:95], v[96:99], v[44:47]
	v_mfma_f32_16x16x32_bf16 v[40:43], v[92:95], v[100:103], v[40:43]
	v_mfma_f32_16x16x32_bf16 v[36:39], v[92:95], v[144:147], v[36:39]
	v_mfma_f32_16x16x32_bf16 v[32:35], v[92:95], v[148:151], v[32:35]
	v_mfma_f32_16x16x32_bf16 v[28:31], v[136:139], v[96:99], v[28:31]
	v_mfma_f32_16x16x32_bf16 v[24:27], v[136:139], v[100:103], v[24:27]
	v_mfma_f32_16x16x32_bf16 v[20:23], v[136:139], v[144:147], v[20:23]
	v_mfma_f32_16x16x32_bf16 v[16:19], v[136:139], v[148:151], v[16:19]
	v_mfma_f32_16x16x32_bf16 v[12:15], v[140:143], v[96:99], v[12:15]
	v_mfma_f32_16x16x32_bf16 v[8:11], v[140:143], v[100:103], v[8:11]
	v_mfma_f32_16x16x32_bf16 v[4:7], v[140:143], v[144:147], v[4:7]
	s_setprio 0
	s_barrier
	ds_write2_b32 v118, v60, v56 offset1:16
	ds_write2_b32 v118, v61, v57 offset0:132 offset1:148
	v_add_u32_e32 v56, 0x400, v118
	ds_write2_b32 v56, v62, v58 offset0:8 offset1:24
	ds_write2_b32 v56, v63, v59 offset0:140 offset1:156
	ds_write2_b32 v118, v52, v48 offset0:32 offset1:48
	ds_write2_b32 v118, v53, v49 offset0:164 offset1:180
	ds_write2_b32 v56, v54, v50 offset0:40 offset1:56
	ds_write2_b32 v56, v55, v51 offset0:172 offset1:188
	v_add_u32_e32 v48, 0x2000, v118
	ds_write2_b32 v48, v44, v40 offset0:64 offset1:80
	ds_write2_b32 v48, v45, v41 offset0:196 offset1:212
	v_add_u32_e32 v40, 0x2400, v118
	ds_write2_b32 v40, v46, v42 offset0:72 offset1:88
	ds_write2_b32 v40, v47, v43 offset0:204 offset1:220
	ds_write2_b32 v48, v36, v32 offset0:96 offset1:112
	ds_write2_b32 v48, v37, v33 offset0:228 offset1:244
	ds_write2_b32 v40, v38, v34 offset0:104 offset1:120
	ds_write2_b32 v40, v39, v35 offset0:236 offset1:252
	v_add_u32_e32 v32, 0x4000, v118
	ds_write2_b32 v32, v28, v24 offset0:128 offset1:144
	v_add_u32_e32 v24, 0x4400, v118
	ds_write2_b32 v24, v29, v25 offset0:4 offset1:20
	ds_write2_b32 v24, v30, v26 offset0:136 offset1:152
	v_add_u32_e32 v25, 0x4800, v118
	ds_write2_b32 v25, v31, v27 offset0:12 offset1:28
	ds_write2_b32 v32, v20, v16 offset0:160 offset1:176
	ds_write2_b32 v24, v21, v17 offset0:36 offset1:52
	ds_write2_b32 v24, v22, v18 offset0:168 offset1:184
	ds_write2_b32 v25, v23, v19 offset0:44 offset1:60
	v_add_u32_e32 v16, 0x6000, v118
	ds_write2_b32 v16, v12, v8 offset0:192 offset1:208
	v_add_u32_e32 v8, 0x6400, v118
	ds_write2_b32 v8, v13, v9 offset0:68 offset1:84
	ds_write2_b32 v8, v14, v10 offset0:200 offset1:216
	v_add_u32_e32 v9, 0x6800, v118
	ds_write2_b32 v9, v15, v11 offset0:76 offset1:92
	ds_write2_b32 v16, v4, v0 offset0:224 offset1:240
	ds_write2_b32 v8, v5, v1 offset0:100 offset1:116
	ds_write2_b32 v8, v6, v2 offset0:232 offset1:248
	ds_write2_b32 v9, v7, v3 offset0:108 offset1:124
	v_or_b32_e32 v0, s16, v119
	v_ashrrev_i32_e32 v1, 31, v0
	v_lshl_add_u64 v[0:1], v[0:1], 1, s[6:7]
	v_add_u32_e32 v2, s15, v127
	s_mov_b32 s8, 0
	s_waitcnt lgkmcnt(0)
	s_barrier

.LBB0_3463:
	s_and_b32 s27, s26, 0x4000
	s_xor_b32 s28, s27, 0x4000
	s_lshl_b32 s28, s28, 1
	s_add_i32 s28, s28, 32
	s_add_u32 s90, s52, s16
	s_addc_u32 s91, s53, s17
	s_add_i32 m0, s28, s82
	s_lshl_b32 s27, s27, 1
	global_load_lds_dwordx4 v184, s[90:91]
	s_add_i32 m0, s28, s83
	s_add_i32 s27, s27, 32
	global_load_lds_dwordx4 v185, s[90:91]
	s_add_i32 m0, s28, s84
	v_add3_u32 v139, s27, v114, v136
	global_load_lds_dwordx4 v186, s[90:91]
	s_add_i32 m0, s28, s85
	v_add3_u32 v172, s27, v115, v136
	global_load_lds_dwordx4 v187, s[90:91]
	s_add_i32 m0, s28, s86
	v_add_u32_e32 v160, v139, v137
	global_load_lds_dwordx4 v188, s[90:91]
	s_add_i32 m0, s28, s87
	v_add_u32_e32 v168, v172, v137
	global_load_lds_dwordx4 v189, s[90:91]
	s_add_i32 m0, s28, s88
	s_addk_i32 s26, 0x4000
	global_load_lds_dwordx4 v190, s[90:91]
	s_add_i32 m0, s28, s89
	s_add_u32 s16, s16, 0x80
	s_addc_u32 s17, s17, 0
	global_load_lds_dwordx4 v191, s[90:91]
	ds_read_b128 v[140:143], v160
	ds_read_b128 v[144:147], v160 offset:2048
	ds_read_b128 v[148:151], v168 offset:16384
	ds_read_b128 v[152:155], v168 offset:18432
	ds_read_b128 v[156:159], v160 offset:4096
	ds_read_b128 v[160:163], v160 offset:6144
	ds_read_b128 v[164:167], v168 offset:20480
	ds_read_b128 v[168:171], v168 offset:22528
	s_setprio 1
	s_waitcnt lgkmcnt(0)
	v_mfma_f32_16x16x32_bf16 v[60:63], v[140:143], v[148:151], v[60:63]
	v_mfma_f32_16x16x32_bf16 v[56:59], v[140:143], v[152:155], v[56:59]
	v_mfma_f32_16x16x32_bf16 v[52:55], v[140:143], v[164:167], v[52:55]
	v_mfma_f32_16x16x32_bf16 v[48:51], v[140:143], v[168:171], v[48:51]
	v_mfma_f32_16x16x32_bf16 v[44:47], v[144:147], v[148:151], v[44:47]
	v_mfma_f32_16x16x32_bf16 v[40:43], v[144:147], v[152:155], v[40:43]
	v_mfma_f32_16x16x32_bf16 v[36:39], v[144:147], v[164:167], v[36:39]
	v_mfma_f32_16x16x32_bf16 v[32:35], v[144:147], v[168:171], v[32:35]
	v_mfma_f32_16x16x32_bf16 v[28:31], v[156:159], v[148:151], v[28:31]
	v_mfma_f32_16x16x32_bf16 v[24:27], v[156:159], v[152:155], v[24:27]
	v_mfma_f32_16x16x32_bf16 v[20:23], v[156:159], v[164:167], v[20:23]
	v_mfma_f32_16x16x32_bf16 v[16:19], v[156:159], v[168:171], v[16:19]
	v_mfma_f32_16x16x32_bf16 v[12:15], v[160:163], v[148:151], v[12:15]
	v_mfma_f32_16x16x32_bf16 v[8:11], v[160:163], v[152:155], v[8:11]
	v_mfma_f32_16x16x32_bf16 v[4:7], v[160:163], v[164:167], v[4:7]
	v_mfma_f32_16x16x32_bf16 v[0:3], v[160:163], v[168:171], v[0:3]
	s_setprio 0
	v_add_u32_e32 v139, v139, v138
	v_add_u32_e32 v168, v172, v138
	ds_read_b128 v[140:143], v139
	ds_read_b128 v[144:147], v139 offset:2048
	ds_read_b128 v[148:151], v168 offset:16384
	ds_read_b128 v[152:155], v168 offset:18432
	ds_read_b128 v[156:159], v139 offset:4096
	ds_read_b128 v[160:163], v139 offset:6144
	ds_read_b128 v[164:167], v168 offset:20480
	ds_read_b128 v[168:171], v168 offset:22528
	s_setprio 1
	s_waitcnt lgkmcnt(0)
	v_mfma_f32_16x16x32_bf16 v[60:63], v[140:143], v[148:151], v[60:63]
	v_mfma_f32_16x16x32_bf16 v[56:59], v[140:143], v[152:155], v[56:59]
	v_mfma_f32_16x16x32_bf16 v[52:55], v[140:143], v[164:167], v[52:55]
	v_mfma_f32_16x16x32_bf16 v[48:51], v[140:143], v[168:171], v[48:51]
	v_mfma_f32_16x16x32_bf16 v[44:47], v[144:147], v[148:151], v[44:47]
	v_mfma_f32_16x16x32_bf16 v[40:43], v[144:147], v[152:155], v[40:43]
	v_mfma_f32_16x16x32_bf16 v[36:39], v[144:147], v[164:167], v[36:39]
	v_mfma_f32_16x16x32_bf16 v[32:35], v[144:147], v[168:171], v[32:35]
	v_mfma_f32_16x16x32_bf16 v[28:31], v[156:159], v[148:151], v[28:31]
	v_mfma_f32_16x16x32_bf16 v[24:27], v[156:159], v[152:155], v[24:27]
	v_mfma_f32_16x16x32_bf16 v[20:23], v[156:159], v[164:167], v[20:23]
	v_mfma_f32_16x16x32_bf16 v[16:19], v[156:159], v[168:171], v[16:19]
	v_mfma_f32_16x16x32_bf16 v[12:15], v[160:163], v[148:151], v[12:15]
	v_mfma_f32_16x16x32_bf16 v[8:11], v[160:163], v[152:155], v[8:11]
	v_mfma_f32_16x16x32_bf16 v[4:7], v[160:163], v[164:167], v[4:7]
	v_mfma_f32_16x16x32_bf16 v[0:3], v[160:163], v[168:171], v[0:3]
	s_setprio 0
	s_cmpk_eq_i32 s16, 0x1f80
	s_waitcnt vmcnt(0)
	s_barrier
	s_cbranch_scc0 .LBB0_3463
	ds_read_b128 v[90:93], v118 offset:55296
	ds_read_b128 v[94:97], v118 offset:53248
	ds_read_b128 v[98:101], v119 offset:38912
	ds_read_b128 v[102:105], v119 offset:36864
	ds_read_b128 v[140:143], v118 offset:51200
	ds_read_b128 v[144:147], v118 offset:49152
	ds_read_b128 v[148:151], v119 offset:34816
	ds_read_b128 v[152:155], v119 offset:32768
	s_setprio 1
	s_waitcnt lgkmcnt(5)
	v_mfma_f32_16x16x32_bf16 v[4:7], v[98:101], v[94:97], v[4:7]
	v_mfma_f32_16x16x32_bf16 v[0:3], v[98:101], v[90:93], v[0:3]
	s_waitcnt lgkmcnt(0)
	v_mfma_f32_16x16x32_bf16 v[60:63], v[152:155], v[144:147], v[60:63]
	v_mfma_f32_16x16x32_bf16 v[56:59], v[152:155], v[140:143], v[56:59]
	v_mfma_f32_16x16x32_bf16 v[52:55], v[152:155], v[94:97], v[52:55]
	v_mfma_f32_16x16x32_bf16 v[48:51], v[152:155], v[90:93], v[48:51]
	v_mfma_f32_16x16x32_bf16 v[44:47], v[148:151], v[144:147], v[44:47]
	v_mfma_f32_16x16x32_bf16 v[40:43], v[148:151], v[140:143], v[40:43]
	v_mfma_f32_16x16x32_bf16 v[36:39], v[148:151], v[94:97], v[36:39]
	v_mfma_f32_16x16x32_bf16 v[32:35], v[148:151], v[90:93], v[32:35]
	v_mfma_f32_16x16x32_bf16 v[28:31], v[102:105], v[144:147], v[28:31]
	v_mfma_f32_16x16x32_bf16 v[24:27], v[102:105], v[140:143], v[24:27]
	v_mfma_f32_16x16x32_bf16 v[20:23], v[102:105], v[94:97], v[20:23]
	v_mfma_f32_16x16x32_bf16 v[16:19], v[102:105], v[90:93], v[16:19]
	v_mfma_f32_16x16x32_bf16 v[12:15], v[98:101], v[144:147], v[12:15]
	v_mfma_f32_16x16x32_bf16 v[8:11], v[98:101], v[140:143], v[8:11]
	s_setprio 0
	ds_read_b128 v[90:93], v120 offset:32768
	ds_read_b128 v[94:97], v120 offset:34816
	ds_read_b128 v[98:101], v121 offset:49152
	ds_read_b128 v[102:105], v121 offset:51200
	ds_read_b128 v[140:143], v120 offset:36864
	ds_read_b128 v[144:147], v120 offset:38912
	ds_read_b128 v[148:151], v121 offset:53248
	ds_read_b128 v[152:155], v121 offset:55296
	s_setprio 1
	s_waitcnt lgkmcnt(1)
	v_mfma_f32_16x16x32_bf16 v[4:7], v[144:147], v[148:151], v[4:7]
	s_waitcnt lgkmcnt(0)
	v_mfma_f32_16x16x32_bf16 v[0:3], v[144:147], v[152:155], v[0:3]
	v_mfma_f32_16x16x32_bf16 v[60:63], v[90:93], v[98:101], v[60:63]
	v_mfma_f32_16x16x32_bf16 v[56:59], v[90:93], v[102:105], v[56:59]
	v_mfma_f32_16x16x32_bf16 v[52:55], v[90:93], v[148:151], v[52:55]
	v_mfma_f32_16x16x32_bf16 v[48:51], v[90:93], v[152:155], v[48:51]
	v_mfma_f32_16x16x32_bf16 v[44:47], v[94:97], v[98:101], v[44:47]
	v_mfma_f32_16x16x32_bf16 v[40:43], v[94:97], v[102:105], v[40:43]
	v_mfma_f32_16x16x32_bf16 v[36:39], v[94:97], v[148:151], v[36:39]
	v_mfma_f32_16x16x32_bf16 v[32:35], v[94:97], v[152:155], v[32:35]
	v_mfma_f32_16x16x32_bf16 v[28:31], v[140:143], v[98:101], v[28:31]
	v_mfma_f32_16x16x32_bf16 v[24:27], v[140:143], v[102:105], v[24:27]
	v_mfma_f32_16x16x32_bf16 v[20:23], v[140:143], v[148:151], v[20:23]
	v_mfma_f32_16x16x32_bf16 v[16:19], v[140:143], v[152:155], v[16:19]
	v_mfma_f32_16x16x32_bf16 v[12:15], v[144:147], v[98:101], v[12:15]
	v_mfma_f32_16x16x32_bf16 v[8:11], v[144:147], v[102:105], v[8:11]
	s_setprio 0
	s_barrier
	ds_write2_b32 v116, v60, v56 offset1:16
	ds_write2_b32 v116, v61, v57 offset0:132 offset1:148
	v_add_u32_e32 v56, 0x400, v116
	ds_write2_b32 v56, v62, v58 offset0:8 offset1:24
	ds_write2_b32 v56, v63, v59 offset0:140 offset1:156
	ds_write2_b32 v116, v52, v48 offset0:32 offset1:48
	ds_write2_b32 v116, v53, v49 offset0:164 offset1:180
	ds_write2_b32 v56, v54, v50 offset0:40 offset1:56
	ds_write2_b32 v56, v55, v51 offset0:172 offset1:188
	v_add_u32_e32 v48, 0x2000, v116
	ds_write2_b32 v48, v44, v40 offset0:64 offset1:80
	ds_write2_b32 v48, v45, v41 offset0:196 offset1:212
	v_add_u32_e32 v40, 0x2400, v116
	ds_write2_b32 v40, v46, v42 offset0:72 offset1:88
	ds_write2_b32 v40, v47, v43 offset0:204 offset1:220
	ds_write2_b32 v48, v36, v32 offset0:96 offset1:112
	ds_write2_b32 v48, v37, v33 offset0:228 offset1:244
	ds_write2_b32 v40, v38, v34 offset0:104 offset1:120
	ds_write2_b32 v40, v39, v35 offset0:236 offset1:252
	v_add_u32_e32 v32, 0x4000, v116
	ds_write2_b32 v32, v28, v24 offset0:128 offset1:144
	v_add_u32_e32 v24, 0x4400, v116
	ds_write2_b32 v24, v29, v25 offset0:4 offset1:20
	ds_write2_b32 v24, v30, v26 offset0:136 offset1:152
	v_add_u32_e32 v25, 0x4800, v116
	ds_write2_b32 v25, v31, v27 offset0:12 offset1:28
	ds_write2_b32 v32, v20, v16 offset0:160 offset1:176
	ds_write2_b32 v24, v21, v17 offset0:36 offset1:52
	ds_write2_b32 v24, v22, v18 offset0:168 offset1:184
	ds_write2_b32 v25, v23, v19 offset0:44 offset1:60
	v_add_u32_e32 v16, 0x6000, v116
	ds_write2_b32 v16, v12, v8 offset0:192 offset1:208
	v_add_u32_e32 v8, 0x6400, v116
	ds_write2_b32 v8, v13, v9 offset0:68 offset1:84
	ds_write2_b32 v8, v14, v10 offset0:200 offset1:216
	v_add_u32_e32 v9, 0x6800, v116
	ds_write2_b32 v9, v15, v11 offset0:76 offset1:92
	ds_write2_b32 v16, v4, v0 offset0:224 offset1:240
	ds_write2_b32 v8, v5, v1 offset0:100 offset1:116
	ds_write2_b32 v8, v6, v2 offset0:232 offset1:248
	ds_write2_b32 v9, v7, v3 offset0:108 offset1:124
	v_or_b32_e32 v0, s25, v117
	v_ashrrev_i32_e32 v1, 31, v0
	v_lshlrev_b64 v[2:3], 2, v[0:1]
	v_lshl_add_u64 v[0:1], s[14:15], 0, v[2:3]
	v_lshl_add_u64 v[2:3], s[6:7], 0, v[2:3]
	v_add_u32_e32 v4, s24, v129
	s_mov_b32 s16, 0
	s_waitcnt lgkmcnt(0)
	s_barrier

.LBB0_3472:
	s_and_b32 s23, s22, 0x4000
	s_xor_b32 s24, s23, 0x4000
	s_lshl_b32 s24, s24, 1
	s_add_i32 s24, s24, 32
	s_add_u32 s90, s52, s8
	s_addc_u32 s91, s53, s9
	s_add_i32 m0, s24, s82
	s_lshl_b32 s23, s23, 1
	global_load_lds_dwordx4 v184, s[90:91]
	s_add_i32 m0, s24, s83
	s_add_i32 s23, s23, 32
	global_load_lds_dwordx4 v185, s[90:91]
	s_add_i32 m0, s24, s84
	v_add3_u32 v170, s23, v112, v135
	global_load_lds_dwordx4 v186, s[90:91]
	s_add_i32 m0, s24, s85
	v_add3_u32 v171, s23, v113, v135
	global_load_lds_dwordx4 v187, s[90:91]
	s_add_i32 m0, s24, s86
	v_add_u32_e32 v158, v170, v136
	global_load_lds_dwordx4 v188, s[90:91]
	s_add_i32 m0, s24, s87
	v_add_u32_e32 v166, v171, v136
	global_load_lds_dwordx4 v189, s[90:91]
	s_add_i32 m0, s24, s88
	s_addk_i32 s22, 0x4000
	global_load_lds_dwordx4 v190, s[90:91]
	s_add_i32 m0, s24, s89
	s_add_u32 s8, s8, 0x80
	s_addc_u32 s9, s9, 0
	global_load_lds_dwordx4 v191, s[90:91]
	ds_read_b128 v[138:141], v158
	ds_read_b128 v[142:145], v158 offset:2048
	ds_read_b128 v[146:149], v166 offset:16384
	ds_read_b128 v[150:153], v166 offset:18432
	ds_read_b128 v[154:157], v158 offset:4096
	ds_read_b128 v[158:161], v158 offset:6144
	ds_read_b128 v[162:165], v166 offset:20480
	ds_read_b128 v[166:169], v166 offset:22528
	s_setprio 1
	s_waitcnt lgkmcnt(0)
	v_mfma_f32_16x16x32_bf16 v[60:63], v[138:141], v[146:149], v[60:63]
	v_mfma_f32_16x16x32_bf16 v[56:59], v[138:141], v[150:153], v[56:59]
	v_mfma_f32_16x16x32_bf16 v[52:55], v[138:141], v[162:165], v[52:55]
	v_mfma_f32_16x16x32_bf16 v[48:51], v[138:141], v[166:169], v[48:51]
	v_mfma_f32_16x16x32_bf16 v[44:47], v[142:145], v[146:149], v[44:47]
	v_mfma_f32_16x16x32_bf16 v[40:43], v[142:145], v[150:153], v[40:43]
	v_mfma_f32_16x16x32_bf16 v[36:39], v[142:145], v[162:165], v[36:39]
	v_mfma_f32_16x16x32_bf16 v[32:35], v[142:145], v[166:169], v[32:35]
	v_mfma_f32_16x16x32_bf16 v[28:31], v[154:157], v[146:149], v[28:31]
	v_mfma_f32_16x16x32_bf16 v[24:27], v[154:157], v[150:153], v[24:27]
	v_mfma_f32_16x16x32_bf16 v[20:23], v[154:157], v[162:165], v[20:23]
	v_mfma_f32_16x16x32_bf16 v[16:19], v[154:157], v[166:169], v[16:19]
	v_mfma_f32_16x16x32_bf16 v[12:15], v[158:161], v[146:149], v[12:15]
	v_mfma_f32_16x16x32_bf16 v[8:11], v[158:161], v[150:153], v[8:11]
	v_mfma_f32_16x16x32_bf16 v[4:7], v[158:161], v[162:165], v[4:7]
	v_mfma_f32_16x16x32_bf16 v[0:3], v[158:161], v[166:169], v[0:3]
	s_setprio 0
	v_add_u32_e32 v158, v170, v137
	v_add_u32_e32 v166, v171, v137
	ds_read_b128 v[138:141], v158
	ds_read_b128 v[142:145], v158 offset:2048
	ds_read_b128 v[146:149], v166 offset:16384
	ds_read_b128 v[150:153], v166 offset:18432
	ds_read_b128 v[154:157], v158 offset:4096
	ds_read_b128 v[158:161], v158 offset:6144
	ds_read_b128 v[162:165], v166 offset:20480
	ds_read_b128 v[166:169], v166 offset:22528
	s_setprio 1
	s_waitcnt lgkmcnt(0)
	v_mfma_f32_16x16x32_bf16 v[60:63], v[138:141], v[146:149], v[60:63]
	v_mfma_f32_16x16x32_bf16 v[56:59], v[138:141], v[150:153], v[56:59]
	v_mfma_f32_16x16x32_bf16 v[52:55], v[138:141], v[162:165], v[52:55]
	v_mfma_f32_16x16x32_bf16 v[48:51], v[138:141], v[166:169], v[48:51]
	v_mfma_f32_16x16x32_bf16 v[44:47], v[142:145], v[146:149], v[44:47]
	v_mfma_f32_16x16x32_bf16 v[40:43], v[142:145], v[150:153], v[40:43]
	v_mfma_f32_16x16x32_bf16 v[36:39], v[142:145], v[162:165], v[36:39]
	v_mfma_f32_16x16x32_bf16 v[32:35], v[142:145], v[166:169], v[32:35]
	v_mfma_f32_16x16x32_bf16 v[28:31], v[154:157], v[146:149], v[28:31]
	v_mfma_f32_16x16x32_bf16 v[24:27], v[154:157], v[150:153], v[24:27]
	v_mfma_f32_16x16x32_bf16 v[20:23], v[154:157], v[162:165], v[20:23]
	v_mfma_f32_16x16x32_bf16 v[16:19], v[154:157], v[166:169], v[16:19]
	v_mfma_f32_16x16x32_bf16 v[12:15], v[158:161], v[146:149], v[12:15]
	v_mfma_f32_16x16x32_bf16 v[8:11], v[158:161], v[150:153], v[8:11]
	v_mfma_f32_16x16x32_bf16 v[4:7], v[158:161], v[162:165], v[4:7]
	v_mfma_f32_16x16x32_bf16 v[0:3], v[158:161], v[166:169], v[0:3]
	s_setprio 0
	s_cmpk_eq_i32 s8, 0x1f80
	s_waitcnt vmcnt(0)
	s_barrier
	s_cbranch_scc0 .LBB0_3472
	ds_read_b128 v[88:91], v116 offset:55296
	ds_read_b128 v[92:95], v116 offset:53248
	ds_read_b128 v[96:99], v117 offset:38912
	ds_read_b128 v[100:103], v117 offset:36864
	ds_read_b128 v[138:141], v116 offset:51200
	ds_read_b128 v[142:145], v116 offset:49152
	ds_read_b128 v[146:149], v117 offset:34816
	ds_read_b128 v[150:153], v117 offset:32768
	s_setprio 1
	s_waitcnt lgkmcnt(5)
	v_mfma_f32_16x16x32_bf16 v[4:7], v[96:99], v[92:95], v[4:7]
	v_mfma_f32_16x16x32_bf16 v[0:3], v[96:99], v[88:91], v[0:3]
	s_waitcnt lgkmcnt(0)
	v_mfma_f32_16x16x32_bf16 v[60:63], v[150:153], v[142:145], v[60:63]
	v_mfma_f32_16x16x32_bf16 v[56:59], v[150:153], v[138:141], v[56:59]
	v_mfma_f32_16x16x32_bf16 v[52:55], v[150:153], v[92:95], v[52:55]
	v_mfma_f32_16x16x32_bf16 v[48:51], v[150:153], v[88:91], v[48:51]
	v_mfma_f32_16x16x32_bf16 v[44:47], v[146:149], v[142:145], v[44:47]
	v_mfma_f32_16x16x32_bf16 v[40:43], v[146:149], v[138:141], v[40:43]
	v_mfma_f32_16x16x32_bf16 v[36:39], v[146:149], v[92:95], v[36:39]
	v_mfma_f32_16x16x32_bf16 v[32:35], v[146:149], v[88:91], v[32:35]
	v_mfma_f32_16x16x32_bf16 v[28:31], v[100:103], v[142:145], v[28:31]
	v_mfma_f32_16x16x32_bf16 v[24:27], v[100:103], v[138:141], v[24:27]
	v_mfma_f32_16x16x32_bf16 v[20:23], v[100:103], v[92:95], v[20:23]
	v_mfma_f32_16x16x32_bf16 v[16:19], v[100:103], v[88:91], v[16:19]
	v_mfma_f32_16x16x32_bf16 v[12:15], v[96:99], v[142:145], v[12:15]
	v_mfma_f32_16x16x32_bf16 v[8:11], v[96:99], v[138:141], v[8:11]
	s_setprio 0
	ds_read_b128 v[88:91], v118 offset:32768
	ds_read_b128 v[92:95], v118 offset:34816
	ds_read_b128 v[96:99], v119 offset:49152
	ds_read_b128 v[100:103], v119 offset:51200
	ds_read_b128 v[138:141], v118 offset:36864
	ds_read_b128 v[142:145], v118 offset:38912
	ds_read_b128 v[146:149], v119 offset:53248
	ds_read_b128 v[150:153], v119 offset:55296
	s_setprio 1
	s_waitcnt lgkmcnt(1)
	v_mfma_f32_16x16x32_bf16 v[4:7], v[142:145], v[146:149], v[4:7]
	s_waitcnt lgkmcnt(0)
	v_mfma_f32_16x16x32_bf16 v[0:3], v[142:145], v[150:153], v[0:3]
	v_mfma_f32_16x16x32_bf16 v[60:63], v[88:91], v[96:99], v[60:63]
	v_mfma_f32_16x16x32_bf16 v[56:59], v[88:91], v[100:103], v[56:59]
	v_mfma_f32_16x16x32_bf16 v[52:55], v[88:91], v[146:149], v[52:55]
	v_mfma_f32_16x16x32_bf16 v[48:51], v[88:91], v[150:153], v[48:51]
	v_mfma_f32_16x16x32_bf16 v[44:47], v[92:95], v[96:99], v[44:47]
	v_mfma_f32_16x16x32_bf16 v[40:43], v[92:95], v[100:103], v[40:43]
	v_mfma_f32_16x16x32_bf16 v[36:39], v[92:95], v[146:149], v[36:39]
	v_mfma_f32_16x16x32_bf16 v[32:35], v[92:95], v[150:153], v[32:35]
	v_mfma_f32_16x16x32_bf16 v[28:31], v[138:141], v[96:99], v[28:31]
	v_mfma_f32_16x16x32_bf16 v[24:27], v[138:141], v[100:103], v[24:27]
	v_mfma_f32_16x16x32_bf16 v[20:23], v[138:141], v[146:149], v[20:23]
	v_mfma_f32_16x16x32_bf16 v[16:19], v[138:141], v[150:153], v[16:19]
	v_mfma_f32_16x16x32_bf16 v[12:15], v[142:145], v[96:99], v[12:15]
	v_mfma_f32_16x16x32_bf16 v[8:11], v[142:145], v[100:103], v[8:11]
	s_setprio 0
	s_barrier
	ds_write2_b32 v114, v60, v56 offset1:16
	ds_write2_b32 v114, v61, v57 offset0:132 offset1:148
	v_add_u32_e32 v56, 0x400, v114
	ds_write2_b32 v56, v62, v58 offset0:8 offset1:24
	ds_write2_b32 v56, v63, v59 offset0:140 offset1:156
	ds_write2_b32 v114, v52, v48 offset0:32 offset1:48
	ds_write2_b32 v114, v53, v49 offset0:164 offset1:180
	ds_write2_b32 v56, v54, v50 offset0:40 offset1:56
	ds_write2_b32 v56, v55, v51 offset0:172 offset1:188
	v_add_u32_e32 v48, 0x2000, v114
	ds_write2_b32 v48, v44, v40 offset0:64 offset1:80
	ds_write2_b32 v48, v45, v41 offset0:196 offset1:212
	v_add_u32_e32 v40, 0x2400, v114
	ds_write2_b32 v40, v46, v42 offset0:72 offset1:88
	ds_write2_b32 v40, v47, v43 offset0:204 offset1:220
	ds_write2_b32 v48, v36, v32 offset0:96 offset1:112
	ds_write2_b32 v48, v37, v33 offset0:228 offset1:244
	ds_write2_b32 v40, v38, v34 offset0:104 offset1:120
	ds_write2_b32 v40, v39, v35 offset0:236 offset1:252
	v_add_u32_e32 v32, 0x4000, v114
	ds_write2_b32 v32, v28, v24 offset0:128 offset1:144
	v_add_u32_e32 v24, 0x4400, v114
	ds_write2_b32 v24, v29, v25 offset0:4 offset1:20
	ds_write2_b32 v24, v30, v26 offset0:136 offset1:152
	v_add_u32_e32 v25, 0x4800, v114
	ds_write2_b32 v25, v31, v27 offset0:12 offset1:28
	ds_write2_b32 v32, v20, v16 offset0:160 offset1:176
	ds_write2_b32 v24, v21, v17 offset0:36 offset1:52
	ds_write2_b32 v24, v22, v18 offset0:168 offset1:184
	ds_write2_b32 v25, v23, v19 offset0:44 offset1:60
	v_add_u32_e32 v16, 0x6000, v114
	ds_write2_b32 v16, v12, v8 offset0:192 offset1:208
	v_add_u32_e32 v8, 0x6400, v114
	ds_write2_b32 v8, v13, v9 offset0:68 offset1:84
	ds_write2_b32 v8, v14, v10 offset0:200 offset1:216
	v_add_u32_e32 v9, 0x6800, v114
	ds_write2_b32 v9, v15, v11 offset0:76 offset1:92
	ds_write2_b32 v16, v4, v0 offset0:224 offset1:240
	ds_write2_b32 v8, v5, v1 offset0:100 offset1:116
	ds_write2_b32 v8, v6, v2 offset0:232 offset1:248
	ds_write2_b32 v9, v7, v3 offset0:108 offset1:124
	v_or_b32_e32 v0, s21, v115
	v_ashrrev_i32_e32 v1, 31, v0
	v_lshlrev_b64 v[2:3], 2, v[0:1]
	v_lshl_add_u64 v[0:1], s[10:11], 0, v[2:3]
	v_lshl_add_u64 v[2:3], s[6:7], 0, v[2:3]
	v_add_u32_e32 v4, s20, v128
	s_mov_b32 s8, 0
	s_waitcnt lgkmcnt(0)
	s_barrier
